# all 640 s_setprio flips deleted from GEMM K-loops (A/B of the per-segment priority flips); nothing else changed
# speedup vs baseline: 1.0103x; 1.0070x over previous
.LBB0_387:
	s_add_u32 s20, s50, 0x100
	s_addc_u32 s21, s51, 0
	s_waitcnt lgkmcnt(0)
	s_add_u32 s46, s48, 0x100
	s_addc_u32 s47, s49, 0
	s_barrier
	v_mfma_f32_16x16x32_bf16 v[32:35], v[16:19], v[76:79], 0
	v_mfma_f32_16x16x32_bf16 v[36:39], v[24:27], v[76:79], 0
	s_waitcnt lgkmcnt(0)
	v_mfma_f32_16x16x32_bf16 v[40:43], v[16:19], v[84:87], 0
	v_mfma_f32_16x16x32_bf16 v[44:47], v[24:27], v[84:87], 0
	v_mfma_f32_16x16x32_bf16 v[48:51], v[16:19], v[92:95], 0
	v_mfma_f32_16x16x32_bf16 v[52:55], v[24:27], v[92:95], 0
	v_mfma_f32_16x16x32_bf16 v[56:59], v[16:19], v[64:67], 0
	v_mfma_f32_16x16x32_bf16 v[60:63], v[24:27], v[64:67], 0
	v_mfma_f32_16x16x32_bf16 v[32:35], v[20:23], v[80:83], v[32:35]
	v_mfma_f32_16x16x32_bf16 v[36:39], v[28:31], v[80:83], v[36:39]
	v_mfma_f32_16x16x32_bf16 v[40:43], v[20:23], v[88:91], v[40:43]
	v_mfma_f32_16x16x32_bf16 v[44:47], v[28:31], v[88:91], v[44:47]
	v_mfma_f32_16x16x32_bf16 v[48:51], v[20:23], v[96:99], v[48:51]
	v_mfma_f32_16x16x32_bf16 v[52:55], v[28:31], v[96:99], v[52:55]
	v_mfma_f32_16x16x32_bf16 v[56:59], v[20:23], v[72:75], v[56:59]
	v_mfma_f32_16x16x32_bf16 v[60:63], v[28:31], v[72:75], v[60:63]
	v_mfma_f32_16x16x32_bf16 v[68:71], v[0:3], v[76:79], 0
	v_mfma_f32_16x16x32_bf16 v[76:79], v[8:11], v[76:79], 0
	v_mfma_f32_16x16x32_bf16 v[68:71], v[4:7], v[80:83], v[68:71]
	v_mfma_f32_16x16x32_bf16 v[76:79], v[12:15], v[80:83], v[76:79]
	v_mfma_f32_16x16x32_bf16 v[80:83], v[0:3], v[84:87], 0
	v_mfma_f32_16x16x32_bf16 v[84:87], v[8:11], v[84:87], 0
	v_mfma_f32_16x16x32_bf16 v[80:83], v[4:7], v[88:91], v[80:83]
	v_mfma_f32_16x16x32_bf16 v[84:87], v[12:15], v[88:91], v[84:87]
	v_mfma_f32_16x16x32_bf16 v[88:91], v[0:3], v[92:95], 0
	v_mfma_f32_16x16x32_bf16 v[92:95], v[8:11], v[92:95], 0
	v_mfma_f32_16x16x32_bf16 v[88:91], v[4:7], v[96:99], v[88:91]
	v_mfma_f32_16x16x32_bf16 v[92:95], v[12:15], v[96:99], v[92:95]
	v_mfma_f32_16x16x32_bf16 v[96:99], v[0:3], v[64:67], 0
	v_mfma_f32_16x16x32_bf16 v[64:67], v[8:11], v[64:67], 0
	v_mfma_f32_16x16x32_bf16 v[128:131], v[4:7], v[72:75], v[96:99]
	v_mfma_f32_16x16x32_bf16 v[132:135], v[12:15], v[72:75], v[64:67]
	s_barrier
	s_mov_b32 m0, s58
	ds_read_b128 v[112:115], v145 offset:16384
	ds_read_b128 v[116:119], v145 offset:17408
	ds_read_b128 v[104:107], v145 offset:18432
	ds_read_b128 v[108:111], v145 offset:19456
	ds_read_b128 v[96:99], v145 offset:20480
	ds_read_b128 v[100:103], v145 offset:21504
	ds_read_b128 v[64:67], v145 offset:22528
	ds_read_b128 v[72:75], v145 offset:23552
	s_nop 0
	global_load_lds_dwordx4 v139, s[46:47]
	s_mov_b32 m0, s59
	s_nop 0
	global_load_lds_dwordx4 v141, s[46:47]
	s_add_u32 s46, s48, 0x80100
	s_addc_u32 s47, s49, 0
	s_mov_b32 m0, s60
	s_and_b64 vcc, exec, s[44:45]
	global_load_lds_dwordx4 v139, s[46:47]
	s_mov_b32 m0, s61
	s_nop 0
	global_load_lds_dwordx4 v141, s[46:47]
	s_mov_b32 m0, s41
	s_mov_b64 s[46:47], -1
	global_load_lds_dwordx4 v138, s[20:21]
	s_mov_b32 m0, s62
	s_nop 0
	global_load_lds_dwordx4 v140, s[20:21]
	s_cbranch_vccz .LBB0_389
	s_waitcnt vmcnt(8)
	s_mov_b64 s[46:47], 0

.LBB0_391:
	s_ashr_i32 s9, s8, 31
	s_lshl_b64 s[20:21], s[8:9], 20
	s_add_u32 s44, s26, s20
	s_addc_u32 s45, s27, s21
	s_ashr_i32 s37, s36, 31
	s_lshl_b64 s[20:21], s[36:37], 20
	s_add_u32 s46, s17, s20
	s_addc_u32 s47, s24, s21
	s_add_u32 s52, s50, 0x180
	s_addc_u32 s53, s51, 0
	s_waitcnt lgkmcnt(0)
	s_and_b64 s[20:21], s[42:43], exec
	s_cselect_b32 s9, s47, s49
	s_cselect_b32 s12, s46, s48
	s_cselect_b32 s20, s45, s51
	s_cselect_b32 s21, s44, s50
	s_add_u32 s54, s48, 0x180
	s_addc_u32 s55, s49, 0
	s_barrier
	s_waitcnt lgkmcnt(0)
	v_mfma_f32_16x16x32_bf16 v[120:123], v[16:19], v[112:115], 0
	v_mfma_f32_16x16x32_bf16 v[148:151], v[20:23], v[116:119], v[120:123]
	v_mfma_f32_16x16x32_bf16 v[120:123], v[24:27], v[112:115], 0
	v_mfma_f32_16x16x32_bf16 v[152:155], v[28:31], v[116:119], v[120:123]
	v_mfma_f32_16x16x32_bf16 v[120:123], v[16:19], v[104:107], 0
	v_mfma_f32_16x16x32_bf16 v[156:159], v[20:23], v[108:111], v[120:123]
	v_mfma_f32_16x16x32_bf16 v[120:123], v[24:27], v[104:107], 0
	v_mfma_f32_16x16x32_bf16 v[160:163], v[28:31], v[108:111], v[120:123]
	v_mfma_f32_16x16x32_bf16 v[120:123], v[16:19], v[96:99], 0
	v_mfma_f32_16x16x32_bf16 v[16:19], v[16:19], v[64:67], 0
	v_mfma_f32_16x16x32_bf16 v[164:167], v[20:23], v[100:103], v[120:123]
	v_mfma_f32_16x16x32_bf16 v[120:123], v[24:27], v[96:99], 0
	v_mfma_f32_16x16x32_bf16 v[20:23], v[20:23], v[72:75], v[16:19]
	v_mfma_f32_16x16x32_bf16 v[16:19], v[24:27], v[64:67], 0
	v_mfma_f32_16x16x32_bf16 v[168:171], v[28:31], v[100:103], v[120:123]
	v_mfma_f32_16x16x32_bf16 v[28:31], v[28:31], v[72:75], v[16:19]
	v_mfma_f32_16x16x32_bf16 v[16:19], v[0:3], v[112:115], 0
	v_mfma_f32_16x16x32_bf16 v[172:175], v[4:7], v[116:119], v[16:19]
	v_mfma_f32_16x16x32_bf16 v[16:19], v[8:11], v[112:115], 0
	v_mfma_f32_16x16x32_bf16 v[176:179], v[12:15], v[116:119], v[16:19]
	v_mfma_f32_16x16x32_bf16 v[16:19], v[0:3], v[104:107], 0
	v_mfma_f32_16x16x32_bf16 v[180:183], v[4:7], v[108:111], v[16:19]
	v_mfma_f32_16x16x32_bf16 v[16:19], v[8:11], v[104:107], 0
	v_mfma_f32_16x16x32_bf16 v[184:187], v[12:15], v[108:111], v[16:19]
	v_mfma_f32_16x16x32_bf16 v[16:19], v[0:3], v[96:99], 0
	v_mfma_f32_16x16x32_bf16 v[0:3], v[0:3], v[64:67], 0
	v_mfma_f32_16x16x32_bf16 v[188:191], v[4:7], v[100:103], v[16:19]
	v_mfma_f32_16x16x32_bf16 v[16:19], v[8:11], v[96:99], 0
	v_mfma_f32_16x16x32_bf16 v[4:7], v[4:7], v[72:75], v[0:3]
	v_mfma_f32_16x16x32_bf16 v[0:3], v[8:11], v[64:67], 0
	v_mfma_f32_16x16x32_bf16 v[192:195], v[12:15], v[100:103], v[16:19]
	v_mfma_f32_16x16x32_bf16 v[196:199], v[12:15], v[72:75], v[0:3]
	s_barrier
	v_add_u32_e32 v146, s71, v142
	v_add_u32_e32 v147, s72, v142
	s_nop 1
	ds_read_b128 v[0:3], v146
	ds_read_b128 v[8:11], v146 offset:1024
	ds_read_b128 v[12:15], v146 offset:2048
	ds_read_b128 v[200:203], v146 offset:3072
	ds_read_b128 v[204:207], v147
	ds_read_b128 v[208:211], v147 offset:1024
	ds_read_b128 v[212:215], v147 offset:2048
	ds_read_b128 v[216:219], v147 offset:3072
	s_add_u32 s56, s50, 0x80100
	s_addc_u32 s57, s51, 0
	s_mov_b32 m0, s63
	ds_read_b128 v[16:19], v145 offset:32768
	ds_read_b128 v[24:27], v145 offset:33792
	ds_read_b128 v[100:103], v145 offset:34816
	ds_read_b128 v[220:223], v145 offset:35840
	ds_read_b128 v[224:227], v145 offset:36864
	ds_read_b128 v[228:231], v145 offset:37888
	ds_read_b128 v[232:235], v145 offset:38912
	ds_read_b128 v[236:239], v145 offset:39936
	s_nop 0
	global_load_lds_dwordx4 v138, s[56:57]
	s_mov_b32 m0, s64
	s_nop 0
	global_load_lds_dwordx4 v140, s[56:57]
	s_waitcnt vmcnt(8)
	s_waitcnt lgkmcnt(0)
	s_barrier
	s_waitcnt lgkmcnt(0)
	v_mfma_f32_16x16x32_bf16 v[32:35], v[0:3], v[16:19], v[32:35]
	v_mfma_f32_16x16x32_bf16 v[120:123], v[8:11], v[24:27], v[32:35]
	v_mfma_f32_16x16x32_bf16 v[32:35], v[12:15], v[16:19], v[36:39]
	v_mfma_f32_16x16x32_bf16 v[112:115], v[200:203], v[24:27], v[32:35]
	v_mfma_f32_16x16x32_bf16 v[32:35], v[0:3], v[100:103], v[40:43]
	v_mfma_f32_16x16x32_bf16 v[104:107], v[8:11], v[220:223], v[32:35]
	v_mfma_f32_16x16x32_bf16 v[32:35], v[12:15], v[100:103], v[44:47]
	v_mfma_f32_16x16x32_bf16 v[96:99], v[200:203], v[220:223], v[32:35]
	v_mfma_f32_16x16x32_bf16 v[32:35], v[0:3], v[224:227], v[48:51]
	v_mfma_f32_16x16x32_bf16 v[72:75], v[8:11], v[228:231], v[32:35]
	v_mfma_f32_16x16x32_bf16 v[32:35], v[12:15], v[224:227], v[52:55]
	v_mfma_f32_16x16x32_bf16 v[64:67], v[200:203], v[228:231], v[32:35]
	v_mfma_f32_16x16x32_bf16 v[32:35], v[0:3], v[232:235], v[56:59]
	v_mfma_f32_16x16x32_bf16 v[40:43], v[8:11], v[236:239], v[32:35]
	v_mfma_f32_16x16x32_bf16 v[32:35], v[12:15], v[232:235], v[60:63]
	v_mfma_f32_16x16x32_bf16 v[32:35], v[200:203], v[236:239], v[32:35]
	v_mfma_f32_16x16x32_bf16 v[36:39], v[204:207], v[16:19], v[68:71]
	v_mfma_f32_16x16x32_bf16 v[16:19], v[212:215], v[16:19], v[76:79]
	v_mfma_f32_16x16x32_bf16 v[116:119], v[216:219], v[24:27], v[16:19]
	v_mfma_f32_16x16x32_bf16 v[16:19], v[204:207], v[100:103], v[80:83]
	v_mfma_f32_16x16x32_bf16 v[108:111], v[208:211], v[220:223], v[16:19]
	v_mfma_f32_16x16x32_bf16 v[16:19], v[212:215], v[100:103], v[84:87]
	v_mfma_f32_16x16x32_bf16 v[100:103], v[216:219], v[220:223], v[16:19]
	v_mfma_f32_16x16x32_bf16 v[16:19], v[204:207], v[224:227], v[88:91]
	v_mfma_f32_16x16x32_bf16 v[76:79], v[208:211], v[228:231], v[16:19]
	v_mfma_f32_16x16x32_bf16 v[16:19], v[212:215], v[224:227], v[92:95]
	v_mfma_f32_16x16x32_bf16 v[68:71], v[216:219], v[228:231], v[16:19]
	v_mfma_f32_16x16x32_bf16 v[16:19], v[204:207], v[232:235], v[128:131]
	v_mfma_f32_16x16x32_bf16 v[44:47], v[208:211], v[236:239], v[16:19]
	v_mfma_f32_16x16x32_bf16 v[16:19], v[212:215], v[232:235], v[132:135]
	v_mfma_f32_16x16x32_bf16 v[124:127], v[208:211], v[24:27], v[36:39]
	v_mfma_f32_16x16x32_bf16 v[36:39], v[216:219], v[236:239], v[16:19]
	s_barrier
	s_add_i32 s37, s71, s25
	s_mov_b32 m0, s37
	s_add_i32 s39, s37, 0x2000
	ds_read_b128 v[52:55], v145 offset:49152
	ds_read_b128 v[60:63], v145 offset:50176
	ds_read_b128 v[128:131], v145 offset:51200
	ds_read_b128 v[132:135], v145 offset:52224
	ds_read_b128 v[220:223], v145 offset:53248
	ds_read_b128 v[224:227], v145 offset:54272
	ds_read_b128 v[228:231], v145 offset:55296
	ds_read_b128 v[232:235], v145 offset:56320
	s_nop 0
	global_load_lds_dwordx4 v139, s[54:55]
	s_mov_b32 m0, s39
	s_nop 0
	global_load_lds_dwordx4 v141, s[54:55]
	s_add_u32 s54, s48, 0x80180
	s_addc_u32 s55, s49, 0
	s_add_i32 s75, s72, s25
	s_mov_b32 m0, s75
	s_add_i32 s76, s75, 0x2000
	s_nop 0
	global_load_lds_dwordx4 v139, s[54:55]
	s_mov_b32 m0, s76
	s_nop 0
	global_load_lds_dwordx4 v141, s[54:55]
	s_mov_b32 m0, s65
	s_nop 0
	global_load_lds_dwordx4 v138, s[52:53]
	s_mov_b32 m0, s66
	s_nop 0
	global_load_lds_dwordx4 v140, s[52:53]
	s_waitcnt vmcnt(8)
	s_waitcnt lgkmcnt(0)
	s_barrier
	s_waitcnt lgkmcnt(0)
	v_mfma_f32_16x16x32_bf16 v[16:19], v[0:3], v[52:55], v[148:151]
	v_mfma_f32_16x16x32_bf16 v[92:95], v[8:11], v[60:63], v[16:19]
	v_mfma_f32_16x16x32_bf16 v[16:19], v[12:15], v[52:55], v[152:155]
	v_mfma_f32_16x16x32_bf16 v[84:87], v[200:203], v[60:63], v[16:19]
	v_mfma_f32_16x16x32_bf16 v[16:19], v[0:3], v[128:131], v[156:159]
	v_mfma_f32_16x16x32_bf16 v[56:59], v[8:11], v[132:135], v[16:19]
	v_mfma_f32_16x16x32_bf16 v[16:19], v[12:15], v[128:131], v[160:163]
	v_mfma_f32_16x16x32_bf16 v[48:51], v[200:203], v[132:135], v[16:19]
	v_mfma_f32_16x16x32_bf16 v[16:19], v[0:3], v[220:223], v[164:167]
	v_mfma_f32_16x16x32_bf16 v[0:3], v[0:3], v[228:231], v[20:23]
	v_mfma_f32_16x16x32_bf16 v[24:27], v[8:11], v[224:227], v[16:19]
	v_mfma_f32_16x16x32_bf16 v[16:19], v[12:15], v[220:223], v[168:171]
	v_mfma_f32_16x16x32_bf16 v[8:11], v[8:11], v[232:235], v[0:3]
	v_mfma_f32_16x16x32_bf16 v[0:3], v[12:15], v[228:231], v[28:31]
	v_mfma_f32_16x16x32_bf16 v[16:19], v[200:203], v[224:227], v[16:19]
	v_mfma_f32_16x16x32_bf16 v[0:3], v[200:203], v[232:235], v[0:3]
	v_mfma_f32_16x16x32_bf16 v[12:15], v[204:207], v[52:55], v[172:175]
	v_mfma_f32_16x16x32_bf16 v[88:91], v[208:211], v[60:63], v[12:15]
	v_mfma_f32_16x16x32_bf16 v[12:15], v[212:215], v[52:55], v[176:179]
	v_mfma_f32_16x16x32_bf16 v[80:83], v[216:219], v[60:63], v[12:15]
	v_mfma_f32_16x16x32_bf16 v[12:15], v[204:207], v[128:131], v[180:183]
	v_mfma_f32_16x16x32_bf16 v[60:63], v[208:211], v[132:135], v[12:15]
	v_mfma_f32_16x16x32_bf16 v[12:15], v[212:215], v[128:131], v[184:187]
	v_mfma_f32_16x16x32_bf16 v[52:55], v[216:219], v[132:135], v[12:15]
	v_mfma_f32_16x16x32_bf16 v[12:15], v[204:207], v[220:223], v[188:191]
	v_mfma_f32_16x16x32_bf16 v[28:31], v[208:211], v[224:227], v[12:15]
	v_mfma_f32_16x16x32_bf16 v[12:15], v[212:215], v[220:223], v[192:195]
	v_mfma_f32_16x16x32_bf16 v[4:7], v[204:207], v[228:231], v[4:7]
	v_mfma_f32_16x16x32_bf16 v[20:23], v[216:219], v[224:227], v[12:15]
	v_mfma_f32_16x16x32_bf16 v[12:15], v[208:211], v[232:235], v[4:7]
	v_mfma_f32_16x16x32_bf16 v[4:7], v[212:215], v[228:231], v[196:199]
	v_mfma_f32_16x16x32_bf16 v[4:7], v[216:219], v[232:235], v[4:7]
	s_barrier
	s_add_u32 s56, s50, 0x100
	s_addc_u32 s57, s51, 0
	s_add_u32 s77, s48, 0x200
	s_addc_u32 s78, s49, 0
	s_mov_b32 s79, 0
.LBB0_392:
	s_add_u32 s48, s56, 0x100
	s_addc_u32 s49, s57, 0
	s_cmp_eq_u32 s79, 28
	s_cselect_b32 s54, s21, s48
	s_cselect_b32 s55, s20, s49
	s_cselect_b32 s52, s12, s77
	s_cselect_b32 s53, s9, s78
	s_add_u32 s50, s54, 0x80
	s_addc_u32 s51, s55, 0
	s_add_i32 s80, 0, 0x10000
	s_add_i32 s82, 0, 0x14000
	v_add_u32_e32 v152, s80, v142
	v_add_u32_e32 v168, s82, v142
	ds_read_b128 v[128:131], v152
	ds_read_b128 v[132:135], v152 offset:1024
	ds_read_b128 v[148:151], v152 offset:2048
	ds_read_b128 v[152:155], v152 offset:3072
	ds_read_b128 v[156:159], v168
	ds_read_b128 v[160:163], v168 offset:1024
	ds_read_b128 v[164:167], v168 offset:2048
	ds_read_b128 v[168:171], v168 offset:3072
	s_add_u32 s56, s56, 0x80080
	s_addc_u32 s57, s57, 0
	s_mov_b32 m0, s0
	ds_read_b128 v[172:175], v145
	ds_read_b128 v[176:179], v145 offset:1024
	ds_read_b128 v[180:183], v145 offset:2048
	ds_read_b128 v[184:187], v145 offset:3072
	ds_read_b128 v[188:191], v145 offset:4096
	ds_read_b128 v[192:195], v145 offset:5120
	ds_read_b128 v[196:199], v145 offset:6144
	ds_read_b128 v[200:203], v145 offset:7168
	s_nop 0
	global_load_lds_dwordx4 v138, s[56:57]
	s_mov_b32 m0, s1
	s_nop 0
	global_load_lds_dwordx4 v140, s[56:57]
	s_waitcnt vmcnt(8)
	s_waitcnt lgkmcnt(0)
	s_barrier
	s_waitcnt lgkmcnt(0)
	v_mfma_f32_16x16x32_bf16 v[120:123], v[128:131], v[172:175], v[120:123]
	v_mfma_f32_16x16x32_bf16 v[112:115], v[148:151], v[172:175], v[112:115]
	v_mfma_f32_16x16x32_bf16 v[104:107], v[128:131], v[180:183], v[104:107]
	v_mfma_f32_16x16x32_bf16 v[96:99], v[148:151], v[180:183], v[96:99]
	v_mfma_f32_16x16x32_bf16 v[72:75], v[128:131], v[188:191], v[72:75]
	v_mfma_f32_16x16x32_bf16 v[64:67], v[148:151], v[188:191], v[64:67]
	v_mfma_f32_16x16x32_bf16 v[40:43], v[128:131], v[196:199], v[40:43]
	v_mfma_f32_16x16x32_bf16 v[32:35], v[148:151], v[196:199], v[32:35]
	v_mfma_f32_16x16x32_bf16 v[120:123], v[132:135], v[176:179], v[120:123]
	v_mfma_f32_16x16x32_bf16 v[112:115], v[152:155], v[176:179], v[112:115]
	v_mfma_f32_16x16x32_bf16 v[104:107], v[132:135], v[184:187], v[104:107]
	v_mfma_f32_16x16x32_bf16 v[96:99], v[152:155], v[184:187], v[96:99]
	v_mfma_f32_16x16x32_bf16 v[72:75], v[132:135], v[192:195], v[72:75]
	v_mfma_f32_16x16x32_bf16 v[64:67], v[152:155], v[192:195], v[64:67]
	v_mfma_f32_16x16x32_bf16 v[40:43], v[132:135], v[200:203], v[40:43]
	v_mfma_f32_16x16x32_bf16 v[32:35], v[152:155], v[200:203], v[32:35]
	v_mfma_f32_16x16x32_bf16 v[124:127], v[156:159], v[172:175], v[124:127]
	v_mfma_f32_16x16x32_bf16 v[116:119], v[164:167], v[172:175], v[116:119]
	v_mfma_f32_16x16x32_bf16 v[108:111], v[156:159], v[180:183], v[108:111]
	v_mfma_f32_16x16x32_bf16 v[100:103], v[164:167], v[180:183], v[100:103]
	v_mfma_f32_16x16x32_bf16 v[76:79], v[156:159], v[188:191], v[76:79]
	v_mfma_f32_16x16x32_bf16 v[68:71], v[164:167], v[188:191], v[68:71]
	v_mfma_f32_16x16x32_bf16 v[44:47], v[156:159], v[196:199], v[44:47]
	v_mfma_f32_16x16x32_bf16 v[36:39], v[164:167], v[196:199], v[36:39]
	v_mfma_f32_16x16x32_bf16 v[124:127], v[160:163], v[176:179], v[124:127]
	v_mfma_f32_16x16x32_bf16 v[116:119], v[168:171], v[176:179], v[116:119]
	v_mfma_f32_16x16x32_bf16 v[108:111], v[160:163], v[184:187], v[108:111]
	v_mfma_f32_16x16x32_bf16 v[100:103], v[168:171], v[184:187], v[100:103]
	v_mfma_f32_16x16x32_bf16 v[76:79], v[160:163], v[192:195], v[76:79]
	v_mfma_f32_16x16x32_bf16 v[68:71], v[168:171], v[192:195], v[68:71]
	v_mfma_f32_16x16x32_bf16 v[44:47], v[160:163], v[200:203], v[44:47]
	v_mfma_f32_16x16x32_bf16 v[36:39], v[168:171], v[200:203], v[36:39]
	s_barrier
	s_add_i32 s56, s80, s25
	s_mov_b32 m0, s56
	ds_read_b128 v[172:175], v145 offset:16384
	ds_read_b128 v[176:179], v145 offset:17408
	ds_read_b128 v[180:183], v145 offset:18432
	ds_read_b128 v[184:187], v145 offset:19456
	ds_read_b128 v[188:191], v145 offset:20480
	ds_read_b128 v[192:195], v145 offset:21504
	ds_read_b128 v[196:199], v145 offset:22528
	ds_read_b128 v[200:203], v145 offset:23552
	s_nop 0
	global_load_lds_dwordx4 v139, s[52:53]
	s_add_i32 m0, s56, 0x2000
	s_add_u32 s56, s52, 0x80000
	s_addc_u32 s57, s53, 0
	s_add_i32 s80, s82, s25
	s_nop 0
	global_load_lds_dwordx4 v141, s[52:53]
	s_mov_b32 m0, s80
	s_nop 0
	global_load_lds_dwordx4 v139, s[56:57]
	s_add_i32 m0, s80, 0x2000
	s_nop 0
	global_load_lds_dwordx4 v141, s[56:57]
	s_mov_b32 m0, s41
	s_nop 0
	global_load_lds_dwordx4 v138, s[54:55]
	s_mov_b32 m0, s62
	s_nop 0
	global_load_lds_dwordx4 v140, s[54:55]
	s_waitcnt vmcnt(8)
	s_waitcnt lgkmcnt(0)
	s_barrier
	s_waitcnt lgkmcnt(0)
	v_mfma_f32_16x16x32_bf16 v[92:95], v[128:131], v[172:175], v[92:95]
	v_mfma_f32_16x16x32_bf16 v[84:87], v[148:151], v[172:175], v[84:87]
	v_mfma_f32_16x16x32_bf16 v[56:59], v[128:131], v[180:183], v[56:59]
	v_mfma_f32_16x16x32_bf16 v[48:51], v[148:151], v[180:183], v[48:51]
	v_mfma_f32_16x16x32_bf16 v[24:27], v[128:131], v[188:191], v[24:27]
	v_mfma_f32_16x16x32_bf16 v[16:19], v[148:151], v[188:191], v[16:19]
	v_mfma_f32_16x16x32_bf16 v[8:11], v[128:131], v[196:199], v[8:11]
	v_mfma_f32_16x16x32_bf16 v[0:3], v[148:151], v[196:199], v[0:3]
	v_mfma_f32_16x16x32_bf16 v[92:95], v[132:135], v[176:179], v[92:95]
	v_mfma_f32_16x16x32_bf16 v[84:87], v[152:155], v[176:179], v[84:87]
	v_mfma_f32_16x16x32_bf16 v[56:59], v[132:135], v[184:187], v[56:59]
	v_mfma_f32_16x16x32_bf16 v[48:51], v[152:155], v[184:187], v[48:51]
	v_mfma_f32_16x16x32_bf16 v[24:27], v[132:135], v[192:195], v[24:27]
	v_mfma_f32_16x16x32_bf16 v[16:19], v[152:155], v[192:195], v[16:19]
	v_mfma_f32_16x16x32_bf16 v[8:11], v[132:135], v[200:203], v[8:11]
	v_mfma_f32_16x16x32_bf16 v[0:3], v[152:155], v[200:203], v[0:3]
	v_mfma_f32_16x16x32_bf16 v[88:91], v[156:159], v[172:175], v[88:91]
	v_mfma_f32_16x16x32_bf16 v[80:83], v[164:167], v[172:175], v[80:83]
	v_mfma_f32_16x16x32_bf16 v[60:63], v[156:159], v[180:183], v[60:63]
	v_mfma_f32_16x16x32_bf16 v[52:55], v[164:167], v[180:183], v[52:55]
	v_mfma_f32_16x16x32_bf16 v[28:31], v[156:159], v[188:191], v[28:31]
	v_mfma_f32_16x16x32_bf16 v[20:23], v[164:167], v[188:191], v[20:23]
	v_mfma_f32_16x16x32_bf16 v[12:15], v[156:159], v[196:199], v[12:15]
	v_mfma_f32_16x16x32_bf16 v[4:7], v[164:167], v[196:199], v[4:7]
	v_mfma_f32_16x16x32_bf16 v[88:91], v[160:163], v[176:179], v[88:91]
	v_mfma_f32_16x16x32_bf16 v[80:83], v[168:171], v[176:179], v[80:83]
	v_mfma_f32_16x16x32_bf16 v[60:63], v[160:163], v[184:187], v[60:63]
	v_mfma_f32_16x16x32_bf16 v[52:55], v[168:171], v[184:187], v[52:55]
	v_mfma_f32_16x16x32_bf16 v[28:31], v[160:163], v[192:195], v[28:31]
	v_mfma_f32_16x16x32_bf16 v[20:23], v[168:171], v[192:195], v[20:23]
	v_mfma_f32_16x16x32_bf16 v[12:15], v[160:163], v[200:203], v[12:15]
	v_mfma_f32_16x16x32_bf16 v[4:7], v[168:171], v[200:203], v[4:7]
	s_barrier
	ds_read_b128 v[128:131], v146
	ds_read_b128 v[132:135], v146 offset:1024
	ds_read_b128 v[148:151], v146 offset:2048
	ds_read_b128 v[152:155], v146 offset:3072
	ds_read_b128 v[156:159], v147
	ds_read_b128 v[160:163], v147 offset:1024
	ds_read_b128 v[164:167], v147 offset:2048
	ds_read_b128 v[168:171], v147 offset:3072
	s_add_u32 s54, s54, 0x80000
	s_addc_u32 s55, s55, 0
	s_mov_b32 m0, s63
	ds_read_b128 v[172:175], v145 offset:32768
	ds_read_b128 v[176:179], v145 offset:33792
	ds_read_b128 v[180:183], v145 offset:34816
	ds_read_b128 v[184:187], v145 offset:35840
	ds_read_b128 v[188:191], v145 offset:36864
	ds_read_b128 v[192:195], v145 offset:37888
	ds_read_b128 v[196:199], v145 offset:38912
	ds_read_b128 v[200:203], v145 offset:39936
	s_nop 0
	global_load_lds_dwordx4 v138, s[54:55]
	s_mov_b32 m0, s64
	s_nop 0
	global_load_lds_dwordx4 v140, s[54:55]
	s_waitcnt vmcnt(8)
	s_waitcnt lgkmcnt(0)
	s_barrier
	s_waitcnt lgkmcnt(0)
	v_mfma_f32_16x16x32_bf16 v[120:123], v[128:131], v[172:175], v[120:123]
	v_mfma_f32_16x16x32_bf16 v[112:115], v[148:151], v[172:175], v[112:115]
	v_mfma_f32_16x16x32_bf16 v[104:107], v[128:131], v[180:183], v[104:107]
	v_mfma_f32_16x16x32_bf16 v[96:99], v[148:151], v[180:183], v[96:99]
	v_mfma_f32_16x16x32_bf16 v[72:75], v[128:131], v[188:191], v[72:75]
	v_mfma_f32_16x16x32_bf16 v[64:67], v[148:151], v[188:191], v[64:67]
	v_mfma_f32_16x16x32_bf16 v[40:43], v[128:131], v[196:199], v[40:43]
	v_mfma_f32_16x16x32_bf16 v[32:35], v[148:151], v[196:199], v[32:35]
	v_mfma_f32_16x16x32_bf16 v[120:123], v[132:135], v[176:179], v[120:123]
	v_mfma_f32_16x16x32_bf16 v[112:115], v[152:155], v[176:179], v[112:115]
	v_mfma_f32_16x16x32_bf16 v[104:107], v[132:135], v[184:187], v[104:107]
	v_mfma_f32_16x16x32_bf16 v[96:99], v[152:155], v[184:187], v[96:99]
	v_mfma_f32_16x16x32_bf16 v[72:75], v[132:135], v[192:195], v[72:75]
	v_mfma_f32_16x16x32_bf16 v[64:67], v[152:155], v[192:195], v[64:67]
	v_mfma_f32_16x16x32_bf16 v[40:43], v[132:135], v[200:203], v[40:43]
	v_mfma_f32_16x16x32_bf16 v[32:35], v[152:155], v[200:203], v[32:35]
	v_mfma_f32_16x16x32_bf16 v[124:127], v[156:159], v[172:175], v[124:127]
	v_mfma_f32_16x16x32_bf16 v[116:119], v[164:167], v[172:175], v[116:119]
	v_mfma_f32_16x16x32_bf16 v[108:111], v[156:159], v[180:183], v[108:111]
	v_mfma_f32_16x16x32_bf16 v[100:103], v[164:167], v[180:183], v[100:103]
	v_mfma_f32_16x16x32_bf16 v[76:79], v[156:159], v[188:191], v[76:79]
	v_mfma_f32_16x16x32_bf16 v[68:71], v[164:167], v[188:191], v[68:71]
	v_mfma_f32_16x16x32_bf16 v[44:47], v[156:159], v[196:199], v[44:47]
	v_mfma_f32_16x16x32_bf16 v[36:39], v[164:167], v[196:199], v[36:39]
	v_mfma_f32_16x16x32_bf16 v[124:127], v[160:163], v[176:179], v[124:127]
	v_mfma_f32_16x16x32_bf16 v[116:119], v[168:171], v[176:179], v[116:119]
	v_mfma_f32_16x16x32_bf16 v[108:111], v[160:163], v[184:187], v[108:111]
	v_mfma_f32_16x16x32_bf16 v[100:103], v[168:171], v[184:187], v[100:103]
	v_mfma_f32_16x16x32_bf16 v[76:79], v[160:163], v[192:195], v[76:79]
	v_mfma_f32_16x16x32_bf16 v[68:71], v[168:171], v[192:195], v[68:71]
	v_mfma_f32_16x16x32_bf16 v[44:47], v[160:163], v[200:203], v[44:47]
	v_mfma_f32_16x16x32_bf16 v[36:39], v[168:171], v[200:203], v[36:39]
	s_barrier
	s_add_u32 s54, s52, 0x80
	s_mov_b32 m0, s37
	s_addc_u32 s55, s53, 0
	ds_read_b128 v[172:175], v145 offset:49152
	ds_read_b128 v[176:179], v145 offset:50176
	ds_read_b128 v[180:183], v145 offset:51200
	ds_read_b128 v[184:187], v145 offset:52224
	ds_read_b128 v[188:191], v145 offset:53248
	ds_read_b128 v[192:195], v145 offset:54272
	ds_read_b128 v[196:199], v145 offset:55296
	ds_read_b128 v[200:203], v145 offset:56320
	s_add_u32 s52, s52, 0x80080
	global_load_lds_dwordx4 v139, s[54:55]
	s_mov_b32 m0, s39
	s_addc_u32 s53, s53, 0
	global_load_lds_dwordx4 v141, s[54:55]
	s_mov_b32 m0, s75
	s_nop 0
	global_load_lds_dwordx4 v139, s[52:53]
	s_mov_b32 m0, s76
	s_nop 0
	global_load_lds_dwordx4 v141, s[52:53]
	s_mov_b32 m0, s65
	s_nop 0
	global_load_lds_dwordx4 v138, s[50:51]
	s_mov_b32 m0, s66
	s_nop 0
	global_load_lds_dwordx4 v140, s[50:51]
	s_waitcnt vmcnt(8)
	s_waitcnt lgkmcnt(0)
	s_barrier
	s_waitcnt lgkmcnt(0)
	v_mfma_f32_16x16x32_bf16 v[92:95], v[128:131], v[172:175], v[92:95]
	v_mfma_f32_16x16x32_bf16 v[84:87], v[148:151], v[172:175], v[84:87]
	v_mfma_f32_16x16x32_bf16 v[56:59], v[128:131], v[180:183], v[56:59]
	v_mfma_f32_16x16x32_bf16 v[48:51], v[148:151], v[180:183], v[48:51]
	v_mfma_f32_16x16x32_bf16 v[24:27], v[128:131], v[188:191], v[24:27]
	v_mfma_f32_16x16x32_bf16 v[16:19], v[148:151], v[188:191], v[16:19]
	v_mfma_f32_16x16x32_bf16 v[8:11], v[128:131], v[196:199], v[8:11]
	v_mfma_f32_16x16x32_bf16 v[0:3], v[148:151], v[196:199], v[0:3]
	v_mfma_f32_16x16x32_bf16 v[92:95], v[132:135], v[176:179], v[92:95]
	v_mfma_f32_16x16x32_bf16 v[84:87], v[152:155], v[176:179], v[84:87]
	v_mfma_f32_16x16x32_bf16 v[56:59], v[132:135], v[184:187], v[56:59]
	v_mfma_f32_16x16x32_bf16 v[48:51], v[152:155], v[184:187], v[48:51]
	v_mfma_f32_16x16x32_bf16 v[24:27], v[132:135], v[192:195], v[24:27]
	v_mfma_f32_16x16x32_bf16 v[16:19], v[152:155], v[192:195], v[16:19]
	v_mfma_f32_16x16x32_bf16 v[8:11], v[132:135], v[200:203], v[8:11]
	v_mfma_f32_16x16x32_bf16 v[0:3], v[152:155], v[200:203], v[0:3]
	v_mfma_f32_16x16x32_bf16 v[88:91], v[156:159], v[172:175], v[88:91]
	v_mfma_f32_16x16x32_bf16 v[80:83], v[164:167], v[172:175], v[80:83]
	v_mfma_f32_16x16x32_bf16 v[60:63], v[156:159], v[180:183], v[60:63]
	v_mfma_f32_16x16x32_bf16 v[52:55], v[164:167], v[180:183], v[52:55]
	v_mfma_f32_16x16x32_bf16 v[28:31], v[156:159], v[188:191], v[28:31]
	v_mfma_f32_16x16x32_bf16 v[20:23], v[164:167], v[188:191], v[20:23]
	v_mfma_f32_16x16x32_bf16 v[12:15], v[156:159], v[196:199], v[12:15]
	v_mfma_f32_16x16x32_bf16 v[4:7], v[164:167], v[196:199], v[4:7]
	v_mfma_f32_16x16x32_bf16 v[88:91], v[160:163], v[176:179], v[88:91]
	v_mfma_f32_16x16x32_bf16 v[80:83], v[168:171], v[176:179], v[80:83]
	v_mfma_f32_16x16x32_bf16 v[60:63], v[160:163], v[184:187], v[60:63]
	v_mfma_f32_16x16x32_bf16 v[52:55], v[168:171], v[184:187], v[52:55]
	v_mfma_f32_16x16x32_bf16 v[28:31], v[160:163], v[192:195], v[28:31]
	v_mfma_f32_16x16x32_bf16 v[20:23], v[168:171], v[192:195], v[20:23]
	v_mfma_f32_16x16x32_bf16 v[12:15], v[160:163], v[200:203], v[12:15]
	v_mfma_f32_16x16x32_bf16 v[4:7], v[168:171], v[200:203], v[4:7]
	s_barrier
	s_add_i32 s79, s79, 2
	s_add_u32 s77, s77, 0x100
	s_addc_u32 s78, s78, 0
	s_cmp_gt_u32 s79, 29
	s_mov_b64 s[56:57], s[48:49]
	s_cbranch_scc0 .LBB0_392
	s_and_b64 vcc, exec, s[4:5]
	s_cbranch_vccz .LBB0_395
	s_barrier

.LBB0_424:
	s_add_u32 s20, s48, 0x100
	s_addc_u32 s21, s49, 0
	s_waitcnt lgkmcnt(0)
	s_add_u32 s44, s46, 0x100
	s_addc_u32 s45, s47, 0
	s_barrier
	s_waitcnt lgkmcnt(0)
	v_mfma_f32_16x16x32_bf16 v[32:35], v[16:19], v[72:75], 0
	v_mfma_f32_16x16x32_bf16 v[36:39], v[24:27], v[72:75], 0
	v_mfma_f32_16x16x32_bf16 v[40:43], v[16:19], v[80:83], 0
	v_mfma_f32_16x16x32_bf16 v[44:47], v[24:27], v[80:83], 0
	v_mfma_f32_16x16x32_bf16 v[48:51], v[16:19], v[92:95], 0
	v_mfma_f32_16x16x32_bf16 v[52:55], v[24:27], v[92:95], 0
	v_mfma_f32_16x16x32_bf16 v[56:59], v[16:19], v[60:63], 0
	v_mfma_f32_16x16x32_bf16 v[64:67], v[24:27], v[60:63], 0
	v_mfma_f32_16x16x32_bf16 v[32:35], v[20:23], v[76:79], v[32:35]
	v_mfma_f32_16x16x32_bf16 v[36:39], v[28:31], v[76:79], v[36:39]
	v_mfma_f32_16x16x32_bf16 v[40:43], v[20:23], v[84:87], v[40:43]
	v_mfma_f32_16x16x32_bf16 v[44:47], v[28:31], v[84:87], v[44:47]
	v_mfma_f32_16x16x32_bf16 v[48:51], v[20:23], v[96:99], v[48:51]
	v_mfma_f32_16x16x32_bf16 v[52:55], v[28:31], v[96:99], v[52:55]
	v_mfma_f32_16x16x32_bf16 v[56:59], v[20:23], v[88:91], v[56:59]
	v_mfma_f32_16x16x32_bf16 v[64:67], v[28:31], v[88:91], v[64:67]
	v_mfma_f32_16x16x32_bf16 v[68:71], v[0:3], v[72:75], 0
	v_mfma_f32_16x16x32_bf16 v[72:75], v[8:11], v[72:75], 0
	v_mfma_f32_16x16x32_bf16 v[68:71], v[4:7], v[76:79], v[68:71]
	v_mfma_f32_16x16x32_bf16 v[72:75], v[12:15], v[76:79], v[72:75]
	v_mfma_f32_16x16x32_bf16 v[76:79], v[0:3], v[80:83], 0
	v_mfma_f32_16x16x32_bf16 v[80:83], v[8:11], v[80:83], 0
	v_mfma_f32_16x16x32_bf16 v[76:79], v[4:7], v[84:87], v[76:79]
	v_mfma_f32_16x16x32_bf16 v[80:83], v[12:15], v[84:87], v[80:83]
	v_mfma_f32_16x16x32_bf16 v[84:87], v[0:3], v[92:95], 0
	v_mfma_f32_16x16x32_bf16 v[92:95], v[8:11], v[92:95], 0
	v_mfma_f32_16x16x32_bf16 v[128:131], v[12:15], v[96:99], v[92:95]
	v_mfma_f32_16x16x32_bf16 v[92:95], v[0:3], v[60:63], 0
	v_mfma_f32_16x16x32_bf16 v[60:63], v[8:11], v[60:63], 0
	v_mfma_f32_16x16x32_bf16 v[84:87], v[4:7], v[96:99], v[84:87]
	v_mfma_f32_16x16x32_bf16 v[132:135], v[4:7], v[88:91], v[92:95]
	v_mfma_f32_16x16x32_bf16 v[136:139], v[12:15], v[88:91], v[60:63]
	s_barrier
	s_mov_b32 m0, s39
	ds_read_b128 v[108:111], v150 offset:16384
	ds_read_b128 v[112:115], v150 offset:17408
	ds_read_b128 v[100:103], v150 offset:18432
	ds_read_b128 v[104:107], v150 offset:19456
	ds_read_b128 v[92:95], v150 offset:20480
	ds_read_b128 v[96:99], v150 offset:21504
	ds_read_b128 v[60:63], v150 offset:22528
	ds_read_b128 v[88:91], v150 offset:23552
	s_nop 0
	global_load_lds_dwordx4 v144, s[44:45]
	s_mov_b32 m0, s56
	s_nop 0
	global_load_lds_dwordx4 v146, s[44:45]
	s_add_u32 s44, s46, 0x80100
	s_addc_u32 s45, s47, 0
	s_mov_b32 m0, s57
	s_and_b64 vcc, exec, s[42:43]
	global_load_lds_dwordx4 v144, s[44:45]
	s_mov_b32 m0, s58
	s_nop 0
	global_load_lds_dwordx4 v146, s[44:45]
	s_mov_b32 m0, s26
	s_mov_b64 s[44:45], -1
	global_load_lds_dwordx4 v143, s[20:21]
	s_mov_b32 m0, s59
	s_nop 0
	global_load_lds_dwordx4 v145, s[20:21]
	s_cbranch_vccz .LBB0_426
	s_waitcnt vmcnt(8)
	s_mov_b64 s[44:45], 0

.LBB0_428:
	s_ashr_i32 s7, s6, 31
	s_lshl_b64 s[20:21], s[6:7], 20
	s_add_u32 s42, s14, s20
	s_addc_u32 s43, s15, s21
	s_ashr_i32 s9, s8, 31
	s_lshl_b64 s[20:21], s[8:9], 20
	s_add_u32 s44, s17, s20
	s_addc_u32 s45, s24, s21
	s_add_u32 s50, s48, 0x180
	s_addc_u32 s51, s49, 0
	s_waitcnt lgkmcnt(0)
	s_and_b64 s[20:21], s[40:41], exec
	s_cselect_b32 s9, s45, s47
	s_cselect_b32 s12, s44, s46
	s_cselect_b32 s20, s43, s49
	s_cselect_b32 s21, s42, s48
	s_add_u32 s52, s46, 0x180
	s_addc_u32 s53, s47, 0
	s_barrier
	s_waitcnt lgkmcnt(0)
	v_mfma_f32_16x16x32_bf16 v[116:119], v[16:19], v[108:111], 0
	v_mfma_f32_16x16x32_bf16 v[156:159], v[20:23], v[112:115], v[116:119]
	v_mfma_f32_16x16x32_bf16 v[116:119], v[24:27], v[108:111], 0
	v_mfma_f32_16x16x32_bf16 v[160:163], v[28:31], v[112:115], v[116:119]
	v_mfma_f32_16x16x32_bf16 v[116:119], v[16:19], v[100:103], 0
	v_mfma_f32_16x16x32_bf16 v[164:167], v[20:23], v[104:107], v[116:119]
	v_mfma_f32_16x16x32_bf16 v[116:119], v[24:27], v[100:103], 0
	v_mfma_f32_16x16x32_bf16 v[168:171], v[28:31], v[104:107], v[116:119]
	v_mfma_f32_16x16x32_bf16 v[116:119], v[16:19], v[92:95], 0
	v_mfma_f32_16x16x32_bf16 v[16:19], v[16:19], v[60:63], 0
	v_mfma_f32_16x16x32_bf16 v[172:175], v[20:23], v[96:99], v[116:119]
	v_mfma_f32_16x16x32_bf16 v[16:19], v[20:23], v[88:91], v[16:19]
	v_mfma_f32_16x16x32_bf16 v[20:23], v[24:27], v[60:63], 0
	v_mfma_f32_16x16x32_bf16 v[116:119], v[24:27], v[92:95], 0
	v_mfma_f32_16x16x32_bf16 v[20:23], v[28:31], v[88:91], v[20:23]
	v_mfma_f32_16x16x32_bf16 v[176:179], v[28:31], v[96:99], v[116:119]
	v_mfma_f32_16x16x32_bf16 v[24:27], v[0:3], v[108:111], 0
	v_mfma_f32_16x16x32_bf16 v[180:183], v[4:7], v[112:115], v[24:27]
	v_mfma_f32_16x16x32_bf16 v[24:27], v[8:11], v[108:111], 0
	v_mfma_f32_16x16x32_bf16 v[184:187], v[12:15], v[112:115], v[24:27]
	v_mfma_f32_16x16x32_bf16 v[24:27], v[0:3], v[100:103], 0
	v_mfma_f32_16x16x32_bf16 v[188:191], v[4:7], v[104:107], v[24:27]
	v_mfma_f32_16x16x32_bf16 v[24:27], v[8:11], v[100:103], 0
	v_mfma_f32_16x16x32_bf16 v[192:195], v[12:15], v[104:107], v[24:27]
	v_mfma_f32_16x16x32_bf16 v[24:27], v[0:3], v[92:95], 0
	v_mfma_f32_16x16x32_bf16 v[0:3], v[0:3], v[60:63], 0
	v_mfma_f32_16x16x32_bf16 v[196:199], v[4:7], v[96:99], v[24:27]
	v_mfma_f32_16x16x32_bf16 v[24:27], v[8:11], v[92:95], 0
	v_mfma_f32_16x16x32_bf16 v[0:3], v[4:7], v[88:91], v[0:3]
	v_mfma_f32_16x16x32_bf16 v[4:7], v[8:11], v[60:63], 0
	v_mfma_f32_16x16x32_bf16 v[200:203], v[12:15], v[96:99], v[24:27]
	v_mfma_f32_16x16x32_bf16 v[204:207], v[12:15], v[88:91], v[4:7]
	s_barrier
	v_add_u32_e32 v153, s69, v147
	v_add_u32_e32 v154, s70, v147
	s_nop 1
	ds_read_b128 v[4:7], v153
	ds_read_b128 v[8:11], v153 offset:1024
	ds_read_b128 v[208:211], v153 offset:2048
	ds_read_b128 v[212:215], v153 offset:3072
	ds_read_b128 v[216:219], v154
	ds_read_b128 v[220:223], v154 offset:1024
	ds_read_b128 v[224:227], v154 offset:2048
	ds_read_b128 v[228:231], v154 offset:3072
	s_add_u32 s54, s48, 0x80100
	s_addc_u32 s55, s49, 0
	s_mov_b32 m0, s60
	ds_read_b128 v[12:15], v150 offset:32768
	ds_read_b128 v[24:27], v150 offset:33792
	ds_read_b128 v[28:31], v150 offset:34816
	ds_read_b128 v[96:99], v150 offset:35840
	ds_read_b128 v[232:235], v150 offset:36864
	ds_read_b128 v[236:239], v150 offset:37888
	ds_read_b128 v[240:243], v150 offset:38912
	ds_read_b128 v[244:247], v150 offset:39936
	s_nop 0
	global_load_lds_dwordx4 v143, s[54:55]
	s_mov_b32 m0, s61
	s_nop 0
	global_load_lds_dwordx4 v145, s[54:55]
	s_waitcnt vmcnt(8)
	s_waitcnt lgkmcnt(0)
	s_barrier
	s_waitcnt lgkmcnt(0)
	v_mfma_f32_16x16x32_bf16 v[32:35], v[4:7], v[12:15], v[32:35]
	v_mfma_f32_16x16x32_bf16 v[124:127], v[8:11], v[24:27], v[32:35]
	v_mfma_f32_16x16x32_bf16 v[32:35], v[208:211], v[12:15], v[36:39]
	v_mfma_f32_16x16x32_bf16 v[120:123], v[212:215], v[24:27], v[32:35]
	v_mfma_f32_16x16x32_bf16 v[32:35], v[4:7], v[28:31], v[40:43]
	v_mfma_f32_16x16x32_bf16 v[108:111], v[8:11], v[96:99], v[32:35]
	v_mfma_f32_16x16x32_bf16 v[32:35], v[208:211], v[28:31], v[44:47]
	v_mfma_f32_16x16x32_bf16 v[104:107], v[212:215], v[96:99], v[32:35]
	v_mfma_f32_16x16x32_bf16 v[32:35], v[4:7], v[232:235], v[48:51]
	v_mfma_f32_16x16x32_bf16 v[92:95], v[8:11], v[236:239], v[32:35]
	v_mfma_f32_16x16x32_bf16 v[32:35], v[208:211], v[232:235], v[52:55]
	v_mfma_f32_16x16x32_bf16 v[88:91], v[212:215], v[236:239], v[32:35]
	v_mfma_f32_16x16x32_bf16 v[32:35], v[4:7], v[240:243], v[56:59]
	v_mfma_f32_16x16x32_bf16 v[60:63], v[8:11], v[244:247], v[32:35]
	v_mfma_f32_16x16x32_bf16 v[32:35], v[208:211], v[240:243], v[64:67]
	v_mfma_f32_16x16x32_bf16 v[56:59], v[212:215], v[244:247], v[32:35]
	v_mfma_f32_16x16x32_bf16 v[32:35], v[216:219], v[12:15], v[68:71]
	v_mfma_f32_16x16x32_bf16 v[12:15], v[224:227], v[12:15], v[72:75]
	v_mfma_f32_16x16x32_bf16 v[112:115], v[228:231], v[24:27], v[12:15]
	v_mfma_f32_16x16x32_bf16 v[12:15], v[216:219], v[28:31], v[76:79]
	v_mfma_f32_16x16x32_bf16 v[100:103], v[220:223], v[96:99], v[12:15]
	v_mfma_f32_16x16x32_bf16 v[12:15], v[224:227], v[28:31], v[80:83]
	v_mfma_f32_16x16x32_bf16 v[96:99], v[228:231], v[96:99], v[12:15]
	v_mfma_f32_16x16x32_bf16 v[12:15], v[216:219], v[232:235], v[84:87]
	v_mfma_f32_16x16x32_bf16 v[84:87], v[220:223], v[236:239], v[12:15]
	v_mfma_f32_16x16x32_bf16 v[12:15], v[224:227], v[232:235], v[128:131]
	v_mfma_f32_16x16x32_bf16 v[80:83], v[228:231], v[236:239], v[12:15]
	v_mfma_f32_16x16x32_bf16 v[12:15], v[216:219], v[240:243], v[132:135]
	v_mfma_f32_16x16x32_bf16 v[52:55], v[220:223], v[244:247], v[12:15]
	v_mfma_f32_16x16x32_bf16 v[12:15], v[224:227], v[240:243], v[136:139]
	v_mfma_f32_16x16x32_bf16 v[116:119], v[220:223], v[24:27], v[32:35]
	v_mfma_f32_16x16x32_bf16 v[48:51], v[228:231], v[244:247], v[12:15]
	s_barrier
	s_add_i32 s37, s69, s25
	s_mov_b32 m0, s37
	s_add_i32 s74, s37, 0x2000
	ds_read_b128 v[32:35], v150 offset:49152
	ds_read_b128 v[36:39], v150 offset:50176
	ds_read_b128 v[128:131], v150 offset:51200
	ds_read_b128 v[132:135], v150 offset:52224
	ds_read_b128 v[136:139], v150 offset:53248
	ds_read_b128 v[232:235], v150 offset:54272
	ds_read_b128 v[236:239], v150 offset:55296
	ds_read_b128 v[240:243], v150 offset:56320
	s_nop 0
	global_load_lds_dwordx4 v144, s[52:53]
	s_mov_b32 m0, s74
	s_nop 0
	global_load_lds_dwordx4 v146, s[52:53]
	s_add_u32 s52, s46, 0x80180
	s_addc_u32 s53, s47, 0
	s_add_i32 s75, s70, s25
	s_mov_b32 m0, s75
	s_add_i32 s76, s75, 0x2000
	s_nop 0
	global_load_lds_dwordx4 v144, s[52:53]
	s_mov_b32 m0, s76
	s_nop 0
	global_load_lds_dwordx4 v146, s[52:53]
	s_mov_b32 m0, s62
	s_nop 0
	global_load_lds_dwordx4 v143, s[50:51]
	s_mov_b32 m0, s63
	s_nop 0
	global_load_lds_dwordx4 v145, s[50:51]
	s_waitcnt vmcnt(8)
	s_waitcnt lgkmcnt(0)
	s_barrier
	s_waitcnt lgkmcnt(0)
	v_mfma_f32_16x16x32_bf16 v[12:15], v[4:7], v[32:35], v[156:159]
	v_mfma_f32_16x16x32_bf16 v[76:79], v[8:11], v[36:39], v[12:15]
	v_mfma_f32_16x16x32_bf16 v[12:15], v[208:211], v[32:35], v[160:163]
	v_mfma_f32_16x16x32_bf16 v[72:75], v[212:215], v[36:39], v[12:15]
	v_mfma_f32_16x16x32_bf16 v[12:15], v[4:7], v[128:131], v[164:167]
	v_mfma_f32_16x16x32_bf16 v[44:47], v[8:11], v[132:135], v[12:15]
	v_mfma_f32_16x16x32_bf16 v[12:15], v[208:211], v[128:131], v[168:171]
	v_mfma_f32_16x16x32_bf16 v[40:43], v[212:215], v[132:135], v[12:15]
	v_mfma_f32_16x16x32_bf16 v[12:15], v[4:7], v[136:139], v[172:175]
	v_mfma_f32_16x16x32_bf16 v[28:31], v[8:11], v[232:235], v[12:15]
	v_mfma_f32_16x16x32_bf16 v[12:15], v[208:211], v[136:139], v[176:179]
	v_mfma_f32_16x16x32_bf16 v[4:7], v[4:7], v[236:239], v[16:19]
	v_mfma_f32_16x16x32_bf16 v[24:27], v[212:215], v[232:235], v[12:15]
	v_mfma_f32_16x16x32_bf16 v[12:15], v[8:11], v[240:243], v[4:7]
	v_mfma_f32_16x16x32_bf16 v[4:7], v[208:211], v[236:239], v[20:23]
	v_mfma_f32_16x16x32_bf16 v[8:11], v[212:215], v[240:243], v[4:7]
	v_mfma_f32_16x16x32_bf16 v[4:7], v[216:219], v[32:35], v[180:183]
	v_mfma_f32_16x16x32_bf16 v[68:71], v[220:223], v[36:39], v[4:7]
	v_mfma_f32_16x16x32_bf16 v[4:7], v[224:227], v[32:35], v[184:187]
	v_mfma_f32_16x16x32_bf16 v[64:67], v[228:231], v[36:39], v[4:7]
	v_mfma_f32_16x16x32_bf16 v[4:7], v[216:219], v[128:131], v[188:191]
	v_mfma_f32_16x16x32_bf16 v[36:39], v[220:223], v[132:135], v[4:7]
	v_mfma_f32_16x16x32_bf16 v[4:7], v[224:227], v[128:131], v[192:195]
	v_mfma_f32_16x16x32_bf16 v[32:35], v[228:231], v[132:135], v[4:7]
	v_mfma_f32_16x16x32_bf16 v[4:7], v[216:219], v[136:139], v[196:199]
	v_mfma_f32_16x16x32_bf16 v[20:23], v[220:223], v[232:235], v[4:7]
	v_mfma_f32_16x16x32_bf16 v[4:7], v[224:227], v[136:139], v[200:203]
	v_mfma_f32_16x16x32_bf16 v[0:3], v[216:219], v[236:239], v[0:3]
	v_mfma_f32_16x16x32_bf16 v[16:19], v[228:231], v[232:235], v[4:7]
	v_mfma_f32_16x16x32_bf16 v[4:7], v[220:223], v[240:243], v[0:3]
	v_mfma_f32_16x16x32_bf16 v[0:3], v[224:227], v[236:239], v[204:207]
	v_mfma_f32_16x16x32_bf16 v[0:3], v[228:231], v[240:243], v[0:3]
	s_barrier
	s_add_u32 s54, s48, 0x100
	s_addc_u32 s55, s49, 0
	s_add_u32 s77, s46, 0x200
	s_addc_u32 s78, s47, 0
	s_mov_b32 s79, 0
.LBB0_429:
	s_add_u32 s46, s54, 0x100
	s_addc_u32 s47, s55, 0
	s_cmp_eq_u32 s79, 28
	s_cselect_b32 s52, s21, s46
	s_cselect_b32 s53, s20, s47
	s_cselect_b32 s50, s12, s77
	s_cselect_b32 s51, s9, s78
	s_add_u32 s48, s52, 0x80
	s_addc_u32 s49, s53, 0
	s_add_i32 s80, 0, 0x10000
	v_add_u32_e32 v155, s80, v147
	s_add_i32 s82, 0, 0x14000
	ds_read_b128 v[128:131], v155
	ds_read_b128 v[132:135], v155 offset:1024
	ds_read_b128 v[136:139], v155 offset:2048
	ds_read_b128 v[156:159], v155 offset:3072
	v_add_u32_e32 v155, s82, v147
	ds_read_b128 v[160:163], v155
	ds_read_b128 v[164:167], v155 offset:1024
	ds_read_b128 v[168:171], v155 offset:2048
	ds_read_b128 v[172:175], v155 offset:3072
	s_add_u32 s54, s54, 0x80080
	s_addc_u32 s55, s55, 0
	s_mov_b32 m0, s0
	ds_read_b128 v[176:179], v150
	ds_read_b128 v[180:183], v150 offset:1024
	ds_read_b128 v[184:187], v150 offset:2048
	ds_read_b128 v[188:191], v150 offset:3072
	ds_read_b128 v[192:195], v150 offset:4096
	ds_read_b128 v[196:199], v150 offset:5120
	ds_read_b128 v[200:203], v150 offset:6144
	ds_read_b128 v[204:207], v150 offset:7168
	s_nop 0
	global_load_lds_dwordx4 v143, s[54:55]
	s_mov_b32 m0, s1
	s_nop 0
	global_load_lds_dwordx4 v145, s[54:55]
	s_waitcnt vmcnt(8)
	s_waitcnt lgkmcnt(0)
	s_barrier
	s_waitcnt lgkmcnt(0)
	v_mfma_f32_16x16x32_bf16 v[124:127], v[128:131], v[176:179], v[124:127]
	v_mfma_f32_16x16x32_bf16 v[120:123], v[136:139], v[176:179], v[120:123]
	v_mfma_f32_16x16x32_bf16 v[108:111], v[128:131], v[184:187], v[108:111]
	v_mfma_f32_16x16x32_bf16 v[104:107], v[136:139], v[184:187], v[104:107]
	v_mfma_f32_16x16x32_bf16 v[92:95], v[128:131], v[192:195], v[92:95]
	v_mfma_f32_16x16x32_bf16 v[88:91], v[136:139], v[192:195], v[88:91]
	v_mfma_f32_16x16x32_bf16 v[60:63], v[128:131], v[200:203], v[60:63]
	v_mfma_f32_16x16x32_bf16 v[56:59], v[136:139], v[200:203], v[56:59]
	v_mfma_f32_16x16x32_bf16 v[124:127], v[132:135], v[180:183], v[124:127]
	v_mfma_f32_16x16x32_bf16 v[120:123], v[156:159], v[180:183], v[120:123]
	v_mfma_f32_16x16x32_bf16 v[108:111], v[132:135], v[188:191], v[108:111]
	v_mfma_f32_16x16x32_bf16 v[104:107], v[156:159], v[188:191], v[104:107]
	v_mfma_f32_16x16x32_bf16 v[92:95], v[132:135], v[196:199], v[92:95]
	v_mfma_f32_16x16x32_bf16 v[88:91], v[156:159], v[196:199], v[88:91]
	v_mfma_f32_16x16x32_bf16 v[60:63], v[132:135], v[204:207], v[60:63]
	v_mfma_f32_16x16x32_bf16 v[56:59], v[156:159], v[204:207], v[56:59]
	v_mfma_f32_16x16x32_bf16 v[116:119], v[160:163], v[176:179], v[116:119]
	v_mfma_f32_16x16x32_bf16 v[112:115], v[168:171], v[176:179], v[112:115]
	v_mfma_f32_16x16x32_bf16 v[100:103], v[160:163], v[184:187], v[100:103]
	v_mfma_f32_16x16x32_bf16 v[96:99], v[168:171], v[184:187], v[96:99]
	v_mfma_f32_16x16x32_bf16 v[84:87], v[160:163], v[192:195], v[84:87]
	v_mfma_f32_16x16x32_bf16 v[80:83], v[168:171], v[192:195], v[80:83]
	v_mfma_f32_16x16x32_bf16 v[52:55], v[160:163], v[200:203], v[52:55]
	v_mfma_f32_16x16x32_bf16 v[48:51], v[168:171], v[200:203], v[48:51]
	v_mfma_f32_16x16x32_bf16 v[116:119], v[164:167], v[180:183], v[116:119]
	v_mfma_f32_16x16x32_bf16 v[112:115], v[172:175], v[180:183], v[112:115]
	v_mfma_f32_16x16x32_bf16 v[100:103], v[164:167], v[188:191], v[100:103]
	v_mfma_f32_16x16x32_bf16 v[96:99], v[172:175], v[188:191], v[96:99]
	v_mfma_f32_16x16x32_bf16 v[84:87], v[164:167], v[196:199], v[84:87]
	v_mfma_f32_16x16x32_bf16 v[80:83], v[172:175], v[196:199], v[80:83]
	v_mfma_f32_16x16x32_bf16 v[52:55], v[164:167], v[204:207], v[52:55]
	v_mfma_f32_16x16x32_bf16 v[48:51], v[172:175], v[204:207], v[48:51]
	s_barrier
	s_add_i32 s54, s80, s25
	s_mov_b32 m0, s54
	ds_read_b128 v[176:179], v150 offset:16384
	ds_read_b128 v[180:183], v150 offset:17408
	ds_read_b128 v[184:187], v150 offset:18432
	ds_read_b128 v[188:191], v150 offset:19456
	ds_read_b128 v[192:195], v150 offset:20480
	ds_read_b128 v[196:199], v150 offset:21504
	ds_read_b128 v[200:203], v150 offset:22528
	ds_read_b128 v[204:207], v150 offset:23552
	s_nop 0
	global_load_lds_dwordx4 v144, s[50:51]
	s_add_i32 m0, s54, 0x2000
	s_add_u32 s54, s50, 0x80000
	s_addc_u32 s55, s51, 0
	s_add_i32 s80, s82, s25
	s_nop 0
	global_load_lds_dwordx4 v146, s[50:51]
	s_mov_b32 m0, s80
	s_nop 0
	global_load_lds_dwordx4 v144, s[54:55]
	s_add_i32 m0, s80, 0x2000
	s_nop 0
	global_load_lds_dwordx4 v146, s[54:55]
	s_mov_b32 m0, s26
	s_nop 0
	global_load_lds_dwordx4 v143, s[52:53]
	s_mov_b32 m0, s59
	s_nop 0
	global_load_lds_dwordx4 v145, s[52:53]
	s_waitcnt vmcnt(8)
	s_waitcnt lgkmcnt(0)
	s_barrier
	s_waitcnt lgkmcnt(0)
	v_mfma_f32_16x16x32_bf16 v[76:79], v[128:131], v[176:179], v[76:79]
	v_mfma_f32_16x16x32_bf16 v[72:75], v[136:139], v[176:179], v[72:75]
	v_mfma_f32_16x16x32_bf16 v[44:47], v[128:131], v[184:187], v[44:47]
	v_mfma_f32_16x16x32_bf16 v[40:43], v[136:139], v[184:187], v[40:43]
	v_mfma_f32_16x16x32_bf16 v[28:31], v[128:131], v[192:195], v[28:31]
	v_mfma_f32_16x16x32_bf16 v[24:27], v[136:139], v[192:195], v[24:27]
	v_mfma_f32_16x16x32_bf16 v[12:15], v[128:131], v[200:203], v[12:15]
	v_mfma_f32_16x16x32_bf16 v[8:11], v[136:139], v[200:203], v[8:11]
	v_mfma_f32_16x16x32_bf16 v[76:79], v[132:135], v[180:183], v[76:79]
	v_mfma_f32_16x16x32_bf16 v[72:75], v[156:159], v[180:183], v[72:75]
	v_mfma_f32_16x16x32_bf16 v[44:47], v[132:135], v[188:191], v[44:47]
	v_mfma_f32_16x16x32_bf16 v[40:43], v[156:159], v[188:191], v[40:43]
	v_mfma_f32_16x16x32_bf16 v[28:31], v[132:135], v[196:199], v[28:31]
	v_mfma_f32_16x16x32_bf16 v[24:27], v[156:159], v[196:199], v[24:27]
	v_mfma_f32_16x16x32_bf16 v[12:15], v[132:135], v[204:207], v[12:15]
	v_mfma_f32_16x16x32_bf16 v[8:11], v[156:159], v[204:207], v[8:11]
	v_mfma_f32_16x16x32_bf16 v[68:71], v[160:163], v[176:179], v[68:71]
	v_mfma_f32_16x16x32_bf16 v[64:67], v[168:171], v[176:179], v[64:67]
	v_mfma_f32_16x16x32_bf16 v[36:39], v[160:163], v[184:187], v[36:39]
	v_mfma_f32_16x16x32_bf16 v[32:35], v[168:171], v[184:187], v[32:35]
	v_mfma_f32_16x16x32_bf16 v[20:23], v[160:163], v[192:195], v[20:23]
	v_mfma_f32_16x16x32_bf16 v[16:19], v[168:171], v[192:195], v[16:19]
	v_mfma_f32_16x16x32_bf16 v[4:7], v[160:163], v[200:203], v[4:7]
	v_mfma_f32_16x16x32_bf16 v[0:3], v[168:171], v[200:203], v[0:3]
	v_mfma_f32_16x16x32_bf16 v[68:71], v[164:167], v[180:183], v[68:71]
	v_mfma_f32_16x16x32_bf16 v[64:67], v[172:175], v[180:183], v[64:67]
	v_mfma_f32_16x16x32_bf16 v[36:39], v[164:167], v[188:191], v[36:39]
	v_mfma_f32_16x16x32_bf16 v[32:35], v[172:175], v[188:191], v[32:35]
	v_mfma_f32_16x16x32_bf16 v[20:23], v[164:167], v[196:199], v[20:23]
	v_mfma_f32_16x16x32_bf16 v[16:19], v[172:175], v[196:199], v[16:19]
	v_mfma_f32_16x16x32_bf16 v[4:7], v[164:167], v[204:207], v[4:7]
	v_mfma_f32_16x16x32_bf16 v[0:3], v[172:175], v[204:207], v[0:3]
	s_barrier
	ds_read_b128 v[128:131], v153
	ds_read_b128 v[132:135], v153 offset:1024
	ds_read_b128 v[136:139], v153 offset:2048
	ds_read_b128 v[156:159], v153 offset:3072
	ds_read_b128 v[160:163], v154
	ds_read_b128 v[164:167], v154 offset:1024
	ds_read_b128 v[168:171], v154 offset:2048
	ds_read_b128 v[172:175], v154 offset:3072
	s_add_u32 s52, s52, 0x80000
	s_addc_u32 s53, s53, 0
	s_mov_b32 m0, s60
	ds_read_b128 v[176:179], v150 offset:32768
	ds_read_b128 v[180:183], v150 offset:33792
	ds_read_b128 v[184:187], v150 offset:34816
	ds_read_b128 v[188:191], v150 offset:35840
	ds_read_b128 v[192:195], v150 offset:36864
	ds_read_b128 v[196:199], v150 offset:37888
	ds_read_b128 v[200:203], v150 offset:38912
	ds_read_b128 v[204:207], v150 offset:39936
	s_nop 0
	global_load_lds_dwordx4 v143, s[52:53]
	s_mov_b32 m0, s61
	s_nop 0
	global_load_lds_dwordx4 v145, s[52:53]
	s_waitcnt vmcnt(8)
	s_waitcnt lgkmcnt(0)
	s_barrier
	s_waitcnt lgkmcnt(0)
	v_mfma_f32_16x16x32_bf16 v[124:127], v[128:131], v[176:179], v[124:127]
	v_mfma_f32_16x16x32_bf16 v[120:123], v[136:139], v[176:179], v[120:123]
	v_mfma_f32_16x16x32_bf16 v[108:111], v[128:131], v[184:187], v[108:111]
	v_mfma_f32_16x16x32_bf16 v[104:107], v[136:139], v[184:187], v[104:107]
	v_mfma_f32_16x16x32_bf16 v[92:95], v[128:131], v[192:195], v[92:95]
	v_mfma_f32_16x16x32_bf16 v[88:91], v[136:139], v[192:195], v[88:91]
	v_mfma_f32_16x16x32_bf16 v[60:63], v[128:131], v[200:203], v[60:63]
	v_mfma_f32_16x16x32_bf16 v[56:59], v[136:139], v[200:203], v[56:59]
	v_mfma_f32_16x16x32_bf16 v[124:127], v[132:135], v[180:183], v[124:127]
	v_mfma_f32_16x16x32_bf16 v[120:123], v[156:159], v[180:183], v[120:123]
	v_mfma_f32_16x16x32_bf16 v[108:111], v[132:135], v[188:191], v[108:111]
	v_mfma_f32_16x16x32_bf16 v[104:107], v[156:159], v[188:191], v[104:107]
	v_mfma_f32_16x16x32_bf16 v[92:95], v[132:135], v[196:199], v[92:95]
	v_mfma_f32_16x16x32_bf16 v[88:91], v[156:159], v[196:199], v[88:91]
	v_mfma_f32_16x16x32_bf16 v[60:63], v[132:135], v[204:207], v[60:63]
	v_mfma_f32_16x16x32_bf16 v[56:59], v[156:159], v[204:207], v[56:59]
	v_mfma_f32_16x16x32_bf16 v[116:119], v[160:163], v[176:179], v[116:119]
	v_mfma_f32_16x16x32_bf16 v[112:115], v[168:171], v[176:179], v[112:115]
	v_mfma_f32_16x16x32_bf16 v[100:103], v[160:163], v[184:187], v[100:103]
	v_mfma_f32_16x16x32_bf16 v[96:99], v[168:171], v[184:187], v[96:99]
	v_mfma_f32_16x16x32_bf16 v[84:87], v[160:163], v[192:195], v[84:87]
	v_mfma_f32_16x16x32_bf16 v[80:83], v[168:171], v[192:195], v[80:83]
	v_mfma_f32_16x16x32_bf16 v[52:55], v[160:163], v[200:203], v[52:55]
	v_mfma_f32_16x16x32_bf16 v[48:51], v[168:171], v[200:203], v[48:51]
	v_mfma_f32_16x16x32_bf16 v[116:119], v[164:167], v[180:183], v[116:119]
	v_mfma_f32_16x16x32_bf16 v[112:115], v[172:175], v[180:183], v[112:115]
	v_mfma_f32_16x16x32_bf16 v[100:103], v[164:167], v[188:191], v[100:103]
	v_mfma_f32_16x16x32_bf16 v[96:99], v[172:175], v[188:191], v[96:99]
	v_mfma_f32_16x16x32_bf16 v[84:87], v[164:167], v[196:199], v[84:87]
	v_mfma_f32_16x16x32_bf16 v[80:83], v[172:175], v[196:199], v[80:83]
	v_mfma_f32_16x16x32_bf16 v[52:55], v[164:167], v[204:207], v[52:55]
	v_mfma_f32_16x16x32_bf16 v[48:51], v[172:175], v[204:207], v[48:51]
	s_barrier
	s_add_u32 s52, s50, 0x80
	s_mov_b32 m0, s37
	s_addc_u32 s53, s51, 0
	ds_read_b128 v[176:179], v150 offset:49152
	ds_read_b128 v[180:183], v150 offset:50176
	ds_read_b128 v[184:187], v150 offset:51200
	ds_read_b128 v[188:191], v150 offset:52224
	ds_read_b128 v[192:195], v150 offset:53248
	ds_read_b128 v[196:199], v150 offset:54272
	ds_read_b128 v[200:203], v150 offset:55296
	ds_read_b128 v[204:207], v150 offset:56320
	s_add_u32 s50, s50, 0x80080
	global_load_lds_dwordx4 v144, s[52:53]
	s_mov_b32 m0, s74
	s_addc_u32 s51, s51, 0
	global_load_lds_dwordx4 v146, s[52:53]
	s_mov_b32 m0, s75
	s_nop 0
	global_load_lds_dwordx4 v144, s[50:51]
	s_mov_b32 m0, s76
	s_nop 0
	global_load_lds_dwordx4 v146, s[50:51]
	s_mov_b32 m0, s62
	s_nop 0
	global_load_lds_dwordx4 v143, s[48:49]
	s_mov_b32 m0, s63
	s_nop 0
	global_load_lds_dwordx4 v145, s[48:49]
	s_waitcnt vmcnt(8)
	s_waitcnt lgkmcnt(0)
	s_barrier
	s_waitcnt lgkmcnt(0)
	v_mfma_f32_16x16x32_bf16 v[76:79], v[128:131], v[176:179], v[76:79]
	v_mfma_f32_16x16x32_bf16 v[72:75], v[136:139], v[176:179], v[72:75]
	v_mfma_f32_16x16x32_bf16 v[44:47], v[128:131], v[184:187], v[44:47]
	v_mfma_f32_16x16x32_bf16 v[40:43], v[136:139], v[184:187], v[40:43]
	v_mfma_f32_16x16x32_bf16 v[28:31], v[128:131], v[192:195], v[28:31]
	v_mfma_f32_16x16x32_bf16 v[24:27], v[136:139], v[192:195], v[24:27]
	v_mfma_f32_16x16x32_bf16 v[12:15], v[128:131], v[200:203], v[12:15]
	v_mfma_f32_16x16x32_bf16 v[8:11], v[136:139], v[200:203], v[8:11]
	v_mfma_f32_16x16x32_bf16 v[76:79], v[132:135], v[180:183], v[76:79]
	v_mfma_f32_16x16x32_bf16 v[72:75], v[156:159], v[180:183], v[72:75]
	v_mfma_f32_16x16x32_bf16 v[44:47], v[132:135], v[188:191], v[44:47]
	v_mfma_f32_16x16x32_bf16 v[40:43], v[156:159], v[188:191], v[40:43]
	v_mfma_f32_16x16x32_bf16 v[28:31], v[132:135], v[196:199], v[28:31]
	v_mfma_f32_16x16x32_bf16 v[24:27], v[156:159], v[196:199], v[24:27]
	v_mfma_f32_16x16x32_bf16 v[12:15], v[132:135], v[204:207], v[12:15]
	v_mfma_f32_16x16x32_bf16 v[8:11], v[156:159], v[204:207], v[8:11]
	v_mfma_f32_16x16x32_bf16 v[68:71], v[160:163], v[176:179], v[68:71]
	v_mfma_f32_16x16x32_bf16 v[64:67], v[168:171], v[176:179], v[64:67]
	v_mfma_f32_16x16x32_bf16 v[36:39], v[160:163], v[184:187], v[36:39]
	v_mfma_f32_16x16x32_bf16 v[32:35], v[168:171], v[184:187], v[32:35]
	v_mfma_f32_16x16x32_bf16 v[20:23], v[160:163], v[192:195], v[20:23]
	v_mfma_f32_16x16x32_bf16 v[16:19], v[168:171], v[192:195], v[16:19]
	v_mfma_f32_16x16x32_bf16 v[4:7], v[160:163], v[200:203], v[4:7]
	v_mfma_f32_16x16x32_bf16 v[0:3], v[168:171], v[200:203], v[0:3]
	v_mfma_f32_16x16x32_bf16 v[68:71], v[164:167], v[180:183], v[68:71]
	v_mfma_f32_16x16x32_bf16 v[64:67], v[172:175], v[180:183], v[64:67]
	v_mfma_f32_16x16x32_bf16 v[36:39], v[164:167], v[188:191], v[36:39]
	v_mfma_f32_16x16x32_bf16 v[32:35], v[172:175], v[188:191], v[32:35]
	v_mfma_f32_16x16x32_bf16 v[20:23], v[164:167], v[196:199], v[20:23]
	v_mfma_f32_16x16x32_bf16 v[16:19], v[172:175], v[196:199], v[16:19]
	v_mfma_f32_16x16x32_bf16 v[4:7], v[164:167], v[204:207], v[4:7]
	v_mfma_f32_16x16x32_bf16 v[0:3], v[172:175], v[204:207], v[0:3]
	s_barrier
	s_add_i32 s79, s79, 2
	s_add_u32 s77, s77, 0x100
	s_addc_u32 s78, s78, 0
	s_cmp_gt_u32 s79, 29
	s_mov_b64 s[54:55], s[46:47]
	s_cbranch_scc0 .LBB0_429
	s_and_b64 vcc, exec, s[4:5]
	s_cbranch_vccz .LBB0_432
	s_barrier

.LBB0_687:
	s_add_u32 s20, s52, 0x100
	s_addc_u32 s21, s53, 0
	s_waitcnt lgkmcnt(0)
	s_add_u32 s48, s50, 0x100
	s_addc_u32 s49, s51, 0
	s_barrier
	v_mfma_f32_16x16x32_bf16 v[32:35], v[16:19], v[68:71], 0
	v_mfma_f32_16x16x32_bf16 v[36:39], v[24:27], v[68:71], 0
	s_waitcnt lgkmcnt(0)
	v_mfma_f32_16x16x32_bf16 v[40:43], v[16:19], v[84:87], 0
	v_mfma_f32_16x16x32_bf16 v[44:47], v[24:27], v[84:87], 0
	v_mfma_f32_16x16x32_bf16 v[48:51], v[16:19], v[92:95], 0
	v_mfma_f32_16x16x32_bf16 v[52:55], v[24:27], v[92:95], 0
	v_mfma_f32_16x16x32_bf16 v[56:59], v[16:19], v[76:79], 0
	v_mfma_f32_16x16x32_bf16 v[60:63], v[24:27], v[76:79], 0
	v_mfma_f32_16x16x32_bf16 v[138:141], v[20:23], v[72:75], v[32:35]
	v_mfma_f32_16x16x32_bf16 v[36:39], v[28:31], v[72:75], v[36:39]
	v_mfma_f32_16x16x32_bf16 v[40:43], v[20:23], v[88:91], v[40:43]
	v_mfma_f32_16x16x32_bf16 v[44:47], v[28:31], v[88:91], v[44:47]
	v_mfma_f32_16x16x32_bf16 v[48:51], v[20:23], v[96:99], v[48:51]
	v_mfma_f32_16x16x32_bf16 v[52:55], v[28:31], v[96:99], v[52:55]
	v_mfma_f32_16x16x32_bf16 v[56:59], v[20:23], v[80:83], v[56:59]
	v_mfma_f32_16x16x32_bf16 v[60:63], v[28:31], v[80:83], v[60:63]
	v_mfma_f32_16x16x32_bf16 v[64:67], v[0:3], v[68:71], 0
	v_mfma_f32_16x16x32_bf16 v[68:71], v[8:11], v[68:71], 0
	v_mfma_f32_16x16x32_bf16 v[64:67], v[4:7], v[72:75], v[64:67]
	v_mfma_f32_16x16x32_bf16 v[68:71], v[12:15], v[72:75], v[68:71]
	v_mfma_f32_16x16x32_bf16 v[72:75], v[0:3], v[84:87], 0
	v_mfma_f32_16x16x32_bf16 v[84:87], v[8:11], v[84:87], 0
	v_mfma_f32_16x16x32_bf16 v[72:75], v[4:7], v[88:91], v[72:75]
	v_mfma_f32_16x16x32_bf16 v[84:87], v[12:15], v[88:91], v[84:87]
	v_mfma_f32_16x16x32_bf16 v[88:91], v[0:3], v[92:95], 0
	v_mfma_f32_16x16x32_bf16 v[92:95], v[8:11], v[92:95], 0
	v_mfma_f32_16x16x32_bf16 v[88:91], v[4:7], v[96:99], v[88:91]
	v_mfma_f32_16x16x32_bf16 v[92:95], v[12:15], v[96:99], v[92:95]
	v_mfma_f32_16x16x32_bf16 v[96:99], v[0:3], v[76:79], 0
	v_mfma_f32_16x16x32_bf16 v[76:79], v[8:11], v[76:79], 0
	v_mfma_f32_16x16x32_bf16 v[108:111], v[4:7], v[80:83], v[96:99]
	v_mfma_f32_16x16x32_bf16 v[120:123], v[12:15], v[80:83], v[76:79]
	s_barrier
	s_mov_b32 m0, s58
	ds_read_b128 v[116:119], v209 offset:16384
	ds_read_b128 v[124:127], v209 offset:17408
	ds_read_b128 v[104:107], v209 offset:18432
	ds_read_b128 v[112:115], v209 offset:19456
	ds_read_b128 v[96:99], v209 offset:20480
	ds_read_b128 v[100:103], v209 offset:21504
	ds_read_b128 v[76:79], v209 offset:22528
	ds_read_b128 v[80:83], v209 offset:23552
	s_nop 0
	global_load_lds_dwordx4 v203, s[48:49]
	s_mov_b32 m0, s59
	s_nop 0
	global_load_lds_dwordx4 v205, s[48:49]
	s_add_u32 s48, s50, 0x80100
	s_addc_u32 s49, s51, 0
	s_mov_b32 m0, s60
	s_and_b64 vcc, exec, s[46:47]
	global_load_lds_dwordx4 v203, s[48:49]
	s_mov_b32 m0, s61
	s_nop 0
	global_load_lds_dwordx4 v205, s[48:49]
	s_mov_b32 m0, s27
	s_mov_b64 s[48:49], -1
	global_load_lds_dwordx4 v202, s[20:21]
	s_mov_b32 m0, s62
	s_nop 0
	global_load_lds_dwordx4 v204, s[20:21]
	s_cbranch_vccz .LBB0_689
	s_waitcnt vmcnt(8)
	s_mov_b64 s[48:49], 0

.LBB0_691:
	s_ashr_i32 s41, s40, 31
	s_lshl_b64 s[20:21], s[40:41], 20
	s_add_u32 s46, s13, s20
	s_addc_u32 s47, s82, s21
	s_and_b64 s[20:21], s[44:45], exec
	s_cselect_b32 s3, s47, s53
	s_cselect_b32 s5, s46, s52
	s_ashr_i32 s43, s42, 31
	s_lshl_b64 s[20:21], s[42:43], 20
	s_add_u32 s48, s24, s20
	s_addc_u32 s49, s25, s21
	s_and_b64 s[20:21], s[44:45], exec
	s_cselect_b32 s12, s49, s51
	s_cselect_b32 s20, s48, s50
	s_add_u32 s54, s52, 0x180
	s_waitcnt lgkmcnt(0)
	s_addc_u32 s55, s53, 0
	s_add_u32 s56, s50, 0x180
	s_addc_u32 s57, s51, 0
	s_barrier
	s_waitcnt lgkmcnt(0)
	v_mfma_f32_16x16x32_bf16 v[128:131], v[16:19], v[116:119], 0
	v_mfma_f32_16x16x32_bf16 v[134:137], v[20:23], v[124:127], v[128:131]
	v_mfma_f32_16x16x32_bf16 v[128:131], v[24:27], v[116:119], 0
	v_mfma_f32_16x16x32_bf16 v[156:159], v[28:31], v[124:127], v[128:131]
	v_mfma_f32_16x16x32_bf16 v[128:131], v[16:19], v[104:107], 0
	v_mfma_f32_16x16x32_bf16 v[160:163], v[20:23], v[112:115], v[128:131]
	v_mfma_f32_16x16x32_bf16 v[128:131], v[24:27], v[104:107], 0
	v_mfma_f32_16x16x32_bf16 v[164:167], v[28:31], v[112:115], v[128:131]
	v_mfma_f32_16x16x32_bf16 v[128:131], v[16:19], v[96:99], 0
	v_mfma_f32_16x16x32_bf16 v[16:19], v[16:19], v[76:79], 0
	v_mfma_f32_16x16x32_bf16 v[168:171], v[20:23], v[100:103], v[128:131]
	v_mfma_f32_16x16x32_bf16 v[16:19], v[20:23], v[80:83], v[16:19]
	v_mfma_f32_16x16x32_bf16 v[20:23], v[24:27], v[76:79], 0
	v_mfma_f32_16x16x32_bf16 v[128:131], v[24:27], v[96:99], 0
	v_mfma_f32_16x16x32_bf16 v[20:23], v[28:31], v[80:83], v[20:23]
	v_mfma_f32_16x16x32_bf16 v[172:175], v[28:31], v[100:103], v[128:131]
	v_mfma_f32_16x16x32_bf16 v[24:27], v[0:3], v[116:119], 0
	v_mfma_f32_16x16x32_bf16 v[176:179], v[4:7], v[124:127], v[24:27]
	v_mfma_f32_16x16x32_bf16 v[24:27], v[8:11], v[116:119], 0
	v_mfma_f32_16x16x32_bf16 v[180:183], v[12:15], v[124:127], v[24:27]
	v_mfma_f32_16x16x32_bf16 v[24:27], v[0:3], v[104:107], 0
	v_mfma_f32_16x16x32_bf16 v[186:189], v[4:7], v[112:115], v[24:27]
	v_mfma_f32_16x16x32_bf16 v[24:27], v[8:11], v[104:107], 0
	v_mfma_f32_16x16x32_bf16 v[190:193], v[12:15], v[112:115], v[24:27]
	v_mfma_f32_16x16x32_bf16 v[24:27], v[0:3], v[96:99], 0
	v_mfma_f32_16x16x32_bf16 v[0:3], v[0:3], v[76:79], 0
	v_mfma_f32_16x16x32_bf16 v[194:197], v[4:7], v[100:103], v[24:27]
	v_mfma_f32_16x16x32_bf16 v[24:27], v[8:11], v[96:99], 0
	v_mfma_f32_16x16x32_bf16 v[0:3], v[4:7], v[80:83], v[0:3]
	v_mfma_f32_16x16x32_bf16 v[4:7], v[8:11], v[76:79], 0
	v_mfma_f32_16x16x32_bf16 v[198:201], v[12:15], v[100:103], v[24:27]
	v_mfma_f32_16x16x32_bf16 v[212:215], v[12:15], v[80:83], v[4:7]
	s_barrier
	v_add_u32_e32 v132, s72, v206
	v_add_u32_e32 v133, s73, v206
	s_nop 1
	ds_read_b128 v[4:7], v132
	ds_read_b128 v[8:11], v132 offset:1024
	ds_read_b128 v[216:219], v132 offset:2048
	ds_read_b128 v[220:223], v132 offset:3072
	ds_read_b128 v[224:227], v133
	ds_read_b128 v[228:231], v133 offset:1024
	ds_read_b128 v[232:235], v133 offset:2048
	ds_read_b128 v[236:239], v133 offset:3072
	s_add_u32 s76, s52, 0x80100
	s_addc_u32 s77, s53, 0
	s_mov_b32 m0, s63
	ds_read_b128 v[12:15], v209 offset:32768
	ds_read_b128 v[24:27], v209 offset:33792
	ds_read_b128 v[28:31], v209 offset:34816
	ds_read_b128 v[96:99], v209 offset:35840
	ds_read_b128 v[240:243], v209 offset:36864
	ds_read_b128 v[244:247], v209 offset:37888
	ds_read_b128 v[248:251], v209 offset:38912
	ds_read_b128 v[32:35], v209 offset:39936
	s_nop 0
	global_load_lds_dwordx4 v202, s[76:77]
	s_mov_b32 m0, s64
	s_nop 0
	global_load_lds_dwordx4 v204, s[76:77]
	s_waitcnt vmcnt(8)
	s_waitcnt lgkmcnt(0)
	s_barrier
	s_waitcnt lgkmcnt(0)
	v_mfma_f32_16x16x32_bf16 v[36:39], v[216:219], v[12:15], v[36:39]
	v_mfma_f32_16x16x32_bf16 v[148:151], v[220:223], v[24:27], v[36:39]
	v_mfma_f32_16x16x32_bf16 v[36:39], v[4:7], v[28:31], v[40:43]
	v_mfma_f32_16x16x32_bf16 v[128:131], v[8:11], v[96:99], v[36:39]
	v_mfma_f32_16x16x32_bf16 v[36:39], v[216:219], v[28:31], v[44:47]
	v_mfma_f32_16x16x32_bf16 v[124:127], v[220:223], v[96:99], v[36:39]
	v_mfma_f32_16x16x32_bf16 v[36:39], v[4:7], v[240:243], v[48:51]
	v_mfma_f32_16x16x32_bf16 v[104:107], v[8:11], v[244:247], v[36:39]
	v_mfma_f32_16x16x32_bf16 v[36:39], v[216:219], v[240:243], v[52:55]
	v_mfma_f32_16x16x32_bf16 v[100:103], v[220:223], v[244:247], v[36:39]
	v_mfma_f32_16x16x32_bf16 v[36:39], v[4:7], v[248:251], v[56:59]
	v_mfma_f32_16x16x32_bf16 v[76:79], v[4:7], v[12:15], v[138:141]
	v_mfma_f32_16x16x32_bf16 v[80:83], v[8:11], v[32:35], v[36:39]
	v_mfma_f32_16x16x32_bf16 v[36:39], v[216:219], v[248:251], v[60:63]
	v_mfma_f32_16x16x32_bf16 v[152:155], v[8:11], v[24:27], v[76:79]
	v_mfma_f32_16x16x32_bf16 v[76:79], v[220:223], v[32:35], v[36:39]
	v_mfma_f32_16x16x32_bf16 v[36:39], v[224:227], v[12:15], v[64:67]
	v_mfma_f32_16x16x32_bf16 v[12:15], v[232:235], v[12:15], v[68:71]
	v_mfma_f32_16x16x32_bf16 v[140:143], v[236:239], v[24:27], v[12:15]
	v_mfma_f32_16x16x32_bf16 v[12:15], v[224:227], v[28:31], v[72:75]
	v_mfma_f32_16x16x32_bf16 v[116:119], v[228:231], v[96:99], v[12:15]
	v_mfma_f32_16x16x32_bf16 v[12:15], v[232:235], v[28:31], v[84:87]
	v_mfma_f32_16x16x32_bf16 v[112:115], v[236:239], v[96:99], v[12:15]
	v_mfma_f32_16x16x32_bf16 v[12:15], v[224:227], v[240:243], v[88:91]
	v_mfma_f32_16x16x32_bf16 v[96:99], v[228:231], v[244:247], v[12:15]
	v_mfma_f32_16x16x32_bf16 v[12:15], v[232:235], v[240:243], v[92:95]
	v_mfma_f32_16x16x32_bf16 v[88:91], v[236:239], v[244:247], v[12:15]
	v_mfma_f32_16x16x32_bf16 v[12:15], v[224:227], v[248:251], v[108:111]
	v_mfma_f32_16x16x32_bf16 v[72:75], v[228:231], v[32:35], v[12:15]
	v_mfma_f32_16x16x32_bf16 v[12:15], v[232:235], v[248:251], v[120:123]
	v_mfma_f32_16x16x32_bf16 v[144:147], v[228:231], v[24:27], v[36:39]
	v_mfma_f32_16x16x32_bf16 v[64:67], v[236:239], v[32:35], v[12:15]
	s_barrier
	s_add_i32 s21, s72, s26
	s_mov_b32 m0, s21
	s_add_i32 s41, s21, 0x2000
	ds_read_b128 v[32:35], v209 offset:49152
	ds_read_b128 v[36:39], v209 offset:50176
	ds_read_b128 v[68:71], v209 offset:51200
	ds_read_b128 v[84:87], v209 offset:52224
	ds_read_b128 v[92:95], v209 offset:53248
	ds_read_b128 v[108:111], v209 offset:54272
	ds_read_b128 v[120:123], v209 offset:55296
	ds_read_b128 v[240:243], v209 offset:56320
	s_nop 0
	global_load_lds_dwordx4 v203, s[56:57]
	s_mov_b32 m0, s41
	s_nop 0
	global_load_lds_dwordx4 v205, s[56:57]
	s_add_u32 s56, s50, 0x80180
	s_addc_u32 s57, s51, 0
	s_add_i32 s43, s73, s26
	s_mov_b32 m0, s43
	s_add_i32 s76, s43, 0x2000
	s_nop 0
	global_load_lds_dwordx4 v203, s[56:57]
	s_mov_b32 m0, s76
	s_nop 0
	global_load_lds_dwordx4 v205, s[56:57]
	s_mov_b32 m0, s65
	s_nop 0
	global_load_lds_dwordx4 v202, s[54:55]
	s_mov_b32 m0, s66
	s_nop 0
	global_load_lds_dwordx4 v204, s[54:55]
	s_waitcnt vmcnt(8)
	s_waitcnt lgkmcnt(0)
	s_barrier
	s_waitcnt lgkmcnt(0)
	v_mfma_f32_16x16x32_bf16 v[12:15], v[4:7], v[32:35], v[134:137]
	v_mfma_f32_16x16x32_bf16 v[60:63], v[8:11], v[36:39], v[12:15]
	v_mfma_f32_16x16x32_bf16 v[12:15], v[216:219], v[32:35], v[156:159]
	v_mfma_f32_16x16x32_bf16 v[56:59], v[220:223], v[36:39], v[12:15]
	v_mfma_f32_16x16x32_bf16 v[12:15], v[4:7], v[68:71], v[160:163]
	v_mfma_f32_16x16x32_bf16 v[44:47], v[8:11], v[84:87], v[12:15]
	v_mfma_f32_16x16x32_bf16 v[12:15], v[216:219], v[68:71], v[164:167]
	v_mfma_f32_16x16x32_bf16 v[40:43], v[220:223], v[84:87], v[12:15]
	v_mfma_f32_16x16x32_bf16 v[12:15], v[4:7], v[92:95], v[168:171]
	v_mfma_f32_16x16x32_bf16 v[28:31], v[8:11], v[108:111], v[12:15]
	v_mfma_f32_16x16x32_bf16 v[12:15], v[216:219], v[92:95], v[172:175]
	v_mfma_f32_16x16x32_bf16 v[4:7], v[4:7], v[120:123], v[16:19]
	v_mfma_f32_16x16x32_bf16 v[24:27], v[220:223], v[108:111], v[12:15]
	v_mfma_f32_16x16x32_bf16 v[12:15], v[8:11], v[240:243], v[4:7]
	v_mfma_f32_16x16x32_bf16 v[4:7], v[216:219], v[120:123], v[20:23]
	v_mfma_f32_16x16x32_bf16 v[8:11], v[220:223], v[240:243], v[4:7]
	v_mfma_f32_16x16x32_bf16 v[4:7], v[224:227], v[32:35], v[176:179]
	v_mfma_f32_16x16x32_bf16 v[52:55], v[228:231], v[36:39], v[4:7]
	v_mfma_f32_16x16x32_bf16 v[4:7], v[232:235], v[32:35], v[180:183]
	v_mfma_f32_16x16x32_bf16 v[48:51], v[236:239], v[36:39], v[4:7]
	v_mfma_f32_16x16x32_bf16 v[4:7], v[224:227], v[68:71], v[186:189]
	v_mfma_f32_16x16x32_bf16 v[36:39], v[228:231], v[84:87], v[4:7]
	v_mfma_f32_16x16x32_bf16 v[4:7], v[232:235], v[68:71], v[190:193]
	v_mfma_f32_16x16x32_bf16 v[32:35], v[236:239], v[84:87], v[4:7]
	v_mfma_f32_16x16x32_bf16 v[4:7], v[224:227], v[92:95], v[194:197]
	v_mfma_f32_16x16x32_bf16 v[20:23], v[228:231], v[108:111], v[4:7]
	v_mfma_f32_16x16x32_bf16 v[4:7], v[232:235], v[92:95], v[198:201]
	v_mfma_f32_16x16x32_bf16 v[0:3], v[224:227], v[120:123], v[0:3]
	v_mfma_f32_16x16x32_bf16 v[16:19], v[236:239], v[108:111], v[4:7]
	v_mfma_f32_16x16x32_bf16 v[4:7], v[228:231], v[240:243], v[0:3]
	v_mfma_f32_16x16x32_bf16 v[0:3], v[232:235], v[120:123], v[212:215]
	v_mfma_f32_16x16x32_bf16 v[0:3], v[236:239], v[240:243], v[0:3]
	s_barrier
	s_add_u32 s77, s52, 0x200
	s_addc_u32 s78, s53, 0
	s_add_u32 s79, s50, 0x200
	s_addc_u32 s80, s51, 0
	s_add_u32 s50, s52, 0x80180
	s_addc_u32 s51, s53, 0
	s_mov_b32 s83, 0
.LBB0_692:
	s_cmp_eq_u32 s83, 28
	s_cselect_b32 s56, s5, s77
	s_cselect_b32 s57, s3, s78
	s_cselect_b32 s54, s20, s79
	s_cselect_b32 s55, s12, s80
	s_add_u32 s52, s56, 0x80
	s_addc_u32 s53, s57, 0
	s_add_i32 s84, 0, 0x10000
	s_add_i32 s86, 0, 0x14000
	v_add_u32_e32 v108, s84, v206
	v_add_u32_e32 v138, s86, v206
	ds_read_b128 v[68:71], v108
	ds_read_b128 v[84:87], v108 offset:1024
	ds_read_b128 v[92:95], v108 offset:2048
	ds_read_b128 v[108:111], v108 offset:3072
	ds_read_b128 v[120:123], v138
	ds_read_b128 v[134:137], v138 offset:1024
	ds_read_b128 v[156:159], v138 offset:2048
	ds_read_b128 v[160:163], v138 offset:3072
	s_mov_b32 m0, s0
	ds_read_b128 v[164:167], v209
	ds_read_b128 v[168:171], v209 offset:1024
	ds_read_b128 v[172:175], v209 offset:2048
	ds_read_b128 v[176:179], v209 offset:3072
	ds_read_b128 v[180:183], v209 offset:4096
	ds_read_b128 v[186:189], v209 offset:5120
	ds_read_b128 v[190:193], v209 offset:6144
	ds_read_b128 v[194:197], v209 offset:7168
	s_nop 0
	global_load_lds_dwordx4 v202, s[50:51]
	s_mov_b32 m0, s1
	s_nop 0
	global_load_lds_dwordx4 v204, s[50:51]
	s_waitcnt vmcnt(8)
	s_waitcnt lgkmcnt(0)
	s_barrier
	s_waitcnt lgkmcnt(0)
	v_mfma_f32_16x16x32_bf16 v[152:155], v[68:71], v[164:167], v[152:155]
	v_mfma_f32_16x16x32_bf16 v[148:151], v[92:95], v[164:167], v[148:151]
	v_mfma_f32_16x16x32_bf16 v[128:131], v[68:71], v[172:175], v[128:131]
	v_mfma_f32_16x16x32_bf16 v[124:127], v[92:95], v[172:175], v[124:127]
	v_mfma_f32_16x16x32_bf16 v[104:107], v[68:71], v[180:183], v[104:107]
	v_mfma_f32_16x16x32_bf16 v[100:103], v[92:95], v[180:183], v[100:103]
	v_mfma_f32_16x16x32_bf16 v[80:83], v[68:71], v[190:193], v[80:83]
	v_mfma_f32_16x16x32_bf16 v[76:79], v[92:95], v[190:193], v[76:79]
	v_mfma_f32_16x16x32_bf16 v[152:155], v[84:87], v[168:171], v[152:155]
	v_mfma_f32_16x16x32_bf16 v[148:151], v[108:111], v[168:171], v[148:151]
	v_mfma_f32_16x16x32_bf16 v[128:131], v[84:87], v[176:179], v[128:131]
	v_mfma_f32_16x16x32_bf16 v[124:127], v[108:111], v[176:179], v[124:127]
	v_mfma_f32_16x16x32_bf16 v[104:107], v[84:87], v[186:189], v[104:107]
	v_mfma_f32_16x16x32_bf16 v[100:103], v[108:111], v[186:189], v[100:103]
	v_mfma_f32_16x16x32_bf16 v[80:83], v[84:87], v[194:197], v[80:83]
	v_mfma_f32_16x16x32_bf16 v[76:79], v[108:111], v[194:197], v[76:79]
	v_mfma_f32_16x16x32_bf16 v[144:147], v[120:123], v[164:167], v[144:147]
	v_mfma_f32_16x16x32_bf16 v[138:141], v[156:159], v[164:167], v[140:143]
	v_mfma_f32_16x16x32_bf16 v[116:119], v[120:123], v[172:175], v[116:119]
	v_mfma_f32_16x16x32_bf16 v[112:115], v[156:159], v[172:175], v[112:115]
	v_mfma_f32_16x16x32_bf16 v[96:99], v[120:123], v[180:183], v[96:99]
	v_mfma_f32_16x16x32_bf16 v[88:91], v[156:159], v[180:183], v[88:91]
	v_mfma_f32_16x16x32_bf16 v[72:75], v[120:123], v[190:193], v[72:75]
	v_mfma_f32_16x16x32_bf16 v[64:67], v[156:159], v[190:193], v[64:67]
	v_mfma_f32_16x16x32_bf16 v[144:147], v[134:137], v[168:171], v[144:147]
	v_mfma_f32_16x16x32_bf16 v[138:141], v[160:163], v[168:171], v[138:141]
	v_mfma_f32_16x16x32_bf16 v[116:119], v[134:137], v[176:179], v[116:119]
	v_mfma_f32_16x16x32_bf16 v[112:115], v[160:163], v[176:179], v[112:115]
	v_mfma_f32_16x16x32_bf16 v[96:99], v[134:137], v[186:189], v[96:99]
	v_mfma_f32_16x16x32_bf16 v[88:91], v[160:163], v[186:189], v[88:91]
	v_mfma_f32_16x16x32_bf16 v[72:75], v[134:137], v[194:197], v[72:75]
	v_mfma_f32_16x16x32_bf16 v[64:67], v[160:163], v[194:197], v[64:67]
	s_barrier
	s_add_i32 s84, s84, s26
	s_mov_b32 m0, s84
	ds_read_b128 v[164:167], v209 offset:16384
	ds_read_b128 v[168:171], v209 offset:17408
	ds_read_b128 v[172:175], v209 offset:18432
	ds_read_b128 v[176:179], v209 offset:19456
	ds_read_b128 v[180:183], v209 offset:20480
	ds_read_b128 v[186:189], v209 offset:21504
	ds_read_b128 v[190:193], v209 offset:22528
	ds_read_b128 v[194:197], v209 offset:23552
	s_nop 0
	global_load_lds_dwordx4 v203, s[54:55]
	s_add_i32 m0, s84, 0x2000
	s_add_u32 s84, s54, 0x80000
	s_addc_u32 s85, s55, 0
	s_add_i32 s86, s86, s26
	s_nop 0
	global_load_lds_dwordx4 v205, s[54:55]
	s_mov_b32 m0, s86
	s_nop 0
	global_load_lds_dwordx4 v203, s[84:85]
	s_add_i32 m0, s86, 0x2000
	s_nop 0
	global_load_lds_dwordx4 v205, s[84:85]
	s_mov_b32 m0, s27
	s_nop 0
	global_load_lds_dwordx4 v202, s[56:57]
	s_mov_b32 m0, s62
	s_nop 0
	global_load_lds_dwordx4 v204, s[56:57]
	s_waitcnt vmcnt(8)
	s_waitcnt lgkmcnt(0)
	s_barrier
	s_waitcnt lgkmcnt(0)
	v_mfma_f32_16x16x32_bf16 v[60:63], v[68:71], v[164:167], v[60:63]
	v_mfma_f32_16x16x32_bf16 v[56:59], v[92:95], v[164:167], v[56:59]
	v_mfma_f32_16x16x32_bf16 v[44:47], v[68:71], v[172:175], v[44:47]
	v_mfma_f32_16x16x32_bf16 v[40:43], v[92:95], v[172:175], v[40:43]
	v_mfma_f32_16x16x32_bf16 v[28:31], v[68:71], v[180:183], v[28:31]
	v_mfma_f32_16x16x32_bf16 v[24:27], v[92:95], v[180:183], v[24:27]
	v_mfma_f32_16x16x32_bf16 v[12:15], v[68:71], v[190:193], v[12:15]
	v_mfma_f32_16x16x32_bf16 v[8:11], v[92:95], v[190:193], v[8:11]
	v_mfma_f32_16x16x32_bf16 v[60:63], v[84:87], v[168:171], v[60:63]
	v_mfma_f32_16x16x32_bf16 v[56:59], v[108:111], v[168:171], v[56:59]
	v_mfma_f32_16x16x32_bf16 v[44:47], v[84:87], v[176:179], v[44:47]
	v_mfma_f32_16x16x32_bf16 v[40:43], v[108:111], v[176:179], v[40:43]
	v_mfma_f32_16x16x32_bf16 v[28:31], v[84:87], v[186:189], v[28:31]
	v_mfma_f32_16x16x32_bf16 v[24:27], v[108:111], v[186:189], v[24:27]
	v_mfma_f32_16x16x32_bf16 v[12:15], v[84:87], v[194:197], v[12:15]
	v_mfma_f32_16x16x32_bf16 v[8:11], v[108:111], v[194:197], v[8:11]
	v_mfma_f32_16x16x32_bf16 v[52:55], v[120:123], v[164:167], v[52:55]
	v_mfma_f32_16x16x32_bf16 v[48:51], v[156:159], v[164:167], v[48:51]
	v_mfma_f32_16x16x32_bf16 v[36:39], v[120:123], v[172:175], v[36:39]
	v_mfma_f32_16x16x32_bf16 v[32:35], v[156:159], v[172:175], v[32:35]
	v_mfma_f32_16x16x32_bf16 v[20:23], v[120:123], v[180:183], v[20:23]
	v_mfma_f32_16x16x32_bf16 v[16:19], v[156:159], v[180:183], v[16:19]
	v_mfma_f32_16x16x32_bf16 v[4:7], v[120:123], v[190:193], v[4:7]
	v_mfma_f32_16x16x32_bf16 v[0:3], v[156:159], v[190:193], v[0:3]
	v_mfma_f32_16x16x32_bf16 v[52:55], v[134:137], v[168:171], v[52:55]
	v_mfma_f32_16x16x32_bf16 v[48:51], v[160:163], v[168:171], v[48:51]
	v_mfma_f32_16x16x32_bf16 v[36:39], v[134:137], v[176:179], v[36:39]
	v_mfma_f32_16x16x32_bf16 v[32:35], v[160:163], v[176:179], v[32:35]
	v_mfma_f32_16x16x32_bf16 v[20:23], v[134:137], v[186:189], v[20:23]
	v_mfma_f32_16x16x32_bf16 v[16:19], v[160:163], v[186:189], v[16:19]
	v_mfma_f32_16x16x32_bf16 v[4:7], v[134:137], v[194:197], v[4:7]
	v_mfma_f32_16x16x32_bf16 v[0:3], v[160:163], v[194:197], v[0:3]
	s_barrier
	ds_read_b128 v[68:71], v132
	ds_read_b128 v[84:87], v132 offset:1024
	ds_read_b128 v[92:95], v132 offset:2048
	ds_read_b128 v[108:111], v132 offset:3072
	ds_read_b128 v[120:123], v133
	ds_read_b128 v[134:137], v133 offset:1024
	ds_read_b128 v[156:159], v133 offset:2048
	ds_read_b128 v[160:163], v133 offset:3072
	s_add_u32 s56, s56, 0x80000
	s_addc_u32 s57, s57, 0
	s_mov_b32 m0, s63
	ds_read_b128 v[164:167], v209 offset:32768
	ds_read_b128 v[168:171], v209 offset:33792
	ds_read_b128 v[172:175], v209 offset:34816
	ds_read_b128 v[176:179], v209 offset:35840
	ds_read_b128 v[180:183], v209 offset:36864
	ds_read_b128 v[186:189], v209 offset:37888
	ds_read_b128 v[190:193], v209 offset:38912
	ds_read_b128 v[194:197], v209 offset:39936
	s_nop 0
	global_load_lds_dwordx4 v202, s[56:57]
	s_mov_b32 m0, s64
	s_nop 0
	global_load_lds_dwordx4 v204, s[56:57]
	s_waitcnt vmcnt(8)
	s_waitcnt lgkmcnt(0)
	s_barrier
	s_waitcnt lgkmcnt(0)
	v_mfma_f32_16x16x32_bf16 v[152:155], v[68:71], v[164:167], v[152:155]
	v_mfma_f32_16x16x32_bf16 v[148:151], v[92:95], v[164:167], v[148:151]
	v_mfma_f32_16x16x32_bf16 v[128:131], v[68:71], v[172:175], v[128:131]
	v_mfma_f32_16x16x32_bf16 v[124:127], v[92:95], v[172:175], v[124:127]
	v_mfma_f32_16x16x32_bf16 v[104:107], v[68:71], v[180:183], v[104:107]
	v_mfma_f32_16x16x32_bf16 v[100:103], v[92:95], v[180:183], v[100:103]
	v_mfma_f32_16x16x32_bf16 v[80:83], v[68:71], v[190:193], v[80:83]
	v_mfma_f32_16x16x32_bf16 v[76:79], v[92:95], v[190:193], v[76:79]
	v_mfma_f32_16x16x32_bf16 v[152:155], v[84:87], v[168:171], v[152:155]
	v_mfma_f32_16x16x32_bf16 v[148:151], v[108:111], v[168:171], v[148:151]
	v_mfma_f32_16x16x32_bf16 v[128:131], v[84:87], v[176:179], v[128:131]
	v_mfma_f32_16x16x32_bf16 v[124:127], v[108:111], v[176:179], v[124:127]
	v_mfma_f32_16x16x32_bf16 v[104:107], v[84:87], v[186:189], v[104:107]
	v_mfma_f32_16x16x32_bf16 v[100:103], v[108:111], v[186:189], v[100:103]
	v_mfma_f32_16x16x32_bf16 v[80:83], v[84:87], v[194:197], v[80:83]
	v_mfma_f32_16x16x32_bf16 v[76:79], v[108:111], v[194:197], v[76:79]
	v_mfma_f32_16x16x32_bf16 v[142:145], v[120:123], v[164:167], v[144:147]
	v_mfma_f32_16x16x32_bf16 v[138:141], v[156:159], v[164:167], v[138:141]
	v_mfma_f32_16x16x32_bf16 v[116:119], v[120:123], v[172:175], v[116:119]
	v_mfma_f32_16x16x32_bf16 v[112:115], v[156:159], v[172:175], v[112:115]
	v_mfma_f32_16x16x32_bf16 v[96:99], v[120:123], v[180:183], v[96:99]
	v_mfma_f32_16x16x32_bf16 v[88:91], v[156:159], v[180:183], v[88:91]
	v_mfma_f32_16x16x32_bf16 v[72:75], v[120:123], v[190:193], v[72:75]
	v_mfma_f32_16x16x32_bf16 v[64:67], v[156:159], v[190:193], v[64:67]
	v_mfma_f32_16x16x32_bf16 v[144:147], v[134:137], v[168:171], v[142:145]
	v_mfma_f32_16x16x32_bf16 v[140:143], v[160:163], v[168:171], v[138:141]
	v_mfma_f32_16x16x32_bf16 v[116:119], v[134:137], v[176:179], v[116:119]
	v_mfma_f32_16x16x32_bf16 v[112:115], v[160:163], v[176:179], v[112:115]
	v_mfma_f32_16x16x32_bf16 v[96:99], v[134:137], v[186:189], v[96:99]
	v_mfma_f32_16x16x32_bf16 v[88:91], v[160:163], v[186:189], v[88:91]
	v_mfma_f32_16x16x32_bf16 v[72:75], v[134:137], v[194:197], v[72:75]
	v_mfma_f32_16x16x32_bf16 v[64:67], v[160:163], v[194:197], v[64:67]
	s_barrier
	s_add_u32 s56, s54, 0x80
	s_mov_b32 m0, s21
	s_addc_u32 s57, s55, 0
	ds_read_b128 v[164:167], v209 offset:49152
	ds_read_b128 v[168:171], v209 offset:50176
	ds_read_b128 v[172:175], v209 offset:51200
	ds_read_b128 v[176:179], v209 offset:52224
	ds_read_b128 v[180:183], v209 offset:53248
	ds_read_b128 v[186:189], v209 offset:54272
	ds_read_b128 v[190:193], v209 offset:55296
	ds_read_b128 v[194:197], v209 offset:56320
	s_add_u32 s54, s54, 0x80080
	global_load_lds_dwordx4 v203, s[56:57]
	s_mov_b32 m0, s41
	s_addc_u32 s55, s55, 0
	global_load_lds_dwordx4 v205, s[56:57]
	s_mov_b32 m0, s43
	s_nop 0
	global_load_lds_dwordx4 v203, s[54:55]
	s_mov_b32 m0, s76
	s_nop 0
	global_load_lds_dwordx4 v205, s[54:55]
	s_mov_b32 m0, s65
	s_nop 0
	global_load_lds_dwordx4 v202, s[52:53]
	s_mov_b32 m0, s66
	s_nop 0
	global_load_lds_dwordx4 v204, s[52:53]
	s_waitcnt vmcnt(8)
	s_waitcnt lgkmcnt(0)
	s_barrier
	s_waitcnt lgkmcnt(0)
	v_mfma_f32_16x16x32_bf16 v[60:63], v[68:71], v[164:167], v[60:63]
	v_mfma_f32_16x16x32_bf16 v[56:59], v[92:95], v[164:167], v[56:59]
	v_mfma_f32_16x16x32_bf16 v[44:47], v[68:71], v[172:175], v[44:47]
	v_mfma_f32_16x16x32_bf16 v[40:43], v[92:95], v[172:175], v[40:43]
	v_mfma_f32_16x16x32_bf16 v[28:31], v[68:71], v[180:183], v[28:31]
	v_mfma_f32_16x16x32_bf16 v[24:27], v[92:95], v[180:183], v[24:27]
	v_mfma_f32_16x16x32_bf16 v[12:15], v[68:71], v[190:193], v[12:15]
	v_mfma_f32_16x16x32_bf16 v[8:11], v[92:95], v[190:193], v[8:11]
	v_mfma_f32_16x16x32_bf16 v[60:63], v[84:87], v[168:171], v[60:63]
	v_mfma_f32_16x16x32_bf16 v[56:59], v[108:111], v[168:171], v[56:59]
	v_mfma_f32_16x16x32_bf16 v[44:47], v[84:87], v[176:179], v[44:47]
	v_mfma_f32_16x16x32_bf16 v[40:43], v[108:111], v[176:179], v[40:43]
	v_mfma_f32_16x16x32_bf16 v[28:31], v[84:87], v[186:189], v[28:31]
	v_mfma_f32_16x16x32_bf16 v[24:27], v[108:111], v[186:189], v[24:27]
	v_mfma_f32_16x16x32_bf16 v[12:15], v[84:87], v[194:197], v[12:15]
	v_mfma_f32_16x16x32_bf16 v[8:11], v[108:111], v[194:197], v[8:11]
	v_mfma_f32_16x16x32_bf16 v[52:55], v[120:123], v[164:167], v[52:55]
	v_mfma_f32_16x16x32_bf16 v[48:51], v[156:159], v[164:167], v[48:51]
	v_mfma_f32_16x16x32_bf16 v[36:39], v[120:123], v[172:175], v[36:39]
	v_mfma_f32_16x16x32_bf16 v[32:35], v[156:159], v[172:175], v[32:35]
	v_mfma_f32_16x16x32_bf16 v[20:23], v[120:123], v[180:183], v[20:23]
	v_mfma_f32_16x16x32_bf16 v[16:19], v[156:159], v[180:183], v[16:19]
	v_mfma_f32_16x16x32_bf16 v[4:7], v[120:123], v[190:193], v[4:7]
	v_mfma_f32_16x16x32_bf16 v[0:3], v[156:159], v[190:193], v[0:3]
	v_mfma_f32_16x16x32_bf16 v[52:55], v[134:137], v[168:171], v[52:55]
	v_mfma_f32_16x16x32_bf16 v[48:51], v[160:163], v[168:171], v[48:51]
	v_mfma_f32_16x16x32_bf16 v[36:39], v[134:137], v[176:179], v[36:39]
	v_mfma_f32_16x16x32_bf16 v[32:35], v[160:163], v[176:179], v[32:35]
	v_mfma_f32_16x16x32_bf16 v[20:23], v[134:137], v[186:189], v[20:23]
	v_mfma_f32_16x16x32_bf16 v[16:19], v[160:163], v[186:189], v[16:19]
	v_mfma_f32_16x16x32_bf16 v[4:7], v[134:137], v[194:197], v[4:7]
	v_mfma_f32_16x16x32_bf16 v[0:3], v[160:163], v[194:197], v[0:3]
	s_barrier
	s_add_i32 s83, s83, 2
	s_add_u32 s77, s77, 0x100
	s_addc_u32 s78, s78, 0
	s_add_u32 s79, s79, 0x100
	s_addc_u32 s80, s80, 0
	s_add_u32 s50, s50, 0x100
	s_addc_u32 s51, s51, 0
	s_cmp_gt_u32 s83, 29
	s_cbranch_scc0 .LBB0_692
	s_and_b64 vcc, exec, s[8:9]
	s_cbranch_vccz .LBB0_695
	s_barrier

.LBB0_797:
	s_add_u32 s20, s46, 0x100
	s_addc_u32 s21, s47, 0
	s_waitcnt lgkmcnt(0)
	s_add_u32 s38, s44, 0x100
	s_addc_u32 s39, s45, 0
	s_barrier
	s_waitcnt lgkmcnt(0)
	v_mfma_f32_16x16x32_bf16 v[32:35], v[16:19], v[72:75], 0
	v_mfma_f32_16x16x32_bf16 v[36:39], v[24:27], v[72:75], 0
	v_mfma_f32_16x16x32_bf16 v[40:43], v[16:19], v[84:87], 0
	v_mfma_f32_16x16x32_bf16 v[44:47], v[24:27], v[84:87], 0
	v_mfma_f32_16x16x32_bf16 v[48:51], v[16:19], v[88:91], 0
	v_mfma_f32_16x16x32_bf16 v[52:55], v[24:27], v[88:91], 0
	v_mfma_f32_16x16x32_bf16 v[56:59], v[16:19], v[68:71], 0
	v_mfma_f32_16x16x32_bf16 v[60:63], v[24:27], v[68:71], 0
	v_mfma_f32_16x16x32_bf16 v[32:35], v[20:23], v[76:79], v[32:35]
	v_mfma_f32_16x16x32_bf16 v[36:39], v[28:31], v[76:79], v[36:39]
	v_mfma_f32_16x16x32_bf16 v[40:43], v[20:23], v[92:95], v[40:43]
	v_mfma_f32_16x16x32_bf16 v[44:47], v[28:31], v[92:95], v[44:47]
	v_mfma_f32_16x16x32_bf16 v[48:51], v[20:23], v[96:99], v[48:51]
	v_mfma_f32_16x16x32_bf16 v[52:55], v[28:31], v[96:99], v[52:55]
	v_mfma_f32_16x16x32_bf16 v[56:59], v[20:23], v[80:83], v[56:59]
	v_mfma_f32_16x16x32_bf16 v[60:63], v[28:31], v[80:83], v[60:63]
	v_mfma_f32_16x16x32_bf16 v[64:67], v[0:3], v[72:75], 0
	v_mfma_f32_16x16x32_bf16 v[72:75], v[8:11], v[72:75], 0
	v_mfma_f32_16x16x32_bf16 v[64:67], v[4:7], v[76:79], v[64:67]
	v_mfma_f32_16x16x32_bf16 v[72:75], v[12:15], v[76:79], v[72:75]
	v_mfma_f32_16x16x32_bf16 v[76:79], v[0:3], v[84:87], 0
	v_mfma_f32_16x16x32_bf16 v[84:87], v[8:11], v[84:87], 0
	v_mfma_f32_16x16x32_bf16 v[76:79], v[4:7], v[92:95], v[76:79]
	v_mfma_f32_16x16x32_bf16 v[84:87], v[12:15], v[92:95], v[84:87]
	v_mfma_f32_16x16x32_bf16 v[92:95], v[0:3], v[88:91], 0
	v_mfma_f32_16x16x32_bf16 v[88:91], v[8:11], v[88:91], 0
	v_mfma_f32_16x16x32_bf16 v[128:131], v[12:15], v[96:99], v[88:91]
	v_mfma_f32_16x16x32_bf16 v[88:91], v[0:3], v[68:71], 0
	v_mfma_f32_16x16x32_bf16 v[68:71], v[8:11], v[68:71], 0
	v_mfma_f32_16x16x32_bf16 v[92:95], v[4:7], v[96:99], v[92:95]
	v_mfma_f32_16x16x32_bf16 v[132:135], v[4:7], v[80:83], v[88:91]
	v_mfma_f32_16x16x32_bf16 v[136:139], v[12:15], v[80:83], v[68:71]
	s_barrier
	s_mov_b32 m0, s41
	ds_read_b128 v[108:111], v150 offset:16384
	ds_read_b128 v[112:115], v150 offset:17408
	ds_read_b128 v[100:103], v150 offset:18432
	ds_read_b128 v[104:107], v150 offset:19456
	ds_read_b128 v[88:91], v150 offset:20480
	ds_read_b128 v[96:99], v150 offset:21504
	ds_read_b128 v[68:71], v150 offset:22528
	ds_read_b128 v[80:83], v150 offset:23552
	s_nop 0
	global_load_lds_dwordx4 v144, s[38:39]
	s_mov_b32 m0, s43
	s_nop 0
	global_load_lds_dwordx4 v146, s[38:39]
	s_add_u32 s38, s44, 0x80100
	s_addc_u32 s39, s45, 0
	s_mov_b32 m0, s55
	s_and_b64 vcc, exec, s[36:37]
	global_load_lds_dwordx4 v144, s[38:39]
	s_mov_b32 m0, s56
	s_nop 0
	global_load_lds_dwordx4 v146, s[38:39]
	s_mov_b32 m0, s27
	s_mov_b64 s[38:39], -1
	global_load_lds_dwordx4 v143, s[20:21]
	s_mov_b32 m0, s57
	s_nop 0
	global_load_lds_dwordx4 v145, s[20:21]
	s_cbranch_vccz .LBB0_799
	s_waitcnt vmcnt(8)
	s_mov_b64 s[38:39], 0

.LBB0_801:
	s_ashr_i32 s7, s6, 31
	s_lshl_b64 s[20:21], s[6:7], 20
	s_add_u32 s36, s14, s20
	s_addc_u32 s37, s15, s21
	s_ashr_i32 s9, s8, 31
	s_lshl_b64 s[20:21], s[8:9], 20
	s_add_u32 s38, s24, s20
	s_addc_u32 s39, s25, s21
	s_add_u32 s48, s46, 0x180
	s_addc_u32 s49, s47, 0
	s_waitcnt lgkmcnt(0)
	s_and_b64 s[20:21], s[34:35], exec
	s_cselect_b32 s9, s39, s45
	s_cselect_b32 s12, s38, s44
	s_cselect_b32 s20, s37, s47
	s_cselect_b32 s21, s36, s46
	s_add_u32 s50, s44, 0x180
	s_addc_u32 s51, s45, 0
	s_barrier
	s_waitcnt lgkmcnt(0)
	v_mfma_f32_16x16x32_bf16 v[116:119], v[16:19], v[108:111], 0
	v_mfma_f32_16x16x32_bf16 v[154:157], v[20:23], v[112:115], v[116:119]
	v_mfma_f32_16x16x32_bf16 v[116:119], v[24:27], v[108:111], 0
	v_mfma_f32_16x16x32_bf16 v[158:161], v[28:31], v[112:115], v[116:119]
	v_mfma_f32_16x16x32_bf16 v[116:119], v[16:19], v[100:103], 0
	v_mfma_f32_16x16x32_bf16 v[162:165], v[20:23], v[104:107], v[116:119]
	v_mfma_f32_16x16x32_bf16 v[116:119], v[24:27], v[100:103], 0
	v_mfma_f32_16x16x32_bf16 v[166:169], v[28:31], v[104:107], v[116:119]
	v_mfma_f32_16x16x32_bf16 v[116:119], v[16:19], v[88:91], 0
	v_mfma_f32_16x16x32_bf16 v[16:19], v[16:19], v[68:71], 0
	v_mfma_f32_16x16x32_bf16 v[170:173], v[20:23], v[96:99], v[116:119]
	v_mfma_f32_16x16x32_bf16 v[116:119], v[24:27], v[88:91], 0
	v_mfma_f32_16x16x32_bf16 v[20:23], v[20:23], v[80:83], v[16:19]
	v_mfma_f32_16x16x32_bf16 v[16:19], v[24:27], v[68:71], 0
	v_mfma_f32_16x16x32_bf16 v[174:177], v[28:31], v[96:99], v[116:119]
	v_mfma_f32_16x16x32_bf16 v[28:31], v[28:31], v[80:83], v[16:19]
	v_mfma_f32_16x16x32_bf16 v[16:19], v[0:3], v[108:111], 0
	v_mfma_f32_16x16x32_bf16 v[178:181], v[4:7], v[112:115], v[16:19]
	v_mfma_f32_16x16x32_bf16 v[16:19], v[8:11], v[108:111], 0
	v_mfma_f32_16x16x32_bf16 v[182:185], v[12:15], v[112:115], v[16:19]
	v_mfma_f32_16x16x32_bf16 v[16:19], v[0:3], v[100:103], 0
	v_mfma_f32_16x16x32_bf16 v[186:189], v[4:7], v[104:107], v[16:19]
	v_mfma_f32_16x16x32_bf16 v[16:19], v[8:11], v[100:103], 0
	v_mfma_f32_16x16x32_bf16 v[190:193], v[12:15], v[104:107], v[16:19]
	v_mfma_f32_16x16x32_bf16 v[16:19], v[0:3], v[88:91], 0
	v_mfma_f32_16x16x32_bf16 v[0:3], v[0:3], v[68:71], 0
	v_mfma_f32_16x16x32_bf16 v[194:197], v[4:7], v[96:99], v[16:19]
	v_mfma_f32_16x16x32_bf16 v[16:19], v[8:11], v[88:91], 0
	v_mfma_f32_16x16x32_bf16 v[4:7], v[4:7], v[80:83], v[0:3]
	v_mfma_f32_16x16x32_bf16 v[0:3], v[8:11], v[68:71], 0
	v_mfma_f32_16x16x32_bf16 v[198:201], v[12:15], v[96:99], v[16:19]
	v_mfma_f32_16x16x32_bf16 v[202:205], v[12:15], v[80:83], v[0:3]
	s_barrier
	v_add_u32_e32 v152, s67, v147
	v_add_u32_e32 v153, s68, v147
	s_nop 1
	ds_read_b128 v[0:3], v152
	ds_read_b128 v[8:11], v152 offset:1024
	ds_read_b128 v[12:15], v152 offset:2048
	ds_read_b128 v[206:209], v152 offset:3072
	ds_read_b128 v[210:213], v153
	ds_read_b128 v[214:217], v153 offset:1024
	ds_read_b128 v[218:221], v153 offset:2048
	ds_read_b128 v[222:225], v153 offset:3072
	s_add_u32 s52, s46, 0x80100
	s_addc_u32 s53, s47, 0
	s_mov_b32 m0, s58
	ds_read_b128 v[16:19], v150 offset:32768
	ds_read_b128 v[24:27], v150 offset:33792
	ds_read_b128 v[100:103], v150 offset:34816
	ds_read_b128 v[226:229], v150 offset:35840
	ds_read_b128 v[230:233], v150 offset:36864
	ds_read_b128 v[234:237], v150 offset:37888
	ds_read_b128 v[238:241], v150 offset:38912
	ds_read_b128 v[242:245], v150 offset:39936
	s_nop 0
	global_load_lds_dwordx4 v143, s[52:53]
	s_mov_b32 m0, s59
	s_nop 0
	global_load_lds_dwordx4 v145, s[52:53]
	s_waitcnt vmcnt(8)
	s_waitcnt lgkmcnt(0)
	s_barrier
	s_waitcnt lgkmcnt(0)
	v_mfma_f32_16x16x32_bf16 v[32:35], v[0:3], v[16:19], v[32:35]
	v_mfma_f32_16x16x32_bf16 v[120:123], v[8:11], v[24:27], v[32:35]
	v_mfma_f32_16x16x32_bf16 v[32:35], v[12:15], v[16:19], v[36:39]
	v_mfma_f32_16x16x32_bf16 v[112:115], v[206:209], v[24:27], v[32:35]
	v_mfma_f32_16x16x32_bf16 v[32:35], v[0:3], v[100:103], v[40:43]
	v_mfma_f32_16x16x32_bf16 v[104:107], v[8:11], v[226:229], v[32:35]
	v_mfma_f32_16x16x32_bf16 v[32:35], v[12:15], v[100:103], v[44:47]
	v_mfma_f32_16x16x32_bf16 v[96:99], v[206:209], v[226:229], v[32:35]
	v_mfma_f32_16x16x32_bf16 v[32:35], v[0:3], v[230:233], v[48:51]
	v_mfma_f32_16x16x32_bf16 v[88:91], v[8:11], v[234:237], v[32:35]
	v_mfma_f32_16x16x32_bf16 v[32:35], v[12:15], v[230:233], v[52:55]
	v_mfma_f32_16x16x32_bf16 v[80:83], v[206:209], v[234:237], v[32:35]
	v_mfma_f32_16x16x32_bf16 v[32:35], v[0:3], v[238:241], v[56:59]
	v_mfma_f32_16x16x32_bf16 v[68:71], v[8:11], v[242:245], v[32:35]
	v_mfma_f32_16x16x32_bf16 v[32:35], v[12:15], v[238:241], v[60:63]
	v_mfma_f32_16x16x32_bf16 v[52:55], v[206:209], v[242:245], v[32:35]
	v_mfma_f32_16x16x32_bf16 v[32:35], v[210:213], v[16:19], v[64:67]
	v_mfma_f32_16x16x32_bf16 v[16:19], v[218:221], v[16:19], v[72:75]
	v_mfma_f32_16x16x32_bf16 v[116:119], v[222:225], v[24:27], v[16:19]
	v_mfma_f32_16x16x32_bf16 v[16:19], v[210:213], v[100:103], v[76:79]
	v_mfma_f32_16x16x32_bf16 v[108:111], v[214:217], v[226:229], v[16:19]
	v_mfma_f32_16x16x32_bf16 v[16:19], v[218:221], v[100:103], v[84:87]
	v_mfma_f32_16x16x32_bf16 v[100:103], v[222:225], v[226:229], v[16:19]
	v_mfma_f32_16x16x32_bf16 v[16:19], v[210:213], v[230:233], v[92:95]
	v_mfma_f32_16x16x32_bf16 v[92:95], v[214:217], v[234:237], v[16:19]
	v_mfma_f32_16x16x32_bf16 v[16:19], v[218:221], v[230:233], v[128:131]
	v_mfma_f32_16x16x32_bf16 v[84:87], v[222:225], v[234:237], v[16:19]
	v_mfma_f32_16x16x32_bf16 v[16:19], v[210:213], v[238:241], v[132:135]
	v_mfma_f32_16x16x32_bf16 v[76:79], v[214:217], v[242:245], v[16:19]
	v_mfma_f32_16x16x32_bf16 v[16:19], v[218:221], v[238:241], v[136:139]
	v_mfma_f32_16x16x32_bf16 v[124:127], v[214:217], v[24:27], v[32:35]
	v_mfma_f32_16x16x32_bf16 v[60:63], v[222:225], v[242:245], v[16:19]
	s_barrier
	s_add_i32 s72, s67, s26
	s_mov_b32 m0, s72
	s_add_i32 s73, s72, 0x2000
	ds_read_b128 v[36:39], v150 offset:49152
	ds_read_b128 v[44:47], v150 offset:50176
	ds_read_b128 v[128:131], v150 offset:51200
	ds_read_b128 v[132:135], v150 offset:52224
	ds_read_b128 v[136:139], v150 offset:53248
	ds_read_b128 v[226:229], v150 offset:54272
	ds_read_b128 v[230:233], v150 offset:55296
	ds_read_b128 v[234:237], v150 offset:56320
	s_nop 0
	global_load_lds_dwordx4 v144, s[50:51]
	s_mov_b32 m0, s73
	s_nop 0
	global_load_lds_dwordx4 v146, s[50:51]
	s_add_u32 s50, s44, 0x80180
	s_addc_u32 s51, s45, 0
	s_add_i32 s74, s68, s26
	s_mov_b32 m0, s74
	s_add_i32 s75, s74, 0x2000
	s_nop 0
	global_load_lds_dwordx4 v144, s[50:51]
	s_mov_b32 m0, s75
	s_nop 0
	global_load_lds_dwordx4 v146, s[50:51]
	s_mov_b32 m0, s60
	s_nop 0
	global_load_lds_dwordx4 v143, s[48:49]
	s_mov_b32 m0, s61
	s_nop 0
	global_load_lds_dwordx4 v145, s[48:49]
	s_waitcnt vmcnt(8)
	s_waitcnt lgkmcnt(0)
	s_barrier
	s_waitcnt lgkmcnt(0)
	v_mfma_f32_16x16x32_bf16 v[16:19], v[0:3], v[36:39], v[154:157]
	v_mfma_f32_16x16x32_bf16 v[64:67], v[8:11], v[44:47], v[16:19]
	v_mfma_f32_16x16x32_bf16 v[16:19], v[12:15], v[36:39], v[158:161]
	v_mfma_f32_16x16x32_bf16 v[48:51], v[206:209], v[44:47], v[16:19]
	v_mfma_f32_16x16x32_bf16 v[16:19], v[0:3], v[128:131], v[162:165]
	v_mfma_f32_16x16x32_bf16 v[40:43], v[8:11], v[132:135], v[16:19]
	v_mfma_f32_16x16x32_bf16 v[16:19], v[12:15], v[128:131], v[166:169]
	v_mfma_f32_16x16x32_bf16 v[32:35], v[206:209], v[132:135], v[16:19]
	v_mfma_f32_16x16x32_bf16 v[16:19], v[0:3], v[136:139], v[170:173]
	v_mfma_f32_16x16x32_bf16 v[0:3], v[0:3], v[230:233], v[20:23]
	v_mfma_f32_16x16x32_bf16 v[24:27], v[8:11], v[226:229], v[16:19]
	v_mfma_f32_16x16x32_bf16 v[16:19], v[12:15], v[136:139], v[174:177]
	v_mfma_f32_16x16x32_bf16 v[8:11], v[8:11], v[234:237], v[0:3]
	v_mfma_f32_16x16x32_bf16 v[0:3], v[12:15], v[230:233], v[28:31]
	v_mfma_f32_16x16x32_bf16 v[16:19], v[206:209], v[226:229], v[16:19]
	v_mfma_f32_16x16x32_bf16 v[0:3], v[206:209], v[234:237], v[0:3]
	v_mfma_f32_16x16x32_bf16 v[12:15], v[210:213], v[36:39], v[178:181]
	v_mfma_f32_16x16x32_bf16 v[72:75], v[214:217], v[44:47], v[12:15]
	v_mfma_f32_16x16x32_bf16 v[12:15], v[218:221], v[36:39], v[182:185]
	v_mfma_f32_16x16x32_bf16 v[56:59], v[222:225], v[44:47], v[12:15]
	v_mfma_f32_16x16x32_bf16 v[12:15], v[210:213], v[128:131], v[186:189]
	v_mfma_f32_16x16x32_bf16 v[44:47], v[214:217], v[132:135], v[12:15]
	v_mfma_f32_16x16x32_bf16 v[12:15], v[218:221], v[128:131], v[190:193]
	v_mfma_f32_16x16x32_bf16 v[36:39], v[222:225], v[132:135], v[12:15]
	v_mfma_f32_16x16x32_bf16 v[12:15], v[210:213], v[136:139], v[194:197]
	v_mfma_f32_16x16x32_bf16 v[28:31], v[214:217], v[226:229], v[12:15]
	v_mfma_f32_16x16x32_bf16 v[12:15], v[218:221], v[136:139], v[198:201]
	v_mfma_f32_16x16x32_bf16 v[4:7], v[210:213], v[230:233], v[4:7]
	v_mfma_f32_16x16x32_bf16 v[20:23], v[222:225], v[226:229], v[12:15]
	v_mfma_f32_16x16x32_bf16 v[12:15], v[214:217], v[234:237], v[4:7]
	v_mfma_f32_16x16x32_bf16 v[4:7], v[218:221], v[230:233], v[202:205]
	v_mfma_f32_16x16x32_bf16 v[4:7], v[222:225], v[234:237], v[4:7]
	s_barrier
	s_add_u32 s52, s46, 0x100
	s_addc_u32 s53, s47, 0
	s_add_u32 s76, s44, 0x200
	s_addc_u32 s77, s45, 0
	s_mov_b32 s78, 0
.LBB0_802:
	s_add_u32 s44, s52, 0x100
	s_addc_u32 s45, s53, 0
	s_cmp_eq_u32 s78, 28
	s_cselect_b32 s50, s21, s44
	s_cselect_b32 s51, s20, s45
	s_cselect_b32 s48, s12, s76
	s_cselect_b32 s49, s9, s77
	s_add_u32 s46, s50, 0x80
	s_addc_u32 s47, s51, 0
	s_add_i32 s79, 0, 0x10000
	s_add_i32 s80, 0, 0x14000
	v_add_u32_e32 v154, s79, v147
	v_add_u32_e32 v170, s80, v147
	ds_read_b128 v[128:131], v154
	ds_read_b128 v[132:135], v154 offset:1024
	ds_read_b128 v[136:139], v154 offset:2048
	ds_read_b128 v[154:157], v154 offset:3072
	ds_read_b128 v[158:161], v170
	ds_read_b128 v[162:165], v170 offset:1024
	ds_read_b128 v[166:169], v170 offset:2048
	ds_read_b128 v[170:173], v170 offset:3072
	s_add_u32 s52, s52, 0x80080
	s_addc_u32 s53, s53, 0
	s_mov_b32 m0, s0
	ds_read_b128 v[174:177], v150
	ds_read_b128 v[178:181], v150 offset:1024
	ds_read_b128 v[182:185], v150 offset:2048
	ds_read_b128 v[186:189], v150 offset:3072
	ds_read_b128 v[190:193], v150 offset:4096
	ds_read_b128 v[194:197], v150 offset:5120
	ds_read_b128 v[198:201], v150 offset:6144
	ds_read_b128 v[202:205], v150 offset:7168
	s_nop 0
	global_load_lds_dwordx4 v143, s[52:53]
	s_mov_b32 m0, s1
	s_nop 0
	global_load_lds_dwordx4 v145, s[52:53]
	s_waitcnt vmcnt(8)
	s_waitcnt lgkmcnt(0)
	s_barrier
	s_waitcnt lgkmcnt(0)
	v_mfma_f32_16x16x32_bf16 v[120:123], v[128:131], v[174:177], v[120:123]
	v_mfma_f32_16x16x32_bf16 v[112:115], v[136:139], v[174:177], v[112:115]
	v_mfma_f32_16x16x32_bf16 v[104:107], v[128:131], v[182:185], v[104:107]
	v_mfma_f32_16x16x32_bf16 v[96:99], v[136:139], v[182:185], v[96:99]
	v_mfma_f32_16x16x32_bf16 v[88:91], v[128:131], v[190:193], v[88:91]
	v_mfma_f32_16x16x32_bf16 v[80:83], v[136:139], v[190:193], v[80:83]
	v_mfma_f32_16x16x32_bf16 v[68:71], v[128:131], v[198:201], v[68:71]
	v_mfma_f32_16x16x32_bf16 v[52:55], v[136:139], v[198:201], v[52:55]
	v_mfma_f32_16x16x32_bf16 v[120:123], v[132:135], v[178:181], v[120:123]
	v_mfma_f32_16x16x32_bf16 v[112:115], v[154:157], v[178:181], v[112:115]
	v_mfma_f32_16x16x32_bf16 v[104:107], v[132:135], v[186:189], v[104:107]
	v_mfma_f32_16x16x32_bf16 v[96:99], v[154:157], v[186:189], v[96:99]
	v_mfma_f32_16x16x32_bf16 v[88:91], v[132:135], v[194:197], v[88:91]
	v_mfma_f32_16x16x32_bf16 v[80:83], v[154:157], v[194:197], v[80:83]
	v_mfma_f32_16x16x32_bf16 v[68:71], v[132:135], v[202:205], v[68:71]
	v_mfma_f32_16x16x32_bf16 v[52:55], v[154:157], v[202:205], v[52:55]
	v_mfma_f32_16x16x32_bf16 v[124:127], v[158:161], v[174:177], v[124:127]
	v_mfma_f32_16x16x32_bf16 v[116:119], v[166:169], v[174:177], v[116:119]
	v_mfma_f32_16x16x32_bf16 v[108:111], v[158:161], v[182:185], v[108:111]
	v_mfma_f32_16x16x32_bf16 v[100:103], v[166:169], v[182:185], v[100:103]
	v_mfma_f32_16x16x32_bf16 v[92:95], v[158:161], v[190:193], v[92:95]
	v_mfma_f32_16x16x32_bf16 v[84:87], v[166:169], v[190:193], v[84:87]
	v_mfma_f32_16x16x32_bf16 v[76:79], v[158:161], v[198:201], v[76:79]
	v_mfma_f32_16x16x32_bf16 v[60:63], v[166:169], v[198:201], v[60:63]
	v_mfma_f32_16x16x32_bf16 v[124:127], v[162:165], v[178:181], v[124:127]
	v_mfma_f32_16x16x32_bf16 v[116:119], v[170:173], v[178:181], v[116:119]
	v_mfma_f32_16x16x32_bf16 v[108:111], v[162:165], v[186:189], v[108:111]
	v_mfma_f32_16x16x32_bf16 v[100:103], v[170:173], v[186:189], v[100:103]
	v_mfma_f32_16x16x32_bf16 v[92:95], v[162:165], v[194:197], v[92:95]
	v_mfma_f32_16x16x32_bf16 v[84:87], v[170:173], v[194:197], v[84:87]
	v_mfma_f32_16x16x32_bf16 v[76:79], v[162:165], v[202:205], v[76:79]
	v_mfma_f32_16x16x32_bf16 v[60:63], v[170:173], v[202:205], v[60:63]
	s_barrier
	s_add_i32 s52, s79, s26
	s_mov_b32 m0, s52
	ds_read_b128 v[174:177], v150 offset:16384
	ds_read_b128 v[178:181], v150 offset:17408
	ds_read_b128 v[182:185], v150 offset:18432
	ds_read_b128 v[186:189], v150 offset:19456
	ds_read_b128 v[190:193], v150 offset:20480
	ds_read_b128 v[194:197], v150 offset:21504
	ds_read_b128 v[198:201], v150 offset:22528
	ds_read_b128 v[202:205], v150 offset:23552
	s_nop 0
	global_load_lds_dwordx4 v144, s[48:49]
	s_add_i32 m0, s52, 0x2000
	s_add_u32 s52, s48, 0x80000
	s_addc_u32 s53, s49, 0
	s_add_i32 s79, s80, s26
	s_nop 0
	global_load_lds_dwordx4 v146, s[48:49]
	s_mov_b32 m0, s79
	s_nop 0
	global_load_lds_dwordx4 v144, s[52:53]
	s_add_i32 m0, s79, 0x2000
	s_nop 0
	global_load_lds_dwordx4 v146, s[52:53]
	s_mov_b32 m0, s27
	s_nop 0
	global_load_lds_dwordx4 v143, s[50:51]
	s_mov_b32 m0, s57
	s_nop 0
	global_load_lds_dwordx4 v145, s[50:51]
	s_waitcnt vmcnt(8)
	s_waitcnt lgkmcnt(0)
	s_barrier
	s_waitcnt lgkmcnt(0)
	v_mfma_f32_16x16x32_bf16 v[64:67], v[128:131], v[174:177], v[64:67]
	v_mfma_f32_16x16x32_bf16 v[48:51], v[136:139], v[174:177], v[48:51]
	v_mfma_f32_16x16x32_bf16 v[40:43], v[128:131], v[182:185], v[40:43]
	v_mfma_f32_16x16x32_bf16 v[32:35], v[136:139], v[182:185], v[32:35]
	v_mfma_f32_16x16x32_bf16 v[24:27], v[128:131], v[190:193], v[24:27]
	v_mfma_f32_16x16x32_bf16 v[16:19], v[136:139], v[190:193], v[16:19]
	v_mfma_f32_16x16x32_bf16 v[8:11], v[128:131], v[198:201], v[8:11]
	v_mfma_f32_16x16x32_bf16 v[0:3], v[136:139], v[198:201], v[0:3]
	v_mfma_f32_16x16x32_bf16 v[64:67], v[132:135], v[178:181], v[64:67]
	v_mfma_f32_16x16x32_bf16 v[48:51], v[154:157], v[178:181], v[48:51]
	v_mfma_f32_16x16x32_bf16 v[40:43], v[132:135], v[186:189], v[40:43]
	v_mfma_f32_16x16x32_bf16 v[32:35], v[154:157], v[186:189], v[32:35]
	v_mfma_f32_16x16x32_bf16 v[24:27], v[132:135], v[194:197], v[24:27]
	v_mfma_f32_16x16x32_bf16 v[16:19], v[154:157], v[194:197], v[16:19]
	v_mfma_f32_16x16x32_bf16 v[8:11], v[132:135], v[202:205], v[8:11]
	v_mfma_f32_16x16x32_bf16 v[0:3], v[154:157], v[202:205], v[0:3]
	v_mfma_f32_16x16x32_bf16 v[72:75], v[158:161], v[174:177], v[72:75]
	v_mfma_f32_16x16x32_bf16 v[56:59], v[166:169], v[174:177], v[56:59]
	v_mfma_f32_16x16x32_bf16 v[44:47], v[158:161], v[182:185], v[44:47]
	v_mfma_f32_16x16x32_bf16 v[36:39], v[166:169], v[182:185], v[36:39]
	v_mfma_f32_16x16x32_bf16 v[28:31], v[158:161], v[190:193], v[28:31]
	v_mfma_f32_16x16x32_bf16 v[20:23], v[166:169], v[190:193], v[20:23]
	v_mfma_f32_16x16x32_bf16 v[12:15], v[158:161], v[198:201], v[12:15]
	v_mfma_f32_16x16x32_bf16 v[4:7], v[166:169], v[198:201], v[4:7]
	v_mfma_f32_16x16x32_bf16 v[72:75], v[162:165], v[178:181], v[72:75]
	v_mfma_f32_16x16x32_bf16 v[56:59], v[170:173], v[178:181], v[56:59]
	v_mfma_f32_16x16x32_bf16 v[44:47], v[162:165], v[186:189], v[44:47]
	v_mfma_f32_16x16x32_bf16 v[36:39], v[170:173], v[186:189], v[36:39]
	v_mfma_f32_16x16x32_bf16 v[28:31], v[162:165], v[194:197], v[28:31]
	v_mfma_f32_16x16x32_bf16 v[20:23], v[170:173], v[194:197], v[20:23]
	v_mfma_f32_16x16x32_bf16 v[12:15], v[162:165], v[202:205], v[12:15]
	v_mfma_f32_16x16x32_bf16 v[4:7], v[170:173], v[202:205], v[4:7]
	s_barrier
	ds_read_b128 v[128:131], v152
	ds_read_b128 v[132:135], v152 offset:1024
	ds_read_b128 v[136:139], v152 offset:2048
	ds_read_b128 v[154:157], v152 offset:3072
	ds_read_b128 v[158:161], v153
	ds_read_b128 v[162:165], v153 offset:1024
	ds_read_b128 v[166:169], v153 offset:2048
	ds_read_b128 v[170:173], v153 offset:3072
	s_add_u32 s50, s50, 0x80000
	s_addc_u32 s51, s51, 0
	s_mov_b32 m0, s58
	ds_read_b128 v[174:177], v150 offset:32768
	ds_read_b128 v[178:181], v150 offset:33792
	ds_read_b128 v[182:185], v150 offset:34816
	ds_read_b128 v[186:189], v150 offset:35840
	ds_read_b128 v[190:193], v150 offset:36864
	ds_read_b128 v[194:197], v150 offset:37888
	ds_read_b128 v[198:201], v150 offset:38912
	ds_read_b128 v[202:205], v150 offset:39936
	s_nop 0
	global_load_lds_dwordx4 v143, s[50:51]
	s_mov_b32 m0, s59
	s_nop 0
	global_load_lds_dwordx4 v145, s[50:51]
	s_waitcnt vmcnt(8)
	s_waitcnt lgkmcnt(0)
	s_barrier
	s_waitcnt lgkmcnt(0)
	v_mfma_f32_16x16x32_bf16 v[120:123], v[128:131], v[174:177], v[120:123]
	v_mfma_f32_16x16x32_bf16 v[112:115], v[136:139], v[174:177], v[112:115]
	v_mfma_f32_16x16x32_bf16 v[104:107], v[128:131], v[182:185], v[104:107]
	v_mfma_f32_16x16x32_bf16 v[96:99], v[136:139], v[182:185], v[96:99]
	v_mfma_f32_16x16x32_bf16 v[88:91], v[128:131], v[190:193], v[88:91]
	v_mfma_f32_16x16x32_bf16 v[80:83], v[136:139], v[190:193], v[80:83]
	v_mfma_f32_16x16x32_bf16 v[68:71], v[128:131], v[198:201], v[68:71]
	v_mfma_f32_16x16x32_bf16 v[52:55], v[136:139], v[198:201], v[52:55]
	v_mfma_f32_16x16x32_bf16 v[120:123], v[132:135], v[178:181], v[120:123]
	v_mfma_f32_16x16x32_bf16 v[112:115], v[154:157], v[178:181], v[112:115]
	v_mfma_f32_16x16x32_bf16 v[104:107], v[132:135], v[186:189], v[104:107]
	v_mfma_f32_16x16x32_bf16 v[96:99], v[154:157], v[186:189], v[96:99]
	v_mfma_f32_16x16x32_bf16 v[88:91], v[132:135], v[194:197], v[88:91]
	v_mfma_f32_16x16x32_bf16 v[80:83], v[154:157], v[194:197], v[80:83]
	v_mfma_f32_16x16x32_bf16 v[68:71], v[132:135], v[202:205], v[68:71]
	v_mfma_f32_16x16x32_bf16 v[52:55], v[154:157], v[202:205], v[52:55]
	v_mfma_f32_16x16x32_bf16 v[124:127], v[158:161], v[174:177], v[124:127]
	v_mfma_f32_16x16x32_bf16 v[116:119], v[166:169], v[174:177], v[116:119]
	v_mfma_f32_16x16x32_bf16 v[108:111], v[158:161], v[182:185], v[108:111]
	v_mfma_f32_16x16x32_bf16 v[100:103], v[166:169], v[182:185], v[100:103]
	v_mfma_f32_16x16x32_bf16 v[92:95], v[158:161], v[190:193], v[92:95]
	v_mfma_f32_16x16x32_bf16 v[84:87], v[166:169], v[190:193], v[84:87]
	v_mfma_f32_16x16x32_bf16 v[76:79], v[158:161], v[198:201], v[76:79]
	v_mfma_f32_16x16x32_bf16 v[60:63], v[166:169], v[198:201], v[60:63]
	v_mfma_f32_16x16x32_bf16 v[124:127], v[162:165], v[178:181], v[124:127]
	v_mfma_f32_16x16x32_bf16 v[116:119], v[170:173], v[178:181], v[116:119]
	v_mfma_f32_16x16x32_bf16 v[108:111], v[162:165], v[186:189], v[108:111]
	v_mfma_f32_16x16x32_bf16 v[100:103], v[170:173], v[186:189], v[100:103]
	v_mfma_f32_16x16x32_bf16 v[92:95], v[162:165], v[194:197], v[92:95]
	v_mfma_f32_16x16x32_bf16 v[84:87], v[170:173], v[194:197], v[84:87]
	v_mfma_f32_16x16x32_bf16 v[76:79], v[162:165], v[202:205], v[76:79]
	v_mfma_f32_16x16x32_bf16 v[60:63], v[170:173], v[202:205], v[60:63]
	s_barrier
	s_add_u32 s50, s48, 0x80
	s_mov_b32 m0, s72
	s_addc_u32 s51, s49, 0
	ds_read_b128 v[174:177], v150 offset:49152
	ds_read_b128 v[178:181], v150 offset:50176
	ds_read_b128 v[182:185], v150 offset:51200
	ds_read_b128 v[186:189], v150 offset:52224
	ds_read_b128 v[190:193], v150 offset:53248
	ds_read_b128 v[194:197], v150 offset:54272
	ds_read_b128 v[198:201], v150 offset:55296
	ds_read_b128 v[202:205], v150 offset:56320
	s_add_u32 s48, s48, 0x80080
	global_load_lds_dwordx4 v144, s[50:51]
	s_mov_b32 m0, s73
	s_addc_u32 s49, s49, 0
	global_load_lds_dwordx4 v146, s[50:51]
	s_mov_b32 m0, s74
	s_nop 0
	global_load_lds_dwordx4 v144, s[48:49]
	s_mov_b32 m0, s75
	s_nop 0
	global_load_lds_dwordx4 v146, s[48:49]
	s_mov_b32 m0, s60
	s_nop 0
	global_load_lds_dwordx4 v143, s[46:47]
	s_mov_b32 m0, s61
	s_nop 0
	global_load_lds_dwordx4 v145, s[46:47]
	s_waitcnt vmcnt(8)
	s_waitcnt lgkmcnt(0)
	s_barrier
	s_waitcnt lgkmcnt(0)
	v_mfma_f32_16x16x32_bf16 v[64:67], v[128:131], v[174:177], v[64:67]
	v_mfma_f32_16x16x32_bf16 v[48:51], v[136:139], v[174:177], v[48:51]
	v_mfma_f32_16x16x32_bf16 v[40:43], v[128:131], v[182:185], v[40:43]
	v_mfma_f32_16x16x32_bf16 v[32:35], v[136:139], v[182:185], v[32:35]
	v_mfma_f32_16x16x32_bf16 v[24:27], v[128:131], v[190:193], v[24:27]
	v_mfma_f32_16x16x32_bf16 v[16:19], v[136:139], v[190:193], v[16:19]
	v_mfma_f32_16x16x32_bf16 v[8:11], v[128:131], v[198:201], v[8:11]
	v_mfma_f32_16x16x32_bf16 v[0:3], v[136:139], v[198:201], v[0:3]
	v_mfma_f32_16x16x32_bf16 v[64:67], v[132:135], v[178:181], v[64:67]
	v_mfma_f32_16x16x32_bf16 v[48:51], v[154:157], v[178:181], v[48:51]
	v_mfma_f32_16x16x32_bf16 v[40:43], v[132:135], v[186:189], v[40:43]
	v_mfma_f32_16x16x32_bf16 v[32:35], v[154:157], v[186:189], v[32:35]
	v_mfma_f32_16x16x32_bf16 v[24:27], v[132:135], v[194:197], v[24:27]
	v_mfma_f32_16x16x32_bf16 v[16:19], v[154:157], v[194:197], v[16:19]
	v_mfma_f32_16x16x32_bf16 v[8:11], v[132:135], v[202:205], v[8:11]
	v_mfma_f32_16x16x32_bf16 v[0:3], v[154:157], v[202:205], v[0:3]
	v_mfma_f32_16x16x32_bf16 v[72:75], v[158:161], v[174:177], v[72:75]
	v_mfma_f32_16x16x32_bf16 v[56:59], v[166:169], v[174:177], v[56:59]
	v_mfma_f32_16x16x32_bf16 v[44:47], v[158:161], v[182:185], v[44:47]
	v_mfma_f32_16x16x32_bf16 v[36:39], v[166:169], v[182:185], v[36:39]
	v_mfma_f32_16x16x32_bf16 v[28:31], v[158:161], v[190:193], v[28:31]
	v_mfma_f32_16x16x32_bf16 v[20:23], v[166:169], v[190:193], v[20:23]
	v_mfma_f32_16x16x32_bf16 v[12:15], v[158:161], v[198:201], v[12:15]
	v_mfma_f32_16x16x32_bf16 v[4:7], v[166:169], v[198:201], v[4:7]
	v_mfma_f32_16x16x32_bf16 v[72:75], v[162:165], v[178:181], v[72:75]
	v_mfma_f32_16x16x32_bf16 v[56:59], v[170:173], v[178:181], v[56:59]
	v_mfma_f32_16x16x32_bf16 v[44:47], v[162:165], v[186:189], v[44:47]
	v_mfma_f32_16x16x32_bf16 v[36:39], v[170:173], v[186:189], v[36:39]
	v_mfma_f32_16x16x32_bf16 v[28:31], v[162:165], v[194:197], v[28:31]
	v_mfma_f32_16x16x32_bf16 v[20:23], v[170:173], v[194:197], v[20:23]
	v_mfma_f32_16x16x32_bf16 v[12:15], v[162:165], v[202:205], v[12:15]
	v_mfma_f32_16x16x32_bf16 v[4:7], v[170:173], v[202:205], v[4:7]
	s_barrier
	s_add_i32 s78, s78, 2
	s_add_u32 s76, s76, 0x100
	s_addc_u32 s77, s77, 0
	s_cmp_gt_u32 s78, 29
	s_mov_b64 s[52:53], s[44:45]
	s_cbranch_scc0 .LBB0_802
	s_and_b64 vcc, exec, s[4:5]
	s_cbranch_vccz .LBB0_805
	s_barrier

.LBB0_895:
	s_add_u32 s20, s48, 0x100
	s_addc_u32 s21, s49, 0
	s_waitcnt lgkmcnt(0)
	s_add_u32 s52, s4, 0x100
	s_addc_u32 s53, s5, 0
	s_barrier
	v_mfma_f32_16x16x32_bf16 v[32:35], v[16:19], v[68:71], 0
	v_mfma_f32_16x16x32_bf16 v[36:39], v[24:27], v[68:71], 0
	s_waitcnt lgkmcnt(0)
	v_mfma_f32_16x16x32_bf16 v[40:43], v[16:19], v[84:87], 0
	v_mfma_f32_16x16x32_bf16 v[44:47], v[24:27], v[84:87], 0
	v_mfma_f32_16x16x32_bf16 v[48:51], v[16:19], v[92:95], 0
	v_mfma_f32_16x16x32_bf16 v[52:55], v[24:27], v[92:95], 0
	v_mfma_f32_16x16x32_bf16 v[56:59], v[16:19], v[76:79], 0
	v_mfma_f32_16x16x32_bf16 v[60:63], v[24:27], v[76:79], 0
	v_mfma_f32_16x16x32_bf16 v[138:141], v[20:23], v[72:75], v[32:35]
	v_mfma_f32_16x16x32_bf16 v[36:39], v[28:31], v[72:75], v[36:39]
	v_mfma_f32_16x16x32_bf16 v[40:43], v[20:23], v[88:91], v[40:43]
	v_mfma_f32_16x16x32_bf16 v[44:47], v[28:31], v[88:91], v[44:47]
	v_mfma_f32_16x16x32_bf16 v[48:51], v[20:23], v[96:99], v[48:51]
	v_mfma_f32_16x16x32_bf16 v[52:55], v[28:31], v[96:99], v[52:55]
	v_mfma_f32_16x16x32_bf16 v[56:59], v[20:23], v[80:83], v[56:59]
	v_mfma_f32_16x16x32_bf16 v[60:63], v[28:31], v[80:83], v[60:63]
	v_mfma_f32_16x16x32_bf16 v[64:67], v[0:3], v[68:71], 0
	v_mfma_f32_16x16x32_bf16 v[68:71], v[8:11], v[68:71], 0
	v_mfma_f32_16x16x32_bf16 v[64:67], v[4:7], v[72:75], v[64:67]
	v_mfma_f32_16x16x32_bf16 v[68:71], v[12:15], v[72:75], v[68:71]
	v_mfma_f32_16x16x32_bf16 v[72:75], v[0:3], v[84:87], 0
	v_mfma_f32_16x16x32_bf16 v[84:87], v[8:11], v[84:87], 0
	v_mfma_f32_16x16x32_bf16 v[72:75], v[4:7], v[88:91], v[72:75]
	v_mfma_f32_16x16x32_bf16 v[84:87], v[12:15], v[88:91], v[84:87]
	v_mfma_f32_16x16x32_bf16 v[88:91], v[0:3], v[92:95], 0
	v_mfma_f32_16x16x32_bf16 v[92:95], v[8:11], v[92:95], 0
	v_mfma_f32_16x16x32_bf16 v[88:91], v[4:7], v[96:99], v[88:91]
	v_mfma_f32_16x16x32_bf16 v[92:95], v[12:15], v[96:99], v[92:95]
	v_mfma_f32_16x16x32_bf16 v[96:99], v[0:3], v[76:79], 0
	v_mfma_f32_16x16x32_bf16 v[76:79], v[8:11], v[76:79], 0
	v_mfma_f32_16x16x32_bf16 v[108:111], v[4:7], v[80:83], v[96:99]
	v_mfma_f32_16x16x32_bf16 v[112:115], v[12:15], v[80:83], v[76:79]
	s_barrier
	s_mov_b32 m0, s54
	ds_read_b128 v[120:123], v209 offset:16384
	ds_read_b128 v[124:127], v209 offset:17408
	ds_read_b128 v[104:107], v209 offset:18432
	ds_read_b128 v[116:119], v209 offset:19456
	ds_read_b128 v[96:99], v209 offset:20480
	ds_read_b128 v[100:103], v209 offset:21504
	ds_read_b128 v[76:79], v209 offset:22528
	ds_read_b128 v[80:83], v209 offset:23552
	s_nop 0
	global_load_lds_dwordx4 v203, s[52:53]
	s_mov_b32 m0, s55
	s_nop 0
	global_load_lds_dwordx4 v205, s[52:53]
	s_add_u32 s52, s4, 0x160100
	s_addc_u32 s53, s5, 0
	s_mov_b32 m0, s56
	s_and_b64 vcc, exec, s[50:51]
	global_load_lds_dwordx4 v203, s[52:53]
	s_mov_b32 m0, s57
	s_nop 0
	global_load_lds_dwordx4 v205, s[52:53]
	s_mov_b32 m0, s27
	s_mov_b64 s[52:53], -1
	global_load_lds_dwordx4 v202, s[20:21]
	s_mov_b32 m0, s58
	s_nop 0
	global_load_lds_dwordx4 v204, s[20:21]
	s_cbranch_vccz .LBB0_897
	s_waitcnt vmcnt(8)
	s_mov_b64 s[52:53], 0

.LBB0_899:
	s_add_u32 s50, s48, 0x180
	s_waitcnt lgkmcnt(0)
	s_addc_u32 s51, s49, 0
	s_add_u32 s52, s4, 0x180
	s_addc_u32 s53, s5, 0
	s_barrier
	s_waitcnt lgkmcnt(0)
	v_mfma_f32_16x16x32_bf16 v[128:131], v[16:19], v[120:123], 0
	v_mfma_f32_16x16x32_bf16 v[134:137], v[20:23], v[124:127], v[128:131]
	v_mfma_f32_16x16x32_bf16 v[128:131], v[24:27], v[120:123], 0
	v_mfma_f32_16x16x32_bf16 v[156:159], v[28:31], v[124:127], v[128:131]
	v_mfma_f32_16x16x32_bf16 v[128:131], v[16:19], v[104:107], 0
	v_mfma_f32_16x16x32_bf16 v[160:163], v[20:23], v[116:119], v[128:131]
	v_mfma_f32_16x16x32_bf16 v[128:131], v[24:27], v[104:107], 0
	v_mfma_f32_16x16x32_bf16 v[164:167], v[28:31], v[116:119], v[128:131]
	v_mfma_f32_16x16x32_bf16 v[128:131], v[16:19], v[96:99], 0
	v_mfma_f32_16x16x32_bf16 v[16:19], v[16:19], v[76:79], 0
	v_mfma_f32_16x16x32_bf16 v[168:171], v[20:23], v[100:103], v[128:131]
	v_mfma_f32_16x16x32_bf16 v[16:19], v[20:23], v[80:83], v[16:19]
	v_mfma_f32_16x16x32_bf16 v[20:23], v[24:27], v[76:79], 0
	v_mfma_f32_16x16x32_bf16 v[128:131], v[24:27], v[96:99], 0
	v_mfma_f32_16x16x32_bf16 v[20:23], v[28:31], v[80:83], v[20:23]
	v_mfma_f32_16x16x32_bf16 v[172:175], v[28:31], v[100:103], v[128:131]
	v_mfma_f32_16x16x32_bf16 v[24:27], v[0:3], v[120:123], 0
	v_mfma_f32_16x16x32_bf16 v[176:179], v[4:7], v[124:127], v[24:27]
	v_mfma_f32_16x16x32_bf16 v[24:27], v[8:11], v[120:123], 0
	v_mfma_f32_16x16x32_bf16 v[180:183], v[12:15], v[124:127], v[24:27]
	v_mfma_f32_16x16x32_bf16 v[24:27], v[0:3], v[104:107], 0
	v_mfma_f32_16x16x32_bf16 v[186:189], v[4:7], v[116:119], v[24:27]
	v_mfma_f32_16x16x32_bf16 v[24:27], v[8:11], v[104:107], 0
	v_mfma_f32_16x16x32_bf16 v[190:193], v[12:15], v[116:119], v[24:27]
	v_mfma_f32_16x16x32_bf16 v[24:27], v[0:3], v[96:99], 0
	v_mfma_f32_16x16x32_bf16 v[0:3], v[0:3], v[76:79], 0
	v_mfma_f32_16x16x32_bf16 v[194:197], v[4:7], v[100:103], v[24:27]
	v_mfma_f32_16x16x32_bf16 v[24:27], v[8:11], v[96:99], 0
	v_mfma_f32_16x16x32_bf16 v[0:3], v[4:7], v[80:83], v[0:3]
	v_mfma_f32_16x16x32_bf16 v[4:7], v[8:11], v[76:79], 0
	v_mfma_f32_16x16x32_bf16 v[198:201], v[12:15], v[100:103], v[24:27]
	v_mfma_f32_16x16x32_bf16 v[212:215], v[12:15], v[80:83], v[4:7]
	s_barrier
	v_add_u32_e32 v132, s68, v206
	v_add_u32_e32 v133, s69, v206
	s_nop 1
	ds_read_b128 v[4:7], v132
	ds_read_b128 v[8:11], v132 offset:1024
	ds_read_b128 v[216:219], v132 offset:2048
	ds_read_b128 v[220:223], v132 offset:3072
	ds_read_b128 v[224:227], v133
	ds_read_b128 v[228:231], v133 offset:1024
	ds_read_b128 v[232:235], v133 offset:2048
	ds_read_b128 v[236:239], v133 offset:3072
	s_add_u32 s20, s48, 0x160100
	s_addc_u32 s21, s49, 0
	s_mov_b32 m0, s59
	ds_read_b128 v[12:15], v209 offset:32768
	ds_read_b128 v[24:27], v209 offset:33792
	ds_read_b128 v[28:31], v209 offset:34816
	ds_read_b128 v[96:99], v209 offset:35840
	ds_read_b128 v[240:243], v209 offset:36864
	ds_read_b128 v[244:247], v209 offset:37888
	ds_read_b128 v[248:251], v209 offset:38912
	ds_read_b128 v[32:35], v209 offset:39936
	s_nop 0
	global_load_lds_dwordx4 v202, s[20:21]
	s_mov_b32 m0, s60
	s_nop 0
	global_load_lds_dwordx4 v204, s[20:21]
	s_waitcnt vmcnt(8)
	s_waitcnt lgkmcnt(0)
	s_barrier
	s_waitcnt lgkmcnt(0)
	v_mfma_f32_16x16x32_bf16 v[36:39], v[216:219], v[12:15], v[36:39]
	v_mfma_f32_16x16x32_bf16 v[148:151], v[220:223], v[24:27], v[36:39]
	v_mfma_f32_16x16x32_bf16 v[36:39], v[4:7], v[28:31], v[40:43]
	v_mfma_f32_16x16x32_bf16 v[128:131], v[8:11], v[96:99], v[36:39]
	v_mfma_f32_16x16x32_bf16 v[36:39], v[216:219], v[28:31], v[44:47]
	v_mfma_f32_16x16x32_bf16 v[124:127], v[220:223], v[96:99], v[36:39]
	v_mfma_f32_16x16x32_bf16 v[36:39], v[4:7], v[240:243], v[48:51]
	v_mfma_f32_16x16x32_bf16 v[104:107], v[8:11], v[244:247], v[36:39]
	v_mfma_f32_16x16x32_bf16 v[36:39], v[216:219], v[240:243], v[52:55]
	v_mfma_f32_16x16x32_bf16 v[100:103], v[220:223], v[244:247], v[36:39]
	v_mfma_f32_16x16x32_bf16 v[36:39], v[4:7], v[248:251], v[56:59]
	v_mfma_f32_16x16x32_bf16 v[76:79], v[4:7], v[12:15], v[138:141]
	v_mfma_f32_16x16x32_bf16 v[80:83], v[8:11], v[32:35], v[36:39]
	v_mfma_f32_16x16x32_bf16 v[36:39], v[216:219], v[248:251], v[60:63]
	v_mfma_f32_16x16x32_bf16 v[152:155], v[8:11], v[24:27], v[76:79]
	v_mfma_f32_16x16x32_bf16 v[76:79], v[220:223], v[32:35], v[36:39]
	v_mfma_f32_16x16x32_bf16 v[36:39], v[224:227], v[12:15], v[64:67]
	v_mfma_f32_16x16x32_bf16 v[12:15], v[232:235], v[12:15], v[68:71]
	v_mfma_f32_16x16x32_bf16 v[140:143], v[236:239], v[24:27], v[12:15]
	v_mfma_f32_16x16x32_bf16 v[12:15], v[224:227], v[28:31], v[72:75]
	v_mfma_f32_16x16x32_bf16 v[120:123], v[228:231], v[96:99], v[12:15]
	v_mfma_f32_16x16x32_bf16 v[12:15], v[232:235], v[28:31], v[84:87]
	v_mfma_f32_16x16x32_bf16 v[116:119], v[236:239], v[96:99], v[12:15]
	v_mfma_f32_16x16x32_bf16 v[12:15], v[224:227], v[240:243], v[88:91]
	v_mfma_f32_16x16x32_bf16 v[96:99], v[228:231], v[244:247], v[12:15]
	v_mfma_f32_16x16x32_bf16 v[12:15], v[232:235], v[240:243], v[92:95]
	v_mfma_f32_16x16x32_bf16 v[92:95], v[236:239], v[244:247], v[12:15]
	v_mfma_f32_16x16x32_bf16 v[12:15], v[224:227], v[248:251], v[108:111]
	v_mfma_f32_16x16x32_bf16 v[72:75], v[228:231], v[32:35], v[12:15]
	v_mfma_f32_16x16x32_bf16 v[12:15], v[232:235], v[248:251], v[112:115]
	v_mfma_f32_16x16x32_bf16 v[144:147], v[228:231], v[24:27], v[36:39]
	v_mfma_f32_16x16x32_bf16 v[68:71], v[236:239], v[32:35], v[12:15]
	s_barrier
	s_add_i32 s12, s68, s26
	s_mov_b32 m0, s12
	s_add_i32 s20, s12, 0x2000
	ds_read_b128 v[32:35], v209 offset:49152
	ds_read_b128 v[36:39], v209 offset:50176
	ds_read_b128 v[60:63], v209 offset:51200
	ds_read_b128 v[84:87], v209 offset:52224
	ds_read_b128 v[88:91], v209 offset:53248
	ds_read_b128 v[108:111], v209 offset:54272
	ds_read_b128 v[112:115], v209 offset:55296
	ds_read_b128 v[240:243], v209 offset:56320
	s_nop 0
	global_load_lds_dwordx4 v203, s[52:53]
	s_mov_b32 m0, s20
	s_nop 0
	global_load_lds_dwordx4 v205, s[52:53]
	s_add_u32 s52, s4, 0x160180
	s_addc_u32 s53, s5, 0
	s_add_i32 s21, s69, s26
	s_mov_b32 m0, s21
	s_add_i32 s74, s21, 0x2000
	s_nop 0
	global_load_lds_dwordx4 v203, s[52:53]
	s_mov_b32 m0, s74
	s_nop 0
	global_load_lds_dwordx4 v205, s[52:53]
	s_mov_b32 m0, s61
	s_nop 0
	global_load_lds_dwordx4 v202, s[50:51]
	s_mov_b32 m0, s62
	s_nop 0
	global_load_lds_dwordx4 v204, s[50:51]
	s_waitcnt vmcnt(8)
	s_waitcnt lgkmcnt(0)
	s_barrier
	s_waitcnt lgkmcnt(0)
	v_mfma_f32_16x16x32_bf16 v[12:15], v[4:7], v[32:35], v[134:137]
	v_mfma_f32_16x16x32_bf16 v[64:67], v[8:11], v[36:39], v[12:15]
	v_mfma_f32_16x16x32_bf16 v[12:15], v[216:219], v[32:35], v[156:159]
	v_mfma_f32_16x16x32_bf16 v[56:59], v[220:223], v[36:39], v[12:15]
	v_mfma_f32_16x16x32_bf16 v[12:15], v[4:7], v[60:63], v[160:163]
	v_mfma_f32_16x16x32_bf16 v[44:47], v[8:11], v[84:87], v[12:15]
	v_mfma_f32_16x16x32_bf16 v[12:15], v[216:219], v[60:63], v[164:167]
	v_mfma_f32_16x16x32_bf16 v[40:43], v[220:223], v[84:87], v[12:15]
	v_mfma_f32_16x16x32_bf16 v[12:15], v[4:7], v[88:91], v[168:171]
	v_mfma_f32_16x16x32_bf16 v[28:31], v[8:11], v[108:111], v[12:15]
	v_mfma_f32_16x16x32_bf16 v[12:15], v[216:219], v[88:91], v[172:175]
	v_mfma_f32_16x16x32_bf16 v[4:7], v[4:7], v[112:115], v[16:19]
	v_mfma_f32_16x16x32_bf16 v[24:27], v[220:223], v[108:111], v[12:15]
	v_mfma_f32_16x16x32_bf16 v[12:15], v[8:11], v[240:243], v[4:7]
	v_mfma_f32_16x16x32_bf16 v[4:7], v[216:219], v[112:115], v[20:23]
	v_mfma_f32_16x16x32_bf16 v[8:11], v[220:223], v[240:243], v[4:7]
	v_mfma_f32_16x16x32_bf16 v[4:7], v[224:227], v[32:35], v[176:179]
	v_mfma_f32_16x16x32_bf16 v[52:55], v[228:231], v[36:39], v[4:7]
	v_mfma_f32_16x16x32_bf16 v[4:7], v[232:235], v[32:35], v[180:183]
	v_mfma_f32_16x16x32_bf16 v[48:51], v[236:239], v[36:39], v[4:7]
	v_mfma_f32_16x16x32_bf16 v[4:7], v[224:227], v[60:63], v[186:189]
	v_mfma_f32_16x16x32_bf16 v[36:39], v[228:231], v[84:87], v[4:7]
	v_mfma_f32_16x16x32_bf16 v[4:7], v[232:235], v[60:63], v[190:193]
	v_mfma_f32_16x16x32_bf16 v[32:35], v[236:239], v[84:87], v[4:7]
	v_mfma_f32_16x16x32_bf16 v[4:7], v[224:227], v[88:91], v[194:197]
	v_mfma_f32_16x16x32_bf16 v[20:23], v[228:231], v[108:111], v[4:7]
	v_mfma_f32_16x16x32_bf16 v[4:7], v[232:235], v[88:91], v[198:201]
	v_mfma_f32_16x16x32_bf16 v[0:3], v[224:227], v[112:115], v[0:3]
	v_mfma_f32_16x16x32_bf16 v[16:19], v[236:239], v[108:111], v[4:7]
	v_mfma_f32_16x16x32_bf16 v[4:7], v[228:231], v[240:243], v[0:3]
	v_mfma_f32_16x16x32_bf16 v[0:3], v[232:235], v[112:115], v[212:215]
	v_mfma_f32_16x16x32_bf16 v[0:3], v[236:239], v[240:243], v[0:3]
	s_barrier
	s_add_u32 s75, s48, 0x200
	s_addc_u32 s76, s49, 0
	s_add_u32 s77, s4, 0x200
	s_addc_u32 s78, s5, 0
	s_add_u32 s4, s48, 0x160180
	s_addc_u32 s5, s49, 0
	s_mov_b32 s79, 0
.LBB0_900:
	s_cmpk_eq_i32 s79, 0x54
	s_cselect_b32 s52, s44, s75
	s_cselect_b32 s53, s45, s76
	s_cselect_b32 s50, s46, s77
	s_cselect_b32 s51, s47, s78
	s_add_u32 s48, s52, 0x80
	s_addc_u32 s49, s53, 0
	s_add_i32 s80, 0, 0x10000
	s_add_i32 s83, 0, 0x14000
	v_add_u32_e32 v108, s80, v206
	v_add_u32_e32 v138, s83, v206
	ds_read_b128 v[60:63], v108
	ds_read_b128 v[84:87], v108 offset:1024
	ds_read_b128 v[88:91], v108 offset:2048
	ds_read_b128 v[108:111], v108 offset:3072
	ds_read_b128 v[112:115], v138
	ds_read_b128 v[134:137], v138 offset:1024
	ds_read_b128 v[156:159], v138 offset:2048
	ds_read_b128 v[160:163], v138 offset:3072
	s_mov_b32 m0, s0
	ds_read_b128 v[164:167], v209
	ds_read_b128 v[168:171], v209 offset:1024
	ds_read_b128 v[172:175], v209 offset:2048
	ds_read_b128 v[176:179], v209 offset:3072
	ds_read_b128 v[180:183], v209 offset:4096
	ds_read_b128 v[186:189], v209 offset:5120
	ds_read_b128 v[190:193], v209 offset:6144
	ds_read_b128 v[194:197], v209 offset:7168
	s_nop 0
	global_load_lds_dwordx4 v202, s[4:5]
	s_mov_b32 m0, s1
	s_nop 0
	global_load_lds_dwordx4 v204, s[4:5]
	s_waitcnt vmcnt(8)
	s_waitcnt lgkmcnt(0)
	s_barrier
	s_waitcnt lgkmcnt(0)
	v_mfma_f32_16x16x32_bf16 v[152:155], v[60:63], v[164:167], v[152:155]
	v_mfma_f32_16x16x32_bf16 v[148:151], v[88:91], v[164:167], v[148:151]
	v_mfma_f32_16x16x32_bf16 v[128:131], v[60:63], v[172:175], v[128:131]
	v_mfma_f32_16x16x32_bf16 v[124:127], v[88:91], v[172:175], v[124:127]
	v_mfma_f32_16x16x32_bf16 v[104:107], v[60:63], v[180:183], v[104:107]
	v_mfma_f32_16x16x32_bf16 v[100:103], v[88:91], v[180:183], v[100:103]
	v_mfma_f32_16x16x32_bf16 v[80:83], v[60:63], v[190:193], v[80:83]
	v_mfma_f32_16x16x32_bf16 v[76:79], v[88:91], v[190:193], v[76:79]
	v_mfma_f32_16x16x32_bf16 v[152:155], v[84:87], v[168:171], v[152:155]
	v_mfma_f32_16x16x32_bf16 v[148:151], v[108:111], v[168:171], v[148:151]
	v_mfma_f32_16x16x32_bf16 v[128:131], v[84:87], v[176:179], v[128:131]
	v_mfma_f32_16x16x32_bf16 v[124:127], v[108:111], v[176:179], v[124:127]
	v_mfma_f32_16x16x32_bf16 v[104:107], v[84:87], v[186:189], v[104:107]
	v_mfma_f32_16x16x32_bf16 v[100:103], v[108:111], v[186:189], v[100:103]
	v_mfma_f32_16x16x32_bf16 v[80:83], v[84:87], v[194:197], v[80:83]
	v_mfma_f32_16x16x32_bf16 v[76:79], v[108:111], v[194:197], v[76:79]
	v_mfma_f32_16x16x32_bf16 v[144:147], v[112:115], v[164:167], v[144:147]
	v_mfma_f32_16x16x32_bf16 v[138:141], v[156:159], v[164:167], v[140:143]
	v_mfma_f32_16x16x32_bf16 v[120:123], v[112:115], v[172:175], v[120:123]
	v_mfma_f32_16x16x32_bf16 v[116:119], v[156:159], v[172:175], v[116:119]
	v_mfma_f32_16x16x32_bf16 v[96:99], v[112:115], v[180:183], v[96:99]
	v_mfma_f32_16x16x32_bf16 v[92:95], v[156:159], v[180:183], v[92:95]
	v_mfma_f32_16x16x32_bf16 v[72:75], v[112:115], v[190:193], v[72:75]
	v_mfma_f32_16x16x32_bf16 v[68:71], v[156:159], v[190:193], v[68:71]
	v_mfma_f32_16x16x32_bf16 v[144:147], v[134:137], v[168:171], v[144:147]
	v_mfma_f32_16x16x32_bf16 v[138:141], v[160:163], v[168:171], v[138:141]
	v_mfma_f32_16x16x32_bf16 v[120:123], v[134:137], v[176:179], v[120:123]
	v_mfma_f32_16x16x32_bf16 v[116:119], v[160:163], v[176:179], v[116:119]
	v_mfma_f32_16x16x32_bf16 v[96:99], v[134:137], v[186:189], v[96:99]
	v_mfma_f32_16x16x32_bf16 v[92:95], v[160:163], v[186:189], v[92:95]
	v_mfma_f32_16x16x32_bf16 v[72:75], v[134:137], v[194:197], v[72:75]
	v_mfma_f32_16x16x32_bf16 v[68:71], v[160:163], v[194:197], v[68:71]
	s_barrier
	s_add_i32 s80, s80, s26
	s_mov_b32 m0, s80
	ds_read_b128 v[164:167], v209 offset:16384
	ds_read_b128 v[168:171], v209 offset:17408
	ds_read_b128 v[172:175], v209 offset:18432
	ds_read_b128 v[176:179], v209 offset:19456
	ds_read_b128 v[180:183], v209 offset:20480
	ds_read_b128 v[186:189], v209 offset:21504
	ds_read_b128 v[190:193], v209 offset:22528
	ds_read_b128 v[194:197], v209 offset:23552
	s_nop 0
	global_load_lds_dwordx4 v203, s[50:51]
	s_add_i32 m0, s80, 0x2000
	s_add_u32 s84, s50, 0x160000
	s_addc_u32 s85, s51, 0
	s_add_i32 s80, s83, s26
	s_nop 0
	global_load_lds_dwordx4 v205, s[50:51]
	s_mov_b32 m0, s80
	s_nop 0
	global_load_lds_dwordx4 v203, s[84:85]
	s_add_i32 m0, s80, 0x2000
	s_nop 0
	global_load_lds_dwordx4 v205, s[84:85]
	s_mov_b32 m0, s27
	s_nop 0
	global_load_lds_dwordx4 v202, s[52:53]
	s_mov_b32 m0, s58
	s_nop 0
	global_load_lds_dwordx4 v204, s[52:53]
	s_waitcnt vmcnt(8)
	s_waitcnt lgkmcnt(0)
	s_barrier
	s_waitcnt lgkmcnt(0)
	v_mfma_f32_16x16x32_bf16 v[64:67], v[60:63], v[164:167], v[64:67]
	v_mfma_f32_16x16x32_bf16 v[56:59], v[88:91], v[164:167], v[56:59]
	v_mfma_f32_16x16x32_bf16 v[44:47], v[60:63], v[172:175], v[44:47]
	v_mfma_f32_16x16x32_bf16 v[40:43], v[88:91], v[172:175], v[40:43]
	v_mfma_f32_16x16x32_bf16 v[28:31], v[60:63], v[180:183], v[28:31]
	v_mfma_f32_16x16x32_bf16 v[24:27], v[88:91], v[180:183], v[24:27]
	v_mfma_f32_16x16x32_bf16 v[12:15], v[60:63], v[190:193], v[12:15]
	v_mfma_f32_16x16x32_bf16 v[8:11], v[88:91], v[190:193], v[8:11]
	v_mfma_f32_16x16x32_bf16 v[64:67], v[84:87], v[168:171], v[64:67]
	v_mfma_f32_16x16x32_bf16 v[56:59], v[108:111], v[168:171], v[56:59]
	v_mfma_f32_16x16x32_bf16 v[44:47], v[84:87], v[176:179], v[44:47]
	v_mfma_f32_16x16x32_bf16 v[40:43], v[108:111], v[176:179], v[40:43]
	v_mfma_f32_16x16x32_bf16 v[28:31], v[84:87], v[186:189], v[28:31]
	v_mfma_f32_16x16x32_bf16 v[24:27], v[108:111], v[186:189], v[24:27]
	v_mfma_f32_16x16x32_bf16 v[12:15], v[84:87], v[194:197], v[12:15]
	v_mfma_f32_16x16x32_bf16 v[8:11], v[108:111], v[194:197], v[8:11]
	v_mfma_f32_16x16x32_bf16 v[52:55], v[112:115], v[164:167], v[52:55]
	v_mfma_f32_16x16x32_bf16 v[48:51], v[156:159], v[164:167], v[48:51]
	v_mfma_f32_16x16x32_bf16 v[36:39], v[112:115], v[172:175], v[36:39]
	v_mfma_f32_16x16x32_bf16 v[32:35], v[156:159], v[172:175], v[32:35]
	v_mfma_f32_16x16x32_bf16 v[20:23], v[112:115], v[180:183], v[20:23]
	v_mfma_f32_16x16x32_bf16 v[16:19], v[156:159], v[180:183], v[16:19]
	v_mfma_f32_16x16x32_bf16 v[4:7], v[112:115], v[190:193], v[4:7]
	v_mfma_f32_16x16x32_bf16 v[0:3], v[156:159], v[190:193], v[0:3]
	v_mfma_f32_16x16x32_bf16 v[52:55], v[134:137], v[168:171], v[52:55]
	v_mfma_f32_16x16x32_bf16 v[48:51], v[160:163], v[168:171], v[48:51]
	v_mfma_f32_16x16x32_bf16 v[36:39], v[134:137], v[176:179], v[36:39]
	v_mfma_f32_16x16x32_bf16 v[32:35], v[160:163], v[176:179], v[32:35]
	v_mfma_f32_16x16x32_bf16 v[20:23], v[134:137], v[186:189], v[20:23]
	v_mfma_f32_16x16x32_bf16 v[16:19], v[160:163], v[186:189], v[16:19]
	v_mfma_f32_16x16x32_bf16 v[4:7], v[134:137], v[194:197], v[4:7]
	v_mfma_f32_16x16x32_bf16 v[0:3], v[160:163], v[194:197], v[0:3]
	s_barrier
	ds_read_b128 v[60:63], v132
	ds_read_b128 v[84:87], v132 offset:1024
	ds_read_b128 v[88:91], v132 offset:2048
	ds_read_b128 v[108:111], v132 offset:3072
	ds_read_b128 v[112:115], v133
	ds_read_b128 v[134:137], v133 offset:1024
	ds_read_b128 v[156:159], v133 offset:2048
	ds_read_b128 v[160:163], v133 offset:3072
	s_add_u32 s52, s52, 0x160000
	s_addc_u32 s53, s53, 0
	s_mov_b32 m0, s59
	ds_read_b128 v[164:167], v209 offset:32768
	ds_read_b128 v[168:171], v209 offset:33792
	ds_read_b128 v[172:175], v209 offset:34816
	ds_read_b128 v[176:179], v209 offset:35840
	ds_read_b128 v[180:183], v209 offset:36864
	ds_read_b128 v[186:189], v209 offset:37888
	ds_read_b128 v[190:193], v209 offset:38912
	ds_read_b128 v[194:197], v209 offset:39936
	s_nop 0
	global_load_lds_dwordx4 v202, s[52:53]
	s_mov_b32 m0, s60
	s_nop 0
	global_load_lds_dwordx4 v204, s[52:53]
	s_waitcnt vmcnt(8)
	s_waitcnt lgkmcnt(0)
	s_barrier
	s_waitcnt lgkmcnt(0)
	v_mfma_f32_16x16x32_bf16 v[152:155], v[60:63], v[164:167], v[152:155]
	v_mfma_f32_16x16x32_bf16 v[148:151], v[88:91], v[164:167], v[148:151]
	v_mfma_f32_16x16x32_bf16 v[128:131], v[60:63], v[172:175], v[128:131]
	v_mfma_f32_16x16x32_bf16 v[124:127], v[88:91], v[172:175], v[124:127]
	v_mfma_f32_16x16x32_bf16 v[104:107], v[60:63], v[180:183], v[104:107]
	v_mfma_f32_16x16x32_bf16 v[100:103], v[88:91], v[180:183], v[100:103]
	v_mfma_f32_16x16x32_bf16 v[80:83], v[60:63], v[190:193], v[80:83]
	v_mfma_f32_16x16x32_bf16 v[76:79], v[88:91], v[190:193], v[76:79]
	v_mfma_f32_16x16x32_bf16 v[152:155], v[84:87], v[168:171], v[152:155]
	v_mfma_f32_16x16x32_bf16 v[148:151], v[108:111], v[168:171], v[148:151]
	v_mfma_f32_16x16x32_bf16 v[128:131], v[84:87], v[176:179], v[128:131]
	v_mfma_f32_16x16x32_bf16 v[124:127], v[108:111], v[176:179], v[124:127]
	v_mfma_f32_16x16x32_bf16 v[104:107], v[84:87], v[186:189], v[104:107]
	v_mfma_f32_16x16x32_bf16 v[100:103], v[108:111], v[186:189], v[100:103]
	v_mfma_f32_16x16x32_bf16 v[80:83], v[84:87], v[194:197], v[80:83]
	v_mfma_f32_16x16x32_bf16 v[76:79], v[108:111], v[194:197], v[76:79]
	v_mfma_f32_16x16x32_bf16 v[142:145], v[112:115], v[164:167], v[144:147]
	v_mfma_f32_16x16x32_bf16 v[138:141], v[156:159], v[164:167], v[138:141]
	v_mfma_f32_16x16x32_bf16 v[120:123], v[112:115], v[172:175], v[120:123]
	v_mfma_f32_16x16x32_bf16 v[116:119], v[156:159], v[172:175], v[116:119]
	v_mfma_f32_16x16x32_bf16 v[96:99], v[112:115], v[180:183], v[96:99]
	v_mfma_f32_16x16x32_bf16 v[92:95], v[156:159], v[180:183], v[92:95]
	v_mfma_f32_16x16x32_bf16 v[72:75], v[112:115], v[190:193], v[72:75]
	v_mfma_f32_16x16x32_bf16 v[68:71], v[156:159], v[190:193], v[68:71]
	v_mfma_f32_16x16x32_bf16 v[144:147], v[134:137], v[168:171], v[142:145]
	v_mfma_f32_16x16x32_bf16 v[140:143], v[160:163], v[168:171], v[138:141]
	v_mfma_f32_16x16x32_bf16 v[120:123], v[134:137], v[176:179], v[120:123]
	v_mfma_f32_16x16x32_bf16 v[116:119], v[160:163], v[176:179], v[116:119]
	v_mfma_f32_16x16x32_bf16 v[96:99], v[134:137], v[186:189], v[96:99]
	v_mfma_f32_16x16x32_bf16 v[92:95], v[160:163], v[186:189], v[92:95]
	v_mfma_f32_16x16x32_bf16 v[72:75], v[134:137], v[194:197], v[72:75]
	v_mfma_f32_16x16x32_bf16 v[68:71], v[160:163], v[194:197], v[68:71]
	s_barrier
	s_add_u32 s52, s50, 0x80
	s_mov_b32 m0, s12
	s_addc_u32 s53, s51, 0
	ds_read_b128 v[164:167], v209 offset:49152
	ds_read_b128 v[168:171], v209 offset:50176
	ds_read_b128 v[172:175], v209 offset:51200
	ds_read_b128 v[176:179], v209 offset:52224
	ds_read_b128 v[180:183], v209 offset:53248
	ds_read_b128 v[186:189], v209 offset:54272
	ds_read_b128 v[190:193], v209 offset:55296
	ds_read_b128 v[194:197], v209 offset:56320
	s_add_u32 s50, s50, 0x160080
	global_load_lds_dwordx4 v203, s[52:53]
	s_mov_b32 m0, s20
	s_addc_u32 s51, s51, 0
	global_load_lds_dwordx4 v205, s[52:53]
	s_mov_b32 m0, s21
	s_nop 0
	global_load_lds_dwordx4 v203, s[50:51]
	s_mov_b32 m0, s74
	s_nop 0
	global_load_lds_dwordx4 v205, s[50:51]
	s_mov_b32 m0, s61
	s_nop 0
	global_load_lds_dwordx4 v202, s[48:49]
	s_mov_b32 m0, s62
	s_nop 0
	global_load_lds_dwordx4 v204, s[48:49]
	s_waitcnt vmcnt(8)
	s_waitcnt lgkmcnt(0)
	s_barrier
	s_waitcnt lgkmcnt(0)
	v_mfma_f32_16x16x32_bf16 v[64:67], v[60:63], v[164:167], v[64:67]
	v_mfma_f32_16x16x32_bf16 v[56:59], v[88:91], v[164:167], v[56:59]
	v_mfma_f32_16x16x32_bf16 v[44:47], v[60:63], v[172:175], v[44:47]
	v_mfma_f32_16x16x32_bf16 v[40:43], v[88:91], v[172:175], v[40:43]
	v_mfma_f32_16x16x32_bf16 v[28:31], v[60:63], v[180:183], v[28:31]
	v_mfma_f32_16x16x32_bf16 v[24:27], v[88:91], v[180:183], v[24:27]
	v_mfma_f32_16x16x32_bf16 v[12:15], v[60:63], v[190:193], v[12:15]
	v_mfma_f32_16x16x32_bf16 v[8:11], v[88:91], v[190:193], v[8:11]
	v_mfma_f32_16x16x32_bf16 v[64:67], v[84:87], v[168:171], v[64:67]
	v_mfma_f32_16x16x32_bf16 v[56:59], v[108:111], v[168:171], v[56:59]
	v_mfma_f32_16x16x32_bf16 v[44:47], v[84:87], v[176:179], v[44:47]
	v_mfma_f32_16x16x32_bf16 v[40:43], v[108:111], v[176:179], v[40:43]
	v_mfma_f32_16x16x32_bf16 v[28:31], v[84:87], v[186:189], v[28:31]
	v_mfma_f32_16x16x32_bf16 v[24:27], v[108:111], v[186:189], v[24:27]
	v_mfma_f32_16x16x32_bf16 v[12:15], v[84:87], v[194:197], v[12:15]
	v_mfma_f32_16x16x32_bf16 v[8:11], v[108:111], v[194:197], v[8:11]
	v_mfma_f32_16x16x32_bf16 v[52:55], v[112:115], v[164:167], v[52:55]
	v_mfma_f32_16x16x32_bf16 v[48:51], v[156:159], v[164:167], v[48:51]
	v_mfma_f32_16x16x32_bf16 v[36:39], v[112:115], v[172:175], v[36:39]
	v_mfma_f32_16x16x32_bf16 v[32:35], v[156:159], v[172:175], v[32:35]
	v_mfma_f32_16x16x32_bf16 v[20:23], v[112:115], v[180:183], v[20:23]
	v_mfma_f32_16x16x32_bf16 v[16:19], v[156:159], v[180:183], v[16:19]
	v_mfma_f32_16x16x32_bf16 v[4:7], v[112:115], v[190:193], v[4:7]
	v_mfma_f32_16x16x32_bf16 v[0:3], v[156:159], v[190:193], v[0:3]
	v_mfma_f32_16x16x32_bf16 v[52:55], v[134:137], v[168:171], v[52:55]
	v_mfma_f32_16x16x32_bf16 v[48:51], v[160:163], v[168:171], v[48:51]
	v_mfma_f32_16x16x32_bf16 v[36:39], v[134:137], v[176:179], v[36:39]
	v_mfma_f32_16x16x32_bf16 v[32:35], v[160:163], v[176:179], v[32:35]
	v_mfma_f32_16x16x32_bf16 v[20:23], v[134:137], v[186:189], v[20:23]
	v_mfma_f32_16x16x32_bf16 v[16:19], v[160:163], v[186:189], v[16:19]
	v_mfma_f32_16x16x32_bf16 v[4:7], v[134:137], v[194:197], v[4:7]
	v_mfma_f32_16x16x32_bf16 v[0:3], v[160:163], v[194:197], v[0:3]
	s_barrier
	s_add_i32 s79, s79, 2
	s_add_u32 s75, s75, 0x100
	s_addc_u32 s76, s76, 0
	s_add_u32 s77, s77, 0x100
	s_addc_u32 s78, s78, 0
	s_add_u32 s4, s4, 0x100
	s_addc_u32 s5, s5, 0
	s_cmpk_gt_u32 s79, 0x55
	s_cbranch_scc0 .LBB0_900
	s_and_b64 vcc, exec, s[34:35]
	s_cbranch_vccz .LBB0_903
	s_barrier

.LBB0_1005:
	s_add_u32 s20, s46, 0x100
	s_addc_u32 s21, s47, 0
	s_waitcnt lgkmcnt(0)
	s_add_u32 s42, s44, 0x100
	s_addc_u32 s43, s45, 0
	s_barrier
	s_waitcnt lgkmcnt(0)
	v_mfma_f32_16x16x32_bf16 v[32:35], v[16:19], v[72:75], 0
	v_mfma_f32_16x16x32_bf16 v[36:39], v[24:27], v[72:75], 0
	v_mfma_f32_16x16x32_bf16 v[40:43], v[16:19], v[80:83], 0
	v_mfma_f32_16x16x32_bf16 v[44:47], v[24:27], v[80:83], 0
	v_mfma_f32_16x16x32_bf16 v[48:51], v[16:19], v[92:95], 0
	v_mfma_f32_16x16x32_bf16 v[52:55], v[24:27], v[92:95], 0
	v_mfma_f32_16x16x32_bf16 v[56:59], v[16:19], v[60:63], 0
	v_mfma_f32_16x16x32_bf16 v[64:67], v[24:27], v[60:63], 0
	v_mfma_f32_16x16x32_bf16 v[32:35], v[20:23], v[76:79], v[32:35]
	v_mfma_f32_16x16x32_bf16 v[36:39], v[28:31], v[76:79], v[36:39]
	v_mfma_f32_16x16x32_bf16 v[40:43], v[20:23], v[84:87], v[40:43]
	v_mfma_f32_16x16x32_bf16 v[44:47], v[28:31], v[84:87], v[44:47]
	v_mfma_f32_16x16x32_bf16 v[48:51], v[20:23], v[96:99], v[48:51]
	v_mfma_f32_16x16x32_bf16 v[52:55], v[28:31], v[96:99], v[52:55]
	v_mfma_f32_16x16x32_bf16 v[56:59], v[20:23], v[88:91], v[56:59]
	v_mfma_f32_16x16x32_bf16 v[64:67], v[28:31], v[88:91], v[64:67]
	v_mfma_f32_16x16x32_bf16 v[68:71], v[0:3], v[72:75], 0
	v_mfma_f32_16x16x32_bf16 v[72:75], v[8:11], v[72:75], 0
	v_mfma_f32_16x16x32_bf16 v[68:71], v[4:7], v[76:79], v[68:71]
	v_mfma_f32_16x16x32_bf16 v[72:75], v[12:15], v[76:79], v[72:75]
	v_mfma_f32_16x16x32_bf16 v[76:79], v[0:3], v[80:83], 0
	v_mfma_f32_16x16x32_bf16 v[80:83], v[8:11], v[80:83], 0
	v_mfma_f32_16x16x32_bf16 v[76:79], v[4:7], v[84:87], v[76:79]
	v_mfma_f32_16x16x32_bf16 v[80:83], v[12:15], v[84:87], v[80:83]
	v_mfma_f32_16x16x32_bf16 v[84:87], v[0:3], v[92:95], 0
	v_mfma_f32_16x16x32_bf16 v[92:95], v[8:11], v[92:95], 0
	v_mfma_f32_16x16x32_bf16 v[128:131], v[12:15], v[96:99], v[92:95]
	v_mfma_f32_16x16x32_bf16 v[92:95], v[0:3], v[60:63], 0
	v_mfma_f32_16x16x32_bf16 v[60:63], v[8:11], v[60:63], 0
	v_mfma_f32_16x16x32_bf16 v[84:87], v[4:7], v[96:99], v[84:87]
	v_mfma_f32_16x16x32_bf16 v[132:135], v[4:7], v[88:91], v[92:95]
	v_mfma_f32_16x16x32_bf16 v[136:139], v[12:15], v[88:91], v[60:63]
	s_barrier
	s_mov_b32 m0, s37
	ds_read_b128 v[108:111], v150 offset:16384
	ds_read_b128 v[112:115], v150 offset:17408
	ds_read_b128 v[100:103], v150 offset:18432
	ds_read_b128 v[104:107], v150 offset:19456
	ds_read_b128 v[92:95], v150 offset:20480
	ds_read_b128 v[96:99], v150 offset:21504
	ds_read_b128 v[60:63], v150 offset:22528
	ds_read_b128 v[88:91], v150 offset:23552
	s_nop 0
	global_load_lds_dwordx4 v144, s[42:43]
	s_mov_b32 m0, s55
	s_nop 0
	global_load_lds_dwordx4 v146, s[42:43]
	s_add_u32 s42, s44, 0x80100
	s_addc_u32 s43, s45, 0
	s_mov_b32 m0, s56
	s_and_b64 vcc, exec, s[40:41]
	global_load_lds_dwordx4 v144, s[42:43]
	s_mov_b32 m0, s57
	s_nop 0
	global_load_lds_dwordx4 v146, s[42:43]
	s_mov_b32 m0, s27
	s_mov_b64 s[42:43], -1
	global_load_lds_dwordx4 v143, s[20:21]
	s_mov_b32 m0, s58
	s_nop 0
	global_load_lds_dwordx4 v145, s[20:21]
	s_cbranch_vccz .LBB0_1007
	s_waitcnt vmcnt(8)
	s_mov_b64 s[42:43], 0

.LBB0_1009:
	s_ashr_i32 s7, s6, 31
	s_lshl_b64 s[20:21], s[6:7], 20
	s_add_u32 s40, s14, s20
	s_addc_u32 s41, s15, s21
	s_ashr_i32 s9, s8, 31
	s_lshl_b64 s[20:21], s[8:9], 20
	s_add_u32 s42, s24, s20
	s_addc_u32 s43, s25, s21
	s_add_u32 s48, s46, 0x180
	s_addc_u32 s49, s47, 0
	s_waitcnt lgkmcnt(0)
	s_and_b64 s[20:21], s[38:39], exec
	s_cselect_b32 s9, s43, s45
	s_cselect_b32 s12, s42, s44
	s_cselect_b32 s20, s41, s47
	s_cselect_b32 s21, s40, s46
	s_add_u32 s50, s44, 0x180
	s_addc_u32 s51, s45, 0
	s_barrier
	s_waitcnt lgkmcnt(0)
	v_mfma_f32_16x16x32_bf16 v[116:119], v[16:19], v[108:111], 0
	v_mfma_f32_16x16x32_bf16 v[156:159], v[20:23], v[112:115], v[116:119]
	v_mfma_f32_16x16x32_bf16 v[116:119], v[24:27], v[108:111], 0
	v_mfma_f32_16x16x32_bf16 v[160:163], v[28:31], v[112:115], v[116:119]
	v_mfma_f32_16x16x32_bf16 v[116:119], v[16:19], v[100:103], 0
	v_mfma_f32_16x16x32_bf16 v[164:167], v[20:23], v[104:107], v[116:119]
	v_mfma_f32_16x16x32_bf16 v[116:119], v[24:27], v[100:103], 0
	v_mfma_f32_16x16x32_bf16 v[168:171], v[28:31], v[104:107], v[116:119]
	v_mfma_f32_16x16x32_bf16 v[116:119], v[16:19], v[92:95], 0
	v_mfma_f32_16x16x32_bf16 v[16:19], v[16:19], v[60:63], 0
	v_mfma_f32_16x16x32_bf16 v[172:175], v[20:23], v[96:99], v[116:119]
	v_mfma_f32_16x16x32_bf16 v[16:19], v[20:23], v[88:91], v[16:19]
	v_mfma_f32_16x16x32_bf16 v[20:23], v[24:27], v[60:63], 0
	v_mfma_f32_16x16x32_bf16 v[116:119], v[24:27], v[92:95], 0
	v_mfma_f32_16x16x32_bf16 v[20:23], v[28:31], v[88:91], v[20:23]
	v_mfma_f32_16x16x32_bf16 v[176:179], v[28:31], v[96:99], v[116:119]
	v_mfma_f32_16x16x32_bf16 v[24:27], v[0:3], v[108:111], 0
	v_mfma_f32_16x16x32_bf16 v[180:183], v[4:7], v[112:115], v[24:27]
	v_mfma_f32_16x16x32_bf16 v[24:27], v[8:11], v[108:111], 0
	v_mfma_f32_16x16x32_bf16 v[184:187], v[12:15], v[112:115], v[24:27]
	v_mfma_f32_16x16x32_bf16 v[24:27], v[0:3], v[100:103], 0
	v_mfma_f32_16x16x32_bf16 v[188:191], v[4:7], v[104:107], v[24:27]
	v_mfma_f32_16x16x32_bf16 v[24:27], v[8:11], v[100:103], 0
	v_mfma_f32_16x16x32_bf16 v[192:195], v[12:15], v[104:107], v[24:27]
	v_mfma_f32_16x16x32_bf16 v[24:27], v[0:3], v[92:95], 0
	v_mfma_f32_16x16x32_bf16 v[0:3], v[0:3], v[60:63], 0
	v_mfma_f32_16x16x32_bf16 v[196:199], v[4:7], v[96:99], v[24:27]
	v_mfma_f32_16x16x32_bf16 v[24:27], v[8:11], v[92:95], 0
	v_mfma_f32_16x16x32_bf16 v[0:3], v[4:7], v[88:91], v[0:3]
	v_mfma_f32_16x16x32_bf16 v[4:7], v[8:11], v[60:63], 0
	v_mfma_f32_16x16x32_bf16 v[200:203], v[12:15], v[96:99], v[24:27]
	v_mfma_f32_16x16x32_bf16 v[204:207], v[12:15], v[88:91], v[4:7]
	s_barrier
	v_add_u32_e32 v153, s68, v147
	v_add_u32_e32 v154, s69, v147
	s_nop 1
	ds_read_b128 v[4:7], v153
	ds_read_b128 v[8:11], v153 offset:1024
	ds_read_b128 v[208:211], v153 offset:2048
	ds_read_b128 v[212:215], v153 offset:3072
	ds_read_b128 v[216:219], v154
	ds_read_b128 v[220:223], v154 offset:1024
	ds_read_b128 v[224:227], v154 offset:2048
	ds_read_b128 v[228:231], v154 offset:3072
	s_add_u32 s52, s46, 0x80100
	s_addc_u32 s53, s47, 0
	s_mov_b32 m0, s59
	ds_read_b128 v[12:15], v150 offset:32768
	ds_read_b128 v[24:27], v150 offset:33792
	ds_read_b128 v[28:31], v150 offset:34816
	ds_read_b128 v[96:99], v150 offset:35840
	ds_read_b128 v[232:235], v150 offset:36864
	ds_read_b128 v[236:239], v150 offset:37888
	ds_read_b128 v[240:243], v150 offset:38912
	ds_read_b128 v[244:247], v150 offset:39936
	s_nop 0
	global_load_lds_dwordx4 v143, s[52:53]
	s_mov_b32 m0, s60
	s_nop 0
	global_load_lds_dwordx4 v145, s[52:53]
	s_waitcnt vmcnt(8)
	s_waitcnt lgkmcnt(0)
	s_barrier
	s_waitcnt lgkmcnt(0)
	v_mfma_f32_16x16x32_bf16 v[32:35], v[4:7], v[12:15], v[32:35]
	v_mfma_f32_16x16x32_bf16 v[124:127], v[8:11], v[24:27], v[32:35]
	v_mfma_f32_16x16x32_bf16 v[32:35], v[208:211], v[12:15], v[36:39]
	v_mfma_f32_16x16x32_bf16 v[120:123], v[212:215], v[24:27], v[32:35]
	v_mfma_f32_16x16x32_bf16 v[32:35], v[4:7], v[28:31], v[40:43]
	v_mfma_f32_16x16x32_bf16 v[108:111], v[8:11], v[96:99], v[32:35]
	v_mfma_f32_16x16x32_bf16 v[32:35], v[208:211], v[28:31], v[44:47]
	v_mfma_f32_16x16x32_bf16 v[104:107], v[212:215], v[96:99], v[32:35]
	v_mfma_f32_16x16x32_bf16 v[32:35], v[4:7], v[232:235], v[48:51]
	v_mfma_f32_16x16x32_bf16 v[92:95], v[8:11], v[236:239], v[32:35]
	v_mfma_f32_16x16x32_bf16 v[32:35], v[208:211], v[232:235], v[52:55]
	v_mfma_f32_16x16x32_bf16 v[88:91], v[212:215], v[236:239], v[32:35]
	v_mfma_f32_16x16x32_bf16 v[32:35], v[4:7], v[240:243], v[56:59]
	v_mfma_f32_16x16x32_bf16 v[60:63], v[8:11], v[244:247], v[32:35]
	v_mfma_f32_16x16x32_bf16 v[32:35], v[208:211], v[240:243], v[64:67]
	v_mfma_f32_16x16x32_bf16 v[56:59], v[212:215], v[244:247], v[32:35]
	v_mfma_f32_16x16x32_bf16 v[32:35], v[216:219], v[12:15], v[68:71]
	v_mfma_f32_16x16x32_bf16 v[12:15], v[224:227], v[12:15], v[72:75]
	v_mfma_f32_16x16x32_bf16 v[112:115], v[228:231], v[24:27], v[12:15]
	v_mfma_f32_16x16x32_bf16 v[12:15], v[216:219], v[28:31], v[76:79]
	v_mfma_f32_16x16x32_bf16 v[100:103], v[220:223], v[96:99], v[12:15]
	v_mfma_f32_16x16x32_bf16 v[12:15], v[224:227], v[28:31], v[80:83]
	v_mfma_f32_16x16x32_bf16 v[96:99], v[228:231], v[96:99], v[12:15]
	v_mfma_f32_16x16x32_bf16 v[12:15], v[216:219], v[232:235], v[84:87]
	v_mfma_f32_16x16x32_bf16 v[84:87], v[220:223], v[236:239], v[12:15]
	v_mfma_f32_16x16x32_bf16 v[12:15], v[224:227], v[232:235], v[128:131]
	v_mfma_f32_16x16x32_bf16 v[80:83], v[228:231], v[236:239], v[12:15]
	v_mfma_f32_16x16x32_bf16 v[12:15], v[216:219], v[240:243], v[132:135]
	v_mfma_f32_16x16x32_bf16 v[52:55], v[220:223], v[244:247], v[12:15]
	v_mfma_f32_16x16x32_bf16 v[12:15], v[224:227], v[240:243], v[136:139]
	v_mfma_f32_16x16x32_bf16 v[116:119], v[220:223], v[24:27], v[32:35]
	v_mfma_f32_16x16x32_bf16 v[48:51], v[228:231], v[244:247], v[12:15]
	s_barrier
	s_add_i32 s35, s68, s26
	s_mov_b32 m0, s35
	s_add_i32 s73, s35, 0x2000
	ds_read_b128 v[32:35], v150 offset:49152
	ds_read_b128 v[36:39], v150 offset:50176
	ds_read_b128 v[128:131], v150 offset:51200
	ds_read_b128 v[132:135], v150 offset:52224
	ds_read_b128 v[136:139], v150 offset:53248
	ds_read_b128 v[232:235], v150 offset:54272
	ds_read_b128 v[236:239], v150 offset:55296
	ds_read_b128 v[240:243], v150 offset:56320
	s_nop 0
	global_load_lds_dwordx4 v144, s[50:51]
	s_mov_b32 m0, s73
	s_nop 0
	global_load_lds_dwordx4 v146, s[50:51]
	s_add_u32 s50, s44, 0x80180
	s_addc_u32 s51, s45, 0
	s_add_i32 s74, s69, s26
	s_mov_b32 m0, s74
	s_add_i32 s75, s74, 0x2000
	s_nop 0
	global_load_lds_dwordx4 v144, s[50:51]
	s_mov_b32 m0, s75
	s_nop 0
	global_load_lds_dwordx4 v146, s[50:51]
	s_mov_b32 m0, s61
	s_nop 0
	global_load_lds_dwordx4 v143, s[48:49]
	s_mov_b32 m0, s62
	s_nop 0
	global_load_lds_dwordx4 v145, s[48:49]
	s_waitcnt vmcnt(8)
	s_waitcnt lgkmcnt(0)
	s_barrier
	s_waitcnt lgkmcnt(0)
	v_mfma_f32_16x16x32_bf16 v[12:15], v[4:7], v[32:35], v[156:159]
	v_mfma_f32_16x16x32_bf16 v[76:79], v[8:11], v[36:39], v[12:15]
	v_mfma_f32_16x16x32_bf16 v[12:15], v[208:211], v[32:35], v[160:163]
	v_mfma_f32_16x16x32_bf16 v[72:75], v[212:215], v[36:39], v[12:15]
	v_mfma_f32_16x16x32_bf16 v[12:15], v[4:7], v[128:131], v[164:167]
	v_mfma_f32_16x16x32_bf16 v[44:47], v[8:11], v[132:135], v[12:15]
	v_mfma_f32_16x16x32_bf16 v[12:15], v[208:211], v[128:131], v[168:171]
	v_mfma_f32_16x16x32_bf16 v[40:43], v[212:215], v[132:135], v[12:15]
	v_mfma_f32_16x16x32_bf16 v[12:15], v[4:7], v[136:139], v[172:175]
	v_mfma_f32_16x16x32_bf16 v[28:31], v[8:11], v[232:235], v[12:15]
	v_mfma_f32_16x16x32_bf16 v[12:15], v[208:211], v[136:139], v[176:179]
	v_mfma_f32_16x16x32_bf16 v[4:7], v[4:7], v[236:239], v[16:19]
	v_mfma_f32_16x16x32_bf16 v[24:27], v[212:215], v[232:235], v[12:15]
	v_mfma_f32_16x16x32_bf16 v[12:15], v[8:11], v[240:243], v[4:7]
	v_mfma_f32_16x16x32_bf16 v[4:7], v[208:211], v[236:239], v[20:23]
	v_mfma_f32_16x16x32_bf16 v[8:11], v[212:215], v[240:243], v[4:7]
	v_mfma_f32_16x16x32_bf16 v[4:7], v[216:219], v[32:35], v[180:183]
	v_mfma_f32_16x16x32_bf16 v[68:71], v[220:223], v[36:39], v[4:7]
	v_mfma_f32_16x16x32_bf16 v[4:7], v[224:227], v[32:35], v[184:187]
	v_mfma_f32_16x16x32_bf16 v[64:67], v[228:231], v[36:39], v[4:7]
	v_mfma_f32_16x16x32_bf16 v[4:7], v[216:219], v[128:131], v[188:191]
	v_mfma_f32_16x16x32_bf16 v[36:39], v[220:223], v[132:135], v[4:7]
	v_mfma_f32_16x16x32_bf16 v[4:7], v[224:227], v[128:131], v[192:195]
	v_mfma_f32_16x16x32_bf16 v[32:35], v[228:231], v[132:135], v[4:7]
	v_mfma_f32_16x16x32_bf16 v[4:7], v[216:219], v[136:139], v[196:199]
	v_mfma_f32_16x16x32_bf16 v[20:23], v[220:223], v[232:235], v[4:7]
	v_mfma_f32_16x16x32_bf16 v[4:7], v[224:227], v[136:139], v[200:203]
	v_mfma_f32_16x16x32_bf16 v[0:3], v[216:219], v[236:239], v[0:3]
	v_mfma_f32_16x16x32_bf16 v[16:19], v[228:231], v[232:235], v[4:7]
	v_mfma_f32_16x16x32_bf16 v[4:7], v[220:223], v[240:243], v[0:3]
	v_mfma_f32_16x16x32_bf16 v[0:3], v[224:227], v[236:239], v[204:207]
	v_mfma_f32_16x16x32_bf16 v[0:3], v[228:231], v[240:243], v[0:3]
	s_barrier
	s_add_u32 s52, s46, 0x100
	s_addc_u32 s53, s47, 0
	s_add_u32 s76, s44, 0x200
	s_addc_u32 s77, s45, 0
	s_mov_b32 s78, 0
.LBB0_1010:
	s_add_u32 s44, s52, 0x100
	s_addc_u32 s45, s53, 0
	s_cmp_eq_u32 s78, 28
	s_cselect_b32 s50, s21, s44
	s_cselect_b32 s51, s20, s45
	s_cselect_b32 s48, s12, s76
	s_cselect_b32 s49, s9, s77
	s_add_u32 s46, s50, 0x80
	s_addc_u32 s47, s51, 0
	s_add_i32 s79, 0, 0x10000
	v_add_u32_e32 v155, s79, v147
	s_add_i32 s80, 0, 0x14000
	ds_read_b128 v[128:131], v155
	ds_read_b128 v[132:135], v155 offset:1024
	ds_read_b128 v[136:139], v155 offset:2048
	ds_read_b128 v[156:159], v155 offset:3072
	v_add_u32_e32 v155, s80, v147
	ds_read_b128 v[160:163], v155
	ds_read_b128 v[164:167], v155 offset:1024
	ds_read_b128 v[168:171], v155 offset:2048
	ds_read_b128 v[172:175], v155 offset:3072
	s_add_u32 s52, s52, 0x80080
	s_addc_u32 s53, s53, 0
	s_mov_b32 m0, s0
	ds_read_b128 v[176:179], v150
	ds_read_b128 v[180:183], v150 offset:1024
	ds_read_b128 v[184:187], v150 offset:2048
	ds_read_b128 v[188:191], v150 offset:3072
	ds_read_b128 v[192:195], v150 offset:4096
	ds_read_b128 v[196:199], v150 offset:5120
	ds_read_b128 v[200:203], v150 offset:6144
	ds_read_b128 v[204:207], v150 offset:7168
	s_nop 0
	global_load_lds_dwordx4 v143, s[52:53]
	s_mov_b32 m0, s1
	s_nop 0
	global_load_lds_dwordx4 v145, s[52:53]
	s_waitcnt vmcnt(8)
	s_waitcnt lgkmcnt(0)
	s_barrier
	s_waitcnt lgkmcnt(0)
	v_mfma_f32_16x16x32_bf16 v[124:127], v[128:131], v[176:179], v[124:127]
	v_mfma_f32_16x16x32_bf16 v[120:123], v[136:139], v[176:179], v[120:123]
	v_mfma_f32_16x16x32_bf16 v[108:111], v[128:131], v[184:187], v[108:111]
	v_mfma_f32_16x16x32_bf16 v[104:107], v[136:139], v[184:187], v[104:107]
	v_mfma_f32_16x16x32_bf16 v[92:95], v[128:131], v[192:195], v[92:95]
	v_mfma_f32_16x16x32_bf16 v[88:91], v[136:139], v[192:195], v[88:91]
	v_mfma_f32_16x16x32_bf16 v[60:63], v[128:131], v[200:203], v[60:63]
	v_mfma_f32_16x16x32_bf16 v[56:59], v[136:139], v[200:203], v[56:59]
	v_mfma_f32_16x16x32_bf16 v[124:127], v[132:135], v[180:183], v[124:127]
	v_mfma_f32_16x16x32_bf16 v[120:123], v[156:159], v[180:183], v[120:123]
	v_mfma_f32_16x16x32_bf16 v[108:111], v[132:135], v[188:191], v[108:111]
	v_mfma_f32_16x16x32_bf16 v[104:107], v[156:159], v[188:191], v[104:107]
	v_mfma_f32_16x16x32_bf16 v[92:95], v[132:135], v[196:199], v[92:95]
	v_mfma_f32_16x16x32_bf16 v[88:91], v[156:159], v[196:199], v[88:91]
	v_mfma_f32_16x16x32_bf16 v[60:63], v[132:135], v[204:207], v[60:63]
	v_mfma_f32_16x16x32_bf16 v[56:59], v[156:159], v[204:207], v[56:59]
	v_mfma_f32_16x16x32_bf16 v[116:119], v[160:163], v[176:179], v[116:119]
	v_mfma_f32_16x16x32_bf16 v[112:115], v[168:171], v[176:179], v[112:115]
	v_mfma_f32_16x16x32_bf16 v[100:103], v[160:163], v[184:187], v[100:103]
	v_mfma_f32_16x16x32_bf16 v[96:99], v[168:171], v[184:187], v[96:99]
	v_mfma_f32_16x16x32_bf16 v[84:87], v[160:163], v[192:195], v[84:87]
	v_mfma_f32_16x16x32_bf16 v[80:83], v[168:171], v[192:195], v[80:83]
	v_mfma_f32_16x16x32_bf16 v[52:55], v[160:163], v[200:203], v[52:55]
	v_mfma_f32_16x16x32_bf16 v[48:51], v[168:171], v[200:203], v[48:51]
	v_mfma_f32_16x16x32_bf16 v[116:119], v[164:167], v[180:183], v[116:119]
	v_mfma_f32_16x16x32_bf16 v[112:115], v[172:175], v[180:183], v[112:115]
	v_mfma_f32_16x16x32_bf16 v[100:103], v[164:167], v[188:191], v[100:103]
	v_mfma_f32_16x16x32_bf16 v[96:99], v[172:175], v[188:191], v[96:99]
	v_mfma_f32_16x16x32_bf16 v[84:87], v[164:167], v[196:199], v[84:87]
	v_mfma_f32_16x16x32_bf16 v[80:83], v[172:175], v[196:199], v[80:83]
	v_mfma_f32_16x16x32_bf16 v[52:55], v[164:167], v[204:207], v[52:55]
	v_mfma_f32_16x16x32_bf16 v[48:51], v[172:175], v[204:207], v[48:51]
	s_barrier
	s_add_i32 s52, s79, s26
	s_mov_b32 m0, s52
	ds_read_b128 v[176:179], v150 offset:16384
	ds_read_b128 v[180:183], v150 offset:17408
	ds_read_b128 v[184:187], v150 offset:18432
	ds_read_b128 v[188:191], v150 offset:19456
	ds_read_b128 v[192:195], v150 offset:20480
	ds_read_b128 v[196:199], v150 offset:21504
	ds_read_b128 v[200:203], v150 offset:22528
	ds_read_b128 v[204:207], v150 offset:23552
	s_nop 0
	global_load_lds_dwordx4 v144, s[48:49]
	s_add_i32 m0, s52, 0x2000
	s_add_u32 s52, s48, 0x80000
	s_addc_u32 s53, s49, 0
	s_add_i32 s79, s80, s26
	s_nop 0
	global_load_lds_dwordx4 v146, s[48:49]
	s_mov_b32 m0, s79
	s_nop 0
	global_load_lds_dwordx4 v144, s[52:53]
	s_add_i32 m0, s79, 0x2000
	s_nop 0
	global_load_lds_dwordx4 v146, s[52:53]
	s_mov_b32 m0, s27
	s_nop 0
	global_load_lds_dwordx4 v143, s[50:51]
	s_mov_b32 m0, s58
	s_nop 0
	global_load_lds_dwordx4 v145, s[50:51]
	s_waitcnt vmcnt(8)
	s_waitcnt lgkmcnt(0)
	s_barrier
	s_waitcnt lgkmcnt(0)
	v_mfma_f32_16x16x32_bf16 v[76:79], v[128:131], v[176:179], v[76:79]
	v_mfma_f32_16x16x32_bf16 v[72:75], v[136:139], v[176:179], v[72:75]
	v_mfma_f32_16x16x32_bf16 v[44:47], v[128:131], v[184:187], v[44:47]
	v_mfma_f32_16x16x32_bf16 v[40:43], v[136:139], v[184:187], v[40:43]
	v_mfma_f32_16x16x32_bf16 v[28:31], v[128:131], v[192:195], v[28:31]
	v_mfma_f32_16x16x32_bf16 v[24:27], v[136:139], v[192:195], v[24:27]
	v_mfma_f32_16x16x32_bf16 v[12:15], v[128:131], v[200:203], v[12:15]
	v_mfma_f32_16x16x32_bf16 v[8:11], v[136:139], v[200:203], v[8:11]
	v_mfma_f32_16x16x32_bf16 v[76:79], v[132:135], v[180:183], v[76:79]
	v_mfma_f32_16x16x32_bf16 v[72:75], v[156:159], v[180:183], v[72:75]
	v_mfma_f32_16x16x32_bf16 v[44:47], v[132:135], v[188:191], v[44:47]
	v_mfma_f32_16x16x32_bf16 v[40:43], v[156:159], v[188:191], v[40:43]
	v_mfma_f32_16x16x32_bf16 v[28:31], v[132:135], v[196:199], v[28:31]
	v_mfma_f32_16x16x32_bf16 v[24:27], v[156:159], v[196:199], v[24:27]
	v_mfma_f32_16x16x32_bf16 v[12:15], v[132:135], v[204:207], v[12:15]
	v_mfma_f32_16x16x32_bf16 v[8:11], v[156:159], v[204:207], v[8:11]
	v_mfma_f32_16x16x32_bf16 v[68:71], v[160:163], v[176:179], v[68:71]
	v_mfma_f32_16x16x32_bf16 v[64:67], v[168:171], v[176:179], v[64:67]
	v_mfma_f32_16x16x32_bf16 v[36:39], v[160:163], v[184:187], v[36:39]
	v_mfma_f32_16x16x32_bf16 v[32:35], v[168:171], v[184:187], v[32:35]
	v_mfma_f32_16x16x32_bf16 v[20:23], v[160:163], v[192:195], v[20:23]
	v_mfma_f32_16x16x32_bf16 v[16:19], v[168:171], v[192:195], v[16:19]
	v_mfma_f32_16x16x32_bf16 v[4:7], v[160:163], v[200:203], v[4:7]
	v_mfma_f32_16x16x32_bf16 v[0:3], v[168:171], v[200:203], v[0:3]
	v_mfma_f32_16x16x32_bf16 v[68:71], v[164:167], v[180:183], v[68:71]
	v_mfma_f32_16x16x32_bf16 v[64:67], v[172:175], v[180:183], v[64:67]
	v_mfma_f32_16x16x32_bf16 v[36:39], v[164:167], v[188:191], v[36:39]
	v_mfma_f32_16x16x32_bf16 v[32:35], v[172:175], v[188:191], v[32:35]
	v_mfma_f32_16x16x32_bf16 v[20:23], v[164:167], v[196:199], v[20:23]
	v_mfma_f32_16x16x32_bf16 v[16:19], v[172:175], v[196:199], v[16:19]
	v_mfma_f32_16x16x32_bf16 v[4:7], v[164:167], v[204:207], v[4:7]
	v_mfma_f32_16x16x32_bf16 v[0:3], v[172:175], v[204:207], v[0:3]
	s_barrier
	ds_read_b128 v[128:131], v153
	ds_read_b128 v[132:135], v153 offset:1024
	ds_read_b128 v[136:139], v153 offset:2048
	ds_read_b128 v[156:159], v153 offset:3072
	ds_read_b128 v[160:163], v154
	ds_read_b128 v[164:167], v154 offset:1024
	ds_read_b128 v[168:171], v154 offset:2048
	ds_read_b128 v[172:175], v154 offset:3072
	s_add_u32 s50, s50, 0x80000
	s_addc_u32 s51, s51, 0
	s_mov_b32 m0, s59
	ds_read_b128 v[176:179], v150 offset:32768
	ds_read_b128 v[180:183], v150 offset:33792
	ds_read_b128 v[184:187], v150 offset:34816
	ds_read_b128 v[188:191], v150 offset:35840
	ds_read_b128 v[192:195], v150 offset:36864
	ds_read_b128 v[196:199], v150 offset:37888
	ds_read_b128 v[200:203], v150 offset:38912
	ds_read_b128 v[204:207], v150 offset:39936
	s_nop 0
	global_load_lds_dwordx4 v143, s[50:51]
	s_mov_b32 m0, s60
	s_nop 0
	global_load_lds_dwordx4 v145, s[50:51]
	s_waitcnt vmcnt(8)
	s_waitcnt lgkmcnt(0)
	s_barrier
	s_waitcnt lgkmcnt(0)
	v_mfma_f32_16x16x32_bf16 v[124:127], v[128:131], v[176:179], v[124:127]
	v_mfma_f32_16x16x32_bf16 v[120:123], v[136:139], v[176:179], v[120:123]
	v_mfma_f32_16x16x32_bf16 v[108:111], v[128:131], v[184:187], v[108:111]
	v_mfma_f32_16x16x32_bf16 v[104:107], v[136:139], v[184:187], v[104:107]
	v_mfma_f32_16x16x32_bf16 v[92:95], v[128:131], v[192:195], v[92:95]
	v_mfma_f32_16x16x32_bf16 v[88:91], v[136:139], v[192:195], v[88:91]
	v_mfma_f32_16x16x32_bf16 v[60:63], v[128:131], v[200:203], v[60:63]
	v_mfma_f32_16x16x32_bf16 v[56:59], v[136:139], v[200:203], v[56:59]
	v_mfma_f32_16x16x32_bf16 v[124:127], v[132:135], v[180:183], v[124:127]
	v_mfma_f32_16x16x32_bf16 v[120:123], v[156:159], v[180:183], v[120:123]
	v_mfma_f32_16x16x32_bf16 v[108:111], v[132:135], v[188:191], v[108:111]
	v_mfma_f32_16x16x32_bf16 v[104:107], v[156:159], v[188:191], v[104:107]
	v_mfma_f32_16x16x32_bf16 v[92:95], v[132:135], v[196:199], v[92:95]
	v_mfma_f32_16x16x32_bf16 v[88:91], v[156:159], v[196:199], v[88:91]
	v_mfma_f32_16x16x32_bf16 v[60:63], v[132:135], v[204:207], v[60:63]
	v_mfma_f32_16x16x32_bf16 v[56:59], v[156:159], v[204:207], v[56:59]
	v_mfma_f32_16x16x32_bf16 v[116:119], v[160:163], v[176:179], v[116:119]
	v_mfma_f32_16x16x32_bf16 v[112:115], v[168:171], v[176:179], v[112:115]
	v_mfma_f32_16x16x32_bf16 v[100:103], v[160:163], v[184:187], v[100:103]
	v_mfma_f32_16x16x32_bf16 v[96:99], v[168:171], v[184:187], v[96:99]
	v_mfma_f32_16x16x32_bf16 v[84:87], v[160:163], v[192:195], v[84:87]
	v_mfma_f32_16x16x32_bf16 v[80:83], v[168:171], v[192:195], v[80:83]
	v_mfma_f32_16x16x32_bf16 v[52:55], v[160:163], v[200:203], v[52:55]
	v_mfma_f32_16x16x32_bf16 v[48:51], v[168:171], v[200:203], v[48:51]
	v_mfma_f32_16x16x32_bf16 v[116:119], v[164:167], v[180:183], v[116:119]
	v_mfma_f32_16x16x32_bf16 v[112:115], v[172:175], v[180:183], v[112:115]
	v_mfma_f32_16x16x32_bf16 v[100:103], v[164:167], v[188:191], v[100:103]
	v_mfma_f32_16x16x32_bf16 v[96:99], v[172:175], v[188:191], v[96:99]
	v_mfma_f32_16x16x32_bf16 v[84:87], v[164:167], v[196:199], v[84:87]
	v_mfma_f32_16x16x32_bf16 v[80:83], v[172:175], v[196:199], v[80:83]
	v_mfma_f32_16x16x32_bf16 v[52:55], v[164:167], v[204:207], v[52:55]
	v_mfma_f32_16x16x32_bf16 v[48:51], v[172:175], v[204:207], v[48:51]
	s_barrier
	s_add_u32 s50, s48, 0x80
	s_mov_b32 m0, s35
	s_addc_u32 s51, s49, 0
	ds_read_b128 v[176:179], v150 offset:49152
	ds_read_b128 v[180:183], v150 offset:50176
	ds_read_b128 v[184:187], v150 offset:51200
	ds_read_b128 v[188:191], v150 offset:52224
	ds_read_b128 v[192:195], v150 offset:53248
	ds_read_b128 v[196:199], v150 offset:54272
	ds_read_b128 v[200:203], v150 offset:55296
	ds_read_b128 v[204:207], v150 offset:56320
	s_add_u32 s48, s48, 0x80080
	global_load_lds_dwordx4 v144, s[50:51]
	s_mov_b32 m0, s73
	s_addc_u32 s49, s49, 0
	global_load_lds_dwordx4 v146, s[50:51]
	s_mov_b32 m0, s74
	s_nop 0
	global_load_lds_dwordx4 v144, s[48:49]
	s_mov_b32 m0, s75
	s_nop 0
	global_load_lds_dwordx4 v146, s[48:49]
	s_mov_b32 m0, s61
	s_nop 0
	global_load_lds_dwordx4 v143, s[46:47]
	s_mov_b32 m0, s62
	s_nop 0
	global_load_lds_dwordx4 v145, s[46:47]
	s_waitcnt vmcnt(8)
	s_waitcnt lgkmcnt(0)
	s_barrier
	s_waitcnt lgkmcnt(0)
	v_mfma_f32_16x16x32_bf16 v[76:79], v[128:131], v[176:179], v[76:79]
	v_mfma_f32_16x16x32_bf16 v[72:75], v[136:139], v[176:179], v[72:75]
	v_mfma_f32_16x16x32_bf16 v[44:47], v[128:131], v[184:187], v[44:47]
	v_mfma_f32_16x16x32_bf16 v[40:43], v[136:139], v[184:187], v[40:43]
	v_mfma_f32_16x16x32_bf16 v[28:31], v[128:131], v[192:195], v[28:31]
	v_mfma_f32_16x16x32_bf16 v[24:27], v[136:139], v[192:195], v[24:27]
	v_mfma_f32_16x16x32_bf16 v[12:15], v[128:131], v[200:203], v[12:15]
	v_mfma_f32_16x16x32_bf16 v[8:11], v[136:139], v[200:203], v[8:11]
	v_mfma_f32_16x16x32_bf16 v[76:79], v[132:135], v[180:183], v[76:79]
	v_mfma_f32_16x16x32_bf16 v[72:75], v[156:159], v[180:183], v[72:75]
	v_mfma_f32_16x16x32_bf16 v[44:47], v[132:135], v[188:191], v[44:47]
	v_mfma_f32_16x16x32_bf16 v[40:43], v[156:159], v[188:191], v[40:43]
	v_mfma_f32_16x16x32_bf16 v[28:31], v[132:135], v[196:199], v[28:31]
	v_mfma_f32_16x16x32_bf16 v[24:27], v[156:159], v[196:199], v[24:27]
	v_mfma_f32_16x16x32_bf16 v[12:15], v[132:135], v[204:207], v[12:15]
	v_mfma_f32_16x16x32_bf16 v[8:11], v[156:159], v[204:207], v[8:11]
	v_mfma_f32_16x16x32_bf16 v[68:71], v[160:163], v[176:179], v[68:71]
	v_mfma_f32_16x16x32_bf16 v[64:67], v[168:171], v[176:179], v[64:67]
	v_mfma_f32_16x16x32_bf16 v[36:39], v[160:163], v[184:187], v[36:39]
	v_mfma_f32_16x16x32_bf16 v[32:35], v[168:171], v[184:187], v[32:35]
	v_mfma_f32_16x16x32_bf16 v[20:23], v[160:163], v[192:195], v[20:23]
	v_mfma_f32_16x16x32_bf16 v[16:19], v[168:171], v[192:195], v[16:19]
	v_mfma_f32_16x16x32_bf16 v[4:7], v[160:163], v[200:203], v[4:7]
	v_mfma_f32_16x16x32_bf16 v[0:3], v[168:171], v[200:203], v[0:3]
	v_mfma_f32_16x16x32_bf16 v[68:71], v[164:167], v[180:183], v[68:71]
	v_mfma_f32_16x16x32_bf16 v[64:67], v[172:175], v[180:183], v[64:67]
	v_mfma_f32_16x16x32_bf16 v[36:39], v[164:167], v[188:191], v[36:39]
	v_mfma_f32_16x16x32_bf16 v[32:35], v[172:175], v[188:191], v[32:35]
	v_mfma_f32_16x16x32_bf16 v[20:23], v[164:167], v[196:199], v[20:23]
	v_mfma_f32_16x16x32_bf16 v[16:19], v[172:175], v[196:199], v[16:19]
	v_mfma_f32_16x16x32_bf16 v[4:7], v[164:167], v[204:207], v[4:7]
	v_mfma_f32_16x16x32_bf16 v[0:3], v[172:175], v[204:207], v[0:3]
	s_barrier
	s_add_i32 s78, s78, 2
	s_add_u32 s76, s76, 0x100
	s_addc_u32 s77, s77, 0
	s_cmp_gt_u32 s78, 29
	s_mov_b64 s[52:53], s[44:45]
	s_cbranch_scc0 .LBB0_1010
	s_and_b64 vcc, exec, s[4:5]
	s_cbranch_vccz .LBB0_1013
	s_barrier

.LBB0_1585:
	s_add_u32 s20, s52, 0x100
	s_addc_u32 s21, s53, 0
	s_waitcnt lgkmcnt(0)
	s_add_u32 s44, s50, 0x100
	s_addc_u32 s45, s51, 0
	s_barrier
	v_mfma_f32_16x16x32_bf16 v[32:35], v[16:19], v[68:71], 0
	v_mfma_f32_16x16x32_bf16 v[36:39], v[24:27], v[68:71], 0
	s_waitcnt lgkmcnt(0)
	v_mfma_f32_16x16x32_bf16 v[40:43], v[16:19], v[84:87], 0
	v_mfma_f32_16x16x32_bf16 v[44:47], v[24:27], v[84:87], 0
	v_mfma_f32_16x16x32_bf16 v[48:51], v[16:19], v[88:91], 0
	v_mfma_f32_16x16x32_bf16 v[52:55], v[24:27], v[88:91], 0
	v_mfma_f32_16x16x32_bf16 v[56:59], v[16:19], v[72:75], 0
	v_mfma_f32_16x16x32_bf16 v[60:63], v[24:27], v[72:75], 0
	v_mfma_f32_16x16x32_bf16 v[116:119], v[20:23], v[80:83], v[32:35]
	v_mfma_f32_16x16x32_bf16 v[36:39], v[28:31], v[80:83], v[36:39]
	v_mfma_f32_16x16x32_bf16 v[40:43], v[20:23], v[96:99], v[40:43]
	v_mfma_f32_16x16x32_bf16 v[44:47], v[28:31], v[96:99], v[44:47]
	v_mfma_f32_16x16x32_bf16 v[48:51], v[20:23], v[92:95], v[48:51]
	v_mfma_f32_16x16x32_bf16 v[52:55], v[28:31], v[92:95], v[52:55]
	v_mfma_f32_16x16x32_bf16 v[56:59], v[20:23], v[76:79], v[56:59]
	v_mfma_f32_16x16x32_bf16 v[60:63], v[28:31], v[76:79], v[60:63]
	v_mfma_f32_16x16x32_bf16 v[64:67], v[0:3], v[68:71], 0
	v_mfma_f32_16x16x32_bf16 v[68:71], v[8:11], v[68:71], 0
	v_mfma_f32_16x16x32_bf16 v[64:67], v[4:7], v[80:83], v[64:67]
	v_mfma_f32_16x16x32_bf16 v[68:71], v[12:15], v[80:83], v[68:71]
	v_mfma_f32_16x16x32_bf16 v[80:83], v[0:3], v[84:87], 0
	v_mfma_f32_16x16x32_bf16 v[84:87], v[8:11], v[84:87], 0
	v_mfma_f32_16x16x32_bf16 v[80:83], v[4:7], v[96:99], v[80:83]
	v_mfma_f32_16x16x32_bf16 v[84:87], v[12:15], v[96:99], v[84:87]
	v_mfma_f32_16x16x32_bf16 v[96:99], v[0:3], v[88:91], 0
	v_mfma_f32_16x16x32_bf16 v[88:91], v[8:11], v[88:91], 0
	v_mfma_f32_16x16x32_bf16 v[132:135], v[12:15], v[92:95], v[88:91]
	v_mfma_f32_16x16x32_bf16 v[88:91], v[0:3], v[72:75], 0
	v_mfma_f32_16x16x32_bf16 v[72:75], v[8:11], v[72:75], 0
	v_mfma_f32_16x16x32_bf16 v[128:131], v[4:7], v[92:95], v[96:99]
	v_mfma_f32_16x16x32_bf16 v[136:139], v[4:7], v[76:79], v[88:91]
	v_mfma_f32_16x16x32_bf16 v[140:143], v[12:15], v[76:79], v[72:75]
	s_barrier
	s_mov_b32 m0, s61
	ds_read_b128 v[104:107], v162 offset:16384
	ds_read_b128 v[108:111], v162 offset:17408
	ds_read_b128 v[96:99], v162 offset:18432
	ds_read_b128 v[100:103], v162 offset:19456
	ds_read_b128 v[88:91], v162 offset:20480
	ds_read_b128 v[92:95], v162 offset:21504
	ds_read_b128 v[72:75], v162 offset:22528
	ds_read_b128 v[76:79], v162 offset:23552
	s_nop 0
	global_load_lds_dwordx4 v156, s[44:45]
	s_mov_b32 m0, s62
	s_nop 0
	global_load_lds_dwordx4 v158, s[44:45]
	s_add_u32 s44, s50, 0x80100
	s_addc_u32 s45, s51, 0
	s_mov_b32 m0, s63
	s_and_b64 vcc, exec, s[42:43]
	global_load_lds_dwordx4 v156, s[44:45]
	s_mov_b32 m0, s64
	s_nop 0
	global_load_lds_dwordx4 v158, s[44:45]
	s_mov_b32 m0, s27
	s_mov_b64 s[44:45], -1
	global_load_lds_dwordx4 v153, s[20:21]
	s_mov_b32 m0, s65
	s_nop 0
	global_load_lds_dwordx4 v157, s[20:21]
	s_cbranch_vccz .LBB0_1587
	s_waitcnt vmcnt(8)
	s_mov_b64 s[44:45], 0

.LBB0_1589:
	s_ashr_i32 s7, s6, 31
	s_lshl_b64 s[20:21], s[6:7], 20
	s_add_u32 s42, s14, s20
	s_addc_u32 s43, s15, s21
	s_ashr_i32 s35, s34, 31
	s_lshl_b64 s[20:21], s[34:35], 20
	s_add_u32 s44, s24, s20
	s_addc_u32 s45, s25, s21
	s_add_u32 s54, s52, 0x180
	s_addc_u32 s55, s53, 0
	s_waitcnt lgkmcnt(0)
	s_and_b64 s[20:21], s[36:37], exec
	s_cselect_b32 s20, s45, s51
	s_cselect_b32 s21, s44, s50
	s_cselect_b32 s35, s43, s53
	s_cselect_b32 s47, s42, s52
	s_add_u32 s56, s50, 0x180
	s_addc_u32 s57, s51, 0
	s_barrier
	s_waitcnt lgkmcnt(0)
	v_mfma_f32_16x16x32_bf16 v[112:115], v[16:19], v[104:107], 0
	v_mfma_f32_16x16x32_bf16 v[166:169], v[20:23], v[108:111], v[112:115]
	v_mfma_f32_16x16x32_bf16 v[112:115], v[24:27], v[104:107], 0
	v_mfma_f32_16x16x32_bf16 v[170:173], v[28:31], v[108:111], v[112:115]
	v_mfma_f32_16x16x32_bf16 v[112:115], v[16:19], v[96:99], 0
	v_mfma_f32_16x16x32_bf16 v[174:177], v[20:23], v[100:103], v[112:115]
	v_mfma_f32_16x16x32_bf16 v[112:115], v[24:27], v[96:99], 0
	v_mfma_f32_16x16x32_bf16 v[178:181], v[28:31], v[100:103], v[112:115]
	v_mfma_f32_16x16x32_bf16 v[112:115], v[16:19], v[88:91], 0
	v_mfma_f32_16x16x32_bf16 v[16:19], v[16:19], v[72:75], 0
	v_mfma_f32_16x16x32_bf16 v[182:185], v[20:23], v[92:95], v[112:115]
	v_mfma_f32_16x16x32_bf16 v[16:19], v[20:23], v[76:79], v[16:19]
	v_mfma_f32_16x16x32_bf16 v[20:23], v[24:27], v[72:75], 0
	v_mfma_f32_16x16x32_bf16 v[112:115], v[24:27], v[88:91], 0
	v_mfma_f32_16x16x32_bf16 v[20:23], v[28:31], v[76:79], v[20:23]
	v_mfma_f32_16x16x32_bf16 v[186:189], v[28:31], v[92:95], v[112:115]
	v_mfma_f32_16x16x32_bf16 v[24:27], v[0:3], v[104:107], 0
	v_mfma_f32_16x16x32_bf16 v[190:193], v[4:7], v[108:111], v[24:27]
	v_mfma_f32_16x16x32_bf16 v[24:27], v[8:11], v[104:107], 0
	v_mfma_f32_16x16x32_bf16 v[194:197], v[12:15], v[108:111], v[24:27]
	v_mfma_f32_16x16x32_bf16 v[24:27], v[0:3], v[96:99], 0
	v_mfma_f32_16x16x32_bf16 v[198:201], v[4:7], v[100:103], v[24:27]
	v_mfma_f32_16x16x32_bf16 v[24:27], v[8:11], v[96:99], 0
	v_mfma_f32_16x16x32_bf16 v[202:205], v[12:15], v[100:103], v[24:27]
	v_mfma_f32_16x16x32_bf16 v[24:27], v[0:3], v[88:91], 0
	v_mfma_f32_16x16x32_bf16 v[0:3], v[0:3], v[72:75], 0
	v_mfma_f32_16x16x32_bf16 v[206:209], v[4:7], v[92:95], v[24:27]
	v_mfma_f32_16x16x32_bf16 v[24:27], v[8:11], v[88:91], 0
	v_mfma_f32_16x16x32_bf16 v[0:3], v[4:7], v[76:79], v[0:3]
	v_mfma_f32_16x16x32_bf16 v[4:7], v[8:11], v[72:75], 0
	v_mfma_f32_16x16x32_bf16 v[210:213], v[12:15], v[92:95], v[24:27]
	v_mfma_f32_16x16x32_bf16 v[214:217], v[12:15], v[76:79], v[4:7]
	s_barrier
	v_add_u32_e32 v144, s74, v159
	v_add_u32_e32 v148, s75, v159
	s_nop 1
	ds_read_b128 v[4:7], v144
	ds_read_b128 v[8:11], v144 offset:1024
	ds_read_b128 v[218:221], v144 offset:2048
	ds_read_b128 v[222:225], v144 offset:3072
	ds_read_b128 v[226:229], v148
	ds_read_b128 v[230:233], v148 offset:1024
	ds_read_b128 v[234:237], v148 offset:2048
	ds_read_b128 v[238:241], v148 offset:3072
	s_add_u32 s58, s52, 0x80100
	s_addc_u32 s59, s53, 0
	s_mov_b32 m0, s66
	ds_read_b128 v[12:15], v162 offset:32768
	ds_read_b128 v[24:27], v162 offset:33792
	ds_read_b128 v[28:31], v162 offset:34816
	ds_read_b128 v[96:99], v162 offset:35840
	ds_read_b128 v[242:245], v162 offset:36864
	ds_read_b128 v[246:249], v162 offset:37888
	ds_read_b128 v[250:253], v162 offset:38912
	ds_read_b128 v[32:35], v162 offset:39936
	s_nop 0
	global_load_lds_dwordx4 v153, s[58:59]
	s_mov_b32 m0, s67
	s_nop 0
	global_load_lds_dwordx4 v157, s[58:59]
	s_waitcnt vmcnt(8)
	s_waitcnt lgkmcnt(0)
	s_barrier
	s_waitcnt lgkmcnt(0)
	v_mfma_f32_16x16x32_bf16 v[36:39], v[218:221], v[12:15], v[36:39]
	v_mfma_f32_16x16x32_bf16 v[120:123], v[222:225], v[24:27], v[36:39]
	v_mfma_f32_16x16x32_bf16 v[36:39], v[4:7], v[28:31], v[40:43]
	v_mfma_f32_16x16x32_bf16 v[108:111], v[8:11], v[96:99], v[36:39]
	v_mfma_f32_16x16x32_bf16 v[36:39], v[218:221], v[28:31], v[44:47]
	v_mfma_f32_16x16x32_bf16 v[104:107], v[222:225], v[96:99], v[36:39]
	v_mfma_f32_16x16x32_bf16 v[36:39], v[4:7], v[242:245], v[48:51]
	v_mfma_f32_16x16x32_bf16 v[92:95], v[8:11], v[246:249], v[36:39]
	v_mfma_f32_16x16x32_bf16 v[36:39], v[218:221], v[242:245], v[52:55]
	v_mfma_f32_16x16x32_bf16 v[88:91], v[222:225], v[246:249], v[36:39]
	v_mfma_f32_16x16x32_bf16 v[36:39], v[4:7], v[250:253], v[56:59]
	v_mfma_f32_16x16x32_bf16 v[72:75], v[4:7], v[12:15], v[116:119]
	v_mfma_f32_16x16x32_bf16 v[76:79], v[8:11], v[32:35], v[36:39]
	v_mfma_f32_16x16x32_bf16 v[36:39], v[218:221], v[250:253], v[60:63]
	v_mfma_f32_16x16x32_bf16 v[124:127], v[8:11], v[24:27], v[72:75]
	v_mfma_f32_16x16x32_bf16 v[72:75], v[222:225], v[32:35], v[36:39]
	v_mfma_f32_16x16x32_bf16 v[36:39], v[226:229], v[12:15], v[64:67]
	v_mfma_f32_16x16x32_bf16 v[12:15], v[234:237], v[12:15], v[68:71]
	v_mfma_f32_16x16x32_bf16 v[112:115], v[238:241], v[24:27], v[12:15]
	v_mfma_f32_16x16x32_bf16 v[12:15], v[226:229], v[28:31], v[80:83]
	v_mfma_f32_16x16x32_bf16 v[100:103], v[230:233], v[96:99], v[12:15]
	v_mfma_f32_16x16x32_bf16 v[12:15], v[234:237], v[28:31], v[84:87]
	v_mfma_f32_16x16x32_bf16 v[96:99], v[238:241], v[96:99], v[12:15]
	v_mfma_f32_16x16x32_bf16 v[12:15], v[226:229], v[242:245], v[128:131]
	v_mfma_f32_16x16x32_bf16 v[84:87], v[230:233], v[246:249], v[12:15]
	v_mfma_f32_16x16x32_bf16 v[12:15], v[234:237], v[242:245], v[132:135]
	v_mfma_f32_16x16x32_bf16 v[80:83], v[238:241], v[246:249], v[12:15]
	v_mfma_f32_16x16x32_bf16 v[12:15], v[226:229], v[250:253], v[136:139]
	v_mfma_f32_16x16x32_bf16 v[68:71], v[230:233], v[32:35], v[12:15]
	v_mfma_f32_16x16x32_bf16 v[12:15], v[234:237], v[250:253], v[140:143]
	v_mfma_f32_16x16x32_bf16 v[116:119], v[230:233], v[24:27], v[36:39]
	v_mfma_f32_16x16x32_bf16 v[60:63], v[238:241], v[32:35], v[12:15]
	s_barrier
	s_add_i32 s49, s74, s26
	s_mov_b32 m0, s49
	s_add_i32 s79, s49, 0x2000
	ds_read_b128 v[32:35], v162 offset:49152
	ds_read_b128 v[36:39], v162 offset:50176
	ds_read_b128 v[128:131], v162 offset:51200
	ds_read_b128 v[132:135], v162 offset:52224
	ds_read_b128 v[136:139], v162 offset:53248
	ds_read_b128 v[140:143], v162 offset:54272
	ds_read_b128 v[242:245], v162 offset:55296
	ds_read_b128 v[246:249], v162 offset:56320
	s_nop 0
	global_load_lds_dwordx4 v156, s[56:57]
	s_mov_b32 m0, s79
	s_nop 0
	global_load_lds_dwordx4 v158, s[56:57]
	s_add_u32 s56, s50, 0x80180
	s_addc_u32 s57, s51, 0
	s_add_i32 s80, s75, s26
	s_mov_b32 m0, s80
	s_add_i32 s83, s80, 0x2000
	s_nop 0
	global_load_lds_dwordx4 v156, s[56:57]
	s_mov_b32 m0, s83
	s_nop 0
	global_load_lds_dwordx4 v158, s[56:57]
	s_mov_b32 m0, s68
	s_nop 0
	global_load_lds_dwordx4 v153, s[54:55]
	s_mov_b32 m0, s69
	s_nop 0
	global_load_lds_dwordx4 v157, s[54:55]
	s_waitcnt vmcnt(8)
	s_waitcnt lgkmcnt(0)
	s_barrier
	s_waitcnt lgkmcnt(0)
	v_mfma_f32_16x16x32_bf16 v[12:15], v[4:7], v[32:35], v[166:169]
	v_mfma_f32_16x16x32_bf16 v[64:67], v[8:11], v[36:39], v[12:15]
	v_mfma_f32_16x16x32_bf16 v[12:15], v[218:221], v[32:35], v[170:173]
	v_mfma_f32_16x16x32_bf16 v[56:59], v[222:225], v[36:39], v[12:15]
	v_mfma_f32_16x16x32_bf16 v[12:15], v[4:7], v[128:131], v[174:177]
	v_mfma_f32_16x16x32_bf16 v[44:47], v[8:11], v[132:135], v[12:15]
	v_mfma_f32_16x16x32_bf16 v[12:15], v[218:221], v[128:131], v[178:181]
	v_mfma_f32_16x16x32_bf16 v[40:43], v[222:225], v[132:135], v[12:15]
	v_mfma_f32_16x16x32_bf16 v[12:15], v[4:7], v[136:139], v[182:185]
	v_mfma_f32_16x16x32_bf16 v[28:31], v[8:11], v[140:143], v[12:15]
	v_mfma_f32_16x16x32_bf16 v[12:15], v[218:221], v[136:139], v[186:189]
	v_mfma_f32_16x16x32_bf16 v[4:7], v[4:7], v[242:245], v[16:19]
	v_mfma_f32_16x16x32_bf16 v[24:27], v[222:225], v[140:143], v[12:15]
	v_mfma_f32_16x16x32_bf16 v[12:15], v[8:11], v[246:249], v[4:7]
	v_mfma_f32_16x16x32_bf16 v[4:7], v[218:221], v[242:245], v[20:23]
	v_mfma_f32_16x16x32_bf16 v[8:11], v[222:225], v[246:249], v[4:7]
	v_mfma_f32_16x16x32_bf16 v[4:7], v[226:229], v[32:35], v[190:193]
	v_mfma_f32_16x16x32_bf16 v[52:55], v[230:233], v[36:39], v[4:7]
	v_mfma_f32_16x16x32_bf16 v[4:7], v[234:237], v[32:35], v[194:197]
	v_mfma_f32_16x16x32_bf16 v[48:51], v[238:241], v[36:39], v[4:7]
	v_mfma_f32_16x16x32_bf16 v[4:7], v[226:229], v[128:131], v[198:201]
	v_mfma_f32_16x16x32_bf16 v[36:39], v[230:233], v[132:135], v[4:7]
	v_mfma_f32_16x16x32_bf16 v[4:7], v[234:237], v[128:131], v[202:205]
	v_mfma_f32_16x16x32_bf16 v[32:35], v[238:241], v[132:135], v[4:7]
	v_mfma_f32_16x16x32_bf16 v[4:7], v[226:229], v[136:139], v[206:209]
	v_mfma_f32_16x16x32_bf16 v[20:23], v[230:233], v[140:143], v[4:7]
	v_mfma_f32_16x16x32_bf16 v[4:7], v[234:237], v[136:139], v[210:213]
	v_mfma_f32_16x16x32_bf16 v[0:3], v[226:229], v[242:245], v[0:3]
	v_mfma_f32_16x16x32_bf16 v[16:19], v[238:241], v[140:143], v[4:7]
	v_mfma_f32_16x16x32_bf16 v[4:7], v[230:233], v[246:249], v[0:3]
	v_mfma_f32_16x16x32_bf16 v[0:3], v[234:237], v[242:245], v[214:217]
	v_mfma_f32_16x16x32_bf16 v[0:3], v[238:241], v[246:249], v[0:3]
	s_barrier
	s_add_u32 s58, s52, 0x100
	s_addc_u32 s59, s53, 0
	s_add_u32 s86, s50, 0x200
	s_addc_u32 s88, s51, 0
	s_mov_b32 s89, 0
.LBB0_1590:
	s_add_u32 s50, s58, 0x100
	s_addc_u32 s51, s59, 0
	s_cmp_eq_u32 s89, 28
	s_cselect_b32 s56, s47, s50
	s_cselect_b32 s57, s35, s51
	s_cselect_b32 s54, s21, s86
	s_cselect_b32 s55, s20, s88
	s_add_u32 s52, s56, 0x80
	s_addc_u32 s53, s57, 0
	s_add_i32 s90, 0, 0x10000
	s_add_i32 s91, 0, 0x14000
	v_add_u32_e32 v140, s90, v159
	v_add_u32_e32 v149, s91, v159
	ds_read_b128 v[128:131], v140
	ds_read_b128 v[132:135], v140 offset:1024
	ds_read_b128 v[136:139], v140 offset:2048
	ds_read_b128 v[140:143], v140 offset:3072
	ds_read_b128 v[166:169], v149
	ds_read_b128 v[170:173], v149 offset:1024
	ds_read_b128 v[174:177], v149 offset:2048
	ds_read_b128 v[178:181], v149 offset:3072
	s_add_u32 s58, s58, 0x80080
	s_addc_u32 s59, s59, 0
	s_mov_b32 m0, s1
	ds_read_b128 v[182:185], v162
	ds_read_b128 v[186:189], v162 offset:1024
	ds_read_b128 v[190:193], v162 offset:2048
	ds_read_b128 v[194:197], v162 offset:3072
	ds_read_b128 v[198:201], v162 offset:4096
	ds_read_b128 v[202:205], v162 offset:5120
	ds_read_b128 v[206:209], v162 offset:6144
	ds_read_b128 v[210:213], v162 offset:7168
	s_nop 0
	global_load_lds_dwordx4 v153, s[58:59]
	s_mov_b32 m0, s12
	s_nop 0
	global_load_lds_dwordx4 v157, s[58:59]
	s_waitcnt vmcnt(8)
	s_waitcnt lgkmcnt(0)
	s_barrier
	s_waitcnt lgkmcnt(0)
	v_mfma_f32_16x16x32_bf16 v[124:127], v[128:131], v[182:185], v[124:127]
	v_mfma_f32_16x16x32_bf16 v[120:123], v[136:139], v[182:185], v[120:123]
	v_mfma_f32_16x16x32_bf16 v[108:111], v[128:131], v[190:193], v[108:111]
	v_mfma_f32_16x16x32_bf16 v[104:107], v[136:139], v[190:193], v[104:107]
	v_mfma_f32_16x16x32_bf16 v[92:95], v[128:131], v[198:201], v[92:95]
	v_mfma_f32_16x16x32_bf16 v[88:91], v[136:139], v[198:201], v[88:91]
	v_mfma_f32_16x16x32_bf16 v[76:79], v[128:131], v[206:209], v[76:79]
	v_mfma_f32_16x16x32_bf16 v[72:75], v[136:139], v[206:209], v[72:75]
	v_mfma_f32_16x16x32_bf16 v[124:127], v[132:135], v[186:189], v[124:127]
	v_mfma_f32_16x16x32_bf16 v[120:123], v[140:143], v[186:189], v[120:123]
	v_mfma_f32_16x16x32_bf16 v[108:111], v[132:135], v[194:197], v[108:111]
	v_mfma_f32_16x16x32_bf16 v[104:107], v[140:143], v[194:197], v[104:107]
	v_mfma_f32_16x16x32_bf16 v[92:95], v[132:135], v[202:205], v[92:95]
	v_mfma_f32_16x16x32_bf16 v[88:91], v[140:143], v[202:205], v[88:91]
	v_mfma_f32_16x16x32_bf16 v[76:79], v[132:135], v[210:213], v[76:79]
	v_mfma_f32_16x16x32_bf16 v[72:75], v[140:143], v[210:213], v[72:75]
	v_mfma_f32_16x16x32_bf16 v[116:119], v[166:169], v[182:185], v[116:119]
	v_mfma_f32_16x16x32_bf16 v[112:115], v[174:177], v[182:185], v[112:115]
	v_mfma_f32_16x16x32_bf16 v[100:103], v[166:169], v[190:193], v[100:103]
	v_mfma_f32_16x16x32_bf16 v[96:99], v[174:177], v[190:193], v[96:99]
	v_mfma_f32_16x16x32_bf16 v[84:87], v[166:169], v[198:201], v[84:87]
	v_mfma_f32_16x16x32_bf16 v[80:83], v[174:177], v[198:201], v[80:83]
	v_mfma_f32_16x16x32_bf16 v[68:71], v[166:169], v[206:209], v[68:71]
	v_mfma_f32_16x16x32_bf16 v[60:63], v[174:177], v[206:209], v[60:63]
	v_mfma_f32_16x16x32_bf16 v[116:119], v[170:173], v[186:189], v[116:119]
	v_mfma_f32_16x16x32_bf16 v[112:115], v[178:181], v[186:189], v[112:115]
	v_mfma_f32_16x16x32_bf16 v[100:103], v[170:173], v[194:197], v[100:103]
	v_mfma_f32_16x16x32_bf16 v[96:99], v[178:181], v[194:197], v[96:99]
	v_mfma_f32_16x16x32_bf16 v[84:87], v[170:173], v[202:205], v[84:87]
	v_mfma_f32_16x16x32_bf16 v[80:83], v[178:181], v[202:205], v[80:83]
	v_mfma_f32_16x16x32_bf16 v[68:71], v[170:173], v[210:213], v[68:71]
	v_mfma_f32_16x16x32_bf16 v[60:63], v[178:181], v[210:213], v[60:63]
	s_barrier
	s_add_i32 s58, s90, s26
	s_mov_b32 m0, s58
	ds_read_b128 v[182:185], v162 offset:16384
	ds_read_b128 v[186:189], v162 offset:17408
	ds_read_b128 v[190:193], v162 offset:18432
	ds_read_b128 v[194:197], v162 offset:19456
	ds_read_b128 v[198:201], v162 offset:20480
	ds_read_b128 v[202:205], v162 offset:21504
	ds_read_b128 v[206:209], v162 offset:22528
	ds_read_b128 v[210:213], v162 offset:23552
	s_nop 0
	global_load_lds_dwordx4 v156, s[54:55]
	s_add_i32 m0, s58, 0x2000
	s_add_u32 s58, s54, 0x80000
	s_addc_u32 s59, s55, 0
	s_add_i32 s90, s91, s26
	s_nop 0
	global_load_lds_dwordx4 v158, s[54:55]
	s_mov_b32 m0, s90
	s_nop 0
	global_load_lds_dwordx4 v156, s[58:59]
	s_add_i32 m0, s90, 0x2000
	s_nop 0
	global_load_lds_dwordx4 v158, s[58:59]
	s_mov_b32 m0, s27
	s_nop 0
	global_load_lds_dwordx4 v153, s[56:57]
	s_mov_b32 m0, s65
	s_nop 0
	global_load_lds_dwordx4 v157, s[56:57]
	s_waitcnt vmcnt(8)
	s_waitcnt lgkmcnt(0)
	s_barrier
	s_waitcnt lgkmcnt(0)
	v_mfma_f32_16x16x32_bf16 v[64:67], v[128:131], v[182:185], v[64:67]
	v_mfma_f32_16x16x32_bf16 v[56:59], v[136:139], v[182:185], v[56:59]
	v_mfma_f32_16x16x32_bf16 v[44:47], v[128:131], v[190:193], v[44:47]
	v_mfma_f32_16x16x32_bf16 v[40:43], v[136:139], v[190:193], v[40:43]
	v_mfma_f32_16x16x32_bf16 v[28:31], v[128:131], v[198:201], v[28:31]
	v_mfma_f32_16x16x32_bf16 v[24:27], v[136:139], v[198:201], v[24:27]
	v_mfma_f32_16x16x32_bf16 v[12:15], v[128:131], v[206:209], v[12:15]
	v_mfma_f32_16x16x32_bf16 v[8:11], v[136:139], v[206:209], v[8:11]
	v_mfma_f32_16x16x32_bf16 v[64:67], v[132:135], v[186:189], v[64:67]
	v_mfma_f32_16x16x32_bf16 v[56:59], v[140:143], v[186:189], v[56:59]
	v_mfma_f32_16x16x32_bf16 v[44:47], v[132:135], v[194:197], v[44:47]
	v_mfma_f32_16x16x32_bf16 v[40:43], v[140:143], v[194:197], v[40:43]
	v_mfma_f32_16x16x32_bf16 v[28:31], v[132:135], v[202:205], v[28:31]
	v_mfma_f32_16x16x32_bf16 v[24:27], v[140:143], v[202:205], v[24:27]
	v_mfma_f32_16x16x32_bf16 v[12:15], v[132:135], v[210:213], v[12:15]
	v_mfma_f32_16x16x32_bf16 v[8:11], v[140:143], v[210:213], v[8:11]
	v_mfma_f32_16x16x32_bf16 v[52:55], v[166:169], v[182:185], v[52:55]
	v_mfma_f32_16x16x32_bf16 v[48:51], v[174:177], v[182:185], v[48:51]
	v_mfma_f32_16x16x32_bf16 v[36:39], v[166:169], v[190:193], v[36:39]
	v_mfma_f32_16x16x32_bf16 v[32:35], v[174:177], v[190:193], v[32:35]
	v_mfma_f32_16x16x32_bf16 v[20:23], v[166:169], v[198:201], v[20:23]
	v_mfma_f32_16x16x32_bf16 v[16:19], v[174:177], v[198:201], v[16:19]
	v_mfma_f32_16x16x32_bf16 v[4:7], v[166:169], v[206:209], v[4:7]
	v_mfma_f32_16x16x32_bf16 v[0:3], v[174:177], v[206:209], v[0:3]
	v_mfma_f32_16x16x32_bf16 v[52:55], v[170:173], v[186:189], v[52:55]
	v_mfma_f32_16x16x32_bf16 v[48:51], v[178:181], v[186:189], v[48:51]
	v_mfma_f32_16x16x32_bf16 v[36:39], v[170:173], v[194:197], v[36:39]
	v_mfma_f32_16x16x32_bf16 v[32:35], v[178:181], v[194:197], v[32:35]
	v_mfma_f32_16x16x32_bf16 v[20:23], v[170:173], v[202:205], v[20:23]
	v_mfma_f32_16x16x32_bf16 v[16:19], v[178:181], v[202:205], v[16:19]
	v_mfma_f32_16x16x32_bf16 v[4:7], v[170:173], v[210:213], v[4:7]
	v_mfma_f32_16x16x32_bf16 v[0:3], v[178:181], v[210:213], v[0:3]
	s_barrier
	ds_read_b128 v[128:131], v144
	ds_read_b128 v[132:135], v144 offset:1024
	ds_read_b128 v[136:139], v144 offset:2048
	ds_read_b128 v[140:143], v144 offset:3072
	ds_read_b128 v[166:169], v148
	ds_read_b128 v[170:173], v148 offset:1024
	ds_read_b128 v[174:177], v148 offset:2048
	ds_read_b128 v[178:181], v148 offset:3072
	s_add_u32 s56, s56, 0x80000
	s_addc_u32 s57, s57, 0
	s_mov_b32 m0, s66
	ds_read_b128 v[182:185], v162 offset:32768
	ds_read_b128 v[186:189], v162 offset:33792
	ds_read_b128 v[190:193], v162 offset:34816
	ds_read_b128 v[194:197], v162 offset:35840
	ds_read_b128 v[198:201], v162 offset:36864
	ds_read_b128 v[202:205], v162 offset:37888
	ds_read_b128 v[206:209], v162 offset:38912
	ds_read_b128 v[210:213], v162 offset:39936
	s_nop 0
	global_load_lds_dwordx4 v153, s[56:57]
	s_mov_b32 m0, s67
	s_nop 0
	global_load_lds_dwordx4 v157, s[56:57]
	s_waitcnt vmcnt(8)
	s_waitcnt lgkmcnt(0)
	s_barrier
	s_waitcnt lgkmcnt(0)
	v_mfma_f32_16x16x32_bf16 v[124:127], v[128:131], v[182:185], v[124:127]
	v_mfma_f32_16x16x32_bf16 v[120:123], v[136:139], v[182:185], v[120:123]
	v_mfma_f32_16x16x32_bf16 v[108:111], v[128:131], v[190:193], v[108:111]
	v_mfma_f32_16x16x32_bf16 v[104:107], v[136:139], v[190:193], v[104:107]
	v_mfma_f32_16x16x32_bf16 v[92:95], v[128:131], v[198:201], v[92:95]
	v_mfma_f32_16x16x32_bf16 v[88:91], v[136:139], v[198:201], v[88:91]
	v_mfma_f32_16x16x32_bf16 v[76:79], v[128:131], v[206:209], v[76:79]
	v_mfma_f32_16x16x32_bf16 v[72:75], v[136:139], v[206:209], v[72:75]
	v_mfma_f32_16x16x32_bf16 v[124:127], v[132:135], v[186:189], v[124:127]
	v_mfma_f32_16x16x32_bf16 v[120:123], v[140:143], v[186:189], v[120:123]
	v_mfma_f32_16x16x32_bf16 v[108:111], v[132:135], v[194:197], v[108:111]
	v_mfma_f32_16x16x32_bf16 v[104:107], v[140:143], v[194:197], v[104:107]
	v_mfma_f32_16x16x32_bf16 v[92:95], v[132:135], v[202:205], v[92:95]
	v_mfma_f32_16x16x32_bf16 v[88:91], v[140:143], v[202:205], v[88:91]
	v_mfma_f32_16x16x32_bf16 v[76:79], v[132:135], v[210:213], v[76:79]
	v_mfma_f32_16x16x32_bf16 v[72:75], v[140:143], v[210:213], v[72:75]
	v_mfma_f32_16x16x32_bf16 v[116:119], v[166:169], v[182:185], v[116:119]
	v_mfma_f32_16x16x32_bf16 v[112:115], v[174:177], v[182:185], v[112:115]
	v_mfma_f32_16x16x32_bf16 v[100:103], v[166:169], v[190:193], v[100:103]
	v_mfma_f32_16x16x32_bf16 v[96:99], v[174:177], v[190:193], v[96:99]
	v_mfma_f32_16x16x32_bf16 v[84:87], v[166:169], v[198:201], v[84:87]
	v_mfma_f32_16x16x32_bf16 v[80:83], v[174:177], v[198:201], v[80:83]
	v_mfma_f32_16x16x32_bf16 v[68:71], v[166:169], v[206:209], v[68:71]
	v_mfma_f32_16x16x32_bf16 v[60:63], v[174:177], v[206:209], v[60:63]
	v_mfma_f32_16x16x32_bf16 v[116:119], v[170:173], v[186:189], v[116:119]
	v_mfma_f32_16x16x32_bf16 v[112:115], v[178:181], v[186:189], v[112:115]
	v_mfma_f32_16x16x32_bf16 v[100:103], v[170:173], v[194:197], v[100:103]
	v_mfma_f32_16x16x32_bf16 v[96:99], v[178:181], v[194:197], v[96:99]
	v_mfma_f32_16x16x32_bf16 v[84:87], v[170:173], v[202:205], v[84:87]
	v_mfma_f32_16x16x32_bf16 v[80:83], v[178:181], v[202:205], v[80:83]
	v_mfma_f32_16x16x32_bf16 v[68:71], v[170:173], v[210:213], v[68:71]
	v_mfma_f32_16x16x32_bf16 v[60:63], v[178:181], v[210:213], v[60:63]
	s_barrier
	s_add_u32 s56, s54, 0x80
	s_mov_b32 m0, s49
	s_addc_u32 s57, s55, 0
	ds_read_b128 v[182:185], v162 offset:49152
	ds_read_b128 v[186:189], v162 offset:50176
	ds_read_b128 v[190:193], v162 offset:51200
	ds_read_b128 v[194:197], v162 offset:52224
	ds_read_b128 v[198:201], v162 offset:53248
	ds_read_b128 v[202:205], v162 offset:54272
	ds_read_b128 v[206:209], v162 offset:55296
	ds_read_b128 v[210:213], v162 offset:56320
	s_add_u32 s54, s54, 0x80080
	global_load_lds_dwordx4 v156, s[56:57]
	s_mov_b32 m0, s79
	s_addc_u32 s55, s55, 0
	global_load_lds_dwordx4 v158, s[56:57]
	s_mov_b32 m0, s80
	s_nop 0
	global_load_lds_dwordx4 v156, s[54:55]
	s_mov_b32 m0, s83
	s_nop 0
	global_load_lds_dwordx4 v158, s[54:55]
	s_mov_b32 m0, s68
	s_nop 0
	global_load_lds_dwordx4 v153, s[52:53]
	s_mov_b32 m0, s69
	s_nop 0
	global_load_lds_dwordx4 v157, s[52:53]
	s_waitcnt vmcnt(8)
	s_waitcnt lgkmcnt(0)
	s_barrier
	s_waitcnt lgkmcnt(0)
	v_mfma_f32_16x16x32_bf16 v[64:67], v[128:131], v[182:185], v[64:67]
	v_mfma_f32_16x16x32_bf16 v[56:59], v[136:139], v[182:185], v[56:59]
	v_mfma_f32_16x16x32_bf16 v[44:47], v[128:131], v[190:193], v[44:47]
	v_mfma_f32_16x16x32_bf16 v[40:43], v[136:139], v[190:193], v[40:43]
	v_mfma_f32_16x16x32_bf16 v[28:31], v[128:131], v[198:201], v[28:31]
	v_mfma_f32_16x16x32_bf16 v[24:27], v[136:139], v[198:201], v[24:27]
	v_mfma_f32_16x16x32_bf16 v[12:15], v[128:131], v[206:209], v[12:15]
	v_mfma_f32_16x16x32_bf16 v[8:11], v[136:139], v[206:209], v[8:11]
	v_mfma_f32_16x16x32_bf16 v[64:67], v[132:135], v[186:189], v[64:67]
	v_mfma_f32_16x16x32_bf16 v[56:59], v[140:143], v[186:189], v[56:59]
	v_mfma_f32_16x16x32_bf16 v[44:47], v[132:135], v[194:197], v[44:47]
	v_mfma_f32_16x16x32_bf16 v[40:43], v[140:143], v[194:197], v[40:43]
	v_mfma_f32_16x16x32_bf16 v[28:31], v[132:135], v[202:205], v[28:31]
	v_mfma_f32_16x16x32_bf16 v[24:27], v[140:143], v[202:205], v[24:27]
	v_mfma_f32_16x16x32_bf16 v[12:15], v[132:135], v[210:213], v[12:15]
	v_mfma_f32_16x16x32_bf16 v[8:11], v[140:143], v[210:213], v[8:11]
	v_mfma_f32_16x16x32_bf16 v[52:55], v[166:169], v[182:185], v[52:55]
	v_mfma_f32_16x16x32_bf16 v[48:51], v[174:177], v[182:185], v[48:51]
	v_mfma_f32_16x16x32_bf16 v[36:39], v[166:169], v[190:193], v[36:39]
	v_mfma_f32_16x16x32_bf16 v[32:35], v[174:177], v[190:193], v[32:35]
	v_mfma_f32_16x16x32_bf16 v[20:23], v[166:169], v[198:201], v[20:23]
	v_mfma_f32_16x16x32_bf16 v[16:19], v[174:177], v[198:201], v[16:19]
	v_mfma_f32_16x16x32_bf16 v[4:7], v[166:169], v[206:209], v[4:7]
	v_mfma_f32_16x16x32_bf16 v[0:3], v[174:177], v[206:209], v[0:3]
	v_mfma_f32_16x16x32_bf16 v[52:55], v[170:173], v[186:189], v[52:55]
	v_mfma_f32_16x16x32_bf16 v[48:51], v[178:181], v[186:189], v[48:51]
	v_mfma_f32_16x16x32_bf16 v[36:39], v[170:173], v[194:197], v[36:39]
	v_mfma_f32_16x16x32_bf16 v[32:35], v[178:181], v[194:197], v[32:35]
	v_mfma_f32_16x16x32_bf16 v[20:23], v[170:173], v[202:205], v[20:23]
	v_mfma_f32_16x16x32_bf16 v[16:19], v[178:181], v[202:205], v[16:19]
	v_mfma_f32_16x16x32_bf16 v[4:7], v[170:173], v[210:213], v[4:7]
	v_mfma_f32_16x16x32_bf16 v[0:3], v[178:181], v[210:213], v[0:3]
	s_barrier
	s_add_i32 s89, s89, 2
	s_add_u32 s86, s86, 0x100
	s_addc_u32 s88, s88, 0
	s_cmp_gt_u32 s89, 29
	s_mov_b64 s[58:59], s[50:51]
	s_cbranch_scc0 .LBB0_1590
	s_and_b64 vcc, exec, s[4:5]
	s_cbranch_vccz .LBB0_1593
	s_barrier

.LBB0_1701:
	s_add_u32 s20, s56, 0x100
	s_addc_u32 s21, s57, 0
	s_waitcnt lgkmcnt(0)
	s_add_u32 s60, s54, 0x100
	s_addc_u32 s61, s55, 0
	s_barrier
	s_waitcnt lgkmcnt(0)
	v_mfma_f32_16x16x32_bf16 v[32:35], v[16:19], v[68:71], 0
	v_mfma_f32_16x16x32_bf16 v[36:39], v[24:27], v[68:71], 0
	v_mfma_f32_16x16x32_bf16 v[40:43], v[16:19], v[76:79], 0
	v_mfma_f32_16x16x32_bf16 v[44:47], v[24:27], v[76:79], 0
	v_mfma_f32_16x16x32_bf16 v[48:51], v[16:19], v[84:87], 0
	v_mfma_f32_16x16x32_bf16 v[52:55], v[24:27], v[84:87], 0
	v_mfma_f32_16x16x32_bf16 v[56:59], v[16:19], v[88:91], 0
	v_mfma_f32_16x16x32_bf16 v[60:63], v[24:27], v[88:91], 0
	v_mfma_f32_16x16x32_bf16 v[136:139], v[20:23], v[72:75], v[32:35]
	v_mfma_f32_16x16x32_bf16 v[140:143], v[28:31], v[72:75], v[36:39]
	v_mfma_f32_16x16x32_bf16 v[40:43], v[20:23], v[80:83], v[40:43]
	v_mfma_f32_16x16x32_bf16 v[44:47], v[28:31], v[80:83], v[44:47]
	v_mfma_f32_16x16x32_bf16 v[48:51], v[20:23], v[96:99], v[48:51]
	v_mfma_f32_16x16x32_bf16 v[52:55], v[28:31], v[96:99], v[52:55]
	v_mfma_f32_16x16x32_bf16 v[56:59], v[20:23], v[92:95], v[56:59]
	v_mfma_f32_16x16x32_bf16 v[60:63], v[28:31], v[92:95], v[60:63]
	v_mfma_f32_16x16x32_bf16 v[64:67], v[0:3], v[68:71], 0
	v_mfma_f32_16x16x32_bf16 v[68:71], v[8:11], v[68:71], 0
	v_mfma_f32_16x16x32_bf16 v[64:67], v[4:7], v[72:75], v[64:67]
	v_mfma_f32_16x16x32_bf16 v[68:71], v[12:15], v[72:75], v[68:71]
	v_mfma_f32_16x16x32_bf16 v[72:75], v[0:3], v[76:79], 0
	v_mfma_f32_16x16x32_bf16 v[76:79], v[8:11], v[76:79], 0
	v_mfma_f32_16x16x32_bf16 v[72:75], v[4:7], v[80:83], v[72:75]
	v_mfma_f32_16x16x32_bf16 v[76:79], v[12:15], v[80:83], v[76:79]
	v_mfma_f32_16x16x32_bf16 v[80:83], v[0:3], v[84:87], 0
	v_mfma_f32_16x16x32_bf16 v[84:87], v[8:11], v[84:87], 0
	v_mfma_f32_16x16x32_bf16 v[80:83], v[4:7], v[96:99], v[80:83]
	v_mfma_f32_16x16x32_bf16 v[84:87], v[12:15], v[96:99], v[84:87]
	v_mfma_f32_16x16x32_bf16 v[96:99], v[0:3], v[88:91], 0
	v_mfma_f32_16x16x32_bf16 v[88:91], v[8:11], v[88:91], 0
	v_mfma_f32_16x16x32_bf16 v[100:103], v[4:7], v[92:95], v[96:99]
	v_mfma_f32_16x16x32_bf16 v[104:107], v[12:15], v[92:95], v[88:91]
	s_barrier
	s_mov_b32 m0, s65
	ds_read_b128 v[120:123], v206 offset:16384
	ds_read_b128 v[124:127], v206 offset:17408
	ds_read_b128 v[112:115], v206 offset:18432
	ds_read_b128 v[116:119], v206 offset:19456
	ds_read_b128 v[96:99], v206 offset:20480
	ds_read_b128 v[108:111], v206 offset:21504
	ds_read_b128 v[88:91], v206 offset:22528
	ds_read_b128 v[92:95], v206 offset:23552
	s_nop 0
	global_load_lds_dwordx4 v200, s[60:61]
	s_mov_b32 m0, s66
	s_nop 0
	global_load_lds_dwordx4 v202, s[60:61]
	s_add_u32 s60, s54, 0x20100
	s_addc_u32 s61, s55, 0
	s_mov_b32 m0, s67
	s_and_b64 vcc, exec, s[50:51]
	global_load_lds_dwordx4 v200, s[60:61]
	s_mov_b32 m0, s68
	s_nop 0
	global_load_lds_dwordx4 v202, s[60:61]
	s_mov_b32 m0, s27
	s_mov_b64 s[60:61], -1
	global_load_lds_dwordx4 v199, s[20:21]
	s_mov_b32 m0, s69
	s_nop 0
	global_load_lds_dwordx4 v201, s[20:21]
	s_cbranch_vccz .LBB0_1703
	s_waitcnt vmcnt(8)
	s_mov_b64 s[60:61], 0

.LBB0_1705:
	s_ashr_i32 s47, s46, 31
	s_lshl_b64 s[20:21], s[46:47], 18
	s_add_u32 s50, s24, s20
	s_addc_u32 s51, s25, s21
	s_add_u32 s60, s56, 0x180
	s_addc_u32 s61, s57, 0
	s_waitcnt lgkmcnt(0)
	s_and_b64 s[20:21], s[58:59], exec
	s_cselect_b32 s12, s51, s55
	s_cselect_b32 s20, s50, s54
	s_add_u32 s58, s54, 0x180
	s_addc_u32 s59, s55, 0
	s_barrier
	s_waitcnt lgkmcnt(0)
	v_mfma_f32_16x16x32_bf16 v[128:131], v[16:19], v[120:123], 0
	v_mfma_f32_16x16x32_bf16 v[132:135], v[20:23], v[124:127], v[128:131]
	v_mfma_f32_16x16x32_bf16 v[128:131], v[24:27], v[120:123], 0
	v_mfma_f32_16x16x32_bf16 v[144:147], v[28:31], v[124:127], v[128:131]
	v_mfma_f32_16x16x32_bf16 v[128:131], v[16:19], v[112:115], 0
	v_mfma_f32_16x16x32_bf16 v[152:155], v[20:23], v[116:119], v[128:131]
	v_mfma_f32_16x16x32_bf16 v[128:131], v[24:27], v[112:115], 0
	v_mfma_f32_16x16x32_bf16 v[168:171], v[28:31], v[116:119], v[128:131]
	v_mfma_f32_16x16x32_bf16 v[128:131], v[16:19], v[96:99], 0
	v_mfma_f32_16x16x32_bf16 v[16:19], v[16:19], v[88:91], 0
	v_mfma_f32_16x16x32_bf16 v[172:175], v[20:23], v[108:111], v[128:131]
	v_mfma_f32_16x16x32_bf16 v[16:19], v[20:23], v[92:95], v[16:19]
	v_mfma_f32_16x16x32_bf16 v[20:23], v[24:27], v[88:91], 0
	v_mfma_f32_16x16x32_bf16 v[128:131], v[24:27], v[96:99], 0
	v_mfma_f32_16x16x32_bf16 v[20:23], v[28:31], v[92:95], v[20:23]
	v_mfma_f32_16x16x32_bf16 v[176:179], v[28:31], v[108:111], v[128:131]
	v_mfma_f32_16x16x32_bf16 v[24:27], v[0:3], v[120:123], 0
	v_mfma_f32_16x16x32_bf16 v[180:183], v[4:7], v[124:127], v[24:27]
	v_mfma_f32_16x16x32_bf16 v[24:27], v[8:11], v[120:123], 0
	v_mfma_f32_16x16x32_bf16 v[188:191], v[12:15], v[124:127], v[24:27]
	v_mfma_f32_16x16x32_bf16 v[24:27], v[0:3], v[112:115], 0
	v_mfma_f32_16x16x32_bf16 v[192:195], v[4:7], v[116:119], v[24:27]
	v_mfma_f32_16x16x32_bf16 v[24:27], v[8:11], v[112:115], 0
	v_mfma_f32_16x16x32_bf16 v[208:211], v[12:15], v[116:119], v[24:27]
	v_mfma_f32_16x16x32_bf16 v[24:27], v[0:3], v[96:99], 0
	v_mfma_f32_16x16x32_bf16 v[0:3], v[0:3], v[88:91], 0
	v_mfma_f32_16x16x32_bf16 v[212:215], v[4:7], v[108:111], v[24:27]
	v_mfma_f32_16x16x32_bf16 v[24:27], v[8:11], v[96:99], 0
	v_mfma_f32_16x16x32_bf16 v[0:3], v[4:7], v[92:95], v[0:3]
	v_mfma_f32_16x16x32_bf16 v[4:7], v[8:11], v[88:91], 0
	v_mfma_f32_16x16x32_bf16 v[216:219], v[12:15], v[108:111], v[24:27]
	v_mfma_f32_16x16x32_bf16 v[220:223], v[12:15], v[92:95], v[4:7]
	s_barrier
	v_add_u32_e32 v124, s78, v203
	v_add_u32_e32 v125, s83, v203
	s_nop 1
	ds_read_b128 v[4:7], v124
	ds_read_b128 v[8:11], v124 offset:1024
	ds_read_b128 v[224:227], v124 offset:2048
	ds_read_b128 v[228:231], v124 offset:3072
	ds_read_b128 v[232:235], v125
	ds_read_b128 v[236:239], v125 offset:1024
	ds_read_b128 v[240:243], v125 offset:2048
	ds_read_b128 v[244:247], v125 offset:3072
	s_add_u32 s62, s56, 0x70100
	s_addc_u32 s63, s57, 0
	s_mov_b32 m0, s70
	ds_read_b128 v[12:15], v206 offset:32768
	ds_read_b128 v[24:27], v206 offset:33792
	ds_read_b128 v[28:31], v206 offset:34816
	ds_read_b128 v[96:99], v206 offset:35840
	ds_read_b128 v[248:251], v206 offset:36864
	ds_read_b128 v[184:187], v206 offset:37888
	ds_read_b128 v[32:35], v206 offset:38912
	ds_read_b128 v[36:39], v206 offset:39936
	s_nop 0
	global_load_lds_dwordx4 v199, s[62:63]
	s_mov_b32 m0, s71
	s_nop 0
	global_load_lds_dwordx4 v201, s[62:63]
	s_waitcnt vmcnt(8)
	s_waitcnt lgkmcnt(0)
	s_barrier
	s_waitcnt lgkmcnt(0)
	v_mfma_f32_16x16x32_bf16 v[88:91], v[4:7], v[12:15], v[136:139]
	v_mfma_f32_16x16x32_bf16 v[40:43], v[4:7], v[28:31], v[40:43]
	v_mfma_f32_16x16x32_bf16 v[164:167], v[8:11], v[24:27], v[88:91]
	v_mfma_f32_16x16x32_bf16 v[88:91], v[224:227], v[12:15], v[140:143]
	v_mfma_f32_16x16x32_bf16 v[140:143], v[8:11], v[96:99], v[40:43]
	v_mfma_f32_16x16x32_bf16 v[40:43], v[224:227], v[28:31], v[44:47]
	v_mfma_f32_16x16x32_bf16 v[136:139], v[228:231], v[96:99], v[40:43]
	v_mfma_f32_16x16x32_bf16 v[40:43], v[4:7], v[248:251], v[48:51]
	v_mfma_f32_16x16x32_bf16 v[116:119], v[8:11], v[184:187], v[40:43]
	v_mfma_f32_16x16x32_bf16 v[40:43], v[224:227], v[248:251], v[52:55]
	v_mfma_f32_16x16x32_bf16 v[112:115], v[228:231], v[184:187], v[40:43]
	v_mfma_f32_16x16x32_bf16 v[40:43], v[4:7], v[32:35], v[56:59]
	v_mfma_f32_16x16x32_bf16 v[92:95], v[8:11], v[36:39], v[40:43]
	v_mfma_f32_16x16x32_bf16 v[40:43], v[224:227], v[32:35], v[60:63]
	v_mfma_f32_16x16x32_bf16 v[160:163], v[228:231], v[24:27], v[88:91]
	v_mfma_f32_16x16x32_bf16 v[88:91], v[228:231], v[36:39], v[40:43]
	v_mfma_f32_16x16x32_bf16 v[40:43], v[232:235], v[12:15], v[64:67]
	v_mfma_f32_16x16x32_bf16 v[12:15], v[240:243], v[12:15], v[68:71]
	v_mfma_f32_16x16x32_bf16 v[148:151], v[244:247], v[24:27], v[12:15]
	v_mfma_f32_16x16x32_bf16 v[12:15], v[232:235], v[28:31], v[72:75]
	v_mfma_f32_16x16x32_bf16 v[128:131], v[236:239], v[96:99], v[12:15]
	v_mfma_f32_16x16x32_bf16 v[12:15], v[240:243], v[28:31], v[76:79]
	v_mfma_f32_16x16x32_bf16 v[120:123], v[244:247], v[96:99], v[12:15]
	v_mfma_f32_16x16x32_bf16 v[12:15], v[232:235], v[248:251], v[80:83]
	v_mfma_f32_16x16x32_bf16 v[108:111], v[236:239], v[184:187], v[12:15]
	v_mfma_f32_16x16x32_bf16 v[12:15], v[240:243], v[248:251], v[84:87]
	v_mfma_f32_16x16x32_bf16 v[96:99], v[244:247], v[184:187], v[12:15]
	v_mfma_f32_16x16x32_bf16 v[12:15], v[232:235], v[32:35], v[100:103]
	v_mfma_f32_16x16x32_bf16 v[84:87], v[236:239], v[36:39], v[12:15]
	v_mfma_f32_16x16x32_bf16 v[12:15], v[240:243], v[32:35], v[104:107]
	v_mfma_f32_16x16x32_bf16 v[156:159], v[236:239], v[24:27], v[40:43]
	v_mfma_f32_16x16x32_bf16 v[72:75], v[244:247], v[36:39], v[12:15]
	s_barrier
	s_add_i32 s21, s78, s26
	s_mov_b32 m0, s21
	s_add_i32 s45, s21, 0x2000
	ds_read_b128 v[32:35], v206 offset:49152
	ds_read_b128 v[36:39], v206 offset:50176
	ds_read_b128 v[48:51], v206 offset:51200
	ds_read_b128 v[52:55], v206 offset:52224
	ds_read_b128 v[76:79], v206 offset:53248
	ds_read_b128 v[80:83], v206 offset:54272
	ds_read_b128 v[100:103], v206 offset:55296
	ds_read_b128 v[104:107], v206 offset:56320
	s_nop 0
	global_load_lds_dwordx4 v200, s[58:59]
	s_mov_b32 m0, s45
	s_nop 0
	global_load_lds_dwordx4 v202, s[58:59]
	s_add_u32 s58, s54, 0x20180
	s_addc_u32 s59, s55, 0
	s_add_i32 s47, s83, s26
	s_mov_b32 m0, s47
	s_add_i32 s53, s47, 0x2000
	s_nop 0
	global_load_lds_dwordx4 v200, s[58:59]
	s_mov_b32 m0, s53
	s_nop 0
	global_load_lds_dwordx4 v202, s[58:59]
	s_mov_b32 m0, s72
	s_nop 0
	global_load_lds_dwordx4 v199, s[60:61]
	s_mov_b32 m0, s73
	s_nop 0
	global_load_lds_dwordx4 v201, s[60:61]
	s_waitcnt vmcnt(8)
	s_waitcnt lgkmcnt(0)
	s_barrier
	s_waitcnt lgkmcnt(0)
	v_mfma_f32_16x16x32_bf16 v[12:15], v[4:7], v[32:35], v[132:135]
	v_mfma_f32_16x16x32_bf16 v[68:71], v[8:11], v[36:39], v[12:15]
	v_mfma_f32_16x16x32_bf16 v[12:15], v[224:227], v[32:35], v[144:147]
	v_mfma_f32_16x16x32_bf16 v[64:67], v[228:231], v[36:39], v[12:15]
	v_mfma_f32_16x16x32_bf16 v[12:15], v[4:7], v[48:51], v[152:155]
	v_mfma_f32_16x16x32_bf16 v[44:47], v[8:11], v[52:55], v[12:15]
	v_mfma_f32_16x16x32_bf16 v[12:15], v[224:227], v[48:51], v[168:171]
	v_mfma_f32_16x16x32_bf16 v[40:43], v[228:231], v[52:55], v[12:15]
	v_mfma_f32_16x16x32_bf16 v[12:15], v[4:7], v[76:79], v[172:175]
	v_mfma_f32_16x16x32_bf16 v[28:31], v[8:11], v[80:83], v[12:15]
	v_mfma_f32_16x16x32_bf16 v[12:15], v[224:227], v[76:79], v[176:179]
	v_mfma_f32_16x16x32_bf16 v[4:7], v[4:7], v[100:103], v[16:19]
	v_mfma_f32_16x16x32_bf16 v[24:27], v[228:231], v[80:83], v[12:15]
	v_mfma_f32_16x16x32_bf16 v[12:15], v[8:11], v[104:107], v[4:7]
	v_mfma_f32_16x16x32_bf16 v[4:7], v[224:227], v[100:103], v[20:23]
	v_mfma_f32_16x16x32_bf16 v[8:11], v[228:231], v[104:107], v[4:7]
	v_mfma_f32_16x16x32_bf16 v[4:7], v[232:235], v[32:35], v[180:183]
	v_mfma_f32_16x16x32_bf16 v[60:63], v[236:239], v[36:39], v[4:7]
	v_mfma_f32_16x16x32_bf16 v[4:7], v[240:243], v[32:35], v[188:191]
	v_mfma_f32_16x16x32_bf16 v[56:59], v[244:247], v[36:39], v[4:7]
	v_mfma_f32_16x16x32_bf16 v[4:7], v[232:235], v[48:51], v[192:195]
	v_mfma_f32_16x16x32_bf16 v[36:39], v[236:239], v[52:55], v[4:7]
	v_mfma_f32_16x16x32_bf16 v[4:7], v[240:243], v[48:51], v[208:211]
	v_mfma_f32_16x16x32_bf16 v[32:35], v[244:247], v[52:55], v[4:7]
	v_mfma_f32_16x16x32_bf16 v[4:7], v[232:235], v[76:79], v[212:215]
	v_mfma_f32_16x16x32_bf16 v[20:23], v[236:239], v[80:83], v[4:7]
	v_mfma_f32_16x16x32_bf16 v[4:7], v[240:243], v[76:79], v[216:219]
	v_mfma_f32_16x16x32_bf16 v[0:3], v[232:235], v[100:103], v[0:3]
	v_mfma_f32_16x16x32_bf16 v[16:19], v[244:247], v[80:83], v[4:7]
	v_mfma_f32_16x16x32_bf16 v[4:7], v[236:239], v[104:107], v[0:3]
	v_mfma_f32_16x16x32_bf16 v[0:3], v[240:243], v[100:103], v[220:223]
	v_mfma_f32_16x16x32_bf16 v[0:3], v[244:247], v[104:107], v[0:3]
	s_barrier
	s_add_u32 s62, s56, 0x100
	s_addc_u32 s63, s57, 0
	s_add_u32 s79, s54, 0x200
	s_addc_u32 s80, s55, 0
	s_mov_b32 s86, 0
.LBB0_1706:
	s_add_u32 s54, s62, 0x100
	s_addc_u32 s55, s63, 0
	s_cmp_eq_u32 s86, 4
	s_cselect_b32 s60, s48, s54
	s_cselect_b32 s61, s49, s55
	s_cselect_b32 s58, s20, s79
	s_cselect_b32 s59, s12, s80
	s_add_u32 s56, s60, 0x80
	s_addc_u32 s57, s61, 0
	s_add_i32 s92, 0, 0x10000
	s_add_i32 s93, 0, 0x14000
	v_add_u32_e32 v80, s92, v203
	v_add_u32_e32 v126, s93, v203
	ds_read_b128 v[48:51], v80
	ds_read_b128 v[52:55], v80 offset:1024
	ds_read_b128 v[76:79], v80 offset:2048
	ds_read_b128 v[80:83], v80 offset:3072
	ds_read_b128 v[100:103], v126
	ds_read_b128 v[104:107], v126 offset:1024
	ds_read_b128 v[132:135], v126 offset:2048
	ds_read_b128 v[144:147], v126 offset:3072
	s_add_u32 s62, s62, 0x70080
	s_addc_u32 s63, s63, 0
	s_mov_b32 m0, s1
	ds_read_b128 v[152:155], v206
	ds_read_b128 v[168:171], v206 offset:1024
	ds_read_b128 v[172:175], v206 offset:2048
	ds_read_b128 v[176:179], v206 offset:3072
	ds_read_b128 v[180:183], v206 offset:4096
	ds_read_b128 v[184:187], v206 offset:5120
	ds_read_b128 v[188:191], v206 offset:6144
	ds_read_b128 v[192:195], v206 offset:7168
	s_nop 0
	global_load_lds_dwordx4 v199, s[62:63]
	s_mov_b32 m0, s5
	s_nop 0
	global_load_lds_dwordx4 v201, s[62:63]
	s_waitcnt vmcnt(8)
	s_waitcnt lgkmcnt(0)
	s_barrier
	s_waitcnt lgkmcnt(0)
	v_mfma_f32_16x16x32_bf16 v[164:167], v[48:51], v[152:155], v[164:167]
	v_mfma_f32_16x16x32_bf16 v[160:163], v[76:79], v[152:155], v[160:163]
	v_mfma_f32_16x16x32_bf16 v[140:143], v[48:51], v[172:175], v[140:143]
	v_mfma_f32_16x16x32_bf16 v[136:139], v[76:79], v[172:175], v[136:139]
	v_mfma_f32_16x16x32_bf16 v[116:119], v[48:51], v[180:183], v[116:119]
	v_mfma_f32_16x16x32_bf16 v[112:115], v[76:79], v[180:183], v[112:115]
	v_mfma_f32_16x16x32_bf16 v[92:95], v[48:51], v[188:191], v[92:95]
	v_mfma_f32_16x16x32_bf16 v[88:91], v[76:79], v[188:191], v[88:91]
	v_mfma_f32_16x16x32_bf16 v[164:167], v[52:55], v[168:171], v[164:167]
	v_mfma_f32_16x16x32_bf16 v[160:163], v[80:83], v[168:171], v[160:163]
	v_mfma_f32_16x16x32_bf16 v[140:143], v[52:55], v[176:179], v[140:143]
	v_mfma_f32_16x16x32_bf16 v[136:139], v[80:83], v[176:179], v[136:139]
	v_mfma_f32_16x16x32_bf16 v[116:119], v[52:55], v[184:187], v[116:119]
	v_mfma_f32_16x16x32_bf16 v[112:115], v[80:83], v[184:187], v[112:115]
	v_mfma_f32_16x16x32_bf16 v[92:95], v[52:55], v[192:195], v[92:95]
	v_mfma_f32_16x16x32_bf16 v[88:91], v[80:83], v[192:195], v[88:91]
	v_mfma_f32_16x16x32_bf16 v[156:159], v[100:103], v[152:155], v[156:159]
	v_mfma_f32_16x16x32_bf16 v[148:151], v[132:135], v[152:155], v[148:151]
	v_mfma_f32_16x16x32_bf16 v[126:129], v[100:103], v[172:175], v[128:131]
	v_mfma_f32_16x16x32_bf16 v[120:123], v[132:135], v[172:175], v[120:123]
	v_mfma_f32_16x16x32_bf16 v[108:111], v[100:103], v[180:183], v[108:111]
	v_mfma_f32_16x16x32_bf16 v[96:99], v[132:135], v[180:183], v[96:99]
	v_mfma_f32_16x16x32_bf16 v[84:87], v[100:103], v[188:191], v[84:87]
	v_mfma_f32_16x16x32_bf16 v[72:75], v[132:135], v[188:191], v[72:75]
	v_mfma_f32_16x16x32_bf16 v[156:159], v[104:107], v[168:171], v[156:159]
	v_mfma_f32_16x16x32_bf16 v[148:151], v[144:147], v[168:171], v[148:151]
	v_mfma_f32_16x16x32_bf16 v[126:129], v[104:107], v[176:179], v[126:129]
	v_mfma_f32_16x16x32_bf16 v[120:123], v[144:147], v[176:179], v[120:123]
	v_mfma_f32_16x16x32_bf16 v[108:111], v[104:107], v[184:187], v[108:111]
	v_mfma_f32_16x16x32_bf16 v[96:99], v[144:147], v[184:187], v[96:99]
	v_mfma_f32_16x16x32_bf16 v[84:87], v[104:107], v[192:195], v[84:87]
	v_mfma_f32_16x16x32_bf16 v[72:75], v[144:147], v[192:195], v[72:75]
	s_barrier
	s_add_i32 s62, s92, s26
	s_mov_b32 m0, s62
	ds_read_b128 v[152:155], v206 offset:16384
	ds_read_b128 v[168:171], v206 offset:17408
	ds_read_b128 v[172:175], v206 offset:18432
	ds_read_b128 v[176:179], v206 offset:19456
	ds_read_b128 v[180:183], v206 offset:20480
	ds_read_b128 v[184:187], v206 offset:21504
	ds_read_b128 v[188:191], v206 offset:22528
	ds_read_b128 v[192:195], v206 offset:23552
	s_nop 0
	global_load_lds_dwordx4 v200, s[58:59]
	s_add_i32 m0, s62, 0x2000
	s_add_u32 s62, s58, 0x20000
	s_addc_u32 s63, s59, 0
	s_add_i32 s92, s93, s26
	s_nop 0
	global_load_lds_dwordx4 v202, s[58:59]
	s_mov_b32 m0, s92
	s_nop 0
	global_load_lds_dwordx4 v200, s[62:63]
	s_add_i32 m0, s92, 0x2000
	s_nop 0
	global_load_lds_dwordx4 v202, s[62:63]
	s_mov_b32 m0, s27
	s_nop 0
	global_load_lds_dwordx4 v199, s[60:61]
	s_mov_b32 m0, s69
	s_nop 0
	global_load_lds_dwordx4 v201, s[60:61]
	s_waitcnt vmcnt(8)
	s_waitcnt lgkmcnt(0)
	s_barrier
	s_waitcnt lgkmcnt(0)
	v_mfma_f32_16x16x32_bf16 v[68:71], v[48:51], v[152:155], v[68:71]
	v_mfma_f32_16x16x32_bf16 v[64:67], v[76:79], v[152:155], v[64:67]
	v_mfma_f32_16x16x32_bf16 v[44:47], v[48:51], v[172:175], v[44:47]
	v_mfma_f32_16x16x32_bf16 v[40:43], v[76:79], v[172:175], v[40:43]
	v_mfma_f32_16x16x32_bf16 v[28:31], v[48:51], v[180:183], v[28:31]
	v_mfma_f32_16x16x32_bf16 v[24:27], v[76:79], v[180:183], v[24:27]
	v_mfma_f32_16x16x32_bf16 v[12:15], v[48:51], v[188:191], v[12:15]
	v_mfma_f32_16x16x32_bf16 v[8:11], v[76:79], v[188:191], v[8:11]
	v_mfma_f32_16x16x32_bf16 v[68:71], v[52:55], v[168:171], v[68:71]
	v_mfma_f32_16x16x32_bf16 v[64:67], v[80:83], v[168:171], v[64:67]
	v_mfma_f32_16x16x32_bf16 v[44:47], v[52:55], v[176:179], v[44:47]
	v_mfma_f32_16x16x32_bf16 v[40:43], v[80:83], v[176:179], v[40:43]
	v_mfma_f32_16x16x32_bf16 v[28:31], v[52:55], v[184:187], v[28:31]
	v_mfma_f32_16x16x32_bf16 v[24:27], v[80:83], v[184:187], v[24:27]
	v_mfma_f32_16x16x32_bf16 v[12:15], v[52:55], v[192:195], v[12:15]
	v_mfma_f32_16x16x32_bf16 v[8:11], v[80:83], v[192:195], v[8:11]
	v_mfma_f32_16x16x32_bf16 v[36:39], v[100:103], v[172:175], v[36:39]
	v_mfma_f32_16x16x32_bf16 v[32:35], v[132:135], v[172:175], v[32:35]
	v_mfma_f32_16x16x32_bf16 v[20:23], v[100:103], v[180:183], v[20:23]
	v_mfma_f32_16x16x32_bf16 v[16:19], v[132:135], v[180:183], v[16:19]
	v_mfma_f32_16x16x32_bf16 v[4:7], v[100:103], v[188:191], v[4:7]
	v_mfma_f32_16x16x32_bf16 v[0:3], v[132:135], v[188:191], v[0:3]
	v_mfma_f32_16x16x32_bf16 v[48:51], v[100:103], v[152:155], v[60:63]
	v_mfma_f32_16x16x32_bf16 v[52:55], v[132:135], v[152:155], v[56:59]
	v_mfma_f32_16x16x32_bf16 v[36:39], v[104:107], v[176:179], v[36:39]
	v_mfma_f32_16x16x32_bf16 v[32:35], v[144:147], v[176:179], v[32:35]
	v_mfma_f32_16x16x32_bf16 v[20:23], v[104:107], v[184:187], v[20:23]
	v_mfma_f32_16x16x32_bf16 v[16:19], v[144:147], v[184:187], v[16:19]
	v_mfma_f32_16x16x32_bf16 v[4:7], v[104:107], v[192:195], v[4:7]
	v_mfma_f32_16x16x32_bf16 v[0:3], v[144:147], v[192:195], v[0:3]
	v_mfma_f32_16x16x32_bf16 v[48:51], v[104:107], v[168:171], v[48:51]
	v_mfma_f32_16x16x32_bf16 v[52:55], v[144:147], v[168:171], v[52:55]
	s_barrier
	ds_read_b128 v[56:59], v124
	ds_read_b128 v[60:63], v124 offset:1024
	ds_read_b128 v[76:79], v124 offset:2048
	ds_read_b128 v[80:83], v124 offset:3072
	ds_read_b128 v[100:103], v125
	ds_read_b128 v[104:107], v125 offset:1024
	ds_read_b128 v[132:135], v125 offset:2048
	ds_read_b128 v[144:147], v125 offset:3072
	s_add_u32 s60, s60, 0x70000
	s_addc_u32 s61, s61, 0
	s_mov_b32 m0, s70
	ds_read_b128 v[152:155], v206 offset:32768
	ds_read_b128 v[168:171], v206 offset:33792
	ds_read_b128 v[172:175], v206 offset:34816
	ds_read_b128 v[176:179], v206 offset:35840
	ds_read_b128 v[180:183], v206 offset:36864
	ds_read_b128 v[184:187], v206 offset:37888
	ds_read_b128 v[188:191], v206 offset:38912
	ds_read_b128 v[192:195], v206 offset:39936
	s_nop 0
	global_load_lds_dwordx4 v199, s[60:61]
	s_mov_b32 m0, s71
	s_nop 0
	global_load_lds_dwordx4 v201, s[60:61]
	s_waitcnt vmcnt(8)
	s_waitcnt lgkmcnt(0)
	s_barrier
	s_waitcnt lgkmcnt(0)
	v_mfma_f32_16x16x32_bf16 v[164:167], v[56:59], v[152:155], v[164:167]
	v_mfma_f32_16x16x32_bf16 v[160:163], v[76:79], v[152:155], v[160:163]
	v_mfma_f32_16x16x32_bf16 v[140:143], v[56:59], v[172:175], v[140:143]
	v_mfma_f32_16x16x32_bf16 v[136:139], v[76:79], v[172:175], v[136:139]
	v_mfma_f32_16x16x32_bf16 v[116:119], v[56:59], v[180:183], v[116:119]
	v_mfma_f32_16x16x32_bf16 v[112:115], v[76:79], v[180:183], v[112:115]
	v_mfma_f32_16x16x32_bf16 v[92:95], v[56:59], v[188:191], v[92:95]
	v_mfma_f32_16x16x32_bf16 v[88:91], v[76:79], v[188:191], v[88:91]
	v_mfma_f32_16x16x32_bf16 v[164:167], v[60:63], v[168:171], v[164:167]
	v_mfma_f32_16x16x32_bf16 v[160:163], v[80:83], v[168:171], v[160:163]
	v_mfma_f32_16x16x32_bf16 v[140:143], v[60:63], v[176:179], v[140:143]
	v_mfma_f32_16x16x32_bf16 v[136:139], v[80:83], v[176:179], v[136:139]
	v_mfma_f32_16x16x32_bf16 v[116:119], v[60:63], v[184:187], v[116:119]
	v_mfma_f32_16x16x32_bf16 v[112:115], v[80:83], v[184:187], v[112:115]
	v_mfma_f32_16x16x32_bf16 v[92:95], v[60:63], v[192:195], v[92:95]
	v_mfma_f32_16x16x32_bf16 v[88:91], v[80:83], v[192:195], v[88:91]
	v_mfma_f32_16x16x32_bf16 v[156:159], v[100:103], v[152:155], v[156:159]
	v_mfma_f32_16x16x32_bf16 v[148:151], v[132:135], v[152:155], v[148:151]
	v_mfma_f32_16x16x32_bf16 v[126:129], v[100:103], v[172:175], v[126:129]
	v_mfma_f32_16x16x32_bf16 v[120:123], v[132:135], v[172:175], v[120:123]
	v_mfma_f32_16x16x32_bf16 v[108:111], v[100:103], v[180:183], v[108:111]
	v_mfma_f32_16x16x32_bf16 v[96:99], v[132:135], v[180:183], v[96:99]
	v_mfma_f32_16x16x32_bf16 v[84:87], v[100:103], v[188:191], v[84:87]
	v_mfma_f32_16x16x32_bf16 v[72:75], v[132:135], v[188:191], v[72:75]
	v_mfma_f32_16x16x32_bf16 v[156:159], v[104:107], v[168:171], v[156:159]
	v_mfma_f32_16x16x32_bf16 v[148:151], v[144:147], v[168:171], v[148:151]
	v_mfma_f32_16x16x32_bf16 v[128:131], v[104:107], v[176:179], v[126:129]
	v_mfma_f32_16x16x32_bf16 v[120:123], v[144:147], v[176:179], v[120:123]
	v_mfma_f32_16x16x32_bf16 v[108:111], v[104:107], v[184:187], v[108:111]
	v_mfma_f32_16x16x32_bf16 v[96:99], v[144:147], v[184:187], v[96:99]
	v_mfma_f32_16x16x32_bf16 v[84:87], v[104:107], v[192:195], v[84:87]
	v_mfma_f32_16x16x32_bf16 v[72:75], v[144:147], v[192:195], v[72:75]
	s_barrier
	s_add_u32 s60, s58, 0x80
	s_mov_b32 m0, s21
	s_addc_u32 s61, s59, 0
	ds_read_b128 v[152:155], v206 offset:49152
	ds_read_b128 v[168:171], v206 offset:50176
	ds_read_b128 v[172:175], v206 offset:51200
	ds_read_b128 v[176:179], v206 offset:52224
	ds_read_b128 v[180:183], v206 offset:53248
	ds_read_b128 v[184:187], v206 offset:54272
	ds_read_b128 v[188:191], v206 offset:55296
	ds_read_b128 v[192:195], v206 offset:56320
	s_add_u32 s58, s58, 0x20080
	global_load_lds_dwordx4 v200, s[60:61]
	s_mov_b32 m0, s45
	s_addc_u32 s59, s59, 0
	global_load_lds_dwordx4 v202, s[60:61]
	s_mov_b32 m0, s47
	s_nop 0
	global_load_lds_dwordx4 v200, s[58:59]
	s_mov_b32 m0, s53
	s_nop 0
	global_load_lds_dwordx4 v202, s[58:59]
	s_mov_b32 m0, s72
	s_nop 0
	global_load_lds_dwordx4 v199, s[56:57]
	s_mov_b32 m0, s73
	s_nop 0
	global_load_lds_dwordx4 v201, s[56:57]
	s_waitcnt vmcnt(8)
	s_waitcnt lgkmcnt(0)
	s_barrier
	s_waitcnt lgkmcnt(0)
	v_mfma_f32_16x16x32_bf16 v[68:71], v[56:59], v[152:155], v[68:71]
	v_mfma_f32_16x16x32_bf16 v[64:67], v[76:79], v[152:155], v[64:67]
	v_mfma_f32_16x16x32_bf16 v[44:47], v[56:59], v[172:175], v[44:47]
	v_mfma_f32_16x16x32_bf16 v[40:43], v[76:79], v[172:175], v[40:43]
	v_mfma_f32_16x16x32_bf16 v[28:31], v[56:59], v[180:183], v[28:31]
	v_mfma_f32_16x16x32_bf16 v[24:27], v[76:79], v[180:183], v[24:27]
	v_mfma_f32_16x16x32_bf16 v[12:15], v[56:59], v[188:191], v[12:15]
	v_mfma_f32_16x16x32_bf16 v[8:11], v[76:79], v[188:191], v[8:11]
	v_mfma_f32_16x16x32_bf16 v[68:71], v[60:63], v[168:171], v[68:71]
	v_mfma_f32_16x16x32_bf16 v[64:67], v[80:83], v[168:171], v[64:67]
	v_mfma_f32_16x16x32_bf16 v[44:47], v[60:63], v[176:179], v[44:47]
	v_mfma_f32_16x16x32_bf16 v[40:43], v[80:83], v[176:179], v[40:43]
	v_mfma_f32_16x16x32_bf16 v[28:31], v[60:63], v[184:187], v[28:31]
	v_mfma_f32_16x16x32_bf16 v[24:27], v[80:83], v[184:187], v[24:27]
	v_mfma_f32_16x16x32_bf16 v[12:15], v[60:63], v[192:195], v[12:15]
	v_mfma_f32_16x16x32_bf16 v[8:11], v[80:83], v[192:195], v[8:11]
	v_mfma_f32_16x16x32_bf16 v[48:51], v[100:103], v[152:155], v[48:51]
	v_mfma_f32_16x16x32_bf16 v[60:63], v[104:107], v[168:171], v[48:51]
	v_mfma_f32_16x16x32_bf16 v[48:51], v[132:135], v[152:155], v[52:55]
	v_mfma_f32_16x16x32_bf16 v[36:39], v[100:103], v[172:175], v[36:39]
	v_mfma_f32_16x16x32_bf16 v[32:35], v[132:135], v[172:175], v[32:35]
	v_mfma_f32_16x16x32_bf16 v[20:23], v[100:103], v[180:183], v[20:23]
	v_mfma_f32_16x16x32_bf16 v[16:19], v[132:135], v[180:183], v[16:19]
	v_mfma_f32_16x16x32_bf16 v[4:7], v[100:103], v[188:191], v[4:7]
	v_mfma_f32_16x16x32_bf16 v[0:3], v[132:135], v[188:191], v[0:3]
	v_mfma_f32_16x16x32_bf16 v[56:59], v[144:147], v[168:171], v[48:51]
	v_mfma_f32_16x16x32_bf16 v[36:39], v[104:107], v[176:179], v[36:39]
	v_mfma_f32_16x16x32_bf16 v[32:35], v[144:147], v[176:179], v[32:35]
	v_mfma_f32_16x16x32_bf16 v[20:23], v[104:107], v[184:187], v[20:23]
	v_mfma_f32_16x16x32_bf16 v[16:19], v[144:147], v[184:187], v[16:19]
	v_mfma_f32_16x16x32_bf16 v[4:7], v[104:107], v[192:195], v[4:7]
	v_mfma_f32_16x16x32_bf16 v[0:3], v[144:147], v[192:195], v[0:3]
	s_barrier
	s_add_i32 s86, s86, 2
	s_add_u32 s79, s79, 0x100
	s_addc_u32 s80, s80, 0
	s_cmp_gt_u32 s86, 5
	s_mov_b64 s[62:63], s[54:55]
	s_cbranch_scc0 .LBB0_1706
	s_and_b64 vcc, exec, s[42:43]
	s_cbranch_vccz .LBB0_1709
	s_barrier

.LBB0_1772:
	s_add_u32 s20, s42, 0x100
	s_addc_u32 s21, s43, 0
	s_waitcnt lgkmcnt(0)
	s_add_u32 s60, s6, 0x100
	s_addc_u32 s61, s7, 0
	s_barrier
	s_waitcnt lgkmcnt(0)
	v_mfma_f32_16x16x32_bf16 v[32:35], v[16:19], v[72:75], 0
	v_mfma_f32_16x16x32_bf16 v[36:39], v[24:27], v[72:75], 0
	v_mfma_f32_16x16x32_bf16 v[40:43], v[16:19], v[80:83], 0
	v_mfma_f32_16x16x32_bf16 v[44:47], v[24:27], v[80:83], 0
	v_mfma_f32_16x16x32_bf16 v[48:51], v[16:19], v[92:95], 0
	v_mfma_f32_16x16x32_bf16 v[52:55], v[24:27], v[92:95], 0
	v_mfma_f32_16x16x32_bf16 v[56:59], v[16:19], v[60:63], 0
	v_mfma_f32_16x16x32_bf16 v[64:67], v[24:27], v[60:63], 0
	v_mfma_f32_16x16x32_bf16 v[32:35], v[20:23], v[76:79], v[32:35]
	v_mfma_f32_16x16x32_bf16 v[36:39], v[28:31], v[76:79], v[36:39]
	v_mfma_f32_16x16x32_bf16 v[40:43], v[20:23], v[84:87], v[40:43]
	v_mfma_f32_16x16x32_bf16 v[44:47], v[28:31], v[84:87], v[44:47]
	v_mfma_f32_16x16x32_bf16 v[48:51], v[20:23], v[96:99], v[48:51]
	v_mfma_f32_16x16x32_bf16 v[52:55], v[28:31], v[96:99], v[52:55]
	v_mfma_f32_16x16x32_bf16 v[56:59], v[20:23], v[88:91], v[56:59]
	v_mfma_f32_16x16x32_bf16 v[64:67], v[28:31], v[88:91], v[64:67]
	v_mfma_f32_16x16x32_bf16 v[68:71], v[0:3], v[72:75], 0
	v_mfma_f32_16x16x32_bf16 v[72:75], v[8:11], v[72:75], 0
	v_mfma_f32_16x16x32_bf16 v[68:71], v[4:7], v[76:79], v[68:71]
	v_mfma_f32_16x16x32_bf16 v[72:75], v[12:15], v[76:79], v[72:75]
	v_mfma_f32_16x16x32_bf16 v[76:79], v[0:3], v[80:83], 0
	v_mfma_f32_16x16x32_bf16 v[80:83], v[8:11], v[80:83], 0
	v_mfma_f32_16x16x32_bf16 v[76:79], v[4:7], v[84:87], v[76:79]
	v_mfma_f32_16x16x32_bf16 v[80:83], v[12:15], v[84:87], v[80:83]
	v_mfma_f32_16x16x32_bf16 v[84:87], v[0:3], v[92:95], 0
	v_mfma_f32_16x16x32_bf16 v[92:95], v[8:11], v[92:95], 0
	v_mfma_f32_16x16x32_bf16 v[128:131], v[12:15], v[96:99], v[92:95]
	v_mfma_f32_16x16x32_bf16 v[92:95], v[0:3], v[60:63], 0
	v_mfma_f32_16x16x32_bf16 v[60:63], v[8:11], v[60:63], 0
	v_mfma_f32_16x16x32_bf16 v[84:87], v[4:7], v[96:99], v[84:87]
	v_mfma_f32_16x16x32_bf16 v[132:135], v[4:7], v[88:91], v[92:95]
	v_mfma_f32_16x16x32_bf16 v[136:139], v[12:15], v[88:91], v[60:63]
	s_barrier
	s_mov_b32 m0, s5
	ds_read_b128 v[108:111], v151 offset:16384
	ds_read_b128 v[112:115], v151 offset:17408
	ds_read_b128 v[100:103], v151 offset:18432
	ds_read_b128 v[104:107], v151 offset:19456
	ds_read_b128 v[92:95], v151 offset:20480
	ds_read_b128 v[96:99], v151 offset:21504
	ds_read_b128 v[60:63], v151 offset:22528
	ds_read_b128 v[88:91], v151 offset:23552
	s_nop 0
	global_load_lds_dwordx4 v145, s[60:61]
	s_mov_b32 m0, s70
	s_nop 0
	global_load_lds_dwordx4 v147, s[60:61]
	s_add_u32 s60, s6, 0x20100
	s_addc_u32 s61, s7, 0
	s_mov_b32 m0, s71
	s_and_b64 vcc, exec, s[58:59]
	global_load_lds_dwordx4 v145, s[60:61]
	s_mov_b32 m0, s72
	s_nop 0
	global_load_lds_dwordx4 v147, s[60:61]
	s_mov_b32 m0, s3
	s_mov_b64 s[60:61], -1
	global_load_lds_dwordx4 v144, s[20:21]
	s_mov_b32 m0, s73
	s_nop 0
	global_load_lds_dwordx4 v146, s[20:21]
	s_cbranch_vccz .LBB0_1774
	s_waitcnt vmcnt(8)
	s_mov_b64 s[60:61], 0

.LBB0_1776:
	s_ashr_i32 s51, s50, 31
	s_lshl_b64 s[20:21], s[50:51], 18
	s_add_u32 s58, s26, s20
	s_addc_u32 s59, s27, s21
	s_add_u32 s60, s42, 0x180
	s_addc_u32 s61, s43, 0
	s_waitcnt lgkmcnt(0)
	s_and_b64 s[20:21], s[52:53], exec
	s_cselect_b32 s20, s59, s7
	s_cselect_b32 s21, s58, s6
	s_add_u32 s62, s6, 0x180
	s_addc_u32 s63, s7, 0
	s_barrier
	s_waitcnt lgkmcnt(0)
	v_mfma_f32_16x16x32_bf16 v[116:119], v[16:19], v[108:111], 0
	v_mfma_f32_16x16x32_bf16 v[154:157], v[20:23], v[112:115], v[116:119]
	v_mfma_f32_16x16x32_bf16 v[116:119], v[24:27], v[108:111], 0
	v_mfma_f32_16x16x32_bf16 v[158:161], v[28:31], v[112:115], v[116:119]
	v_mfma_f32_16x16x32_bf16 v[116:119], v[16:19], v[100:103], 0
	v_mfma_f32_16x16x32_bf16 v[162:165], v[20:23], v[104:107], v[116:119]
	v_mfma_f32_16x16x32_bf16 v[116:119], v[24:27], v[100:103], 0
	v_mfma_f32_16x16x32_bf16 v[166:169], v[28:31], v[104:107], v[116:119]
	v_mfma_f32_16x16x32_bf16 v[116:119], v[16:19], v[92:95], 0
	v_mfma_f32_16x16x32_bf16 v[16:19], v[16:19], v[60:63], 0
	v_mfma_f32_16x16x32_bf16 v[170:173], v[20:23], v[96:99], v[116:119]
	v_mfma_f32_16x16x32_bf16 v[16:19], v[20:23], v[88:91], v[16:19]
	v_mfma_f32_16x16x32_bf16 v[20:23], v[24:27], v[60:63], 0
	v_mfma_f32_16x16x32_bf16 v[116:119], v[24:27], v[92:95], 0
	v_mfma_f32_16x16x32_bf16 v[20:23], v[28:31], v[88:91], v[20:23]
	v_mfma_f32_16x16x32_bf16 v[174:177], v[28:31], v[96:99], v[116:119]
	v_mfma_f32_16x16x32_bf16 v[24:27], v[0:3], v[108:111], 0
	v_mfma_f32_16x16x32_bf16 v[178:181], v[4:7], v[112:115], v[24:27]
	v_mfma_f32_16x16x32_bf16 v[24:27], v[8:11], v[108:111], 0
	v_mfma_f32_16x16x32_bf16 v[182:185], v[12:15], v[112:115], v[24:27]
	v_mfma_f32_16x16x32_bf16 v[24:27], v[0:3], v[100:103], 0
	v_mfma_f32_16x16x32_bf16 v[186:189], v[4:7], v[104:107], v[24:27]
	v_mfma_f32_16x16x32_bf16 v[24:27], v[8:11], v[100:103], 0
	v_mfma_f32_16x16x32_bf16 v[190:193], v[12:15], v[104:107], v[24:27]
	v_mfma_f32_16x16x32_bf16 v[24:27], v[0:3], v[92:95], 0
	v_mfma_f32_16x16x32_bf16 v[0:3], v[0:3], v[60:63], 0
	v_mfma_f32_16x16x32_bf16 v[194:197], v[4:7], v[96:99], v[24:27]
	v_mfma_f32_16x16x32_bf16 v[24:27], v[8:11], v[92:95], 0
	v_mfma_f32_16x16x32_bf16 v[0:3], v[4:7], v[88:91], v[0:3]
	v_mfma_f32_16x16x32_bf16 v[4:7], v[8:11], v[60:63], 0
	v_mfma_f32_16x16x32_bf16 v[198:201], v[12:15], v[96:99], v[24:27]
	v_mfma_f32_16x16x32_bf16 v[202:205], v[12:15], v[88:91], v[4:7]
	s_barrier
	v_add_u32_e32 v142, s88, v148
	v_add_u32_e32 v153, s89, v148
	s_nop 1
	ds_read_b128 v[4:7], v142
	ds_read_b128 v[8:11], v142 offset:1024
	ds_read_b128 v[206:209], v142 offset:2048
	ds_read_b128 v[210:213], v142 offset:3072
	ds_read_b128 v[214:217], v153
	ds_read_b128 v[218:221], v153 offset:1024
	ds_read_b128 v[222:225], v153 offset:2048
	ds_read_b128 v[226:229], v153 offset:3072
	s_add_u32 s64, s42, 0x70100
	s_addc_u32 s65, s43, 0
	s_mov_b32 m0, s74
	ds_read_b128 v[12:15], v151 offset:32768
	ds_read_b128 v[24:27], v151 offset:33792
	ds_read_b128 v[28:31], v151 offset:34816
	ds_read_b128 v[96:99], v151 offset:35840
	ds_read_b128 v[230:233], v151 offset:36864
	ds_read_b128 v[234:237], v151 offset:37888
	ds_read_b128 v[238:241], v151 offset:38912
	ds_read_b128 v[242:245], v151 offset:39936
	s_nop 0
	global_load_lds_dwordx4 v144, s[64:65]
	s_mov_b32 m0, s75
	s_nop 0
	global_load_lds_dwordx4 v146, s[64:65]
	s_waitcnt vmcnt(8)
	s_waitcnt lgkmcnt(0)
	s_barrier
	s_waitcnt lgkmcnt(0)
	v_mfma_f32_16x16x32_bf16 v[32:35], v[4:7], v[12:15], v[32:35]
	v_mfma_f32_16x16x32_bf16 v[124:127], v[8:11], v[24:27], v[32:35]
	v_mfma_f32_16x16x32_bf16 v[32:35], v[206:209], v[12:15], v[36:39]
	v_mfma_f32_16x16x32_bf16 v[120:123], v[210:213], v[24:27], v[32:35]
	v_mfma_f32_16x16x32_bf16 v[32:35], v[4:7], v[28:31], v[40:43]
	v_mfma_f32_16x16x32_bf16 v[108:111], v[8:11], v[96:99], v[32:35]
	v_mfma_f32_16x16x32_bf16 v[32:35], v[206:209], v[28:31], v[44:47]
	v_mfma_f32_16x16x32_bf16 v[104:107], v[210:213], v[96:99], v[32:35]
	v_mfma_f32_16x16x32_bf16 v[32:35], v[4:7], v[230:233], v[48:51]
	v_mfma_f32_16x16x32_bf16 v[92:95], v[8:11], v[234:237], v[32:35]
	v_mfma_f32_16x16x32_bf16 v[32:35], v[206:209], v[230:233], v[52:55]
	v_mfma_f32_16x16x32_bf16 v[88:91], v[210:213], v[234:237], v[32:35]
	v_mfma_f32_16x16x32_bf16 v[32:35], v[4:7], v[238:241], v[56:59]
	v_mfma_f32_16x16x32_bf16 v[60:63], v[8:11], v[242:245], v[32:35]
	v_mfma_f32_16x16x32_bf16 v[32:35], v[206:209], v[238:241], v[64:67]
	v_mfma_f32_16x16x32_bf16 v[56:59], v[210:213], v[242:245], v[32:35]
	v_mfma_f32_16x16x32_bf16 v[32:35], v[214:217], v[12:15], v[68:71]
	v_mfma_f32_16x16x32_bf16 v[12:15], v[222:225], v[12:15], v[72:75]
	v_mfma_f32_16x16x32_bf16 v[112:115], v[226:229], v[24:27], v[12:15]
	v_mfma_f32_16x16x32_bf16 v[12:15], v[214:217], v[28:31], v[76:79]
	v_mfma_f32_16x16x32_bf16 v[100:103], v[218:221], v[96:99], v[12:15]
	v_mfma_f32_16x16x32_bf16 v[12:15], v[222:225], v[28:31], v[80:83]
	v_mfma_f32_16x16x32_bf16 v[96:99], v[226:229], v[96:99], v[12:15]
	v_mfma_f32_16x16x32_bf16 v[12:15], v[214:217], v[230:233], v[84:87]
	v_mfma_f32_16x16x32_bf16 v[84:87], v[218:221], v[234:237], v[12:15]
	v_mfma_f32_16x16x32_bf16 v[12:15], v[222:225], v[230:233], v[128:131]
	v_mfma_f32_16x16x32_bf16 v[80:83], v[226:229], v[234:237], v[12:15]
	v_mfma_f32_16x16x32_bf16 v[12:15], v[214:217], v[238:241], v[132:135]
	v_mfma_f32_16x16x32_bf16 v[52:55], v[218:221], v[242:245], v[12:15]
	v_mfma_f32_16x16x32_bf16 v[12:15], v[222:225], v[238:241], v[136:139]
	v_mfma_f32_16x16x32_bf16 v[116:119], v[218:221], v[24:27], v[32:35]
	v_mfma_f32_16x16x32_bf16 v[48:51], v[226:229], v[242:245], v[12:15]
	s_barrier
	s_add_i32 s49, s88, s68
	s_mov_b32 m0, s49
	s_add_i32 s51, s49, 0x2000
	ds_read_b128 v[32:35], v151 offset:49152
	ds_read_b128 v[36:39], v151 offset:50176
	ds_read_b128 v[128:131], v151 offset:51200
	ds_read_b128 v[132:135], v151 offset:52224
	ds_read_b128 v[136:139], v151 offset:53248
	ds_read_b128 v[230:233], v151 offset:54272
	ds_read_b128 v[234:237], v151 offset:55296
	ds_read_b128 v[238:241], v151 offset:56320
	s_nop 0
	global_load_lds_dwordx4 v145, s[62:63]
	s_mov_b32 m0, s51
	s_nop 0
	global_load_lds_dwordx4 v147, s[62:63]
	s_add_u32 s62, s6, 0x20180
	s_addc_u32 s63, s7, 0
	s_add_i32 s79, s89, s68
	s_mov_b32 m0, s79
	s_add_i32 s86, s79, 0x2000
	s_nop 0
	global_load_lds_dwordx4 v145, s[62:63]
	s_mov_b32 m0, s86
	s_nop 0
	global_load_lds_dwordx4 v147, s[62:63]
	s_mov_b32 m0, s76
	s_nop 0
	global_load_lds_dwordx4 v144, s[60:61]
	s_mov_b32 m0, s77
	s_nop 0
	global_load_lds_dwordx4 v146, s[60:61]
	s_waitcnt vmcnt(8)
	s_waitcnt lgkmcnt(0)
	s_barrier
	s_waitcnt lgkmcnt(0)
	v_mfma_f32_16x16x32_bf16 v[12:15], v[4:7], v[32:35], v[154:157]
	v_mfma_f32_16x16x32_bf16 v[76:79], v[8:11], v[36:39], v[12:15]
	v_mfma_f32_16x16x32_bf16 v[12:15], v[206:209], v[32:35], v[158:161]
	v_mfma_f32_16x16x32_bf16 v[72:75], v[210:213], v[36:39], v[12:15]
	v_mfma_f32_16x16x32_bf16 v[12:15], v[4:7], v[128:131], v[162:165]
	v_mfma_f32_16x16x32_bf16 v[44:47], v[8:11], v[132:135], v[12:15]
	v_mfma_f32_16x16x32_bf16 v[12:15], v[206:209], v[128:131], v[166:169]
	v_mfma_f32_16x16x32_bf16 v[40:43], v[210:213], v[132:135], v[12:15]
	v_mfma_f32_16x16x32_bf16 v[12:15], v[4:7], v[136:139], v[170:173]
	v_mfma_f32_16x16x32_bf16 v[28:31], v[8:11], v[230:233], v[12:15]
	v_mfma_f32_16x16x32_bf16 v[12:15], v[206:209], v[136:139], v[174:177]
	v_mfma_f32_16x16x32_bf16 v[4:7], v[4:7], v[234:237], v[16:19]
	v_mfma_f32_16x16x32_bf16 v[24:27], v[210:213], v[230:233], v[12:15]
	v_mfma_f32_16x16x32_bf16 v[12:15], v[8:11], v[238:241], v[4:7]
	v_mfma_f32_16x16x32_bf16 v[4:7], v[206:209], v[234:237], v[20:23]
	v_mfma_f32_16x16x32_bf16 v[8:11], v[210:213], v[238:241], v[4:7]
	v_mfma_f32_16x16x32_bf16 v[4:7], v[214:217], v[32:35], v[178:181]
	v_mfma_f32_16x16x32_bf16 v[68:71], v[218:221], v[36:39], v[4:7]
	v_mfma_f32_16x16x32_bf16 v[4:7], v[222:225], v[32:35], v[182:185]
	v_mfma_f32_16x16x32_bf16 v[64:67], v[226:229], v[36:39], v[4:7]
	v_mfma_f32_16x16x32_bf16 v[4:7], v[214:217], v[128:131], v[186:189]
	v_mfma_f32_16x16x32_bf16 v[36:39], v[218:221], v[132:135], v[4:7]
	v_mfma_f32_16x16x32_bf16 v[4:7], v[222:225], v[128:131], v[190:193]
	v_mfma_f32_16x16x32_bf16 v[32:35], v[226:229], v[132:135], v[4:7]
	v_mfma_f32_16x16x32_bf16 v[4:7], v[214:217], v[136:139], v[194:197]
	v_mfma_f32_16x16x32_bf16 v[20:23], v[218:221], v[230:233], v[4:7]
	v_mfma_f32_16x16x32_bf16 v[4:7], v[222:225], v[136:139], v[198:201]
	v_mfma_f32_16x16x32_bf16 v[0:3], v[214:217], v[234:237], v[0:3]
	v_mfma_f32_16x16x32_bf16 v[16:19], v[226:229], v[230:233], v[4:7]
	v_mfma_f32_16x16x32_bf16 v[4:7], v[218:221], v[238:241], v[0:3]
	v_mfma_f32_16x16x32_bf16 v[0:3], v[222:225], v[234:237], v[202:205]
	v_mfma_f32_16x16x32_bf16 v[0:3], v[226:229], v[238:241], v[0:3]
	s_barrier
	s_mov_b32 s93, 0
	s_mov_b64 s[60:61], 0
.LBB0_1777:
	s_add_u32 s94, s42, s60
	s_addc_u32 s95, s43, s61
	s_add_u32 s62, s94, 0x200
	s_addc_u32 s63, s95, 0
	s_add_u32 s64, s6, s60
	s_addc_u32 s65, s7, s61
	s_add_u32 s64, s64, 0x200
	s_addc_u32 s65, s65, 0
	s_cmp_eq_u32 s93, 4
	s_cselect_b32 s66, s56, s62
	s_cselect_b32 s67, s57, s63
	s_cselect_b32 s64, s21, s64
	s_cselect_b32 s65, s20, s65
	s_add_u32 s62, s66, 0x80
	s_addc_u32 s63, s67, 0
	s_add_i32 s96, 0, 0x10000
	s_add_i32 s97, 0, 0x14000
	v_add_u32_e32 v154, s96, v148
	v_add_u32_e32 v170, s97, v148
	ds_read_b128 v[128:131], v154
	ds_read_b128 v[132:135], v154 offset:1024
	ds_read_b128 v[136:139], v154 offset:2048
	ds_read_b128 v[154:157], v154 offset:3072
	ds_read_b128 v[158:161], v170
	ds_read_b128 v[162:165], v170 offset:1024
	ds_read_b128 v[166:169], v170 offset:2048
	ds_read_b128 v[170:173], v170 offset:3072
	s_add_u32 s94, s94, 0x70180
	s_addc_u32 s95, s95, 0
	s_mov_b32 m0, s1
	ds_read_b128 v[174:177], v151
	ds_read_b128 v[178:181], v151 offset:1024
	ds_read_b128 v[182:185], v151 offset:2048
	ds_read_b128 v[186:189], v151 offset:3072
	ds_read_b128 v[190:193], v151 offset:4096
	ds_read_b128 v[194:197], v151 offset:5120
	ds_read_b128 v[198:201], v151 offset:6144
	ds_read_b128 v[202:205], v151 offset:7168
	s_nop 0
	global_load_lds_dwordx4 v144, s[94:95]
	s_mov_b32 m0, s12
	s_nop 0
	global_load_lds_dwordx4 v146, s[94:95]
	s_waitcnt vmcnt(8)
	s_waitcnt lgkmcnt(0)
	s_barrier
	s_waitcnt lgkmcnt(0)
	v_mfma_f32_16x16x32_bf16 v[124:127], v[128:131], v[174:177], v[124:127]
	v_mfma_f32_16x16x32_bf16 v[120:123], v[136:139], v[174:177], v[120:123]
	v_mfma_f32_16x16x32_bf16 v[108:111], v[128:131], v[182:185], v[108:111]
	v_mfma_f32_16x16x32_bf16 v[104:107], v[136:139], v[182:185], v[104:107]
	v_mfma_f32_16x16x32_bf16 v[92:95], v[128:131], v[190:193], v[92:95]
	v_mfma_f32_16x16x32_bf16 v[88:91], v[136:139], v[190:193], v[88:91]
	v_mfma_f32_16x16x32_bf16 v[60:63], v[128:131], v[198:201], v[60:63]
	v_mfma_f32_16x16x32_bf16 v[56:59], v[136:139], v[198:201], v[56:59]
	v_mfma_f32_16x16x32_bf16 v[124:127], v[132:135], v[178:181], v[124:127]
	v_mfma_f32_16x16x32_bf16 v[120:123], v[154:157], v[178:181], v[120:123]
	v_mfma_f32_16x16x32_bf16 v[108:111], v[132:135], v[186:189], v[108:111]
	v_mfma_f32_16x16x32_bf16 v[104:107], v[154:157], v[186:189], v[104:107]
	v_mfma_f32_16x16x32_bf16 v[92:95], v[132:135], v[194:197], v[92:95]
	v_mfma_f32_16x16x32_bf16 v[88:91], v[154:157], v[194:197], v[88:91]
	v_mfma_f32_16x16x32_bf16 v[60:63], v[132:135], v[202:205], v[60:63]
	v_mfma_f32_16x16x32_bf16 v[56:59], v[154:157], v[202:205], v[56:59]
	v_mfma_f32_16x16x32_bf16 v[116:119], v[158:161], v[174:177], v[116:119]
	v_mfma_f32_16x16x32_bf16 v[112:115], v[166:169], v[174:177], v[112:115]
	v_mfma_f32_16x16x32_bf16 v[100:103], v[158:161], v[182:185], v[100:103]
	v_mfma_f32_16x16x32_bf16 v[96:99], v[166:169], v[182:185], v[96:99]
	v_mfma_f32_16x16x32_bf16 v[84:87], v[158:161], v[190:193], v[84:87]
	v_mfma_f32_16x16x32_bf16 v[80:83], v[166:169], v[190:193], v[80:83]
	v_mfma_f32_16x16x32_bf16 v[52:55], v[158:161], v[198:201], v[52:55]
	v_mfma_f32_16x16x32_bf16 v[48:51], v[166:169], v[198:201], v[48:51]
	v_mfma_f32_16x16x32_bf16 v[116:119], v[162:165], v[178:181], v[116:119]
	v_mfma_f32_16x16x32_bf16 v[112:115], v[170:173], v[178:181], v[112:115]
	v_mfma_f32_16x16x32_bf16 v[100:103], v[162:165], v[186:189], v[100:103]
	v_mfma_f32_16x16x32_bf16 v[96:99], v[170:173], v[186:189], v[96:99]
	v_mfma_f32_16x16x32_bf16 v[84:87], v[162:165], v[194:197], v[84:87]
	v_mfma_f32_16x16x32_bf16 v[80:83], v[170:173], v[194:197], v[80:83]
	v_mfma_f32_16x16x32_bf16 v[52:55], v[162:165], v[202:205], v[52:55]
	v_mfma_f32_16x16x32_bf16 v[48:51], v[170:173], v[202:205], v[48:51]
	s_barrier
	s_add_i32 s94, s96, s68
	s_mov_b32 m0, s94
	ds_read_b128 v[174:177], v151 offset:16384
	ds_read_b128 v[178:181], v151 offset:17408
	ds_read_b128 v[182:185], v151 offset:18432
	ds_read_b128 v[186:189], v151 offset:19456
	ds_read_b128 v[190:193], v151 offset:20480
	ds_read_b128 v[194:197], v151 offset:21504
	ds_read_b128 v[198:201], v151 offset:22528
	ds_read_b128 v[202:205], v151 offset:23552
	s_nop 0
	global_load_lds_dwordx4 v145, s[64:65]
	s_add_i32 m0, s94, 0x2000
	s_add_u32 s94, s64, 0x20000
	s_addc_u32 s95, s65, 0
	s_add_i32 s96, s97, s68
	s_nop 0
	global_load_lds_dwordx4 v147, s[64:65]
	s_mov_b32 m0, s96
	s_nop 0
	global_load_lds_dwordx4 v145, s[94:95]
	s_add_i32 m0, s96, 0x2000
	s_nop 0
	global_load_lds_dwordx4 v147, s[94:95]
	s_mov_b32 m0, s3
	s_nop 0
	global_load_lds_dwordx4 v144, s[66:67]
	s_mov_b32 m0, s73
	s_nop 0
	global_load_lds_dwordx4 v146, s[66:67]
	s_waitcnt vmcnt(8)
	s_waitcnt lgkmcnt(0)
	s_barrier
	s_waitcnt lgkmcnt(0)
	v_mfma_f32_16x16x32_bf16 v[76:79], v[128:131], v[174:177], v[76:79]
	v_mfma_f32_16x16x32_bf16 v[72:75], v[136:139], v[174:177], v[72:75]
	v_mfma_f32_16x16x32_bf16 v[44:47], v[128:131], v[182:185], v[44:47]
	v_mfma_f32_16x16x32_bf16 v[40:43], v[136:139], v[182:185], v[40:43]
	v_mfma_f32_16x16x32_bf16 v[28:31], v[128:131], v[190:193], v[28:31]
	v_mfma_f32_16x16x32_bf16 v[24:27], v[136:139], v[190:193], v[24:27]
	v_mfma_f32_16x16x32_bf16 v[12:15], v[128:131], v[198:201], v[12:15]
	v_mfma_f32_16x16x32_bf16 v[8:11], v[136:139], v[198:201], v[8:11]
	v_mfma_f32_16x16x32_bf16 v[76:79], v[132:135], v[178:181], v[76:79]
	v_mfma_f32_16x16x32_bf16 v[72:75], v[154:157], v[178:181], v[72:75]
	v_mfma_f32_16x16x32_bf16 v[44:47], v[132:135], v[186:189], v[44:47]
	v_mfma_f32_16x16x32_bf16 v[40:43], v[154:157], v[186:189], v[40:43]
	v_mfma_f32_16x16x32_bf16 v[28:31], v[132:135], v[194:197], v[28:31]
	v_mfma_f32_16x16x32_bf16 v[24:27], v[154:157], v[194:197], v[24:27]
	v_mfma_f32_16x16x32_bf16 v[12:15], v[132:135], v[202:205], v[12:15]
	v_mfma_f32_16x16x32_bf16 v[8:11], v[154:157], v[202:205], v[8:11]
	v_mfma_f32_16x16x32_bf16 v[68:71], v[158:161], v[174:177], v[68:71]
	v_mfma_f32_16x16x32_bf16 v[64:67], v[166:169], v[174:177], v[64:67]
	v_mfma_f32_16x16x32_bf16 v[36:39], v[158:161], v[182:185], v[36:39]
	v_mfma_f32_16x16x32_bf16 v[32:35], v[166:169], v[182:185], v[32:35]
	v_mfma_f32_16x16x32_bf16 v[20:23], v[158:161], v[190:193], v[20:23]
	v_mfma_f32_16x16x32_bf16 v[16:19], v[166:169], v[190:193], v[16:19]
	v_mfma_f32_16x16x32_bf16 v[4:7], v[158:161], v[198:201], v[4:7]
	v_mfma_f32_16x16x32_bf16 v[0:3], v[166:169], v[198:201], v[0:3]
	v_mfma_f32_16x16x32_bf16 v[68:71], v[162:165], v[178:181], v[68:71]
	v_mfma_f32_16x16x32_bf16 v[64:67], v[170:173], v[178:181], v[64:67]
	v_mfma_f32_16x16x32_bf16 v[36:39], v[162:165], v[186:189], v[36:39]
	v_mfma_f32_16x16x32_bf16 v[32:35], v[170:173], v[186:189], v[32:35]
	v_mfma_f32_16x16x32_bf16 v[20:23], v[162:165], v[194:197], v[20:23]
	v_mfma_f32_16x16x32_bf16 v[16:19], v[170:173], v[194:197], v[16:19]
	v_mfma_f32_16x16x32_bf16 v[4:7], v[162:165], v[202:205], v[4:7]
	v_mfma_f32_16x16x32_bf16 v[0:3], v[170:173], v[202:205], v[0:3]
	s_barrier
	ds_read_b128 v[128:131], v142
	ds_read_b128 v[132:135], v142 offset:1024
	ds_read_b128 v[136:139], v142 offset:2048
	ds_read_b128 v[154:157], v142 offset:3072
	ds_read_b128 v[158:161], v153
	ds_read_b128 v[162:165], v153 offset:1024
	ds_read_b128 v[166:169], v153 offset:2048
	ds_read_b128 v[170:173], v153 offset:3072
	s_add_u32 s66, s66, 0x70000
	s_addc_u32 s67, s67, 0
	s_mov_b32 m0, s74
	ds_read_b128 v[174:177], v151 offset:32768
	ds_read_b128 v[178:181], v151 offset:33792
	ds_read_b128 v[182:185], v151 offset:34816
	ds_read_b128 v[186:189], v151 offset:35840
	ds_read_b128 v[190:193], v151 offset:36864
	ds_read_b128 v[194:197], v151 offset:37888
	ds_read_b128 v[198:201], v151 offset:38912
	ds_read_b128 v[202:205], v151 offset:39936
	s_nop 0
	global_load_lds_dwordx4 v144, s[66:67]
	s_mov_b32 m0, s75
	s_nop 0
	global_load_lds_dwordx4 v146, s[66:67]
	s_waitcnt vmcnt(8)
	s_waitcnt lgkmcnt(0)
	s_barrier
	s_waitcnt lgkmcnt(0)
	v_mfma_f32_16x16x32_bf16 v[124:127], v[128:131], v[174:177], v[124:127]
	v_mfma_f32_16x16x32_bf16 v[120:123], v[136:139], v[174:177], v[120:123]
	v_mfma_f32_16x16x32_bf16 v[108:111], v[128:131], v[182:185], v[108:111]
	v_mfma_f32_16x16x32_bf16 v[104:107], v[136:139], v[182:185], v[104:107]
	v_mfma_f32_16x16x32_bf16 v[92:95], v[128:131], v[190:193], v[92:95]
	v_mfma_f32_16x16x32_bf16 v[88:91], v[136:139], v[190:193], v[88:91]
	v_mfma_f32_16x16x32_bf16 v[60:63], v[128:131], v[198:201], v[60:63]
	v_mfma_f32_16x16x32_bf16 v[56:59], v[136:139], v[198:201], v[56:59]
	v_mfma_f32_16x16x32_bf16 v[124:127], v[132:135], v[178:181], v[124:127]
	v_mfma_f32_16x16x32_bf16 v[120:123], v[154:157], v[178:181], v[120:123]
	v_mfma_f32_16x16x32_bf16 v[108:111], v[132:135], v[186:189], v[108:111]
	v_mfma_f32_16x16x32_bf16 v[104:107], v[154:157], v[186:189], v[104:107]
	v_mfma_f32_16x16x32_bf16 v[92:95], v[132:135], v[194:197], v[92:95]
	v_mfma_f32_16x16x32_bf16 v[88:91], v[154:157], v[194:197], v[88:91]
	v_mfma_f32_16x16x32_bf16 v[60:63], v[132:135], v[202:205], v[60:63]
	v_mfma_f32_16x16x32_bf16 v[56:59], v[154:157], v[202:205], v[56:59]
	v_mfma_f32_16x16x32_bf16 v[116:119], v[158:161], v[174:177], v[116:119]
	v_mfma_f32_16x16x32_bf16 v[112:115], v[166:169], v[174:177], v[112:115]
	v_mfma_f32_16x16x32_bf16 v[100:103], v[158:161], v[182:185], v[100:103]
	v_mfma_f32_16x16x32_bf16 v[96:99], v[166:169], v[182:185], v[96:99]
	v_mfma_f32_16x16x32_bf16 v[84:87], v[158:161], v[190:193], v[84:87]
	v_mfma_f32_16x16x32_bf16 v[80:83], v[166:169], v[190:193], v[80:83]
	v_mfma_f32_16x16x32_bf16 v[52:55], v[158:161], v[198:201], v[52:55]
	v_mfma_f32_16x16x32_bf16 v[48:51], v[166:169], v[198:201], v[48:51]
	v_mfma_f32_16x16x32_bf16 v[116:119], v[162:165], v[178:181], v[116:119]
	v_mfma_f32_16x16x32_bf16 v[112:115], v[170:173], v[178:181], v[112:115]
	v_mfma_f32_16x16x32_bf16 v[100:103], v[162:165], v[186:189], v[100:103]
	v_mfma_f32_16x16x32_bf16 v[96:99], v[170:173], v[186:189], v[96:99]
	v_mfma_f32_16x16x32_bf16 v[84:87], v[162:165], v[194:197], v[84:87]
	v_mfma_f32_16x16x32_bf16 v[80:83], v[170:173], v[194:197], v[80:83]
	v_mfma_f32_16x16x32_bf16 v[52:55], v[162:165], v[202:205], v[52:55]
	v_mfma_f32_16x16x32_bf16 v[48:51], v[170:173], v[202:205], v[48:51]
	s_barrier
	s_add_u32 s66, s64, 0x80
	s_mov_b32 m0, s49
	s_addc_u32 s67, s65, 0
	ds_read_b128 v[174:177], v151 offset:49152
	ds_read_b128 v[178:181], v151 offset:50176
	ds_read_b128 v[182:185], v151 offset:51200
	ds_read_b128 v[186:189], v151 offset:52224
	ds_read_b128 v[190:193], v151 offset:53248
	ds_read_b128 v[194:197], v151 offset:54272
	ds_read_b128 v[198:201], v151 offset:55296
	ds_read_b128 v[202:205], v151 offset:56320
	s_add_u32 s64, s64, 0x20080
	global_load_lds_dwordx4 v145, s[66:67]
	s_mov_b32 m0, s51
	s_addc_u32 s65, s65, 0
	global_load_lds_dwordx4 v147, s[66:67]
	s_mov_b32 m0, s79
	s_nop 0
	global_load_lds_dwordx4 v145, s[64:65]
	s_mov_b32 m0, s86
	s_nop 0
	global_load_lds_dwordx4 v147, s[64:65]
	s_mov_b32 m0, s76
	s_nop 0
	global_load_lds_dwordx4 v144, s[62:63]
	s_mov_b32 m0, s77
	s_nop 0
	global_load_lds_dwordx4 v146, s[62:63]
	s_waitcnt vmcnt(8)
	s_waitcnt lgkmcnt(0)
	s_barrier
	s_waitcnt lgkmcnt(0)
	v_mfma_f32_16x16x32_bf16 v[76:79], v[128:131], v[174:177], v[76:79]
	v_mfma_f32_16x16x32_bf16 v[72:75], v[136:139], v[174:177], v[72:75]
	v_mfma_f32_16x16x32_bf16 v[44:47], v[128:131], v[182:185], v[44:47]
	v_mfma_f32_16x16x32_bf16 v[40:43], v[136:139], v[182:185], v[40:43]
	v_mfma_f32_16x16x32_bf16 v[28:31], v[128:131], v[190:193], v[28:31]
	v_mfma_f32_16x16x32_bf16 v[24:27], v[136:139], v[190:193], v[24:27]
	v_mfma_f32_16x16x32_bf16 v[12:15], v[128:131], v[198:201], v[12:15]
	v_mfma_f32_16x16x32_bf16 v[8:11], v[136:139], v[198:201], v[8:11]
	v_mfma_f32_16x16x32_bf16 v[76:79], v[132:135], v[178:181], v[76:79]
	v_mfma_f32_16x16x32_bf16 v[72:75], v[154:157], v[178:181], v[72:75]
	v_mfma_f32_16x16x32_bf16 v[44:47], v[132:135], v[186:189], v[44:47]
	v_mfma_f32_16x16x32_bf16 v[40:43], v[154:157], v[186:189], v[40:43]
	v_mfma_f32_16x16x32_bf16 v[28:31], v[132:135], v[194:197], v[28:31]
	v_mfma_f32_16x16x32_bf16 v[24:27], v[154:157], v[194:197], v[24:27]
	v_mfma_f32_16x16x32_bf16 v[12:15], v[132:135], v[202:205], v[12:15]
	v_mfma_f32_16x16x32_bf16 v[8:11], v[154:157], v[202:205], v[8:11]
	v_mfma_f32_16x16x32_bf16 v[68:71], v[158:161], v[174:177], v[68:71]
	v_mfma_f32_16x16x32_bf16 v[64:67], v[166:169], v[174:177], v[64:67]
	v_mfma_f32_16x16x32_bf16 v[36:39], v[158:161], v[182:185], v[36:39]
	v_mfma_f32_16x16x32_bf16 v[32:35], v[166:169], v[182:185], v[32:35]
	v_mfma_f32_16x16x32_bf16 v[20:23], v[158:161], v[190:193], v[20:23]
	v_mfma_f32_16x16x32_bf16 v[16:19], v[166:169], v[190:193], v[16:19]
	v_mfma_f32_16x16x32_bf16 v[4:7], v[158:161], v[198:201], v[4:7]
	v_mfma_f32_16x16x32_bf16 v[0:3], v[166:169], v[198:201], v[0:3]
	v_mfma_f32_16x16x32_bf16 v[68:71], v[162:165], v[178:181], v[68:71]
	v_mfma_f32_16x16x32_bf16 v[64:67], v[170:173], v[178:181], v[64:67]
	v_mfma_f32_16x16x32_bf16 v[36:39], v[162:165], v[186:189], v[36:39]
	v_mfma_f32_16x16x32_bf16 v[32:35], v[170:173], v[186:189], v[32:35]
	v_mfma_f32_16x16x32_bf16 v[20:23], v[162:165], v[194:197], v[20:23]
	v_mfma_f32_16x16x32_bf16 v[16:19], v[170:173], v[194:197], v[16:19]
	v_mfma_f32_16x16x32_bf16 v[4:7], v[162:165], v[202:205], v[4:7]
	v_mfma_f32_16x16x32_bf16 v[0:3], v[170:173], v[202:205], v[0:3]
	s_barrier
	s_add_i32 s93, s93, 2
	s_add_u32 s60, s60, 0x100
	s_addc_u32 s61, s61, 0
	s_cmp_gt_u32 s93, 5
	s_cbranch_scc0 .LBB0_1777
	s_and_b64 vcc, exec, s[46:47]
	s_cbranch_vccz .LBB0_1780
	s_barrier

.LBB0_2038:
	s_add_u32 s20, s56, 0x100
	s_addc_u32 s21, s57, 0
	s_waitcnt lgkmcnt(0)
	s_add_u32 s52, s54, 0x100
	s_addc_u32 s53, s55, 0
	s_barrier
	s_waitcnt lgkmcnt(0)
	v_mfma_f32_16x16x32_bf16 v[32:35], v[16:19], v[68:71], 0
	v_mfma_f32_16x16x32_bf16 v[36:39], v[24:27], v[68:71], 0
	v_mfma_f32_16x16x32_bf16 v[40:43], v[16:19], v[84:87], 0
	v_mfma_f32_16x16x32_bf16 v[44:47], v[24:27], v[84:87], 0
	v_mfma_f32_16x16x32_bf16 v[48:51], v[16:19], v[92:95], 0
	v_mfma_f32_16x16x32_bf16 v[52:55], v[24:27], v[92:95], 0
	v_mfma_f32_16x16x32_bf16 v[56:59], v[16:19], v[76:79], 0
	v_mfma_f32_16x16x32_bf16 v[60:63], v[24:27], v[76:79], 0
	v_mfma_f32_16x16x32_bf16 v[134:137], v[20:23], v[72:75], v[32:35]
	v_mfma_f32_16x16x32_bf16 v[36:39], v[28:31], v[72:75], v[36:39]
	v_mfma_f32_16x16x32_bf16 v[40:43], v[20:23], v[88:91], v[40:43]
	v_mfma_f32_16x16x32_bf16 v[44:47], v[28:31], v[88:91], v[44:47]
	v_mfma_f32_16x16x32_bf16 v[48:51], v[20:23], v[96:99], v[48:51]
	v_mfma_f32_16x16x32_bf16 v[52:55], v[28:31], v[96:99], v[52:55]
	v_mfma_f32_16x16x32_bf16 v[56:59], v[20:23], v[80:83], v[56:59]
	v_mfma_f32_16x16x32_bf16 v[60:63], v[28:31], v[80:83], v[60:63]
	v_mfma_f32_16x16x32_bf16 v[64:67], v[0:3], v[68:71], 0
	v_mfma_f32_16x16x32_bf16 v[68:71], v[8:11], v[68:71], 0
	v_mfma_f32_16x16x32_bf16 v[64:67], v[4:7], v[72:75], v[64:67]
	v_mfma_f32_16x16x32_bf16 v[68:71], v[12:15], v[72:75], v[68:71]
	v_mfma_f32_16x16x32_bf16 v[72:75], v[0:3], v[84:87], 0
	v_mfma_f32_16x16x32_bf16 v[84:87], v[8:11], v[84:87], 0
	v_mfma_f32_16x16x32_bf16 v[72:75], v[4:7], v[88:91], v[72:75]
	v_mfma_f32_16x16x32_bf16 v[84:87], v[12:15], v[88:91], v[84:87]
	v_mfma_f32_16x16x32_bf16 v[88:91], v[0:3], v[92:95], 0
	v_mfma_f32_16x16x32_bf16 v[92:95], v[8:11], v[92:95], 0
	v_mfma_f32_16x16x32_bf16 v[88:91], v[4:7], v[96:99], v[88:91]
	v_mfma_f32_16x16x32_bf16 v[96:99], v[12:15], v[96:99], v[92:95]
	v_mfma_f32_16x16x32_bf16 v[92:95], v[0:3], v[76:79], 0
	v_mfma_f32_16x16x32_bf16 v[76:79], v[8:11], v[76:79], 0
	v_mfma_f32_16x16x32_bf16 v[108:111], v[4:7], v[80:83], v[92:95]
	v_mfma_f32_16x16x32_bf16 v[120:123], v[12:15], v[80:83], v[76:79]
	s_barrier
	s_mov_b32 m0, s62
	ds_read_b128 v[116:119], v209 offset:16384
	ds_read_b128 v[124:127], v209 offset:17408
	ds_read_b128 v[104:107], v209 offset:18432
	ds_read_b128 v[112:115], v209 offset:19456
	ds_read_b128 v[92:95], v209 offset:20480
	ds_read_b128 v[100:103], v209 offset:21504
	ds_read_b128 v[76:79], v209 offset:22528
	ds_read_b128 v[80:83], v209 offset:23552
	s_nop 0
	global_load_lds_dwordx4 v203, s[52:53]
	s_mov_b32 m0, s63
	s_nop 0
	global_load_lds_dwordx4 v205, s[52:53]
	s_add_u32 s52, s54, 0x80100
	s_addc_u32 s53, s55, 0
	s_mov_b32 m0, s64
	s_and_b64 vcc, exec, s[50:51]
	global_load_lds_dwordx4 v203, s[52:53]
	s_mov_b32 m0, s65
	s_nop 0
	global_load_lds_dwordx4 v205, s[52:53]
	s_mov_b32 m0, s27
	s_mov_b64 s[52:53], -1
	global_load_lds_dwordx4 v202, s[20:21]
	s_mov_b32 m0, s66
	s_nop 0
	global_load_lds_dwordx4 v204, s[20:21]
	s_cbranch_vccz .LBB0_2040
	s_waitcnt vmcnt(8)
	s_mov_b64 s[52:53], 0

.LBB0_2042:
	s_ashr_i32 s45, s44, 31
	s_lshl_b64 s[20:21], s[44:45], 20
	s_add_u32 s50, s13, s20
	s_addc_u32 s51, s82, s21
	s_and_b64 s[20:21], s[48:49], exec
	s_cselect_b32 s5, s51, s57
	s_cselect_b32 s12, s50, s56
	s_ashr_i32 s47, s46, 31
	s_lshl_b64 s[20:21], s[46:47], 20
	s_add_u32 s52, s24, s20
	s_addc_u32 s53, s25, s21
	s_and_b64 s[20:21], s[48:49], exec
	s_cselect_b32 s20, s53, s55
	s_cselect_b32 s21, s52, s54
	s_add_u32 s58, s56, 0x180
	s_waitcnt lgkmcnt(0)
	s_addc_u32 s59, s57, 0
	s_add_u32 s60, s54, 0x180
	s_addc_u32 s61, s55, 0
	s_barrier
	s_waitcnt lgkmcnt(0)
	v_mfma_f32_16x16x32_bf16 v[128:131], v[16:19], v[116:119], 0
	v_mfma_f32_16x16x32_bf16 v[140:143], v[20:23], v[124:127], v[128:131]
	v_mfma_f32_16x16x32_bf16 v[128:131], v[24:27], v[116:119], 0
	v_mfma_f32_16x16x32_bf16 v[156:159], v[28:31], v[124:127], v[128:131]
	v_mfma_f32_16x16x32_bf16 v[128:131], v[16:19], v[104:107], 0
	v_mfma_f32_16x16x32_bf16 v[160:163], v[20:23], v[112:115], v[128:131]
	v_mfma_f32_16x16x32_bf16 v[128:131], v[24:27], v[104:107], 0
	v_mfma_f32_16x16x32_bf16 v[164:167], v[28:31], v[112:115], v[128:131]
	v_mfma_f32_16x16x32_bf16 v[128:131], v[16:19], v[92:95], 0
	v_mfma_f32_16x16x32_bf16 v[16:19], v[16:19], v[76:79], 0
	v_mfma_f32_16x16x32_bf16 v[168:171], v[20:23], v[100:103], v[128:131]
	v_mfma_f32_16x16x32_bf16 v[16:19], v[20:23], v[80:83], v[16:19]
	v_mfma_f32_16x16x32_bf16 v[20:23], v[24:27], v[76:79], 0
	v_mfma_f32_16x16x32_bf16 v[128:131], v[24:27], v[92:95], 0
	v_mfma_f32_16x16x32_bf16 v[20:23], v[28:31], v[80:83], v[20:23]
	v_mfma_f32_16x16x32_bf16 v[172:175], v[28:31], v[100:103], v[128:131]
	v_mfma_f32_16x16x32_bf16 v[24:27], v[0:3], v[116:119], 0
	v_mfma_f32_16x16x32_bf16 v[176:179], v[4:7], v[124:127], v[24:27]
	v_mfma_f32_16x16x32_bf16 v[24:27], v[8:11], v[116:119], 0
	v_mfma_f32_16x16x32_bf16 v[180:183], v[12:15], v[124:127], v[24:27]
	v_mfma_f32_16x16x32_bf16 v[24:27], v[0:3], v[104:107], 0
	v_mfma_f32_16x16x32_bf16 v[186:189], v[4:7], v[112:115], v[24:27]
	v_mfma_f32_16x16x32_bf16 v[24:27], v[8:11], v[104:107], 0
	v_mfma_f32_16x16x32_bf16 v[190:193], v[12:15], v[112:115], v[24:27]
	v_mfma_f32_16x16x32_bf16 v[24:27], v[0:3], v[92:95], 0
	v_mfma_f32_16x16x32_bf16 v[0:3], v[0:3], v[76:79], 0
	v_mfma_f32_16x16x32_bf16 v[194:197], v[4:7], v[100:103], v[24:27]
	v_mfma_f32_16x16x32_bf16 v[24:27], v[8:11], v[92:95], 0
	v_mfma_f32_16x16x32_bf16 v[0:3], v[4:7], v[80:83], v[0:3]
	v_mfma_f32_16x16x32_bf16 v[4:7], v[8:11], v[76:79], 0
	v_mfma_f32_16x16x32_bf16 v[198:201], v[12:15], v[100:103], v[24:27]
	v_mfma_f32_16x16x32_bf16 v[212:215], v[12:15], v[80:83], v[4:7]
	s_barrier
	v_add_u32_e32 v132, s75, v206
	v_add_u32_e32 v133, s76, v206
	s_nop 1
	ds_read_b128 v[4:7], v132
	ds_read_b128 v[8:11], v132 offset:1024
	ds_read_b128 v[216:219], v132 offset:2048
	ds_read_b128 v[220:223], v132 offset:3072
	ds_read_b128 v[224:227], v133
	ds_read_b128 v[228:231], v133 offset:1024
	ds_read_b128 v[232:235], v133 offset:2048
	ds_read_b128 v[236:239], v133 offset:3072
	s_add_u32 s88, s56, 0x80100
	s_addc_u32 s89, s57, 0
	s_mov_b32 m0, s67
	ds_read_b128 v[12:15], v209 offset:32768
	ds_read_b128 v[24:27], v209 offset:33792
	ds_read_b128 v[28:31], v209 offset:34816
	ds_read_b128 v[92:95], v209 offset:35840
	ds_read_b128 v[240:243], v209 offset:36864
	ds_read_b128 v[244:247], v209 offset:37888
	ds_read_b128 v[248:251], v209 offset:38912
	ds_read_b128 v[32:35], v209 offset:39936
	s_nop 0
	global_load_lds_dwordx4 v202, s[88:89]
	s_mov_b32 m0, s68
	s_nop 0
	global_load_lds_dwordx4 v204, s[88:89]
	s_waitcnt vmcnt(8)
	s_waitcnt lgkmcnt(0)
	s_barrier
	s_waitcnt lgkmcnt(0)
	v_mfma_f32_16x16x32_bf16 v[36:39], v[216:219], v[12:15], v[36:39]
	v_mfma_f32_16x16x32_bf16 v[148:151], v[220:223], v[24:27], v[36:39]
	v_mfma_f32_16x16x32_bf16 v[36:39], v[4:7], v[28:31], v[40:43]
	v_mfma_f32_16x16x32_bf16 v[128:131], v[8:11], v[92:95], v[36:39]
	v_mfma_f32_16x16x32_bf16 v[36:39], v[216:219], v[28:31], v[44:47]
	v_mfma_f32_16x16x32_bf16 v[124:127], v[220:223], v[92:95], v[36:39]
	v_mfma_f32_16x16x32_bf16 v[36:39], v[4:7], v[240:243], v[48:51]
	v_mfma_f32_16x16x32_bf16 v[104:107], v[8:11], v[244:247], v[36:39]
	v_mfma_f32_16x16x32_bf16 v[36:39], v[216:219], v[240:243], v[52:55]
	v_mfma_f32_16x16x32_bf16 v[100:103], v[220:223], v[244:247], v[36:39]
	v_mfma_f32_16x16x32_bf16 v[36:39], v[4:7], v[248:251], v[56:59]
	v_mfma_f32_16x16x32_bf16 v[76:79], v[4:7], v[12:15], v[134:137]
	v_mfma_f32_16x16x32_bf16 v[80:83], v[8:11], v[32:35], v[36:39]
	v_mfma_f32_16x16x32_bf16 v[36:39], v[216:219], v[248:251], v[60:63]
	v_mfma_f32_16x16x32_bf16 v[152:155], v[8:11], v[24:27], v[76:79]
	v_mfma_f32_16x16x32_bf16 v[76:79], v[220:223], v[32:35], v[36:39]
	v_mfma_f32_16x16x32_bf16 v[36:39], v[224:227], v[12:15], v[64:67]
	v_mfma_f32_16x16x32_bf16 v[12:15], v[232:235], v[12:15], v[68:71]
	v_mfma_f32_16x16x32_bf16 v[136:139], v[236:239], v[24:27], v[12:15]
	v_mfma_f32_16x16x32_bf16 v[12:15], v[224:227], v[28:31], v[72:75]
	v_mfma_f32_16x16x32_bf16 v[116:119], v[228:231], v[92:95], v[12:15]
	v_mfma_f32_16x16x32_bf16 v[12:15], v[232:235], v[28:31], v[84:87]
	v_mfma_f32_16x16x32_bf16 v[112:115], v[236:239], v[92:95], v[12:15]
	v_mfma_f32_16x16x32_bf16 v[12:15], v[224:227], v[240:243], v[88:91]
	v_mfma_f32_16x16x32_bf16 v[92:95], v[228:231], v[244:247], v[12:15]
	v_mfma_f32_16x16x32_bf16 v[12:15], v[232:235], v[240:243], v[96:99]
	v_mfma_f32_16x16x32_bf16 v[88:91], v[236:239], v[244:247], v[12:15]
	v_mfma_f32_16x16x32_bf16 v[12:15], v[224:227], v[248:251], v[108:111]
	v_mfma_f32_16x16x32_bf16 v[68:71], v[228:231], v[32:35], v[12:15]
	v_mfma_f32_16x16x32_bf16 v[12:15], v[232:235], v[248:251], v[120:123]
	v_mfma_f32_16x16x32_bf16 v[144:147], v[228:231], v[24:27], v[36:39]
	v_mfma_f32_16x16x32_bf16 v[64:67], v[236:239], v[32:35], v[12:15]
	s_barrier
	s_add_i32 s45, s75, s26
	s_mov_b32 m0, s45
	s_add_i32 s47, s45, 0x2000
	ds_read_b128 v[32:35], v209 offset:49152
	ds_read_b128 v[36:39], v209 offset:50176
	ds_read_b128 v[72:75], v209 offset:51200
	ds_read_b128 v[84:87], v209 offset:52224
	ds_read_b128 v[96:99], v209 offset:53248
	ds_read_b128 v[108:111], v209 offset:54272
	ds_read_b128 v[120:123], v209 offset:55296
	ds_read_b128 v[240:243], v209 offset:56320
	s_nop 0
	global_load_lds_dwordx4 v203, s[60:61]
	s_mov_b32 m0, s47
	s_nop 0
	global_load_lds_dwordx4 v205, s[60:61]
	s_add_u32 s60, s54, 0x80180
	s_addc_u32 s61, s55, 0
	s_add_i32 s79, s76, s26
	s_mov_b32 m0, s79
	s_add_i32 s80, s79, 0x2000
	s_nop 0
	global_load_lds_dwordx4 v203, s[60:61]
	s_mov_b32 m0, s80
	s_nop 0
	global_load_lds_dwordx4 v205, s[60:61]
	s_mov_b32 m0, s69
	s_nop 0
	global_load_lds_dwordx4 v202, s[58:59]
	s_mov_b32 m0, s70
	s_nop 0
	global_load_lds_dwordx4 v204, s[58:59]
	s_waitcnt vmcnt(8)
	s_waitcnt lgkmcnt(0)
	s_barrier
	s_waitcnt lgkmcnt(0)
	v_mfma_f32_16x16x32_bf16 v[12:15], v[4:7], v[32:35], v[140:143]
	v_mfma_f32_16x16x32_bf16 v[60:63], v[8:11], v[36:39], v[12:15]
	v_mfma_f32_16x16x32_bf16 v[12:15], v[216:219], v[32:35], v[156:159]
	v_mfma_f32_16x16x32_bf16 v[56:59], v[220:223], v[36:39], v[12:15]
	v_mfma_f32_16x16x32_bf16 v[12:15], v[4:7], v[72:75], v[160:163]
	v_mfma_f32_16x16x32_bf16 v[44:47], v[8:11], v[84:87], v[12:15]
	v_mfma_f32_16x16x32_bf16 v[12:15], v[216:219], v[72:75], v[164:167]
	v_mfma_f32_16x16x32_bf16 v[40:43], v[220:223], v[84:87], v[12:15]
	v_mfma_f32_16x16x32_bf16 v[12:15], v[4:7], v[96:99], v[168:171]
	v_mfma_f32_16x16x32_bf16 v[28:31], v[8:11], v[108:111], v[12:15]
	v_mfma_f32_16x16x32_bf16 v[12:15], v[216:219], v[96:99], v[172:175]
	v_mfma_f32_16x16x32_bf16 v[4:7], v[4:7], v[120:123], v[16:19]
	v_mfma_f32_16x16x32_bf16 v[24:27], v[220:223], v[108:111], v[12:15]
	v_mfma_f32_16x16x32_bf16 v[12:15], v[8:11], v[240:243], v[4:7]
	v_mfma_f32_16x16x32_bf16 v[4:7], v[216:219], v[120:123], v[20:23]
	v_mfma_f32_16x16x32_bf16 v[8:11], v[220:223], v[240:243], v[4:7]
	v_mfma_f32_16x16x32_bf16 v[4:7], v[224:227], v[32:35], v[176:179]
	v_mfma_f32_16x16x32_bf16 v[52:55], v[228:231], v[36:39], v[4:7]
	v_mfma_f32_16x16x32_bf16 v[4:7], v[232:235], v[32:35], v[180:183]
	v_mfma_f32_16x16x32_bf16 v[48:51], v[236:239], v[36:39], v[4:7]
	v_mfma_f32_16x16x32_bf16 v[4:7], v[224:227], v[72:75], v[186:189]
	v_mfma_f32_16x16x32_bf16 v[36:39], v[228:231], v[84:87], v[4:7]
	v_mfma_f32_16x16x32_bf16 v[4:7], v[232:235], v[72:75], v[190:193]
	v_mfma_f32_16x16x32_bf16 v[32:35], v[236:239], v[84:87], v[4:7]
	v_mfma_f32_16x16x32_bf16 v[4:7], v[224:227], v[96:99], v[194:197]
	v_mfma_f32_16x16x32_bf16 v[20:23], v[228:231], v[108:111], v[4:7]
	v_mfma_f32_16x16x32_bf16 v[4:7], v[232:235], v[96:99], v[198:201]
	v_mfma_f32_16x16x32_bf16 v[0:3], v[224:227], v[120:123], v[0:3]
	v_mfma_f32_16x16x32_bf16 v[16:19], v[236:239], v[108:111], v[4:7]
	v_mfma_f32_16x16x32_bf16 v[4:7], v[228:231], v[240:243], v[0:3]
	v_mfma_f32_16x16x32_bf16 v[0:3], v[232:235], v[120:123], v[212:215]
	v_mfma_f32_16x16x32_bf16 v[0:3], v[236:239], v[240:243], v[0:3]
	s_barrier
	s_add_u32 s83, s56, 0x200
	s_addc_u32 s86, s57, 0
	s_add_u32 s88, s54, 0x200
	s_addc_u32 s89, s55, 0
	s_add_u32 s54, s56, 0x80180
	s_addc_u32 s55, s57, 0
	s_mov_b32 s90, 0
.LBB0_2043:
	s_cmp_eq_u32 s90, 28
	s_cselect_b32 s60, s12, s83
	s_cselect_b32 s61, s5, s86
	s_cselect_b32 s58, s21, s88
	s_cselect_b32 s59, s20, s89
	s_add_u32 s56, s60, 0x80
	s_addc_u32 s57, s61, 0
	s_add_i32 s91, 0, 0x10000
	s_add_i32 s94, 0, 0x14000
	v_add_u32_e32 v108, s91, v206
	v_add_u32_e32 v134, s94, v206
	ds_read_b128 v[72:75], v108
	ds_read_b128 v[84:87], v108 offset:1024
	ds_read_b128 v[96:99], v108 offset:2048
	ds_read_b128 v[108:111], v108 offset:3072
	ds_read_b128 v[120:123], v134
	ds_read_b128 v[140:143], v134 offset:1024
	ds_read_b128 v[156:159], v134 offset:2048
	ds_read_b128 v[160:163], v134 offset:3072
	s_mov_b32 m0, s1
	ds_read_b128 v[164:167], v209
	ds_read_b128 v[168:171], v209 offset:1024
	ds_read_b128 v[172:175], v209 offset:2048
	ds_read_b128 v[176:179], v209 offset:3072
	ds_read_b128 v[180:183], v209 offset:4096
	ds_read_b128 v[186:189], v209 offset:5120
	ds_read_b128 v[190:193], v209 offset:6144
	ds_read_b128 v[194:197], v209 offset:7168
	s_nop 0
	global_load_lds_dwordx4 v202, s[54:55]
	s_mov_b32 m0, s3
	s_nop 0
	global_load_lds_dwordx4 v204, s[54:55]
	s_waitcnt vmcnt(8)
	s_waitcnt lgkmcnt(0)
	s_barrier
	s_waitcnt lgkmcnt(0)
	v_mfma_f32_16x16x32_bf16 v[152:155], v[72:75], v[164:167], v[152:155]
	v_mfma_f32_16x16x32_bf16 v[148:151], v[96:99], v[164:167], v[148:151]
	v_mfma_f32_16x16x32_bf16 v[128:131], v[72:75], v[172:175], v[128:131]
	v_mfma_f32_16x16x32_bf16 v[124:127], v[96:99], v[172:175], v[124:127]
	v_mfma_f32_16x16x32_bf16 v[104:107], v[72:75], v[180:183], v[104:107]
	v_mfma_f32_16x16x32_bf16 v[100:103], v[96:99], v[180:183], v[100:103]
	v_mfma_f32_16x16x32_bf16 v[80:83], v[72:75], v[190:193], v[80:83]
	v_mfma_f32_16x16x32_bf16 v[76:79], v[96:99], v[190:193], v[76:79]
	v_mfma_f32_16x16x32_bf16 v[152:155], v[84:87], v[168:171], v[152:155]
	v_mfma_f32_16x16x32_bf16 v[148:151], v[108:111], v[168:171], v[148:151]
	v_mfma_f32_16x16x32_bf16 v[128:131], v[84:87], v[176:179], v[128:131]
	v_mfma_f32_16x16x32_bf16 v[124:127], v[108:111], v[176:179], v[124:127]
	v_mfma_f32_16x16x32_bf16 v[104:107], v[84:87], v[186:189], v[104:107]
	v_mfma_f32_16x16x32_bf16 v[100:103], v[108:111], v[186:189], v[100:103]
	v_mfma_f32_16x16x32_bf16 v[80:83], v[84:87], v[194:197], v[80:83]
	v_mfma_f32_16x16x32_bf16 v[76:79], v[108:111], v[194:197], v[76:79]
	v_mfma_f32_16x16x32_bf16 v[144:147], v[120:123], v[164:167], v[144:147]
	v_mfma_f32_16x16x32_bf16 v[134:137], v[156:159], v[164:167], v[136:139]
	v_mfma_f32_16x16x32_bf16 v[116:119], v[120:123], v[172:175], v[116:119]
	v_mfma_f32_16x16x32_bf16 v[112:115], v[156:159], v[172:175], v[112:115]
	v_mfma_f32_16x16x32_bf16 v[92:95], v[120:123], v[180:183], v[92:95]
	v_mfma_f32_16x16x32_bf16 v[88:91], v[156:159], v[180:183], v[88:91]
	v_mfma_f32_16x16x32_bf16 v[68:71], v[120:123], v[190:193], v[68:71]
	v_mfma_f32_16x16x32_bf16 v[64:67], v[156:159], v[190:193], v[64:67]
	v_mfma_f32_16x16x32_bf16 v[144:147], v[140:143], v[168:171], v[144:147]
	v_mfma_f32_16x16x32_bf16 v[134:137], v[160:163], v[168:171], v[134:137]
	v_mfma_f32_16x16x32_bf16 v[116:119], v[140:143], v[176:179], v[116:119]
	v_mfma_f32_16x16x32_bf16 v[112:115], v[160:163], v[176:179], v[112:115]
	v_mfma_f32_16x16x32_bf16 v[92:95], v[140:143], v[186:189], v[92:95]
	v_mfma_f32_16x16x32_bf16 v[88:91], v[160:163], v[186:189], v[88:91]
	v_mfma_f32_16x16x32_bf16 v[68:71], v[140:143], v[194:197], v[68:71]
	v_mfma_f32_16x16x32_bf16 v[64:67], v[160:163], v[194:197], v[64:67]
	s_barrier
	s_add_i32 s91, s91, s26
	s_mov_b32 m0, s91
	ds_read_b128 v[164:167], v209 offset:16384
	ds_read_b128 v[168:171], v209 offset:17408
	ds_read_b128 v[172:175], v209 offset:18432
	ds_read_b128 v[176:179], v209 offset:19456
	ds_read_b128 v[180:183], v209 offset:20480
	ds_read_b128 v[186:189], v209 offset:21504
	ds_read_b128 v[190:193], v209 offset:22528
	ds_read_b128 v[194:197], v209 offset:23552
	s_nop 0
	global_load_lds_dwordx4 v203, s[58:59]
	s_add_i32 m0, s91, 0x2000
	s_add_u32 s92, s58, 0x80000
	s_addc_u32 s93, s59, 0
	s_add_i32 s91, s94, s26
	s_nop 0
	global_load_lds_dwordx4 v205, s[58:59]
	s_mov_b32 m0, s91
	s_nop 0
	global_load_lds_dwordx4 v203, s[92:93]
	s_add_i32 m0, s91, 0x2000
	s_nop 0
	global_load_lds_dwordx4 v205, s[92:93]
	s_mov_b32 m0, s27
	s_nop 0
	global_load_lds_dwordx4 v202, s[60:61]
	s_mov_b32 m0, s66
	s_nop 0
	global_load_lds_dwordx4 v204, s[60:61]
	s_waitcnt vmcnt(8)
	s_waitcnt lgkmcnt(0)
	s_barrier
	s_waitcnt lgkmcnt(0)
	v_mfma_f32_16x16x32_bf16 v[60:63], v[72:75], v[164:167], v[60:63]
	v_mfma_f32_16x16x32_bf16 v[56:59], v[96:99], v[164:167], v[56:59]
	v_mfma_f32_16x16x32_bf16 v[44:47], v[72:75], v[172:175], v[44:47]
	v_mfma_f32_16x16x32_bf16 v[40:43], v[96:99], v[172:175], v[40:43]
	v_mfma_f32_16x16x32_bf16 v[28:31], v[72:75], v[180:183], v[28:31]
	v_mfma_f32_16x16x32_bf16 v[24:27], v[96:99], v[180:183], v[24:27]
	v_mfma_f32_16x16x32_bf16 v[12:15], v[72:75], v[190:193], v[12:15]
	v_mfma_f32_16x16x32_bf16 v[8:11], v[96:99], v[190:193], v[8:11]
	v_mfma_f32_16x16x32_bf16 v[60:63], v[84:87], v[168:171], v[60:63]
	v_mfma_f32_16x16x32_bf16 v[56:59], v[108:111], v[168:171], v[56:59]
	v_mfma_f32_16x16x32_bf16 v[44:47], v[84:87], v[176:179], v[44:47]
	v_mfma_f32_16x16x32_bf16 v[40:43], v[108:111], v[176:179], v[40:43]
	v_mfma_f32_16x16x32_bf16 v[28:31], v[84:87], v[186:189], v[28:31]
	v_mfma_f32_16x16x32_bf16 v[24:27], v[108:111], v[186:189], v[24:27]
	v_mfma_f32_16x16x32_bf16 v[12:15], v[84:87], v[194:197], v[12:15]
	v_mfma_f32_16x16x32_bf16 v[8:11], v[108:111], v[194:197], v[8:11]
	v_mfma_f32_16x16x32_bf16 v[52:55], v[120:123], v[164:167], v[52:55]
	v_mfma_f32_16x16x32_bf16 v[48:51], v[156:159], v[164:167], v[48:51]
	v_mfma_f32_16x16x32_bf16 v[36:39], v[120:123], v[172:175], v[36:39]
	v_mfma_f32_16x16x32_bf16 v[32:35], v[156:159], v[172:175], v[32:35]
	v_mfma_f32_16x16x32_bf16 v[20:23], v[120:123], v[180:183], v[20:23]
	v_mfma_f32_16x16x32_bf16 v[16:19], v[156:159], v[180:183], v[16:19]
	v_mfma_f32_16x16x32_bf16 v[4:7], v[120:123], v[190:193], v[4:7]
	v_mfma_f32_16x16x32_bf16 v[0:3], v[156:159], v[190:193], v[0:3]
	v_mfma_f32_16x16x32_bf16 v[52:55], v[140:143], v[168:171], v[52:55]
	v_mfma_f32_16x16x32_bf16 v[48:51], v[160:163], v[168:171], v[48:51]
	v_mfma_f32_16x16x32_bf16 v[36:39], v[140:143], v[176:179], v[36:39]
	v_mfma_f32_16x16x32_bf16 v[32:35], v[160:163], v[176:179], v[32:35]
	v_mfma_f32_16x16x32_bf16 v[20:23], v[140:143], v[186:189], v[20:23]
	v_mfma_f32_16x16x32_bf16 v[16:19], v[160:163], v[186:189], v[16:19]
	v_mfma_f32_16x16x32_bf16 v[4:7], v[140:143], v[194:197], v[4:7]
	v_mfma_f32_16x16x32_bf16 v[0:3], v[160:163], v[194:197], v[0:3]
	s_barrier
	ds_read_b128 v[72:75], v132
	ds_read_b128 v[84:87], v132 offset:1024
	ds_read_b128 v[96:99], v132 offset:2048
	ds_read_b128 v[108:111], v132 offset:3072
	ds_read_b128 v[120:123], v133
	ds_read_b128 v[140:143], v133 offset:1024
	ds_read_b128 v[156:159], v133 offset:2048
	ds_read_b128 v[160:163], v133 offset:3072
	s_add_u32 s60, s60, 0x80000
	s_addc_u32 s61, s61, 0
	s_mov_b32 m0, s67
	ds_read_b128 v[164:167], v209 offset:32768
	ds_read_b128 v[168:171], v209 offset:33792
	ds_read_b128 v[172:175], v209 offset:34816
	ds_read_b128 v[176:179], v209 offset:35840
	ds_read_b128 v[180:183], v209 offset:36864
	ds_read_b128 v[186:189], v209 offset:37888
	ds_read_b128 v[190:193], v209 offset:38912
	ds_read_b128 v[194:197], v209 offset:39936
	s_nop 0
	global_load_lds_dwordx4 v202, s[60:61]
	s_mov_b32 m0, s68
	s_nop 0
	global_load_lds_dwordx4 v204, s[60:61]
	s_waitcnt vmcnt(8)
	s_waitcnt lgkmcnt(0)
	s_barrier
	s_waitcnt lgkmcnt(0)
	v_mfma_f32_16x16x32_bf16 v[152:155], v[72:75], v[164:167], v[152:155]
	v_mfma_f32_16x16x32_bf16 v[148:151], v[96:99], v[164:167], v[148:151]
	v_mfma_f32_16x16x32_bf16 v[128:131], v[72:75], v[172:175], v[128:131]
	v_mfma_f32_16x16x32_bf16 v[124:127], v[96:99], v[172:175], v[124:127]
	v_mfma_f32_16x16x32_bf16 v[104:107], v[72:75], v[180:183], v[104:107]
	v_mfma_f32_16x16x32_bf16 v[100:103], v[96:99], v[180:183], v[100:103]
	v_mfma_f32_16x16x32_bf16 v[80:83], v[72:75], v[190:193], v[80:83]
	v_mfma_f32_16x16x32_bf16 v[76:79], v[96:99], v[190:193], v[76:79]
	v_mfma_f32_16x16x32_bf16 v[152:155], v[84:87], v[168:171], v[152:155]
	v_mfma_f32_16x16x32_bf16 v[148:151], v[108:111], v[168:171], v[148:151]
	v_mfma_f32_16x16x32_bf16 v[128:131], v[84:87], v[176:179], v[128:131]
	v_mfma_f32_16x16x32_bf16 v[124:127], v[108:111], v[176:179], v[124:127]
	v_mfma_f32_16x16x32_bf16 v[104:107], v[84:87], v[186:189], v[104:107]
	v_mfma_f32_16x16x32_bf16 v[100:103], v[108:111], v[186:189], v[100:103]
	v_mfma_f32_16x16x32_bf16 v[80:83], v[84:87], v[194:197], v[80:83]
	v_mfma_f32_16x16x32_bf16 v[76:79], v[108:111], v[194:197], v[76:79]
	v_mfma_f32_16x16x32_bf16 v[144:147], v[120:123], v[164:167], v[144:147]
	v_mfma_f32_16x16x32_bf16 v[134:137], v[156:159], v[164:167], v[134:137]
	v_mfma_f32_16x16x32_bf16 v[116:119], v[120:123], v[172:175], v[116:119]
	v_mfma_f32_16x16x32_bf16 v[112:115], v[156:159], v[172:175], v[112:115]
	v_mfma_f32_16x16x32_bf16 v[92:95], v[120:123], v[180:183], v[92:95]
	v_mfma_f32_16x16x32_bf16 v[88:91], v[156:159], v[180:183], v[88:91]
	v_mfma_f32_16x16x32_bf16 v[68:71], v[120:123], v[190:193], v[68:71]
	v_mfma_f32_16x16x32_bf16 v[64:67], v[156:159], v[190:193], v[64:67]
	v_mfma_f32_16x16x32_bf16 v[144:147], v[140:143], v[168:171], v[144:147]
	v_mfma_f32_16x16x32_bf16 v[136:139], v[160:163], v[168:171], v[134:137]
	v_mfma_f32_16x16x32_bf16 v[116:119], v[140:143], v[176:179], v[116:119]
	v_mfma_f32_16x16x32_bf16 v[112:115], v[160:163], v[176:179], v[112:115]
	v_mfma_f32_16x16x32_bf16 v[92:95], v[140:143], v[186:189], v[92:95]
	v_mfma_f32_16x16x32_bf16 v[88:91], v[160:163], v[186:189], v[88:91]
	v_mfma_f32_16x16x32_bf16 v[68:71], v[140:143], v[194:197], v[68:71]
	v_mfma_f32_16x16x32_bf16 v[64:67], v[160:163], v[194:197], v[64:67]
	s_barrier
	s_add_u32 s60, s58, 0x80
	s_mov_b32 m0, s45
	s_addc_u32 s61, s59, 0
	ds_read_b128 v[164:167], v209 offset:49152
	ds_read_b128 v[168:171], v209 offset:50176
	ds_read_b128 v[172:175], v209 offset:51200
	ds_read_b128 v[176:179], v209 offset:52224
	ds_read_b128 v[180:183], v209 offset:53248
	ds_read_b128 v[186:189], v209 offset:54272
	ds_read_b128 v[190:193], v209 offset:55296
	ds_read_b128 v[194:197], v209 offset:56320
	s_add_u32 s58, s58, 0x80080
	global_load_lds_dwordx4 v203, s[60:61]
	s_mov_b32 m0, s47
	s_addc_u32 s59, s59, 0
	global_load_lds_dwordx4 v205, s[60:61]
	s_mov_b32 m0, s79
	s_nop 0
	global_load_lds_dwordx4 v203, s[58:59]
	s_mov_b32 m0, s80
	s_nop 0
	global_load_lds_dwordx4 v205, s[58:59]
	s_mov_b32 m0, s69
	s_nop 0
	global_load_lds_dwordx4 v202, s[56:57]
	s_mov_b32 m0, s70
	s_nop 0
	global_load_lds_dwordx4 v204, s[56:57]
	s_waitcnt vmcnt(8)
	s_waitcnt lgkmcnt(0)
	s_barrier
	s_waitcnt lgkmcnt(0)
	v_mfma_f32_16x16x32_bf16 v[60:63], v[72:75], v[164:167], v[60:63]
	v_mfma_f32_16x16x32_bf16 v[56:59], v[96:99], v[164:167], v[56:59]
	v_mfma_f32_16x16x32_bf16 v[44:47], v[72:75], v[172:175], v[44:47]
	v_mfma_f32_16x16x32_bf16 v[40:43], v[96:99], v[172:175], v[40:43]
	v_mfma_f32_16x16x32_bf16 v[28:31], v[72:75], v[180:183], v[28:31]
	v_mfma_f32_16x16x32_bf16 v[24:27], v[96:99], v[180:183], v[24:27]
	v_mfma_f32_16x16x32_bf16 v[12:15], v[72:75], v[190:193], v[12:15]
	v_mfma_f32_16x16x32_bf16 v[8:11], v[96:99], v[190:193], v[8:11]
	v_mfma_f32_16x16x32_bf16 v[60:63], v[84:87], v[168:171], v[60:63]
	v_mfma_f32_16x16x32_bf16 v[56:59], v[108:111], v[168:171], v[56:59]
	v_mfma_f32_16x16x32_bf16 v[44:47], v[84:87], v[176:179], v[44:47]
	v_mfma_f32_16x16x32_bf16 v[40:43], v[108:111], v[176:179], v[40:43]
	v_mfma_f32_16x16x32_bf16 v[28:31], v[84:87], v[186:189], v[28:31]
	v_mfma_f32_16x16x32_bf16 v[24:27], v[108:111], v[186:189], v[24:27]
	v_mfma_f32_16x16x32_bf16 v[12:15], v[84:87], v[194:197], v[12:15]
	v_mfma_f32_16x16x32_bf16 v[8:11], v[108:111], v[194:197], v[8:11]
	v_mfma_f32_16x16x32_bf16 v[52:55], v[120:123], v[164:167], v[52:55]
	v_mfma_f32_16x16x32_bf16 v[48:51], v[156:159], v[164:167], v[48:51]
	v_mfma_f32_16x16x32_bf16 v[36:39], v[120:123], v[172:175], v[36:39]
	v_mfma_f32_16x16x32_bf16 v[32:35], v[156:159], v[172:175], v[32:35]
	v_mfma_f32_16x16x32_bf16 v[20:23], v[120:123], v[180:183], v[20:23]
	v_mfma_f32_16x16x32_bf16 v[16:19], v[156:159], v[180:183], v[16:19]
	v_mfma_f32_16x16x32_bf16 v[4:7], v[120:123], v[190:193], v[4:7]
	v_mfma_f32_16x16x32_bf16 v[0:3], v[156:159], v[190:193], v[0:3]
	v_mfma_f32_16x16x32_bf16 v[52:55], v[140:143], v[168:171], v[52:55]
	v_mfma_f32_16x16x32_bf16 v[48:51], v[160:163], v[168:171], v[48:51]
	v_mfma_f32_16x16x32_bf16 v[36:39], v[140:143], v[176:179], v[36:39]
	v_mfma_f32_16x16x32_bf16 v[32:35], v[160:163], v[176:179], v[32:35]
	v_mfma_f32_16x16x32_bf16 v[20:23], v[140:143], v[186:189], v[20:23]
	v_mfma_f32_16x16x32_bf16 v[16:19], v[160:163], v[186:189], v[16:19]
	v_mfma_f32_16x16x32_bf16 v[4:7], v[140:143], v[194:197], v[4:7]
	v_mfma_f32_16x16x32_bf16 v[0:3], v[160:163], v[194:197], v[0:3]
	s_barrier
	s_add_i32 s90, s90, 2
	s_add_u32 s83, s83, 0x100
	s_addc_u32 s86, s86, 0
	s_add_u32 s88, s88, 0x100
	s_addc_u32 s89, s89, 0
	s_add_u32 s54, s54, 0x100
	s_addc_u32 s55, s55, 0
	s_cmp_gt_u32 s90, 29
	s_cbranch_scc0 .LBB0_2043
	s_and_b64 vcc, exec, s[42:43]
	s_cbranch_vccz .LBB0_2046
	s_barrier

.LBB0_2148:
	s_add_u32 s20, s56, 0x100
	s_addc_u32 s21, s57, 0
	s_waitcnt lgkmcnt(0)
	s_add_u32 s48, s54, 0x100
	s_addc_u32 s49, s55, 0
	s_barrier
	s_waitcnt lgkmcnt(0)
	v_mfma_f32_16x16x32_bf16 v[32:35], v[16:19], v[72:75], 0
	v_mfma_f32_16x16x32_bf16 v[36:39], v[24:27], v[72:75], 0
	v_mfma_f32_16x16x32_bf16 v[40:43], v[16:19], v[84:87], 0
	v_mfma_f32_16x16x32_bf16 v[44:47], v[24:27], v[84:87], 0
	v_mfma_f32_16x16x32_bf16 v[48:51], v[16:19], v[88:91], 0
	v_mfma_f32_16x16x32_bf16 v[52:55], v[24:27], v[88:91], 0
	v_mfma_f32_16x16x32_bf16 v[56:59], v[16:19], v[68:71], 0
	v_mfma_f32_16x16x32_bf16 v[60:63], v[24:27], v[68:71], 0
	v_mfma_f32_16x16x32_bf16 v[32:35], v[20:23], v[76:79], v[32:35]
	v_mfma_f32_16x16x32_bf16 v[36:39], v[28:31], v[76:79], v[36:39]
	v_mfma_f32_16x16x32_bf16 v[40:43], v[20:23], v[92:95], v[40:43]
	v_mfma_f32_16x16x32_bf16 v[44:47], v[28:31], v[92:95], v[44:47]
	v_mfma_f32_16x16x32_bf16 v[48:51], v[20:23], v[96:99], v[48:51]
	v_mfma_f32_16x16x32_bf16 v[52:55], v[28:31], v[96:99], v[52:55]
	v_mfma_f32_16x16x32_bf16 v[56:59], v[20:23], v[80:83], v[56:59]
	v_mfma_f32_16x16x32_bf16 v[60:63], v[28:31], v[80:83], v[60:63]
	v_mfma_f32_16x16x32_bf16 v[64:67], v[0:3], v[72:75], 0
	v_mfma_f32_16x16x32_bf16 v[72:75], v[8:11], v[72:75], 0
	v_mfma_f32_16x16x32_bf16 v[64:67], v[4:7], v[76:79], v[64:67]
	v_mfma_f32_16x16x32_bf16 v[72:75], v[12:15], v[76:79], v[72:75]
	v_mfma_f32_16x16x32_bf16 v[76:79], v[0:3], v[84:87], 0
	v_mfma_f32_16x16x32_bf16 v[84:87], v[8:11], v[84:87], 0
	v_mfma_f32_16x16x32_bf16 v[76:79], v[4:7], v[92:95], v[76:79]
	v_mfma_f32_16x16x32_bf16 v[84:87], v[12:15], v[92:95], v[84:87]
	v_mfma_f32_16x16x32_bf16 v[92:95], v[0:3], v[88:91], 0
	v_mfma_f32_16x16x32_bf16 v[88:91], v[8:11], v[88:91], 0
	v_mfma_f32_16x16x32_bf16 v[128:131], v[12:15], v[96:99], v[88:91]
	v_mfma_f32_16x16x32_bf16 v[88:91], v[0:3], v[68:71], 0
	v_mfma_f32_16x16x32_bf16 v[68:71], v[8:11], v[68:71], 0
	v_mfma_f32_16x16x32_bf16 v[92:95], v[4:7], v[96:99], v[92:95]
	v_mfma_f32_16x16x32_bf16 v[132:135], v[4:7], v[80:83], v[88:91]
	v_mfma_f32_16x16x32_bf16 v[136:139], v[12:15], v[80:83], v[68:71]
	s_barrier
	s_mov_b32 m0, s51
	ds_read_b128 v[108:111], v150 offset:16384
	ds_read_b128 v[112:115], v150 offset:17408
	ds_read_b128 v[100:103], v150 offset:18432
	ds_read_b128 v[104:107], v150 offset:19456
	ds_read_b128 v[88:91], v150 offset:20480
	ds_read_b128 v[96:99], v150 offset:21504
	ds_read_b128 v[68:71], v150 offset:22528
	ds_read_b128 v[80:83], v150 offset:23552
	s_nop 0
	global_load_lds_dwordx4 v144, s[48:49]
	s_mov_b32 m0, s53
	s_nop 0
	global_load_lds_dwordx4 v146, s[48:49]
	s_add_u32 s48, s54, 0x80100
	s_addc_u32 s49, s55, 0
	s_mov_b32 m0, s65
	s_and_b64 vcc, exec, s[46:47]
	global_load_lds_dwordx4 v144, s[48:49]
	s_mov_b32 m0, s66
	s_nop 0
	global_load_lds_dwordx4 v146, s[48:49]
	s_mov_b32 m0, s27
	s_mov_b64 s[48:49], -1
	global_load_lds_dwordx4 v143, s[20:21]
	s_mov_b32 m0, s67
	s_nop 0
	global_load_lds_dwordx4 v145, s[20:21]
	s_cbranch_vccz .LBB0_2150
	s_waitcnt vmcnt(8)
	s_mov_b64 s[48:49], 0

.LBB0_2152:
	s_ashr_i32 s7, s6, 31
	s_lshl_b64 s[20:21], s[6:7], 20
	s_add_u32 s46, s14, s20
	s_addc_u32 s47, s15, s21
	s_ashr_i32 s43, s42, 31
	s_lshl_b64 s[20:21], s[42:43], 20
	s_add_u32 s48, s24, s20
	s_addc_u32 s49, s25, s21
	s_add_u32 s58, s56, 0x180
	s_addc_u32 s59, s57, 0
	s_waitcnt lgkmcnt(0)
	s_and_b64 s[20:21], s[44:45], exec
	s_cselect_b32 s20, s49, s55
	s_cselect_b32 s21, s48, s54
	s_cselect_b32 s43, s47, s57
	s_cselect_b32 s79, s46, s56
	s_add_u32 s60, s54, 0x180
	s_addc_u32 s61, s55, 0
	s_barrier
	s_waitcnt lgkmcnt(0)
	v_mfma_f32_16x16x32_bf16 v[116:119], v[16:19], v[108:111], 0
	v_mfma_f32_16x16x32_bf16 v[154:157], v[20:23], v[112:115], v[116:119]
	v_mfma_f32_16x16x32_bf16 v[116:119], v[24:27], v[108:111], 0
	v_mfma_f32_16x16x32_bf16 v[158:161], v[28:31], v[112:115], v[116:119]
	v_mfma_f32_16x16x32_bf16 v[116:119], v[16:19], v[100:103], 0
	v_mfma_f32_16x16x32_bf16 v[162:165], v[20:23], v[104:107], v[116:119]
	v_mfma_f32_16x16x32_bf16 v[116:119], v[24:27], v[100:103], 0
	v_mfma_f32_16x16x32_bf16 v[166:169], v[28:31], v[104:107], v[116:119]
	v_mfma_f32_16x16x32_bf16 v[116:119], v[16:19], v[88:91], 0
	v_mfma_f32_16x16x32_bf16 v[16:19], v[16:19], v[68:71], 0
	v_mfma_f32_16x16x32_bf16 v[170:173], v[20:23], v[96:99], v[116:119]
	v_mfma_f32_16x16x32_bf16 v[116:119], v[24:27], v[88:91], 0
	v_mfma_f32_16x16x32_bf16 v[20:23], v[20:23], v[80:83], v[16:19]
	v_mfma_f32_16x16x32_bf16 v[16:19], v[24:27], v[68:71], 0
	v_mfma_f32_16x16x32_bf16 v[174:177], v[28:31], v[96:99], v[116:119]
	v_mfma_f32_16x16x32_bf16 v[28:31], v[28:31], v[80:83], v[16:19]
	v_mfma_f32_16x16x32_bf16 v[16:19], v[0:3], v[108:111], 0
	v_mfma_f32_16x16x32_bf16 v[178:181], v[4:7], v[112:115], v[16:19]
	v_mfma_f32_16x16x32_bf16 v[16:19], v[8:11], v[108:111], 0
	v_mfma_f32_16x16x32_bf16 v[182:185], v[12:15], v[112:115], v[16:19]
	v_mfma_f32_16x16x32_bf16 v[16:19], v[0:3], v[100:103], 0
	v_mfma_f32_16x16x32_bf16 v[186:189], v[4:7], v[104:107], v[16:19]
	v_mfma_f32_16x16x32_bf16 v[16:19], v[8:11], v[100:103], 0
	v_mfma_f32_16x16x32_bf16 v[190:193], v[12:15], v[104:107], v[16:19]
	v_mfma_f32_16x16x32_bf16 v[16:19], v[0:3], v[88:91], 0
	v_mfma_f32_16x16x32_bf16 v[0:3], v[0:3], v[68:71], 0
	v_mfma_f32_16x16x32_bf16 v[194:197], v[4:7], v[96:99], v[16:19]
	v_mfma_f32_16x16x32_bf16 v[16:19], v[8:11], v[88:91], 0
	v_mfma_f32_16x16x32_bf16 v[4:7], v[4:7], v[80:83], v[0:3]
	v_mfma_f32_16x16x32_bf16 v[0:3], v[8:11], v[68:71], 0
	v_mfma_f32_16x16x32_bf16 v[198:201], v[12:15], v[96:99], v[16:19]
	v_mfma_f32_16x16x32_bf16 v[202:205], v[12:15], v[80:83], v[0:3]
	s_barrier
	v_add_u32_e32 v152, s76, v147
	v_add_u32_e32 v153, s77, v147
	s_nop 1
	ds_read_b128 v[0:3], v152
	ds_read_b128 v[8:11], v152 offset:1024
	ds_read_b128 v[12:15], v152 offset:2048
	ds_read_b128 v[206:209], v152 offset:3072
	ds_read_b128 v[210:213], v153
	ds_read_b128 v[214:217], v153 offset:1024
	ds_read_b128 v[218:221], v153 offset:2048
	ds_read_b128 v[222:225], v153 offset:3072
	s_add_u32 s62, s56, 0x80100
	s_addc_u32 s63, s57, 0
	s_mov_b32 m0, s68
	ds_read_b128 v[16:19], v150 offset:32768
	ds_read_b128 v[24:27], v150 offset:33792
	ds_read_b128 v[100:103], v150 offset:34816
	ds_read_b128 v[226:229], v150 offset:35840
	ds_read_b128 v[230:233], v150 offset:36864
	ds_read_b128 v[234:237], v150 offset:37888
	ds_read_b128 v[238:241], v150 offset:38912
	ds_read_b128 v[242:245], v150 offset:39936
	s_nop 0
	global_load_lds_dwordx4 v143, s[62:63]
	s_mov_b32 m0, s69
	s_nop 0
	global_load_lds_dwordx4 v145, s[62:63]
	s_waitcnt vmcnt(8)
	s_waitcnt lgkmcnt(0)
	s_barrier
	s_waitcnt lgkmcnt(0)
	v_mfma_f32_16x16x32_bf16 v[32:35], v[0:3], v[16:19], v[32:35]
	v_mfma_f32_16x16x32_bf16 v[120:123], v[8:11], v[24:27], v[32:35]
	v_mfma_f32_16x16x32_bf16 v[32:35], v[12:15], v[16:19], v[36:39]
	v_mfma_f32_16x16x32_bf16 v[112:115], v[206:209], v[24:27], v[32:35]
	v_mfma_f32_16x16x32_bf16 v[32:35], v[0:3], v[100:103], v[40:43]
	v_mfma_f32_16x16x32_bf16 v[104:107], v[8:11], v[226:229], v[32:35]
	v_mfma_f32_16x16x32_bf16 v[32:35], v[12:15], v[100:103], v[44:47]
	v_mfma_f32_16x16x32_bf16 v[96:99], v[206:209], v[226:229], v[32:35]
	v_mfma_f32_16x16x32_bf16 v[32:35], v[0:3], v[230:233], v[48:51]
	v_mfma_f32_16x16x32_bf16 v[88:91], v[8:11], v[234:237], v[32:35]
	v_mfma_f32_16x16x32_bf16 v[32:35], v[12:15], v[230:233], v[52:55]
	v_mfma_f32_16x16x32_bf16 v[80:83], v[206:209], v[234:237], v[32:35]
	v_mfma_f32_16x16x32_bf16 v[32:35], v[0:3], v[238:241], v[56:59]
	v_mfma_f32_16x16x32_bf16 v[68:71], v[8:11], v[242:245], v[32:35]
	v_mfma_f32_16x16x32_bf16 v[32:35], v[12:15], v[238:241], v[60:63]
	v_mfma_f32_16x16x32_bf16 v[52:55], v[206:209], v[242:245], v[32:35]
	v_mfma_f32_16x16x32_bf16 v[32:35], v[210:213], v[16:19], v[64:67]
	v_mfma_f32_16x16x32_bf16 v[16:19], v[218:221], v[16:19], v[72:75]
	v_mfma_f32_16x16x32_bf16 v[116:119], v[222:225], v[24:27], v[16:19]
	v_mfma_f32_16x16x32_bf16 v[16:19], v[210:213], v[100:103], v[76:79]
	v_mfma_f32_16x16x32_bf16 v[108:111], v[214:217], v[226:229], v[16:19]
	v_mfma_f32_16x16x32_bf16 v[16:19], v[218:221], v[100:103], v[84:87]
	v_mfma_f32_16x16x32_bf16 v[100:103], v[222:225], v[226:229], v[16:19]
	v_mfma_f32_16x16x32_bf16 v[16:19], v[210:213], v[230:233], v[92:95]
	v_mfma_f32_16x16x32_bf16 v[92:95], v[214:217], v[234:237], v[16:19]
	v_mfma_f32_16x16x32_bf16 v[16:19], v[218:221], v[230:233], v[128:131]
	v_mfma_f32_16x16x32_bf16 v[84:87], v[222:225], v[234:237], v[16:19]
	v_mfma_f32_16x16x32_bf16 v[16:19], v[210:213], v[238:241], v[132:135]
	v_mfma_f32_16x16x32_bf16 v[76:79], v[214:217], v[242:245], v[16:19]
	v_mfma_f32_16x16x32_bf16 v[16:19], v[218:221], v[238:241], v[136:139]
	v_mfma_f32_16x16x32_bf16 v[124:127], v[214:217], v[24:27], v[32:35]
	v_mfma_f32_16x16x32_bf16 v[60:63], v[222:225], v[242:245], v[16:19]
	s_barrier
	s_add_i32 s80, s76, s26
	s_mov_b32 m0, s80
	s_add_i32 s86, s80, 0x2000
	ds_read_b128 v[36:39], v150 offset:49152
	ds_read_b128 v[44:47], v150 offset:50176
	ds_read_b128 v[128:131], v150 offset:51200
	ds_read_b128 v[132:135], v150 offset:52224
	ds_read_b128 v[136:139], v150 offset:53248
	ds_read_b128 v[226:229], v150 offset:54272
	ds_read_b128 v[230:233], v150 offset:55296
	ds_read_b128 v[234:237], v150 offset:56320
	s_nop 0
	global_load_lds_dwordx4 v144, s[60:61]
	s_mov_b32 m0, s86
	s_nop 0
	global_load_lds_dwordx4 v146, s[60:61]
	s_add_u32 s60, s54, 0x80180
	s_addc_u32 s61, s55, 0
	s_add_i32 s89, s77, s26
	s_mov_b32 m0, s89
	s_add_i32 s90, s89, 0x2000
	s_nop 0
	global_load_lds_dwordx4 v144, s[60:61]
	s_mov_b32 m0, s90
	s_nop 0
	global_load_lds_dwordx4 v146, s[60:61]
	s_mov_b32 m0, s70
	s_nop 0
	global_load_lds_dwordx4 v143, s[58:59]
	s_mov_b32 m0, s71
	s_nop 0
	global_load_lds_dwordx4 v145, s[58:59]
	s_waitcnt vmcnt(8)
	s_waitcnt lgkmcnt(0)
	s_barrier
	s_waitcnt lgkmcnt(0)
	v_mfma_f32_16x16x32_bf16 v[16:19], v[0:3], v[36:39], v[154:157]
	v_mfma_f32_16x16x32_bf16 v[64:67], v[8:11], v[44:47], v[16:19]
	v_mfma_f32_16x16x32_bf16 v[16:19], v[12:15], v[36:39], v[158:161]
	v_mfma_f32_16x16x32_bf16 v[48:51], v[206:209], v[44:47], v[16:19]
	v_mfma_f32_16x16x32_bf16 v[16:19], v[0:3], v[128:131], v[162:165]
	v_mfma_f32_16x16x32_bf16 v[40:43], v[8:11], v[132:135], v[16:19]
	v_mfma_f32_16x16x32_bf16 v[16:19], v[12:15], v[128:131], v[166:169]
	v_mfma_f32_16x16x32_bf16 v[32:35], v[206:209], v[132:135], v[16:19]
	v_mfma_f32_16x16x32_bf16 v[16:19], v[0:3], v[136:139], v[170:173]
	v_mfma_f32_16x16x32_bf16 v[0:3], v[0:3], v[230:233], v[20:23]
	v_mfma_f32_16x16x32_bf16 v[24:27], v[8:11], v[226:229], v[16:19]
	v_mfma_f32_16x16x32_bf16 v[16:19], v[12:15], v[136:139], v[174:177]
	v_mfma_f32_16x16x32_bf16 v[8:11], v[8:11], v[234:237], v[0:3]
	v_mfma_f32_16x16x32_bf16 v[0:3], v[12:15], v[230:233], v[28:31]
	v_mfma_f32_16x16x32_bf16 v[16:19], v[206:209], v[226:229], v[16:19]
	v_mfma_f32_16x16x32_bf16 v[0:3], v[206:209], v[234:237], v[0:3]
	v_mfma_f32_16x16x32_bf16 v[12:15], v[210:213], v[36:39], v[178:181]
	v_mfma_f32_16x16x32_bf16 v[72:75], v[214:217], v[44:47], v[12:15]
	v_mfma_f32_16x16x32_bf16 v[12:15], v[218:221], v[36:39], v[182:185]
	v_mfma_f32_16x16x32_bf16 v[56:59], v[222:225], v[44:47], v[12:15]
	v_mfma_f32_16x16x32_bf16 v[12:15], v[210:213], v[128:131], v[186:189]
	v_mfma_f32_16x16x32_bf16 v[44:47], v[214:217], v[132:135], v[12:15]
	v_mfma_f32_16x16x32_bf16 v[12:15], v[218:221], v[128:131], v[190:193]
	v_mfma_f32_16x16x32_bf16 v[36:39], v[222:225], v[132:135], v[12:15]
	v_mfma_f32_16x16x32_bf16 v[12:15], v[210:213], v[136:139], v[194:197]
	v_mfma_f32_16x16x32_bf16 v[28:31], v[214:217], v[226:229], v[12:15]
	v_mfma_f32_16x16x32_bf16 v[12:15], v[218:221], v[136:139], v[198:201]
	v_mfma_f32_16x16x32_bf16 v[4:7], v[210:213], v[230:233], v[4:7]
	v_mfma_f32_16x16x32_bf16 v[20:23], v[222:225], v[226:229], v[12:15]
	v_mfma_f32_16x16x32_bf16 v[12:15], v[214:217], v[234:237], v[4:7]
	v_mfma_f32_16x16x32_bf16 v[4:7], v[218:221], v[230:233], v[202:205]
	v_mfma_f32_16x16x32_bf16 v[4:7], v[222:225], v[234:237], v[4:7]
	s_barrier
	s_add_u32 s62, s56, 0x100
	s_addc_u32 s63, s57, 0
	s_add_u32 s91, s54, 0x200
	s_addc_u32 s92, s55, 0
	s_mov_b32 s93, 0
.LBB0_2153:
	s_add_u32 s54, s62, 0x100
	s_addc_u32 s55, s63, 0
	s_cmp_eq_u32 s93, 28
	s_cselect_b32 s60, s79, s54
	s_cselect_b32 s61, s43, s55
	s_cselect_b32 s58, s21, s91
	s_cselect_b32 s59, s20, s92
	s_add_u32 s56, s60, 0x80
	s_addc_u32 s57, s61, 0
	s_add_i32 s94, 0, 0x10000
	s_add_i32 s95, 0, 0x14000
	v_add_u32_e32 v154, s94, v147
	v_add_u32_e32 v170, s95, v147
	ds_read_b128 v[128:131], v154
	ds_read_b128 v[132:135], v154 offset:1024
	ds_read_b128 v[136:139], v154 offset:2048
	ds_read_b128 v[154:157], v154 offset:3072
	ds_read_b128 v[158:161], v170
	ds_read_b128 v[162:165], v170 offset:1024
	ds_read_b128 v[166:169], v170 offset:2048
	ds_read_b128 v[170:173], v170 offset:3072
	s_add_u32 s62, s62, 0x80080
	s_addc_u32 s63, s63, 0
	s_mov_b32 m0, s1
	ds_read_b128 v[174:177], v150
	ds_read_b128 v[178:181], v150 offset:1024
	ds_read_b128 v[182:185], v150 offset:2048
	ds_read_b128 v[186:189], v150 offset:3072
	ds_read_b128 v[190:193], v150 offset:4096
	ds_read_b128 v[194:197], v150 offset:5120
	ds_read_b128 v[198:201], v150 offset:6144
	ds_read_b128 v[202:205], v150 offset:7168
	s_nop 0
	global_load_lds_dwordx4 v143, s[62:63]
	s_mov_b32 m0, s12
	s_nop 0
	global_load_lds_dwordx4 v145, s[62:63]
	s_waitcnt vmcnt(8)
	s_waitcnt lgkmcnt(0)
	s_barrier
	s_waitcnt lgkmcnt(0)
	v_mfma_f32_16x16x32_bf16 v[120:123], v[128:131], v[174:177], v[120:123]
	v_mfma_f32_16x16x32_bf16 v[112:115], v[136:139], v[174:177], v[112:115]
	v_mfma_f32_16x16x32_bf16 v[104:107], v[128:131], v[182:185], v[104:107]
	v_mfma_f32_16x16x32_bf16 v[96:99], v[136:139], v[182:185], v[96:99]
	v_mfma_f32_16x16x32_bf16 v[88:91], v[128:131], v[190:193], v[88:91]
	v_mfma_f32_16x16x32_bf16 v[80:83], v[136:139], v[190:193], v[80:83]
	v_mfma_f32_16x16x32_bf16 v[68:71], v[128:131], v[198:201], v[68:71]
	v_mfma_f32_16x16x32_bf16 v[52:55], v[136:139], v[198:201], v[52:55]
	v_mfma_f32_16x16x32_bf16 v[120:123], v[132:135], v[178:181], v[120:123]
	v_mfma_f32_16x16x32_bf16 v[112:115], v[154:157], v[178:181], v[112:115]
	v_mfma_f32_16x16x32_bf16 v[104:107], v[132:135], v[186:189], v[104:107]
	v_mfma_f32_16x16x32_bf16 v[96:99], v[154:157], v[186:189], v[96:99]
	v_mfma_f32_16x16x32_bf16 v[88:91], v[132:135], v[194:197], v[88:91]
	v_mfma_f32_16x16x32_bf16 v[80:83], v[154:157], v[194:197], v[80:83]
	v_mfma_f32_16x16x32_bf16 v[68:71], v[132:135], v[202:205], v[68:71]
	v_mfma_f32_16x16x32_bf16 v[52:55], v[154:157], v[202:205], v[52:55]
	v_mfma_f32_16x16x32_bf16 v[124:127], v[158:161], v[174:177], v[124:127]
	v_mfma_f32_16x16x32_bf16 v[116:119], v[166:169], v[174:177], v[116:119]
	v_mfma_f32_16x16x32_bf16 v[108:111], v[158:161], v[182:185], v[108:111]
	v_mfma_f32_16x16x32_bf16 v[100:103], v[166:169], v[182:185], v[100:103]
	v_mfma_f32_16x16x32_bf16 v[92:95], v[158:161], v[190:193], v[92:95]
	v_mfma_f32_16x16x32_bf16 v[84:87], v[166:169], v[190:193], v[84:87]
	v_mfma_f32_16x16x32_bf16 v[76:79], v[158:161], v[198:201], v[76:79]
	v_mfma_f32_16x16x32_bf16 v[60:63], v[166:169], v[198:201], v[60:63]
	v_mfma_f32_16x16x32_bf16 v[124:127], v[162:165], v[178:181], v[124:127]
	v_mfma_f32_16x16x32_bf16 v[116:119], v[170:173], v[178:181], v[116:119]
	v_mfma_f32_16x16x32_bf16 v[108:111], v[162:165], v[186:189], v[108:111]
	v_mfma_f32_16x16x32_bf16 v[100:103], v[170:173], v[186:189], v[100:103]
	v_mfma_f32_16x16x32_bf16 v[92:95], v[162:165], v[194:197], v[92:95]
	v_mfma_f32_16x16x32_bf16 v[84:87], v[170:173], v[194:197], v[84:87]
	v_mfma_f32_16x16x32_bf16 v[76:79], v[162:165], v[202:205], v[76:79]
	v_mfma_f32_16x16x32_bf16 v[60:63], v[170:173], v[202:205], v[60:63]
	s_barrier
	s_add_i32 s62, s94, s26
	s_mov_b32 m0, s62
	ds_read_b128 v[174:177], v150 offset:16384
	ds_read_b128 v[178:181], v150 offset:17408
	ds_read_b128 v[182:185], v150 offset:18432
	ds_read_b128 v[186:189], v150 offset:19456
	ds_read_b128 v[190:193], v150 offset:20480
	ds_read_b128 v[194:197], v150 offset:21504
	ds_read_b128 v[198:201], v150 offset:22528
	ds_read_b128 v[202:205], v150 offset:23552
	s_nop 0
	global_load_lds_dwordx4 v144, s[58:59]
	s_add_i32 m0, s62, 0x2000
	s_add_u32 s62, s58, 0x80000
	s_addc_u32 s63, s59, 0
	s_add_i32 s94, s95, s26
	s_nop 0
	global_load_lds_dwordx4 v146, s[58:59]
	s_mov_b32 m0, s94
	s_nop 0
	global_load_lds_dwordx4 v144, s[62:63]
	s_add_i32 m0, s94, 0x2000
	s_nop 0
	global_load_lds_dwordx4 v146, s[62:63]
	s_mov_b32 m0, s27
	s_nop 0
	global_load_lds_dwordx4 v143, s[60:61]
	s_mov_b32 m0, s67
	s_nop 0
	global_load_lds_dwordx4 v145, s[60:61]
	s_waitcnt vmcnt(8)
	s_waitcnt lgkmcnt(0)
	s_barrier
	s_waitcnt lgkmcnt(0)
	v_mfma_f32_16x16x32_bf16 v[64:67], v[128:131], v[174:177], v[64:67]
	v_mfma_f32_16x16x32_bf16 v[48:51], v[136:139], v[174:177], v[48:51]
	v_mfma_f32_16x16x32_bf16 v[40:43], v[128:131], v[182:185], v[40:43]
	v_mfma_f32_16x16x32_bf16 v[32:35], v[136:139], v[182:185], v[32:35]
	v_mfma_f32_16x16x32_bf16 v[24:27], v[128:131], v[190:193], v[24:27]
	v_mfma_f32_16x16x32_bf16 v[16:19], v[136:139], v[190:193], v[16:19]
	v_mfma_f32_16x16x32_bf16 v[8:11], v[128:131], v[198:201], v[8:11]
	v_mfma_f32_16x16x32_bf16 v[0:3], v[136:139], v[198:201], v[0:3]
	v_mfma_f32_16x16x32_bf16 v[64:67], v[132:135], v[178:181], v[64:67]
	v_mfma_f32_16x16x32_bf16 v[48:51], v[154:157], v[178:181], v[48:51]
	v_mfma_f32_16x16x32_bf16 v[40:43], v[132:135], v[186:189], v[40:43]
	v_mfma_f32_16x16x32_bf16 v[32:35], v[154:157], v[186:189], v[32:35]
	v_mfma_f32_16x16x32_bf16 v[24:27], v[132:135], v[194:197], v[24:27]
	v_mfma_f32_16x16x32_bf16 v[16:19], v[154:157], v[194:197], v[16:19]
	v_mfma_f32_16x16x32_bf16 v[8:11], v[132:135], v[202:205], v[8:11]
	v_mfma_f32_16x16x32_bf16 v[0:3], v[154:157], v[202:205], v[0:3]
	v_mfma_f32_16x16x32_bf16 v[72:75], v[158:161], v[174:177], v[72:75]
	v_mfma_f32_16x16x32_bf16 v[56:59], v[166:169], v[174:177], v[56:59]
	v_mfma_f32_16x16x32_bf16 v[44:47], v[158:161], v[182:185], v[44:47]
	v_mfma_f32_16x16x32_bf16 v[36:39], v[166:169], v[182:185], v[36:39]
	v_mfma_f32_16x16x32_bf16 v[28:31], v[158:161], v[190:193], v[28:31]
	v_mfma_f32_16x16x32_bf16 v[20:23], v[166:169], v[190:193], v[20:23]
	v_mfma_f32_16x16x32_bf16 v[12:15], v[158:161], v[198:201], v[12:15]
	v_mfma_f32_16x16x32_bf16 v[4:7], v[166:169], v[198:201], v[4:7]
	v_mfma_f32_16x16x32_bf16 v[72:75], v[162:165], v[178:181], v[72:75]
	v_mfma_f32_16x16x32_bf16 v[56:59], v[170:173], v[178:181], v[56:59]
	v_mfma_f32_16x16x32_bf16 v[44:47], v[162:165], v[186:189], v[44:47]
	v_mfma_f32_16x16x32_bf16 v[36:39], v[170:173], v[186:189], v[36:39]
	v_mfma_f32_16x16x32_bf16 v[28:31], v[162:165], v[194:197], v[28:31]
	v_mfma_f32_16x16x32_bf16 v[20:23], v[170:173], v[194:197], v[20:23]
	v_mfma_f32_16x16x32_bf16 v[12:15], v[162:165], v[202:205], v[12:15]
	v_mfma_f32_16x16x32_bf16 v[4:7], v[170:173], v[202:205], v[4:7]
	s_barrier
	ds_read_b128 v[128:131], v152
	ds_read_b128 v[132:135], v152 offset:1024
	ds_read_b128 v[136:139], v152 offset:2048
	ds_read_b128 v[154:157], v152 offset:3072
	ds_read_b128 v[158:161], v153
	ds_read_b128 v[162:165], v153 offset:1024
	ds_read_b128 v[166:169], v153 offset:2048
	ds_read_b128 v[170:173], v153 offset:3072
	s_add_u32 s60, s60, 0x80000
	s_addc_u32 s61, s61, 0
	s_mov_b32 m0, s68
	ds_read_b128 v[174:177], v150 offset:32768
	ds_read_b128 v[178:181], v150 offset:33792
	ds_read_b128 v[182:185], v150 offset:34816
	ds_read_b128 v[186:189], v150 offset:35840
	ds_read_b128 v[190:193], v150 offset:36864
	ds_read_b128 v[194:197], v150 offset:37888
	ds_read_b128 v[198:201], v150 offset:38912
	ds_read_b128 v[202:205], v150 offset:39936
	s_nop 0
	global_load_lds_dwordx4 v143, s[60:61]
	s_mov_b32 m0, s69
	s_nop 0
	global_load_lds_dwordx4 v145, s[60:61]
	s_waitcnt vmcnt(8)
	s_waitcnt lgkmcnt(0)
	s_barrier
	s_waitcnt lgkmcnt(0)
	v_mfma_f32_16x16x32_bf16 v[120:123], v[128:131], v[174:177], v[120:123]
	v_mfma_f32_16x16x32_bf16 v[112:115], v[136:139], v[174:177], v[112:115]
	v_mfma_f32_16x16x32_bf16 v[104:107], v[128:131], v[182:185], v[104:107]
	v_mfma_f32_16x16x32_bf16 v[96:99], v[136:139], v[182:185], v[96:99]
	v_mfma_f32_16x16x32_bf16 v[88:91], v[128:131], v[190:193], v[88:91]
	v_mfma_f32_16x16x32_bf16 v[80:83], v[136:139], v[190:193], v[80:83]
	v_mfma_f32_16x16x32_bf16 v[68:71], v[128:131], v[198:201], v[68:71]
	v_mfma_f32_16x16x32_bf16 v[52:55], v[136:139], v[198:201], v[52:55]
	v_mfma_f32_16x16x32_bf16 v[120:123], v[132:135], v[178:181], v[120:123]
	v_mfma_f32_16x16x32_bf16 v[112:115], v[154:157], v[178:181], v[112:115]
	v_mfma_f32_16x16x32_bf16 v[104:107], v[132:135], v[186:189], v[104:107]
	v_mfma_f32_16x16x32_bf16 v[96:99], v[154:157], v[186:189], v[96:99]
	v_mfma_f32_16x16x32_bf16 v[88:91], v[132:135], v[194:197], v[88:91]
	v_mfma_f32_16x16x32_bf16 v[80:83], v[154:157], v[194:197], v[80:83]
	v_mfma_f32_16x16x32_bf16 v[68:71], v[132:135], v[202:205], v[68:71]
	v_mfma_f32_16x16x32_bf16 v[52:55], v[154:157], v[202:205], v[52:55]
	v_mfma_f32_16x16x32_bf16 v[124:127], v[158:161], v[174:177], v[124:127]
	v_mfma_f32_16x16x32_bf16 v[116:119], v[166:169], v[174:177], v[116:119]
	v_mfma_f32_16x16x32_bf16 v[108:111], v[158:161], v[182:185], v[108:111]
	v_mfma_f32_16x16x32_bf16 v[100:103], v[166:169], v[182:185], v[100:103]
	v_mfma_f32_16x16x32_bf16 v[92:95], v[158:161], v[190:193], v[92:95]
	v_mfma_f32_16x16x32_bf16 v[84:87], v[166:169], v[190:193], v[84:87]
	v_mfma_f32_16x16x32_bf16 v[76:79], v[158:161], v[198:201], v[76:79]
	v_mfma_f32_16x16x32_bf16 v[60:63], v[166:169], v[198:201], v[60:63]
	v_mfma_f32_16x16x32_bf16 v[124:127], v[162:165], v[178:181], v[124:127]
	v_mfma_f32_16x16x32_bf16 v[116:119], v[170:173], v[178:181], v[116:119]
	v_mfma_f32_16x16x32_bf16 v[108:111], v[162:165], v[186:189], v[108:111]
	v_mfma_f32_16x16x32_bf16 v[100:103], v[170:173], v[186:189], v[100:103]
	v_mfma_f32_16x16x32_bf16 v[92:95], v[162:165], v[194:197], v[92:95]
	v_mfma_f32_16x16x32_bf16 v[84:87], v[170:173], v[194:197], v[84:87]
	v_mfma_f32_16x16x32_bf16 v[76:79], v[162:165], v[202:205], v[76:79]
	v_mfma_f32_16x16x32_bf16 v[60:63], v[170:173], v[202:205], v[60:63]
	s_barrier
	s_add_u32 s60, s58, 0x80
	s_mov_b32 m0, s80
	s_addc_u32 s61, s59, 0
	ds_read_b128 v[174:177], v150 offset:49152
	ds_read_b128 v[178:181], v150 offset:50176
	ds_read_b128 v[182:185], v150 offset:51200
	ds_read_b128 v[186:189], v150 offset:52224
	ds_read_b128 v[190:193], v150 offset:53248
	ds_read_b128 v[194:197], v150 offset:54272
	ds_read_b128 v[198:201], v150 offset:55296
	ds_read_b128 v[202:205], v150 offset:56320
	s_add_u32 s58, s58, 0x80080
	global_load_lds_dwordx4 v144, s[60:61]
	s_mov_b32 m0, s86
	s_addc_u32 s59, s59, 0
	global_load_lds_dwordx4 v146, s[60:61]
	s_mov_b32 m0, s89
	s_nop 0
	global_load_lds_dwordx4 v144, s[58:59]
	s_mov_b32 m0, s90
	s_nop 0
	global_load_lds_dwordx4 v146, s[58:59]
	s_mov_b32 m0, s70
	s_nop 0
	global_load_lds_dwordx4 v143, s[56:57]
	s_mov_b32 m0, s71
	s_nop 0
	global_load_lds_dwordx4 v145, s[56:57]
	s_waitcnt vmcnt(8)
	s_waitcnt lgkmcnt(0)
	s_barrier
	s_waitcnt lgkmcnt(0)
	v_mfma_f32_16x16x32_bf16 v[64:67], v[128:131], v[174:177], v[64:67]
	v_mfma_f32_16x16x32_bf16 v[48:51], v[136:139], v[174:177], v[48:51]
	v_mfma_f32_16x16x32_bf16 v[40:43], v[128:131], v[182:185], v[40:43]
	v_mfma_f32_16x16x32_bf16 v[32:35], v[136:139], v[182:185], v[32:35]
	v_mfma_f32_16x16x32_bf16 v[24:27], v[128:131], v[190:193], v[24:27]
	v_mfma_f32_16x16x32_bf16 v[16:19], v[136:139], v[190:193], v[16:19]
	v_mfma_f32_16x16x32_bf16 v[8:11], v[128:131], v[198:201], v[8:11]
	v_mfma_f32_16x16x32_bf16 v[0:3], v[136:139], v[198:201], v[0:3]
	v_mfma_f32_16x16x32_bf16 v[64:67], v[132:135], v[178:181], v[64:67]
	v_mfma_f32_16x16x32_bf16 v[48:51], v[154:157], v[178:181], v[48:51]
	v_mfma_f32_16x16x32_bf16 v[40:43], v[132:135], v[186:189], v[40:43]
	v_mfma_f32_16x16x32_bf16 v[32:35], v[154:157], v[186:189], v[32:35]
	v_mfma_f32_16x16x32_bf16 v[24:27], v[132:135], v[194:197], v[24:27]
	v_mfma_f32_16x16x32_bf16 v[16:19], v[154:157], v[194:197], v[16:19]
	v_mfma_f32_16x16x32_bf16 v[8:11], v[132:135], v[202:205], v[8:11]
	v_mfma_f32_16x16x32_bf16 v[0:3], v[154:157], v[202:205], v[0:3]
	v_mfma_f32_16x16x32_bf16 v[72:75], v[158:161], v[174:177], v[72:75]
	v_mfma_f32_16x16x32_bf16 v[56:59], v[166:169], v[174:177], v[56:59]
	v_mfma_f32_16x16x32_bf16 v[44:47], v[158:161], v[182:185], v[44:47]
	v_mfma_f32_16x16x32_bf16 v[36:39], v[166:169], v[182:185], v[36:39]
	v_mfma_f32_16x16x32_bf16 v[28:31], v[158:161], v[190:193], v[28:31]
	v_mfma_f32_16x16x32_bf16 v[20:23], v[166:169], v[190:193], v[20:23]
	v_mfma_f32_16x16x32_bf16 v[12:15], v[158:161], v[198:201], v[12:15]
	v_mfma_f32_16x16x32_bf16 v[4:7], v[166:169], v[198:201], v[4:7]
	v_mfma_f32_16x16x32_bf16 v[72:75], v[162:165], v[178:181], v[72:75]
	v_mfma_f32_16x16x32_bf16 v[56:59], v[170:173], v[178:181], v[56:59]
	v_mfma_f32_16x16x32_bf16 v[44:47], v[162:165], v[186:189], v[44:47]
	v_mfma_f32_16x16x32_bf16 v[36:39], v[170:173], v[186:189], v[36:39]
	v_mfma_f32_16x16x32_bf16 v[28:31], v[162:165], v[194:197], v[28:31]
	v_mfma_f32_16x16x32_bf16 v[20:23], v[170:173], v[194:197], v[20:23]
	v_mfma_f32_16x16x32_bf16 v[12:15], v[162:165], v[202:205], v[12:15]
	v_mfma_f32_16x16x32_bf16 v[4:7], v[170:173], v[202:205], v[4:7]
	s_barrier
	s_add_i32 s93, s93, 2
	s_add_u32 s91, s91, 0x100
	s_addc_u32 s92, s92, 0
	s_cmp_gt_u32 s93, 29
	s_mov_b64 s[62:63], s[54:55]
	s_cbranch_scc0 .LBB0_2153
	s_and_b64 vcc, exec, s[4:5]
	s_cbranch_vccz .LBB0_2156
	s_barrier

.LBB0_2246:
	s_add_u32 s20, s50, 0x100
	s_addc_u32 s21, s51, 0
	s_waitcnt lgkmcnt(0)
	s_add_u32 s54, s4, 0x100
	s_addc_u32 s55, s5, 0
	s_barrier
	s_waitcnt lgkmcnt(0)
	v_mfma_f32_16x16x32_bf16 v[32:35], v[16:19], v[68:71], 0
	v_mfma_f32_16x16x32_bf16 v[36:39], v[24:27], v[68:71], 0
	v_mfma_f32_16x16x32_bf16 v[40:43], v[16:19], v[84:87], 0
	v_mfma_f32_16x16x32_bf16 v[44:47], v[24:27], v[84:87], 0
	v_mfma_f32_16x16x32_bf16 v[48:51], v[16:19], v[92:95], 0
	v_mfma_f32_16x16x32_bf16 v[52:55], v[24:27], v[92:95], 0
	v_mfma_f32_16x16x32_bf16 v[56:59], v[16:19], v[76:79], 0
	v_mfma_f32_16x16x32_bf16 v[60:63], v[24:27], v[76:79], 0
	v_mfma_f32_16x16x32_bf16 v[134:137], v[20:23], v[72:75], v[32:35]
	v_mfma_f32_16x16x32_bf16 v[36:39], v[28:31], v[72:75], v[36:39]
	v_mfma_f32_16x16x32_bf16 v[40:43], v[20:23], v[88:91], v[40:43]
	v_mfma_f32_16x16x32_bf16 v[44:47], v[28:31], v[88:91], v[44:47]
	v_mfma_f32_16x16x32_bf16 v[48:51], v[20:23], v[96:99], v[48:51]
	v_mfma_f32_16x16x32_bf16 v[52:55], v[28:31], v[96:99], v[52:55]
	v_mfma_f32_16x16x32_bf16 v[56:59], v[20:23], v[80:83], v[56:59]
	v_mfma_f32_16x16x32_bf16 v[60:63], v[28:31], v[80:83], v[60:63]
	v_mfma_f32_16x16x32_bf16 v[64:67], v[0:3], v[68:71], 0
	v_mfma_f32_16x16x32_bf16 v[68:71], v[8:11], v[68:71], 0
	v_mfma_f32_16x16x32_bf16 v[64:67], v[4:7], v[72:75], v[64:67]
	v_mfma_f32_16x16x32_bf16 v[68:71], v[12:15], v[72:75], v[68:71]
	v_mfma_f32_16x16x32_bf16 v[72:75], v[0:3], v[84:87], 0
	v_mfma_f32_16x16x32_bf16 v[84:87], v[8:11], v[84:87], 0
	v_mfma_f32_16x16x32_bf16 v[72:75], v[4:7], v[88:91], v[72:75]
	v_mfma_f32_16x16x32_bf16 v[84:87], v[12:15], v[88:91], v[84:87]
	v_mfma_f32_16x16x32_bf16 v[88:91], v[0:3], v[92:95], 0
	v_mfma_f32_16x16x32_bf16 v[92:95], v[8:11], v[92:95], 0
	v_mfma_f32_16x16x32_bf16 v[88:91], v[4:7], v[96:99], v[88:91]
	v_mfma_f32_16x16x32_bf16 v[96:99], v[12:15], v[96:99], v[92:95]
	v_mfma_f32_16x16x32_bf16 v[92:95], v[0:3], v[76:79], 0
	v_mfma_f32_16x16x32_bf16 v[76:79], v[8:11], v[76:79], 0
	v_mfma_f32_16x16x32_bf16 v[108:111], v[4:7], v[80:83], v[92:95]
	v_mfma_f32_16x16x32_bf16 v[120:123], v[12:15], v[80:83], v[76:79]
	s_barrier
	s_mov_b32 m0, s56
	ds_read_b128 v[116:119], v209 offset:16384
	ds_read_b128 v[124:127], v209 offset:17408
	ds_read_b128 v[104:107], v209 offset:18432
	ds_read_b128 v[112:115], v209 offset:19456
	ds_read_b128 v[92:95], v209 offset:20480
	ds_read_b128 v[100:103], v209 offset:21504
	ds_read_b128 v[76:79], v209 offset:22528
	ds_read_b128 v[80:83], v209 offset:23552
	s_nop 0
	global_load_lds_dwordx4 v203, s[54:55]
	s_mov_b32 m0, s57
	s_nop 0
	global_load_lds_dwordx4 v205, s[54:55]
	s_add_u32 s54, s4, 0x160100
	s_addc_u32 s55, s5, 0
	s_mov_b32 m0, s58
	s_and_b64 vcc, exec, s[52:53]
	global_load_lds_dwordx4 v203, s[54:55]
	s_mov_b32 m0, s59
	s_nop 0
	global_load_lds_dwordx4 v205, s[54:55]
	s_mov_b32 m0, s27
	s_mov_b64 s[54:55], -1
	global_load_lds_dwordx4 v202, s[20:21]
	s_mov_b32 m0, s60
	s_nop 0
	global_load_lds_dwordx4 v204, s[20:21]
	s_cbranch_vccz .LBB0_2248
	s_waitcnt vmcnt(8)
	s_mov_b64 s[54:55], 0

.LBB0_2250:
	s_add_u32 s52, s50, 0x180
	s_waitcnt lgkmcnt(0)
	s_addc_u32 s53, s51, 0
	s_add_u32 s54, s4, 0x180
	s_addc_u32 s55, s5, 0
	s_barrier
	s_waitcnt lgkmcnt(0)
	v_mfma_f32_16x16x32_bf16 v[128:131], v[16:19], v[116:119], 0
	v_mfma_f32_16x16x32_bf16 v[140:143], v[20:23], v[124:127], v[128:131]
	v_mfma_f32_16x16x32_bf16 v[128:131], v[24:27], v[116:119], 0
	v_mfma_f32_16x16x32_bf16 v[156:159], v[28:31], v[124:127], v[128:131]
	v_mfma_f32_16x16x32_bf16 v[128:131], v[16:19], v[104:107], 0
	v_mfma_f32_16x16x32_bf16 v[160:163], v[20:23], v[112:115], v[128:131]
	v_mfma_f32_16x16x32_bf16 v[128:131], v[24:27], v[104:107], 0
	v_mfma_f32_16x16x32_bf16 v[164:167], v[28:31], v[112:115], v[128:131]
	v_mfma_f32_16x16x32_bf16 v[128:131], v[16:19], v[92:95], 0
	v_mfma_f32_16x16x32_bf16 v[16:19], v[16:19], v[76:79], 0
	v_mfma_f32_16x16x32_bf16 v[168:171], v[20:23], v[100:103], v[128:131]
	v_mfma_f32_16x16x32_bf16 v[16:19], v[20:23], v[80:83], v[16:19]
	v_mfma_f32_16x16x32_bf16 v[20:23], v[24:27], v[76:79], 0
	v_mfma_f32_16x16x32_bf16 v[128:131], v[24:27], v[92:95], 0
	v_mfma_f32_16x16x32_bf16 v[20:23], v[28:31], v[80:83], v[20:23]
	v_mfma_f32_16x16x32_bf16 v[172:175], v[28:31], v[100:103], v[128:131]
	v_mfma_f32_16x16x32_bf16 v[24:27], v[0:3], v[116:119], 0
	v_mfma_f32_16x16x32_bf16 v[176:179], v[4:7], v[124:127], v[24:27]
	v_mfma_f32_16x16x32_bf16 v[24:27], v[8:11], v[116:119], 0
	v_mfma_f32_16x16x32_bf16 v[180:183], v[12:15], v[124:127], v[24:27]
	v_mfma_f32_16x16x32_bf16 v[24:27], v[0:3], v[104:107], 0
	v_mfma_f32_16x16x32_bf16 v[186:189], v[4:7], v[112:115], v[24:27]
	v_mfma_f32_16x16x32_bf16 v[24:27], v[8:11], v[104:107], 0
	v_mfma_f32_16x16x32_bf16 v[190:193], v[12:15], v[112:115], v[24:27]
	v_mfma_f32_16x16x32_bf16 v[24:27], v[0:3], v[92:95], 0
	v_mfma_f32_16x16x32_bf16 v[0:3], v[0:3], v[76:79], 0
	v_mfma_f32_16x16x32_bf16 v[194:197], v[4:7], v[100:103], v[24:27]
	v_mfma_f32_16x16x32_bf16 v[24:27], v[8:11], v[92:95], 0
	v_mfma_f32_16x16x32_bf16 v[0:3], v[4:7], v[80:83], v[0:3]
	v_mfma_f32_16x16x32_bf16 v[4:7], v[8:11], v[76:79], 0
	v_mfma_f32_16x16x32_bf16 v[198:201], v[12:15], v[100:103], v[24:27]
	v_mfma_f32_16x16x32_bf16 v[212:215], v[12:15], v[80:83], v[4:7]
	s_barrier
	v_add_u32_e32 v132, s69, v206
	v_add_u32_e32 v133, s70, v206
	s_nop 1
	ds_read_b128 v[4:7], v132
	ds_read_b128 v[8:11], v132 offset:1024
	ds_read_b128 v[216:219], v132 offset:2048
	ds_read_b128 v[220:223], v132 offset:3072
	ds_read_b128 v[224:227], v133
	ds_read_b128 v[228:231], v133 offset:1024
	ds_read_b128 v[232:235], v133 offset:2048
	ds_read_b128 v[236:239], v133 offset:3072
	s_add_u32 s20, s50, 0x160100
	s_addc_u32 s21, s51, 0
	s_mov_b32 m0, s61
	ds_read_b128 v[12:15], v209 offset:32768
	ds_read_b128 v[24:27], v209 offset:33792
	ds_read_b128 v[28:31], v209 offset:34816
	ds_read_b128 v[92:95], v209 offset:35840
	ds_read_b128 v[240:243], v209 offset:36864
	ds_read_b128 v[244:247], v209 offset:37888
	ds_read_b128 v[248:251], v209 offset:38912
	ds_read_b128 v[32:35], v209 offset:39936
	s_nop 0
	global_load_lds_dwordx4 v202, s[20:21]
	s_mov_b32 m0, s62
	s_nop 0
	global_load_lds_dwordx4 v204, s[20:21]
	s_waitcnt vmcnt(8)
	s_waitcnt lgkmcnt(0)
	s_barrier
	s_waitcnt lgkmcnt(0)
	v_mfma_f32_16x16x32_bf16 v[36:39], v[216:219], v[12:15], v[36:39]
	v_mfma_f32_16x16x32_bf16 v[148:151], v[220:223], v[24:27], v[36:39]
	v_mfma_f32_16x16x32_bf16 v[36:39], v[4:7], v[28:31], v[40:43]
	v_mfma_f32_16x16x32_bf16 v[128:131], v[8:11], v[92:95], v[36:39]
	v_mfma_f32_16x16x32_bf16 v[36:39], v[216:219], v[28:31], v[44:47]
	v_mfma_f32_16x16x32_bf16 v[124:127], v[220:223], v[92:95], v[36:39]
	v_mfma_f32_16x16x32_bf16 v[36:39], v[4:7], v[240:243], v[48:51]
	v_mfma_f32_16x16x32_bf16 v[104:107], v[8:11], v[244:247], v[36:39]
	v_mfma_f32_16x16x32_bf16 v[36:39], v[216:219], v[240:243], v[52:55]
	v_mfma_f32_16x16x32_bf16 v[100:103], v[220:223], v[244:247], v[36:39]
	v_mfma_f32_16x16x32_bf16 v[36:39], v[4:7], v[248:251], v[56:59]
	v_mfma_f32_16x16x32_bf16 v[76:79], v[4:7], v[12:15], v[134:137]
	v_mfma_f32_16x16x32_bf16 v[80:83], v[8:11], v[32:35], v[36:39]
	v_mfma_f32_16x16x32_bf16 v[36:39], v[216:219], v[248:251], v[60:63]
	v_mfma_f32_16x16x32_bf16 v[152:155], v[8:11], v[24:27], v[76:79]
	v_mfma_f32_16x16x32_bf16 v[76:79], v[220:223], v[32:35], v[36:39]
	v_mfma_f32_16x16x32_bf16 v[36:39], v[224:227], v[12:15], v[64:67]
	v_mfma_f32_16x16x32_bf16 v[12:15], v[232:235], v[12:15], v[68:71]
	v_mfma_f32_16x16x32_bf16 v[136:139], v[236:239], v[24:27], v[12:15]
	v_mfma_f32_16x16x32_bf16 v[12:15], v[224:227], v[28:31], v[72:75]
	v_mfma_f32_16x16x32_bf16 v[116:119], v[228:231], v[92:95], v[12:15]
	v_mfma_f32_16x16x32_bf16 v[12:15], v[232:235], v[28:31], v[84:87]
	v_mfma_f32_16x16x32_bf16 v[112:115], v[236:239], v[92:95], v[12:15]
	v_mfma_f32_16x16x32_bf16 v[12:15], v[224:227], v[240:243], v[88:91]
	v_mfma_f32_16x16x32_bf16 v[92:95], v[228:231], v[244:247], v[12:15]
	v_mfma_f32_16x16x32_bf16 v[12:15], v[232:235], v[240:243], v[96:99]
	v_mfma_f32_16x16x32_bf16 v[88:91], v[236:239], v[244:247], v[12:15]
	v_mfma_f32_16x16x32_bf16 v[12:15], v[224:227], v[248:251], v[108:111]
	v_mfma_f32_16x16x32_bf16 v[68:71], v[228:231], v[32:35], v[12:15]
	v_mfma_f32_16x16x32_bf16 v[12:15], v[232:235], v[248:251], v[120:123]
	v_mfma_f32_16x16x32_bf16 v[144:147], v[228:231], v[24:27], v[36:39]
	v_mfma_f32_16x16x32_bf16 v[64:67], v[236:239], v[32:35], v[12:15]
	s_barrier
	s_add_i32 s20, s69, s26
	s_mov_b32 m0, s20
	s_add_i32 s21, s20, 0x2000
	ds_read_b128 v[32:35], v209 offset:49152
	ds_read_b128 v[36:39], v209 offset:50176
	ds_read_b128 v[72:75], v209 offset:51200
	ds_read_b128 v[84:87], v209 offset:52224
	ds_read_b128 v[96:99], v209 offset:53248
	ds_read_b128 v[108:111], v209 offset:54272
	ds_read_b128 v[120:123], v209 offset:55296
	ds_read_b128 v[240:243], v209 offset:56320
	s_nop 0
	global_load_lds_dwordx4 v203, s[54:55]
	s_mov_b32 m0, s21
	s_nop 0
	global_load_lds_dwordx4 v205, s[54:55]
	s_add_u32 s54, s4, 0x160180
	s_addc_u32 s55, s5, 0
	s_add_i32 s75, s70, s26
	s_mov_b32 m0, s75
	s_add_i32 s76, s75, 0x2000
	s_nop 0
	global_load_lds_dwordx4 v203, s[54:55]
	s_mov_b32 m0, s76
	s_nop 0
	global_load_lds_dwordx4 v205, s[54:55]
	s_mov_b32 m0, s63
	s_nop 0
	global_load_lds_dwordx4 v202, s[52:53]
	s_mov_b32 m0, s64
	s_nop 0
	global_load_lds_dwordx4 v204, s[52:53]
	s_waitcnt vmcnt(8)
	s_waitcnt lgkmcnt(0)
	s_barrier
	s_waitcnt lgkmcnt(0)
	v_mfma_f32_16x16x32_bf16 v[12:15], v[4:7], v[32:35], v[140:143]
	v_mfma_f32_16x16x32_bf16 v[60:63], v[8:11], v[36:39], v[12:15]
	v_mfma_f32_16x16x32_bf16 v[12:15], v[216:219], v[32:35], v[156:159]
	v_mfma_f32_16x16x32_bf16 v[56:59], v[220:223], v[36:39], v[12:15]
	v_mfma_f32_16x16x32_bf16 v[12:15], v[4:7], v[72:75], v[160:163]
	v_mfma_f32_16x16x32_bf16 v[44:47], v[8:11], v[84:87], v[12:15]
	v_mfma_f32_16x16x32_bf16 v[12:15], v[216:219], v[72:75], v[164:167]
	v_mfma_f32_16x16x32_bf16 v[40:43], v[220:223], v[84:87], v[12:15]
	v_mfma_f32_16x16x32_bf16 v[12:15], v[4:7], v[96:99], v[168:171]
	v_mfma_f32_16x16x32_bf16 v[28:31], v[8:11], v[108:111], v[12:15]
	v_mfma_f32_16x16x32_bf16 v[12:15], v[216:219], v[96:99], v[172:175]
	v_mfma_f32_16x16x32_bf16 v[4:7], v[4:7], v[120:123], v[16:19]
	v_mfma_f32_16x16x32_bf16 v[24:27], v[220:223], v[108:111], v[12:15]
	v_mfma_f32_16x16x32_bf16 v[12:15], v[8:11], v[240:243], v[4:7]
	v_mfma_f32_16x16x32_bf16 v[4:7], v[216:219], v[120:123], v[20:23]
	v_mfma_f32_16x16x32_bf16 v[8:11], v[220:223], v[240:243], v[4:7]
	v_mfma_f32_16x16x32_bf16 v[4:7], v[224:227], v[32:35], v[176:179]
	v_mfma_f32_16x16x32_bf16 v[52:55], v[228:231], v[36:39], v[4:7]
	v_mfma_f32_16x16x32_bf16 v[4:7], v[232:235], v[32:35], v[180:183]
	v_mfma_f32_16x16x32_bf16 v[48:51], v[236:239], v[36:39], v[4:7]
	v_mfma_f32_16x16x32_bf16 v[4:7], v[224:227], v[72:75], v[186:189]
	v_mfma_f32_16x16x32_bf16 v[36:39], v[228:231], v[84:87], v[4:7]
	v_mfma_f32_16x16x32_bf16 v[4:7], v[232:235], v[72:75], v[190:193]
	v_mfma_f32_16x16x32_bf16 v[32:35], v[236:239], v[84:87], v[4:7]
	v_mfma_f32_16x16x32_bf16 v[4:7], v[224:227], v[96:99], v[194:197]
	v_mfma_f32_16x16x32_bf16 v[20:23], v[228:231], v[108:111], v[4:7]
	v_mfma_f32_16x16x32_bf16 v[4:7], v[232:235], v[96:99], v[198:201]
	v_mfma_f32_16x16x32_bf16 v[0:3], v[224:227], v[120:123], v[0:3]
	v_mfma_f32_16x16x32_bf16 v[16:19], v[236:239], v[108:111], v[4:7]
	v_mfma_f32_16x16x32_bf16 v[4:7], v[228:231], v[240:243], v[0:3]
	v_mfma_f32_16x16x32_bf16 v[0:3], v[232:235], v[120:123], v[212:215]
	v_mfma_f32_16x16x32_bf16 v[0:3], v[236:239], v[240:243], v[0:3]
	s_barrier
	s_add_u32 s77, s50, 0x200
	s_addc_u32 s78, s51, 0
	s_add_u32 s79, s4, 0x200
	s_addc_u32 s80, s5, 0
	s_add_u32 s4, s50, 0x160180
	s_addc_u32 s5, s51, 0
	s_mov_b32 s83, 0
.LBB0_2251:
	s_cmpk_eq_i32 s83, 0x54
	s_cselect_b32 s54, s46, s77
	s_cselect_b32 s55, s47, s78
	s_cselect_b32 s52, s48, s79
	s_cselect_b32 s53, s49, s80
	s_add_u32 s50, s54, 0x80
	s_addc_u32 s51, s55, 0
	s_add_i32 s86, 0, 0x10000
	s_add_i32 s90, 0, 0x14000
	v_add_u32_e32 v108, s86, v206
	v_add_u32_e32 v134, s90, v206
	ds_read_b128 v[72:75], v108
	ds_read_b128 v[84:87], v108 offset:1024
	ds_read_b128 v[96:99], v108 offset:2048
	ds_read_b128 v[108:111], v108 offset:3072
	ds_read_b128 v[120:123], v134
	ds_read_b128 v[140:143], v134 offset:1024
	ds_read_b128 v[156:159], v134 offset:2048
	ds_read_b128 v[160:163], v134 offset:3072
	s_mov_b32 m0, s1
	ds_read_b128 v[164:167], v209
	ds_read_b128 v[168:171], v209 offset:1024
	ds_read_b128 v[172:175], v209 offset:2048
	ds_read_b128 v[176:179], v209 offset:3072
	ds_read_b128 v[180:183], v209 offset:4096
	ds_read_b128 v[186:189], v209 offset:5120
	ds_read_b128 v[190:193], v209 offset:6144
	ds_read_b128 v[194:197], v209 offset:7168
	s_nop 0
	global_load_lds_dwordx4 v202, s[4:5]
	s_mov_b32 m0, s12
	s_nop 0
	global_load_lds_dwordx4 v204, s[4:5]
	s_waitcnt vmcnt(8)
	s_waitcnt lgkmcnt(0)
	s_barrier
	s_waitcnt lgkmcnt(0)
	v_mfma_f32_16x16x32_bf16 v[152:155], v[72:75], v[164:167], v[152:155]
	v_mfma_f32_16x16x32_bf16 v[148:151], v[96:99], v[164:167], v[148:151]
	v_mfma_f32_16x16x32_bf16 v[128:131], v[72:75], v[172:175], v[128:131]
	v_mfma_f32_16x16x32_bf16 v[124:127], v[96:99], v[172:175], v[124:127]
	v_mfma_f32_16x16x32_bf16 v[104:107], v[72:75], v[180:183], v[104:107]
	v_mfma_f32_16x16x32_bf16 v[100:103], v[96:99], v[180:183], v[100:103]
	v_mfma_f32_16x16x32_bf16 v[80:83], v[72:75], v[190:193], v[80:83]
	v_mfma_f32_16x16x32_bf16 v[76:79], v[96:99], v[190:193], v[76:79]
	v_mfma_f32_16x16x32_bf16 v[152:155], v[84:87], v[168:171], v[152:155]
	v_mfma_f32_16x16x32_bf16 v[148:151], v[108:111], v[168:171], v[148:151]
	v_mfma_f32_16x16x32_bf16 v[128:131], v[84:87], v[176:179], v[128:131]
	v_mfma_f32_16x16x32_bf16 v[124:127], v[108:111], v[176:179], v[124:127]
	v_mfma_f32_16x16x32_bf16 v[104:107], v[84:87], v[186:189], v[104:107]
	v_mfma_f32_16x16x32_bf16 v[100:103], v[108:111], v[186:189], v[100:103]
	v_mfma_f32_16x16x32_bf16 v[80:83], v[84:87], v[194:197], v[80:83]
	v_mfma_f32_16x16x32_bf16 v[76:79], v[108:111], v[194:197], v[76:79]
	v_mfma_f32_16x16x32_bf16 v[144:147], v[120:123], v[164:167], v[144:147]
	v_mfma_f32_16x16x32_bf16 v[134:137], v[156:159], v[164:167], v[136:139]
	v_mfma_f32_16x16x32_bf16 v[116:119], v[120:123], v[172:175], v[116:119]
	v_mfma_f32_16x16x32_bf16 v[112:115], v[156:159], v[172:175], v[112:115]
	v_mfma_f32_16x16x32_bf16 v[92:95], v[120:123], v[180:183], v[92:95]
	v_mfma_f32_16x16x32_bf16 v[88:91], v[156:159], v[180:183], v[88:91]
	v_mfma_f32_16x16x32_bf16 v[68:71], v[120:123], v[190:193], v[68:71]
	v_mfma_f32_16x16x32_bf16 v[64:67], v[156:159], v[190:193], v[64:67]
	v_mfma_f32_16x16x32_bf16 v[144:147], v[140:143], v[168:171], v[144:147]
	v_mfma_f32_16x16x32_bf16 v[134:137], v[160:163], v[168:171], v[134:137]
	v_mfma_f32_16x16x32_bf16 v[116:119], v[140:143], v[176:179], v[116:119]
	v_mfma_f32_16x16x32_bf16 v[112:115], v[160:163], v[176:179], v[112:115]
	v_mfma_f32_16x16x32_bf16 v[92:95], v[140:143], v[186:189], v[92:95]
	v_mfma_f32_16x16x32_bf16 v[88:91], v[160:163], v[186:189], v[88:91]
	v_mfma_f32_16x16x32_bf16 v[68:71], v[140:143], v[194:197], v[68:71]
	v_mfma_f32_16x16x32_bf16 v[64:67], v[160:163], v[194:197], v[64:67]
	s_barrier
	s_add_i32 s86, s86, s26
	s_mov_b32 m0, s86
	ds_read_b128 v[164:167], v209 offset:16384
	ds_read_b128 v[168:171], v209 offset:17408
	ds_read_b128 v[172:175], v209 offset:18432
	ds_read_b128 v[176:179], v209 offset:19456
	ds_read_b128 v[180:183], v209 offset:20480
	ds_read_b128 v[186:189], v209 offset:21504
	ds_read_b128 v[190:193], v209 offset:22528
	ds_read_b128 v[194:197], v209 offset:23552
	s_nop 0
	global_load_lds_dwordx4 v203, s[52:53]
	s_add_i32 m0, s86, 0x2000
	s_add_u32 s88, s52, 0x160000
	s_addc_u32 s89, s53, 0
	s_add_i32 s86, s90, s26
	s_nop 0
	global_load_lds_dwordx4 v205, s[52:53]
	s_mov_b32 m0, s86
	s_nop 0
	global_load_lds_dwordx4 v203, s[88:89]
	s_add_i32 m0, s86, 0x2000
	s_nop 0
	global_load_lds_dwordx4 v205, s[88:89]
	s_mov_b32 m0, s27
	s_nop 0
	global_load_lds_dwordx4 v202, s[54:55]
	s_mov_b32 m0, s60
	s_nop 0
	global_load_lds_dwordx4 v204, s[54:55]
	s_waitcnt vmcnt(8)
	s_waitcnt lgkmcnt(0)
	s_barrier
	s_waitcnt lgkmcnt(0)
	v_mfma_f32_16x16x32_bf16 v[60:63], v[72:75], v[164:167], v[60:63]
	v_mfma_f32_16x16x32_bf16 v[56:59], v[96:99], v[164:167], v[56:59]
	v_mfma_f32_16x16x32_bf16 v[44:47], v[72:75], v[172:175], v[44:47]
	v_mfma_f32_16x16x32_bf16 v[40:43], v[96:99], v[172:175], v[40:43]
	v_mfma_f32_16x16x32_bf16 v[28:31], v[72:75], v[180:183], v[28:31]
	v_mfma_f32_16x16x32_bf16 v[24:27], v[96:99], v[180:183], v[24:27]
	v_mfma_f32_16x16x32_bf16 v[12:15], v[72:75], v[190:193], v[12:15]
	v_mfma_f32_16x16x32_bf16 v[8:11], v[96:99], v[190:193], v[8:11]
	v_mfma_f32_16x16x32_bf16 v[60:63], v[84:87], v[168:171], v[60:63]
	v_mfma_f32_16x16x32_bf16 v[56:59], v[108:111], v[168:171], v[56:59]
	v_mfma_f32_16x16x32_bf16 v[44:47], v[84:87], v[176:179], v[44:47]
	v_mfma_f32_16x16x32_bf16 v[40:43], v[108:111], v[176:179], v[40:43]
	v_mfma_f32_16x16x32_bf16 v[28:31], v[84:87], v[186:189], v[28:31]
	v_mfma_f32_16x16x32_bf16 v[24:27], v[108:111], v[186:189], v[24:27]
	v_mfma_f32_16x16x32_bf16 v[12:15], v[84:87], v[194:197], v[12:15]
	v_mfma_f32_16x16x32_bf16 v[8:11], v[108:111], v[194:197], v[8:11]
	v_mfma_f32_16x16x32_bf16 v[52:55], v[120:123], v[164:167], v[52:55]
	v_mfma_f32_16x16x32_bf16 v[48:51], v[156:159], v[164:167], v[48:51]
	v_mfma_f32_16x16x32_bf16 v[36:39], v[120:123], v[172:175], v[36:39]
	v_mfma_f32_16x16x32_bf16 v[32:35], v[156:159], v[172:175], v[32:35]
	v_mfma_f32_16x16x32_bf16 v[20:23], v[120:123], v[180:183], v[20:23]
	v_mfma_f32_16x16x32_bf16 v[16:19], v[156:159], v[180:183], v[16:19]
	v_mfma_f32_16x16x32_bf16 v[4:7], v[120:123], v[190:193], v[4:7]
	v_mfma_f32_16x16x32_bf16 v[0:3], v[156:159], v[190:193], v[0:3]
	v_mfma_f32_16x16x32_bf16 v[52:55], v[140:143], v[168:171], v[52:55]
	v_mfma_f32_16x16x32_bf16 v[48:51], v[160:163], v[168:171], v[48:51]
	v_mfma_f32_16x16x32_bf16 v[36:39], v[140:143], v[176:179], v[36:39]
	v_mfma_f32_16x16x32_bf16 v[32:35], v[160:163], v[176:179], v[32:35]
	v_mfma_f32_16x16x32_bf16 v[20:23], v[140:143], v[186:189], v[20:23]
	v_mfma_f32_16x16x32_bf16 v[16:19], v[160:163], v[186:189], v[16:19]
	v_mfma_f32_16x16x32_bf16 v[4:7], v[140:143], v[194:197], v[4:7]
	v_mfma_f32_16x16x32_bf16 v[0:3], v[160:163], v[194:197], v[0:3]
	s_barrier
	ds_read_b128 v[72:75], v132
	ds_read_b128 v[84:87], v132 offset:1024
	ds_read_b128 v[96:99], v132 offset:2048
	ds_read_b128 v[108:111], v132 offset:3072
	ds_read_b128 v[120:123], v133
	ds_read_b128 v[140:143], v133 offset:1024
	ds_read_b128 v[156:159], v133 offset:2048
	ds_read_b128 v[160:163], v133 offset:3072
	s_add_u32 s54, s54, 0x160000
	s_addc_u32 s55, s55, 0
	s_mov_b32 m0, s61
	ds_read_b128 v[164:167], v209 offset:32768
	ds_read_b128 v[168:171], v209 offset:33792
	ds_read_b128 v[172:175], v209 offset:34816
	ds_read_b128 v[176:179], v209 offset:35840
	ds_read_b128 v[180:183], v209 offset:36864
	ds_read_b128 v[186:189], v209 offset:37888
	ds_read_b128 v[190:193], v209 offset:38912
	ds_read_b128 v[194:197], v209 offset:39936
	s_nop 0
	global_load_lds_dwordx4 v202, s[54:55]
	s_mov_b32 m0, s62
	s_nop 0
	global_load_lds_dwordx4 v204, s[54:55]
	s_waitcnt vmcnt(8)
	s_waitcnt lgkmcnt(0)
	s_barrier
	s_waitcnt lgkmcnt(0)
	v_mfma_f32_16x16x32_bf16 v[152:155], v[72:75], v[164:167], v[152:155]
	v_mfma_f32_16x16x32_bf16 v[148:151], v[96:99], v[164:167], v[148:151]
	v_mfma_f32_16x16x32_bf16 v[128:131], v[72:75], v[172:175], v[128:131]
	v_mfma_f32_16x16x32_bf16 v[124:127], v[96:99], v[172:175], v[124:127]
	v_mfma_f32_16x16x32_bf16 v[104:107], v[72:75], v[180:183], v[104:107]
	v_mfma_f32_16x16x32_bf16 v[100:103], v[96:99], v[180:183], v[100:103]
	v_mfma_f32_16x16x32_bf16 v[80:83], v[72:75], v[190:193], v[80:83]
	v_mfma_f32_16x16x32_bf16 v[76:79], v[96:99], v[190:193], v[76:79]
	v_mfma_f32_16x16x32_bf16 v[152:155], v[84:87], v[168:171], v[152:155]
	v_mfma_f32_16x16x32_bf16 v[148:151], v[108:111], v[168:171], v[148:151]
	v_mfma_f32_16x16x32_bf16 v[128:131], v[84:87], v[176:179], v[128:131]
	v_mfma_f32_16x16x32_bf16 v[124:127], v[108:111], v[176:179], v[124:127]
	v_mfma_f32_16x16x32_bf16 v[104:107], v[84:87], v[186:189], v[104:107]
	v_mfma_f32_16x16x32_bf16 v[100:103], v[108:111], v[186:189], v[100:103]
	v_mfma_f32_16x16x32_bf16 v[80:83], v[84:87], v[194:197], v[80:83]
	v_mfma_f32_16x16x32_bf16 v[76:79], v[108:111], v[194:197], v[76:79]
	v_mfma_f32_16x16x32_bf16 v[144:147], v[120:123], v[164:167], v[144:147]
	v_mfma_f32_16x16x32_bf16 v[134:137], v[156:159], v[164:167], v[134:137]
	v_mfma_f32_16x16x32_bf16 v[116:119], v[120:123], v[172:175], v[116:119]
	v_mfma_f32_16x16x32_bf16 v[112:115], v[156:159], v[172:175], v[112:115]
	v_mfma_f32_16x16x32_bf16 v[92:95], v[120:123], v[180:183], v[92:95]
	v_mfma_f32_16x16x32_bf16 v[88:91], v[156:159], v[180:183], v[88:91]
	v_mfma_f32_16x16x32_bf16 v[68:71], v[120:123], v[190:193], v[68:71]
	v_mfma_f32_16x16x32_bf16 v[64:67], v[156:159], v[190:193], v[64:67]
	v_mfma_f32_16x16x32_bf16 v[144:147], v[140:143], v[168:171], v[144:147]
	v_mfma_f32_16x16x32_bf16 v[136:139], v[160:163], v[168:171], v[134:137]
	v_mfma_f32_16x16x32_bf16 v[116:119], v[140:143], v[176:179], v[116:119]
	v_mfma_f32_16x16x32_bf16 v[112:115], v[160:163], v[176:179], v[112:115]
	v_mfma_f32_16x16x32_bf16 v[92:95], v[140:143], v[186:189], v[92:95]
	v_mfma_f32_16x16x32_bf16 v[88:91], v[160:163], v[186:189], v[88:91]
	v_mfma_f32_16x16x32_bf16 v[68:71], v[140:143], v[194:197], v[68:71]
	v_mfma_f32_16x16x32_bf16 v[64:67], v[160:163], v[194:197], v[64:67]
	s_barrier
	s_add_u32 s54, s52, 0x80
	s_mov_b32 m0, s20
	s_addc_u32 s55, s53, 0
	ds_read_b128 v[164:167], v209 offset:49152
	ds_read_b128 v[168:171], v209 offset:50176
	ds_read_b128 v[172:175], v209 offset:51200
	ds_read_b128 v[176:179], v209 offset:52224
	ds_read_b128 v[180:183], v209 offset:53248
	ds_read_b128 v[186:189], v209 offset:54272
	ds_read_b128 v[190:193], v209 offset:55296
	ds_read_b128 v[194:197], v209 offset:56320
	s_add_u32 s52, s52, 0x160080
	global_load_lds_dwordx4 v203, s[54:55]
	s_mov_b32 m0, s21
	s_addc_u32 s53, s53, 0
	global_load_lds_dwordx4 v205, s[54:55]
	s_mov_b32 m0, s75
	s_nop 0
	global_load_lds_dwordx4 v203, s[52:53]
	s_mov_b32 m0, s76
	s_nop 0
	global_load_lds_dwordx4 v205, s[52:53]
	s_mov_b32 m0, s63
	s_nop 0
	global_load_lds_dwordx4 v202, s[50:51]
	s_mov_b32 m0, s64
	s_nop 0
	global_load_lds_dwordx4 v204, s[50:51]
	s_waitcnt vmcnt(8)
	s_waitcnt lgkmcnt(0)
	s_barrier
	s_waitcnt lgkmcnt(0)
	v_mfma_f32_16x16x32_bf16 v[60:63], v[72:75], v[164:167], v[60:63]
	v_mfma_f32_16x16x32_bf16 v[56:59], v[96:99], v[164:167], v[56:59]
	v_mfma_f32_16x16x32_bf16 v[44:47], v[72:75], v[172:175], v[44:47]
	v_mfma_f32_16x16x32_bf16 v[40:43], v[96:99], v[172:175], v[40:43]
	v_mfma_f32_16x16x32_bf16 v[28:31], v[72:75], v[180:183], v[28:31]
	v_mfma_f32_16x16x32_bf16 v[24:27], v[96:99], v[180:183], v[24:27]
	v_mfma_f32_16x16x32_bf16 v[12:15], v[72:75], v[190:193], v[12:15]
	v_mfma_f32_16x16x32_bf16 v[8:11], v[96:99], v[190:193], v[8:11]
	v_mfma_f32_16x16x32_bf16 v[60:63], v[84:87], v[168:171], v[60:63]
	v_mfma_f32_16x16x32_bf16 v[56:59], v[108:111], v[168:171], v[56:59]
	v_mfma_f32_16x16x32_bf16 v[44:47], v[84:87], v[176:179], v[44:47]
	v_mfma_f32_16x16x32_bf16 v[40:43], v[108:111], v[176:179], v[40:43]
	v_mfma_f32_16x16x32_bf16 v[28:31], v[84:87], v[186:189], v[28:31]
	v_mfma_f32_16x16x32_bf16 v[24:27], v[108:111], v[186:189], v[24:27]
	v_mfma_f32_16x16x32_bf16 v[12:15], v[84:87], v[194:197], v[12:15]
	v_mfma_f32_16x16x32_bf16 v[8:11], v[108:111], v[194:197], v[8:11]
	v_mfma_f32_16x16x32_bf16 v[52:55], v[120:123], v[164:167], v[52:55]
	v_mfma_f32_16x16x32_bf16 v[48:51], v[156:159], v[164:167], v[48:51]
	v_mfma_f32_16x16x32_bf16 v[36:39], v[120:123], v[172:175], v[36:39]
	v_mfma_f32_16x16x32_bf16 v[32:35], v[156:159], v[172:175], v[32:35]
	v_mfma_f32_16x16x32_bf16 v[20:23], v[120:123], v[180:183], v[20:23]
	v_mfma_f32_16x16x32_bf16 v[16:19], v[156:159], v[180:183], v[16:19]
	v_mfma_f32_16x16x32_bf16 v[4:7], v[120:123], v[190:193], v[4:7]
	v_mfma_f32_16x16x32_bf16 v[0:3], v[156:159], v[190:193], v[0:3]
	v_mfma_f32_16x16x32_bf16 v[52:55], v[140:143], v[168:171], v[52:55]
	v_mfma_f32_16x16x32_bf16 v[48:51], v[160:163], v[168:171], v[48:51]
	v_mfma_f32_16x16x32_bf16 v[36:39], v[140:143], v[176:179], v[36:39]
	v_mfma_f32_16x16x32_bf16 v[32:35], v[160:163], v[176:179], v[32:35]
	v_mfma_f32_16x16x32_bf16 v[20:23], v[140:143], v[186:189], v[20:23]
	v_mfma_f32_16x16x32_bf16 v[16:19], v[160:163], v[186:189], v[16:19]
	v_mfma_f32_16x16x32_bf16 v[4:7], v[140:143], v[194:197], v[4:7]
	v_mfma_f32_16x16x32_bf16 v[0:3], v[160:163], v[194:197], v[0:3]
	s_barrier
	s_add_i32 s83, s83, 2
	s_add_u32 s77, s77, 0x100
	s_addc_u32 s78, s78, 0
	s_add_u32 s79, s79, 0x100
	s_addc_u32 s80, s80, 0
	s_add_u32 s4, s4, 0x100
	s_addc_u32 s5, s5, 0
	s_cmpk_gt_u32 s83, 0x55
	s_cbranch_scc0 .LBB0_2251
	s_and_b64 vcc, exec, s[44:45]
	s_cbranch_vccz .LBB0_2254
	s_barrier

.LBB0_2360:
	s_add_u32 s20, s56, 0x100
	s_addc_u32 s21, s57, 0
	s_waitcnt lgkmcnt(0)
	s_add_u32 s48, s54, 0x100
	s_addc_u32 s49, s55, 0
	s_barrier
	s_waitcnt lgkmcnt(0)
	v_mfma_f32_16x16x32_bf16 v[32:35], v[16:19], v[68:71], 0
	v_mfma_f32_16x16x32_bf16 v[36:39], v[24:27], v[68:71], 0
	v_mfma_f32_16x16x32_bf16 v[40:43], v[16:19], v[84:87], 0
	v_mfma_f32_16x16x32_bf16 v[44:47], v[24:27], v[84:87], 0
	v_mfma_f32_16x16x32_bf16 v[48:51], v[16:19], v[88:91], 0
	v_mfma_f32_16x16x32_bf16 v[52:55], v[24:27], v[88:91], 0
	v_mfma_f32_16x16x32_bf16 v[56:59], v[16:19], v[72:75], 0
	v_mfma_f32_16x16x32_bf16 v[60:63], v[24:27], v[72:75], 0
	v_mfma_f32_16x16x32_bf16 v[116:119], v[20:23], v[80:83], v[32:35]
	v_mfma_f32_16x16x32_bf16 v[36:39], v[28:31], v[80:83], v[36:39]
	v_mfma_f32_16x16x32_bf16 v[40:43], v[20:23], v[96:99], v[40:43]
	v_mfma_f32_16x16x32_bf16 v[44:47], v[28:31], v[96:99], v[44:47]
	v_mfma_f32_16x16x32_bf16 v[48:51], v[20:23], v[92:95], v[48:51]
	v_mfma_f32_16x16x32_bf16 v[52:55], v[28:31], v[92:95], v[52:55]
	v_mfma_f32_16x16x32_bf16 v[56:59], v[20:23], v[76:79], v[56:59]
	v_mfma_f32_16x16x32_bf16 v[60:63], v[28:31], v[76:79], v[60:63]
	v_mfma_f32_16x16x32_bf16 v[64:67], v[0:3], v[68:71], 0
	v_mfma_f32_16x16x32_bf16 v[68:71], v[8:11], v[68:71], 0
	v_mfma_f32_16x16x32_bf16 v[64:67], v[4:7], v[80:83], v[64:67]
	v_mfma_f32_16x16x32_bf16 v[68:71], v[12:15], v[80:83], v[68:71]
	v_mfma_f32_16x16x32_bf16 v[80:83], v[0:3], v[84:87], 0
	v_mfma_f32_16x16x32_bf16 v[84:87], v[8:11], v[84:87], 0
	v_mfma_f32_16x16x32_bf16 v[80:83], v[4:7], v[96:99], v[80:83]
	v_mfma_f32_16x16x32_bf16 v[84:87], v[12:15], v[96:99], v[84:87]
	v_mfma_f32_16x16x32_bf16 v[96:99], v[0:3], v[88:91], 0
	v_mfma_f32_16x16x32_bf16 v[88:91], v[8:11], v[88:91], 0
	v_mfma_f32_16x16x32_bf16 v[132:135], v[12:15], v[92:95], v[88:91]
	v_mfma_f32_16x16x32_bf16 v[88:91], v[0:3], v[72:75], 0
	v_mfma_f32_16x16x32_bf16 v[72:75], v[8:11], v[72:75], 0
	v_mfma_f32_16x16x32_bf16 v[128:131], v[4:7], v[92:95], v[96:99]
	v_mfma_f32_16x16x32_bf16 v[136:139], v[4:7], v[76:79], v[88:91]
	v_mfma_f32_16x16x32_bf16 v[140:143], v[12:15], v[76:79], v[72:75]
	s_barrier
	s_mov_b32 m0, s65
	ds_read_b128 v[104:107], v162 offset:16384
	ds_read_b128 v[108:111], v162 offset:17408
	ds_read_b128 v[96:99], v162 offset:18432
	ds_read_b128 v[100:103], v162 offset:19456
	ds_read_b128 v[88:91], v162 offset:20480
	ds_read_b128 v[92:95], v162 offset:21504
	ds_read_b128 v[72:75], v162 offset:22528
	ds_read_b128 v[76:79], v162 offset:23552
	s_nop 0
	global_load_lds_dwordx4 v156, s[48:49]
	s_mov_b32 m0, s66
	s_nop 0
	global_load_lds_dwordx4 v158, s[48:49]
	s_add_u32 s48, s54, 0x80100
	s_addc_u32 s49, s55, 0
	s_mov_b32 m0, s67
	s_and_b64 vcc, exec, s[46:47]
	global_load_lds_dwordx4 v156, s[48:49]
	s_mov_b32 m0, s68
	s_nop 0
	global_load_lds_dwordx4 v158, s[48:49]
	s_mov_b32 m0, s27
	s_mov_b64 s[48:49], -1
	global_load_lds_dwordx4 v153, s[20:21]
	s_mov_b32 m0, s69
	s_nop 0
	global_load_lds_dwordx4 v157, s[20:21]
	s_cbranch_vccz .LBB0_2362
	s_waitcnt vmcnt(8)
	s_mov_b64 s[48:49], 0

.LBB0_2364:
	s_ashr_i32 s7, s6, 31
	s_lshl_b64 s[20:21], s[6:7], 20
	s_add_u32 s46, s14, s20
	s_addc_u32 s47, s15, s21
	s_ashr_i32 s43, s42, 31
	s_lshl_b64 s[20:21], s[42:43], 20
	s_add_u32 s48, s24, s20
	s_addc_u32 s49, s25, s21
	s_add_u32 s58, s56, 0x180
	s_addc_u32 s59, s57, 0
	s_waitcnt lgkmcnt(0)
	s_and_b64 s[20:21], s[44:45], exec
	s_cselect_b32 s20, s49, s55
	s_cselect_b32 s21, s48, s54
	s_cselect_b32 s43, s47, s57
	s_cselect_b32 s51, s46, s56
	s_add_u32 s60, s54, 0x180
	s_addc_u32 s61, s55, 0
	s_barrier
	s_waitcnt lgkmcnt(0)
	v_mfma_f32_16x16x32_bf16 v[112:115], v[16:19], v[104:107], 0
	v_mfma_f32_16x16x32_bf16 v[166:169], v[20:23], v[108:111], v[112:115]
	v_mfma_f32_16x16x32_bf16 v[112:115], v[24:27], v[104:107], 0
	v_mfma_f32_16x16x32_bf16 v[170:173], v[28:31], v[108:111], v[112:115]
	v_mfma_f32_16x16x32_bf16 v[112:115], v[16:19], v[96:99], 0
	v_mfma_f32_16x16x32_bf16 v[174:177], v[20:23], v[100:103], v[112:115]
	v_mfma_f32_16x16x32_bf16 v[112:115], v[24:27], v[96:99], 0
	v_mfma_f32_16x16x32_bf16 v[178:181], v[28:31], v[100:103], v[112:115]
	v_mfma_f32_16x16x32_bf16 v[112:115], v[16:19], v[88:91], 0
	v_mfma_f32_16x16x32_bf16 v[16:19], v[16:19], v[72:75], 0
	v_mfma_f32_16x16x32_bf16 v[182:185], v[20:23], v[92:95], v[112:115]
	v_mfma_f32_16x16x32_bf16 v[16:19], v[20:23], v[76:79], v[16:19]
	v_mfma_f32_16x16x32_bf16 v[20:23], v[24:27], v[72:75], 0
	v_mfma_f32_16x16x32_bf16 v[112:115], v[24:27], v[88:91], 0
	v_mfma_f32_16x16x32_bf16 v[20:23], v[28:31], v[76:79], v[20:23]
	v_mfma_f32_16x16x32_bf16 v[186:189], v[28:31], v[92:95], v[112:115]
	v_mfma_f32_16x16x32_bf16 v[24:27], v[0:3], v[104:107], 0
	v_mfma_f32_16x16x32_bf16 v[190:193], v[4:7], v[108:111], v[24:27]
	v_mfma_f32_16x16x32_bf16 v[24:27], v[8:11], v[104:107], 0
	v_mfma_f32_16x16x32_bf16 v[194:197], v[12:15], v[108:111], v[24:27]
	v_mfma_f32_16x16x32_bf16 v[24:27], v[0:3], v[96:99], 0
	v_mfma_f32_16x16x32_bf16 v[198:201], v[4:7], v[100:103], v[24:27]
	v_mfma_f32_16x16x32_bf16 v[24:27], v[8:11], v[96:99], 0
	v_mfma_f32_16x16x32_bf16 v[202:205], v[12:15], v[100:103], v[24:27]
	v_mfma_f32_16x16x32_bf16 v[24:27], v[0:3], v[88:91], 0
	v_mfma_f32_16x16x32_bf16 v[0:3], v[0:3], v[72:75], 0
	v_mfma_f32_16x16x32_bf16 v[206:209], v[4:7], v[92:95], v[24:27]
	v_mfma_f32_16x16x32_bf16 v[24:27], v[8:11], v[88:91], 0
	v_mfma_f32_16x16x32_bf16 v[0:3], v[4:7], v[76:79], v[0:3]
	v_mfma_f32_16x16x32_bf16 v[4:7], v[8:11], v[72:75], 0
	v_mfma_f32_16x16x32_bf16 v[210:213], v[12:15], v[92:95], v[24:27]
	v_mfma_f32_16x16x32_bf16 v[214:217], v[12:15], v[76:79], v[4:7]
	s_barrier
	v_add_u32_e32 v144, s78, v159
	v_add_u32_e32 v148, s83, v159
	s_nop 1
	ds_read_b128 v[4:7], v144
	ds_read_b128 v[8:11], v144 offset:1024
	ds_read_b128 v[218:221], v144 offset:2048
	ds_read_b128 v[222:225], v144 offset:3072
	ds_read_b128 v[226:229], v148
	ds_read_b128 v[230:233], v148 offset:1024
	ds_read_b128 v[234:237], v148 offset:2048
	ds_read_b128 v[238:241], v148 offset:3072
	s_add_u32 s62, s56, 0x80100
	s_addc_u32 s63, s57, 0
	s_mov_b32 m0, s70
	ds_read_b128 v[12:15], v162 offset:32768
	ds_read_b128 v[24:27], v162 offset:33792
	ds_read_b128 v[28:31], v162 offset:34816
	ds_read_b128 v[96:99], v162 offset:35840
	ds_read_b128 v[242:245], v162 offset:36864
	ds_read_b128 v[246:249], v162 offset:37888
	ds_read_b128 v[250:253], v162 offset:38912
	ds_read_b128 v[32:35], v162 offset:39936
	s_nop 0
	global_load_lds_dwordx4 v153, s[62:63]
	s_mov_b32 m0, s71
	s_nop 0
	global_load_lds_dwordx4 v157, s[62:63]
	s_waitcnt vmcnt(8)
	s_waitcnt lgkmcnt(0)
	s_barrier
	s_waitcnt lgkmcnt(0)
	v_mfma_f32_16x16x32_bf16 v[36:39], v[218:221], v[12:15], v[36:39]
	v_mfma_f32_16x16x32_bf16 v[120:123], v[222:225], v[24:27], v[36:39]
	v_mfma_f32_16x16x32_bf16 v[36:39], v[4:7], v[28:31], v[40:43]
	v_mfma_f32_16x16x32_bf16 v[108:111], v[8:11], v[96:99], v[36:39]
	v_mfma_f32_16x16x32_bf16 v[36:39], v[218:221], v[28:31], v[44:47]
	v_mfma_f32_16x16x32_bf16 v[104:107], v[222:225], v[96:99], v[36:39]
	v_mfma_f32_16x16x32_bf16 v[36:39], v[4:7], v[242:245], v[48:51]
	v_mfma_f32_16x16x32_bf16 v[92:95], v[8:11], v[246:249], v[36:39]
	v_mfma_f32_16x16x32_bf16 v[36:39], v[218:221], v[242:245], v[52:55]
	v_mfma_f32_16x16x32_bf16 v[88:91], v[222:225], v[246:249], v[36:39]
	v_mfma_f32_16x16x32_bf16 v[36:39], v[4:7], v[250:253], v[56:59]
	v_mfma_f32_16x16x32_bf16 v[72:75], v[4:7], v[12:15], v[116:119]
	v_mfma_f32_16x16x32_bf16 v[76:79], v[8:11], v[32:35], v[36:39]
	v_mfma_f32_16x16x32_bf16 v[36:39], v[218:221], v[250:253], v[60:63]
	v_mfma_f32_16x16x32_bf16 v[124:127], v[8:11], v[24:27], v[72:75]
	v_mfma_f32_16x16x32_bf16 v[72:75], v[222:225], v[32:35], v[36:39]
	v_mfma_f32_16x16x32_bf16 v[36:39], v[226:229], v[12:15], v[64:67]
	v_mfma_f32_16x16x32_bf16 v[12:15], v[234:237], v[12:15], v[68:71]
	v_mfma_f32_16x16x32_bf16 v[112:115], v[238:241], v[24:27], v[12:15]
	v_mfma_f32_16x16x32_bf16 v[12:15], v[226:229], v[28:31], v[80:83]
	v_mfma_f32_16x16x32_bf16 v[100:103], v[230:233], v[96:99], v[12:15]
	v_mfma_f32_16x16x32_bf16 v[12:15], v[234:237], v[28:31], v[84:87]
	v_mfma_f32_16x16x32_bf16 v[96:99], v[238:241], v[96:99], v[12:15]
	v_mfma_f32_16x16x32_bf16 v[12:15], v[226:229], v[242:245], v[128:131]
	v_mfma_f32_16x16x32_bf16 v[84:87], v[230:233], v[246:249], v[12:15]
	v_mfma_f32_16x16x32_bf16 v[12:15], v[234:237], v[242:245], v[132:135]
	v_mfma_f32_16x16x32_bf16 v[80:83], v[238:241], v[246:249], v[12:15]
	v_mfma_f32_16x16x32_bf16 v[12:15], v[226:229], v[250:253], v[136:139]
	v_mfma_f32_16x16x32_bf16 v[68:71], v[230:233], v[32:35], v[12:15]
	v_mfma_f32_16x16x32_bf16 v[12:15], v[234:237], v[250:253], v[140:143]
	v_mfma_f32_16x16x32_bf16 v[116:119], v[230:233], v[24:27], v[36:39]
	v_mfma_f32_16x16x32_bf16 v[60:63], v[238:241], v[32:35], v[12:15]
	s_barrier
	s_add_i32 s53, s78, s26
	s_mov_b32 m0, s53
	s_add_i32 s79, s53, 0x2000
	ds_read_b128 v[32:35], v162 offset:49152
	ds_read_b128 v[36:39], v162 offset:50176
	ds_read_b128 v[128:131], v162 offset:51200
	ds_read_b128 v[132:135], v162 offset:52224
	ds_read_b128 v[136:139], v162 offset:53248
	ds_read_b128 v[140:143], v162 offset:54272
	ds_read_b128 v[242:245], v162 offset:55296
	ds_read_b128 v[246:249], v162 offset:56320
	s_nop 0
	global_load_lds_dwordx4 v156, s[60:61]
	s_mov_b32 m0, s79
	s_nop 0
	global_load_lds_dwordx4 v158, s[60:61]
	s_add_u32 s60, s54, 0x80180
	s_addc_u32 s61, s55, 0
	s_add_i32 s80, s83, s26
	s_mov_b32 m0, s80
	s_add_i32 s86, s80, 0x2000
	s_nop 0
	global_load_lds_dwordx4 v156, s[60:61]
	s_mov_b32 m0, s86
	s_nop 0
	global_load_lds_dwordx4 v158, s[60:61]
	s_mov_b32 m0, s72
	s_nop 0
	global_load_lds_dwordx4 v153, s[58:59]
	s_mov_b32 m0, s73
	s_nop 0
	global_load_lds_dwordx4 v157, s[58:59]
	s_waitcnt vmcnt(8)
	s_waitcnt lgkmcnt(0)
	s_barrier
	s_waitcnt lgkmcnt(0)
	v_mfma_f32_16x16x32_bf16 v[12:15], v[4:7], v[32:35], v[166:169]
	v_mfma_f32_16x16x32_bf16 v[64:67], v[8:11], v[36:39], v[12:15]
	v_mfma_f32_16x16x32_bf16 v[12:15], v[218:221], v[32:35], v[170:173]
	v_mfma_f32_16x16x32_bf16 v[56:59], v[222:225], v[36:39], v[12:15]
	v_mfma_f32_16x16x32_bf16 v[12:15], v[4:7], v[128:131], v[174:177]
	v_mfma_f32_16x16x32_bf16 v[44:47], v[8:11], v[132:135], v[12:15]
	v_mfma_f32_16x16x32_bf16 v[12:15], v[218:221], v[128:131], v[178:181]
	v_mfma_f32_16x16x32_bf16 v[40:43], v[222:225], v[132:135], v[12:15]
	v_mfma_f32_16x16x32_bf16 v[12:15], v[4:7], v[136:139], v[182:185]
	v_mfma_f32_16x16x32_bf16 v[28:31], v[8:11], v[140:143], v[12:15]
	v_mfma_f32_16x16x32_bf16 v[12:15], v[218:221], v[136:139], v[186:189]
	v_mfma_f32_16x16x32_bf16 v[4:7], v[4:7], v[242:245], v[16:19]
	v_mfma_f32_16x16x32_bf16 v[24:27], v[222:225], v[140:143], v[12:15]
	v_mfma_f32_16x16x32_bf16 v[12:15], v[8:11], v[246:249], v[4:7]
	v_mfma_f32_16x16x32_bf16 v[4:7], v[218:221], v[242:245], v[20:23]
	v_mfma_f32_16x16x32_bf16 v[8:11], v[222:225], v[246:249], v[4:7]
	v_mfma_f32_16x16x32_bf16 v[4:7], v[226:229], v[32:35], v[190:193]
	v_mfma_f32_16x16x32_bf16 v[52:55], v[230:233], v[36:39], v[4:7]
	v_mfma_f32_16x16x32_bf16 v[4:7], v[234:237], v[32:35], v[194:197]
	v_mfma_f32_16x16x32_bf16 v[48:51], v[238:241], v[36:39], v[4:7]
	v_mfma_f32_16x16x32_bf16 v[4:7], v[226:229], v[128:131], v[198:201]
	v_mfma_f32_16x16x32_bf16 v[36:39], v[230:233], v[132:135], v[4:7]
	v_mfma_f32_16x16x32_bf16 v[4:7], v[234:237], v[128:131], v[202:205]
	v_mfma_f32_16x16x32_bf16 v[32:35], v[238:241], v[132:135], v[4:7]
	v_mfma_f32_16x16x32_bf16 v[4:7], v[226:229], v[136:139], v[206:209]
	v_mfma_f32_16x16x32_bf16 v[20:23], v[230:233], v[140:143], v[4:7]
	v_mfma_f32_16x16x32_bf16 v[4:7], v[234:237], v[136:139], v[210:213]
	v_mfma_f32_16x16x32_bf16 v[0:3], v[226:229], v[242:245], v[0:3]
	v_mfma_f32_16x16x32_bf16 v[16:19], v[238:241], v[140:143], v[4:7]
	v_mfma_f32_16x16x32_bf16 v[4:7], v[230:233], v[246:249], v[0:3]
	v_mfma_f32_16x16x32_bf16 v[0:3], v[234:237], v[242:245], v[214:217]
	v_mfma_f32_16x16x32_bf16 v[0:3], v[238:241], v[246:249], v[0:3]
	s_barrier
	s_add_u32 s62, s56, 0x100
	s_addc_u32 s63, s57, 0
	s_add_u32 s91, s54, 0x200
	s_addc_u32 s92, s55, 0
	s_mov_b32 s93, 0
.LBB0_2365:
	s_add_u32 s54, s62, 0x100
	s_addc_u32 s55, s63, 0
	s_cmp_eq_u32 s93, 28
	s_cselect_b32 s60, s51, s54
	s_cselect_b32 s61, s43, s55
	s_cselect_b32 s58, s21, s91
	s_cselect_b32 s59, s20, s92
	s_add_u32 s56, s60, 0x80
	s_addc_u32 s57, s61, 0
	s_add_i32 s94, 0, 0x10000
	s_add_i32 s95, 0, 0x14000
	v_add_u32_e32 v140, s94, v159
	v_add_u32_e32 v149, s95, v159
	ds_read_b128 v[128:131], v140
	ds_read_b128 v[132:135], v140 offset:1024
	ds_read_b128 v[136:139], v140 offset:2048
	ds_read_b128 v[140:143], v140 offset:3072
	ds_read_b128 v[166:169], v149
	ds_read_b128 v[170:173], v149 offset:1024
	ds_read_b128 v[174:177], v149 offset:2048
	ds_read_b128 v[178:181], v149 offset:3072
	s_add_u32 s62, s62, 0x80080
	s_addc_u32 s63, s63, 0
	s_mov_b32 m0, s1
	ds_read_b128 v[182:185], v162
	ds_read_b128 v[186:189], v162 offset:1024
	ds_read_b128 v[190:193], v162 offset:2048
	ds_read_b128 v[194:197], v162 offset:3072
	ds_read_b128 v[198:201], v162 offset:4096
	ds_read_b128 v[202:205], v162 offset:5120
	ds_read_b128 v[206:209], v162 offset:6144
	ds_read_b128 v[210:213], v162 offset:7168
	s_nop 0
	global_load_lds_dwordx4 v153, s[62:63]
	s_mov_b32 m0, s12
	s_nop 0
	global_load_lds_dwordx4 v157, s[62:63]
	s_waitcnt vmcnt(8)
	s_waitcnt lgkmcnt(0)
	s_barrier
	s_waitcnt lgkmcnt(0)
	v_mfma_f32_16x16x32_bf16 v[124:127], v[128:131], v[182:185], v[124:127]
	v_mfma_f32_16x16x32_bf16 v[120:123], v[136:139], v[182:185], v[120:123]
	v_mfma_f32_16x16x32_bf16 v[108:111], v[128:131], v[190:193], v[108:111]
	v_mfma_f32_16x16x32_bf16 v[104:107], v[136:139], v[190:193], v[104:107]
	v_mfma_f32_16x16x32_bf16 v[92:95], v[128:131], v[198:201], v[92:95]
	v_mfma_f32_16x16x32_bf16 v[88:91], v[136:139], v[198:201], v[88:91]
	v_mfma_f32_16x16x32_bf16 v[76:79], v[128:131], v[206:209], v[76:79]
	v_mfma_f32_16x16x32_bf16 v[72:75], v[136:139], v[206:209], v[72:75]
	v_mfma_f32_16x16x32_bf16 v[124:127], v[132:135], v[186:189], v[124:127]
	v_mfma_f32_16x16x32_bf16 v[120:123], v[140:143], v[186:189], v[120:123]
	v_mfma_f32_16x16x32_bf16 v[108:111], v[132:135], v[194:197], v[108:111]
	v_mfma_f32_16x16x32_bf16 v[104:107], v[140:143], v[194:197], v[104:107]
	v_mfma_f32_16x16x32_bf16 v[92:95], v[132:135], v[202:205], v[92:95]
	v_mfma_f32_16x16x32_bf16 v[88:91], v[140:143], v[202:205], v[88:91]
	v_mfma_f32_16x16x32_bf16 v[76:79], v[132:135], v[210:213], v[76:79]
	v_mfma_f32_16x16x32_bf16 v[72:75], v[140:143], v[210:213], v[72:75]
	v_mfma_f32_16x16x32_bf16 v[116:119], v[166:169], v[182:185], v[116:119]
	v_mfma_f32_16x16x32_bf16 v[112:115], v[174:177], v[182:185], v[112:115]
	v_mfma_f32_16x16x32_bf16 v[100:103], v[166:169], v[190:193], v[100:103]
	v_mfma_f32_16x16x32_bf16 v[96:99], v[174:177], v[190:193], v[96:99]
	v_mfma_f32_16x16x32_bf16 v[84:87], v[166:169], v[198:201], v[84:87]
	v_mfma_f32_16x16x32_bf16 v[80:83], v[174:177], v[198:201], v[80:83]
	v_mfma_f32_16x16x32_bf16 v[68:71], v[166:169], v[206:209], v[68:71]
	v_mfma_f32_16x16x32_bf16 v[60:63], v[174:177], v[206:209], v[60:63]
	v_mfma_f32_16x16x32_bf16 v[116:119], v[170:173], v[186:189], v[116:119]
	v_mfma_f32_16x16x32_bf16 v[112:115], v[178:181], v[186:189], v[112:115]
	v_mfma_f32_16x16x32_bf16 v[100:103], v[170:173], v[194:197], v[100:103]
	v_mfma_f32_16x16x32_bf16 v[96:99], v[178:181], v[194:197], v[96:99]
	v_mfma_f32_16x16x32_bf16 v[84:87], v[170:173], v[202:205], v[84:87]
	v_mfma_f32_16x16x32_bf16 v[80:83], v[178:181], v[202:205], v[80:83]
	v_mfma_f32_16x16x32_bf16 v[68:71], v[170:173], v[210:213], v[68:71]
	v_mfma_f32_16x16x32_bf16 v[60:63], v[178:181], v[210:213], v[60:63]
	s_barrier
	s_add_i32 s62, s94, s26
	s_mov_b32 m0, s62
	ds_read_b128 v[182:185], v162 offset:16384
	ds_read_b128 v[186:189], v162 offset:17408
	ds_read_b128 v[190:193], v162 offset:18432
	ds_read_b128 v[194:197], v162 offset:19456
	ds_read_b128 v[198:201], v162 offset:20480
	ds_read_b128 v[202:205], v162 offset:21504
	ds_read_b128 v[206:209], v162 offset:22528
	ds_read_b128 v[210:213], v162 offset:23552
	s_nop 0
	global_load_lds_dwordx4 v156, s[58:59]
	s_add_i32 m0, s62, 0x2000
	s_add_u32 s62, s58, 0x80000
	s_addc_u32 s63, s59, 0
	s_add_i32 s94, s95, s26
	s_nop 0
	global_load_lds_dwordx4 v158, s[58:59]
	s_mov_b32 m0, s94
	s_nop 0
	global_load_lds_dwordx4 v156, s[62:63]
	s_add_i32 m0, s94, 0x2000
	s_nop 0
	global_load_lds_dwordx4 v158, s[62:63]
	s_mov_b32 m0, s27
	s_nop 0
	global_load_lds_dwordx4 v153, s[60:61]
	s_mov_b32 m0, s69
	s_nop 0
	global_load_lds_dwordx4 v157, s[60:61]
	s_waitcnt vmcnt(8)
	s_waitcnt lgkmcnt(0)
	s_barrier
	s_waitcnt lgkmcnt(0)
	v_mfma_f32_16x16x32_bf16 v[64:67], v[128:131], v[182:185], v[64:67]
	v_mfma_f32_16x16x32_bf16 v[56:59], v[136:139], v[182:185], v[56:59]
	v_mfma_f32_16x16x32_bf16 v[44:47], v[128:131], v[190:193], v[44:47]
	v_mfma_f32_16x16x32_bf16 v[40:43], v[136:139], v[190:193], v[40:43]
	v_mfma_f32_16x16x32_bf16 v[28:31], v[128:131], v[198:201], v[28:31]
	v_mfma_f32_16x16x32_bf16 v[24:27], v[136:139], v[198:201], v[24:27]
	v_mfma_f32_16x16x32_bf16 v[12:15], v[128:131], v[206:209], v[12:15]
	v_mfma_f32_16x16x32_bf16 v[8:11], v[136:139], v[206:209], v[8:11]
	v_mfma_f32_16x16x32_bf16 v[64:67], v[132:135], v[186:189], v[64:67]
	v_mfma_f32_16x16x32_bf16 v[56:59], v[140:143], v[186:189], v[56:59]
	v_mfma_f32_16x16x32_bf16 v[44:47], v[132:135], v[194:197], v[44:47]
	v_mfma_f32_16x16x32_bf16 v[40:43], v[140:143], v[194:197], v[40:43]
	v_mfma_f32_16x16x32_bf16 v[28:31], v[132:135], v[202:205], v[28:31]
	v_mfma_f32_16x16x32_bf16 v[24:27], v[140:143], v[202:205], v[24:27]
	v_mfma_f32_16x16x32_bf16 v[12:15], v[132:135], v[210:213], v[12:15]
	v_mfma_f32_16x16x32_bf16 v[8:11], v[140:143], v[210:213], v[8:11]
	v_mfma_f32_16x16x32_bf16 v[52:55], v[166:169], v[182:185], v[52:55]
	v_mfma_f32_16x16x32_bf16 v[48:51], v[174:177], v[182:185], v[48:51]
	v_mfma_f32_16x16x32_bf16 v[36:39], v[166:169], v[190:193], v[36:39]
	v_mfma_f32_16x16x32_bf16 v[32:35], v[174:177], v[190:193], v[32:35]
	v_mfma_f32_16x16x32_bf16 v[20:23], v[166:169], v[198:201], v[20:23]
	v_mfma_f32_16x16x32_bf16 v[16:19], v[174:177], v[198:201], v[16:19]
	v_mfma_f32_16x16x32_bf16 v[4:7], v[166:169], v[206:209], v[4:7]
	v_mfma_f32_16x16x32_bf16 v[0:3], v[174:177], v[206:209], v[0:3]
	v_mfma_f32_16x16x32_bf16 v[52:55], v[170:173], v[186:189], v[52:55]
	v_mfma_f32_16x16x32_bf16 v[48:51], v[178:181], v[186:189], v[48:51]
	v_mfma_f32_16x16x32_bf16 v[36:39], v[170:173], v[194:197], v[36:39]
	v_mfma_f32_16x16x32_bf16 v[32:35], v[178:181], v[194:197], v[32:35]
	v_mfma_f32_16x16x32_bf16 v[20:23], v[170:173], v[202:205], v[20:23]
	v_mfma_f32_16x16x32_bf16 v[16:19], v[178:181], v[202:205], v[16:19]
	v_mfma_f32_16x16x32_bf16 v[4:7], v[170:173], v[210:213], v[4:7]
	v_mfma_f32_16x16x32_bf16 v[0:3], v[178:181], v[210:213], v[0:3]
	s_barrier
	ds_read_b128 v[128:131], v144
	ds_read_b128 v[132:135], v144 offset:1024
	ds_read_b128 v[136:139], v144 offset:2048
	ds_read_b128 v[140:143], v144 offset:3072
	ds_read_b128 v[166:169], v148
	ds_read_b128 v[170:173], v148 offset:1024
	ds_read_b128 v[174:177], v148 offset:2048
	ds_read_b128 v[178:181], v148 offset:3072
	s_add_u32 s60, s60, 0x80000
	s_addc_u32 s61, s61, 0
	s_mov_b32 m0, s70
	ds_read_b128 v[182:185], v162 offset:32768
	ds_read_b128 v[186:189], v162 offset:33792
	ds_read_b128 v[190:193], v162 offset:34816
	ds_read_b128 v[194:197], v162 offset:35840
	ds_read_b128 v[198:201], v162 offset:36864
	ds_read_b128 v[202:205], v162 offset:37888
	ds_read_b128 v[206:209], v162 offset:38912
	ds_read_b128 v[210:213], v162 offset:39936
	s_nop 0
	global_load_lds_dwordx4 v153, s[60:61]
	s_mov_b32 m0, s71
	s_nop 0
	global_load_lds_dwordx4 v157, s[60:61]
	s_waitcnt vmcnt(8)
	s_waitcnt lgkmcnt(0)
	s_barrier
	s_waitcnt lgkmcnt(0)
	v_mfma_f32_16x16x32_bf16 v[124:127], v[128:131], v[182:185], v[124:127]
	v_mfma_f32_16x16x32_bf16 v[120:123], v[136:139], v[182:185], v[120:123]
	v_mfma_f32_16x16x32_bf16 v[108:111], v[128:131], v[190:193], v[108:111]
	v_mfma_f32_16x16x32_bf16 v[104:107], v[136:139], v[190:193], v[104:107]
	v_mfma_f32_16x16x32_bf16 v[92:95], v[128:131], v[198:201], v[92:95]
	v_mfma_f32_16x16x32_bf16 v[88:91], v[136:139], v[198:201], v[88:91]
	v_mfma_f32_16x16x32_bf16 v[76:79], v[128:131], v[206:209], v[76:79]
	v_mfma_f32_16x16x32_bf16 v[72:75], v[136:139], v[206:209], v[72:75]
	v_mfma_f32_16x16x32_bf16 v[124:127], v[132:135], v[186:189], v[124:127]
	v_mfma_f32_16x16x32_bf16 v[120:123], v[140:143], v[186:189], v[120:123]
	v_mfma_f32_16x16x32_bf16 v[108:111], v[132:135], v[194:197], v[108:111]
	v_mfma_f32_16x16x32_bf16 v[104:107], v[140:143], v[194:197], v[104:107]
	v_mfma_f32_16x16x32_bf16 v[92:95], v[132:135], v[202:205], v[92:95]
	v_mfma_f32_16x16x32_bf16 v[88:91], v[140:143], v[202:205], v[88:91]
	v_mfma_f32_16x16x32_bf16 v[76:79], v[132:135], v[210:213], v[76:79]
	v_mfma_f32_16x16x32_bf16 v[72:75], v[140:143], v[210:213], v[72:75]
	v_mfma_f32_16x16x32_bf16 v[116:119], v[166:169], v[182:185], v[116:119]
	v_mfma_f32_16x16x32_bf16 v[112:115], v[174:177], v[182:185], v[112:115]
	v_mfma_f32_16x16x32_bf16 v[100:103], v[166:169], v[190:193], v[100:103]
	v_mfma_f32_16x16x32_bf16 v[96:99], v[174:177], v[190:193], v[96:99]
	v_mfma_f32_16x16x32_bf16 v[84:87], v[166:169], v[198:201], v[84:87]
	v_mfma_f32_16x16x32_bf16 v[80:83], v[174:177], v[198:201], v[80:83]
	v_mfma_f32_16x16x32_bf16 v[68:71], v[166:169], v[206:209], v[68:71]
	v_mfma_f32_16x16x32_bf16 v[60:63], v[174:177], v[206:209], v[60:63]
	v_mfma_f32_16x16x32_bf16 v[116:119], v[170:173], v[186:189], v[116:119]
	v_mfma_f32_16x16x32_bf16 v[112:115], v[178:181], v[186:189], v[112:115]
	v_mfma_f32_16x16x32_bf16 v[100:103], v[170:173], v[194:197], v[100:103]
	v_mfma_f32_16x16x32_bf16 v[96:99], v[178:181], v[194:197], v[96:99]
	v_mfma_f32_16x16x32_bf16 v[84:87], v[170:173], v[202:205], v[84:87]
	v_mfma_f32_16x16x32_bf16 v[80:83], v[178:181], v[202:205], v[80:83]
	v_mfma_f32_16x16x32_bf16 v[68:71], v[170:173], v[210:213], v[68:71]
	v_mfma_f32_16x16x32_bf16 v[60:63], v[178:181], v[210:213], v[60:63]
	s_barrier
	s_add_u32 s60, s58, 0x80
	s_mov_b32 m0, s53
	s_addc_u32 s61, s59, 0
	ds_read_b128 v[182:185], v162 offset:49152
	ds_read_b128 v[186:189], v162 offset:50176
	ds_read_b128 v[190:193], v162 offset:51200
	ds_read_b128 v[194:197], v162 offset:52224
	ds_read_b128 v[198:201], v162 offset:53248
	ds_read_b128 v[202:205], v162 offset:54272
	ds_read_b128 v[206:209], v162 offset:55296
	ds_read_b128 v[210:213], v162 offset:56320
	s_add_u32 s58, s58, 0x80080
	global_load_lds_dwordx4 v156, s[60:61]
	s_mov_b32 m0, s79
	s_addc_u32 s59, s59, 0
	global_load_lds_dwordx4 v158, s[60:61]
	s_mov_b32 m0, s80
	s_nop 0
	global_load_lds_dwordx4 v156, s[58:59]
	s_mov_b32 m0, s86
	s_nop 0
	global_load_lds_dwordx4 v158, s[58:59]
	s_mov_b32 m0, s72
	s_nop 0
	global_load_lds_dwordx4 v153, s[56:57]
	s_mov_b32 m0, s73
	s_nop 0
	global_load_lds_dwordx4 v157, s[56:57]
	s_waitcnt vmcnt(8)
	s_waitcnt lgkmcnt(0)
	s_barrier
	s_waitcnt lgkmcnt(0)
	v_mfma_f32_16x16x32_bf16 v[64:67], v[128:131], v[182:185], v[64:67]
	v_mfma_f32_16x16x32_bf16 v[56:59], v[136:139], v[182:185], v[56:59]
	v_mfma_f32_16x16x32_bf16 v[44:47], v[128:131], v[190:193], v[44:47]
	v_mfma_f32_16x16x32_bf16 v[40:43], v[136:139], v[190:193], v[40:43]
	v_mfma_f32_16x16x32_bf16 v[28:31], v[128:131], v[198:201], v[28:31]
	v_mfma_f32_16x16x32_bf16 v[24:27], v[136:139], v[198:201], v[24:27]
	v_mfma_f32_16x16x32_bf16 v[12:15], v[128:131], v[206:209], v[12:15]
	v_mfma_f32_16x16x32_bf16 v[8:11], v[136:139], v[206:209], v[8:11]
	v_mfma_f32_16x16x32_bf16 v[64:67], v[132:135], v[186:189], v[64:67]
	v_mfma_f32_16x16x32_bf16 v[56:59], v[140:143], v[186:189], v[56:59]
	v_mfma_f32_16x16x32_bf16 v[44:47], v[132:135], v[194:197], v[44:47]
	v_mfma_f32_16x16x32_bf16 v[40:43], v[140:143], v[194:197], v[40:43]
	v_mfma_f32_16x16x32_bf16 v[28:31], v[132:135], v[202:205], v[28:31]
	v_mfma_f32_16x16x32_bf16 v[24:27], v[140:143], v[202:205], v[24:27]
	v_mfma_f32_16x16x32_bf16 v[12:15], v[132:135], v[210:213], v[12:15]
	v_mfma_f32_16x16x32_bf16 v[8:11], v[140:143], v[210:213], v[8:11]
	v_mfma_f32_16x16x32_bf16 v[52:55], v[166:169], v[182:185], v[52:55]
	v_mfma_f32_16x16x32_bf16 v[48:51], v[174:177], v[182:185], v[48:51]
	v_mfma_f32_16x16x32_bf16 v[36:39], v[166:169], v[190:193], v[36:39]
	v_mfma_f32_16x16x32_bf16 v[32:35], v[174:177], v[190:193], v[32:35]
	v_mfma_f32_16x16x32_bf16 v[20:23], v[166:169], v[198:201], v[20:23]
	v_mfma_f32_16x16x32_bf16 v[16:19], v[174:177], v[198:201], v[16:19]
	v_mfma_f32_16x16x32_bf16 v[4:7], v[166:169], v[206:209], v[4:7]
	v_mfma_f32_16x16x32_bf16 v[0:3], v[174:177], v[206:209], v[0:3]
	v_mfma_f32_16x16x32_bf16 v[52:55], v[170:173], v[186:189], v[52:55]
	v_mfma_f32_16x16x32_bf16 v[48:51], v[178:181], v[186:189], v[48:51]
	v_mfma_f32_16x16x32_bf16 v[36:39], v[170:173], v[194:197], v[36:39]
	v_mfma_f32_16x16x32_bf16 v[32:35], v[178:181], v[194:197], v[32:35]
	v_mfma_f32_16x16x32_bf16 v[20:23], v[170:173], v[202:205], v[20:23]
	v_mfma_f32_16x16x32_bf16 v[16:19], v[178:181], v[202:205], v[16:19]
	v_mfma_f32_16x16x32_bf16 v[4:7], v[170:173], v[210:213], v[4:7]
	v_mfma_f32_16x16x32_bf16 v[0:3], v[178:181], v[210:213], v[0:3]
	s_barrier
	s_add_i32 s93, s93, 2
	s_add_u32 s91, s91, 0x100
	s_addc_u32 s92, s92, 0
	s_cmp_gt_u32 s93, 29
	s_mov_b64 s[62:63], s[54:55]
	s_cbranch_scc0 .LBB0_2365
	s_and_b64 vcc, exec, s[4:5]
	s_cbranch_vccz .LBB0_2368
	s_barrier

.LBB0_2480:
	s_ashr_i32 s47, s46, 31
	s_lshl_b64 s[20:21], s[46:47], 18
	s_add_u32 s50, s24, s20
	s_addc_u32 s51, s25, s21
	s_add_u32 s60, s56, 0x180
	s_addc_u32 s61, s57, 0
	s_waitcnt lgkmcnt(0)
	s_and_b64 s[20:21], s[58:59], exec
	s_cselect_b32 s5, s51, s55
	s_cselect_b32 s12, s50, s54
	s_add_u32 s58, s54, 0x180
	s_addc_u32 s59, s55, 0
	s_barrier
	s_waitcnt lgkmcnt(0)
	v_mfma_f32_16x16x32_bf16 v[128:131], v[16:19], v[120:123], 0
	v_mfma_f32_16x16x32_bf16 v[132:135], v[20:23], v[124:127], v[128:131]
	v_mfma_f32_16x16x32_bf16 v[128:131], v[24:27], v[120:123], 0
	v_mfma_f32_16x16x32_bf16 v[144:147], v[28:31], v[124:127], v[128:131]
	v_mfma_f32_16x16x32_bf16 v[128:131], v[16:19], v[112:115], 0
	v_mfma_f32_16x16x32_bf16 v[152:155], v[20:23], v[116:119], v[128:131]
	v_mfma_f32_16x16x32_bf16 v[128:131], v[24:27], v[112:115], 0
	v_mfma_f32_16x16x32_bf16 v[168:171], v[28:31], v[116:119], v[128:131]
	v_mfma_f32_16x16x32_bf16 v[128:131], v[16:19], v[96:99], 0
	v_mfma_f32_16x16x32_bf16 v[16:19], v[16:19], v[88:91], 0
	v_mfma_f32_16x16x32_bf16 v[172:175], v[20:23], v[108:111], v[128:131]
	v_mfma_f32_16x16x32_bf16 v[16:19], v[20:23], v[92:95], v[16:19]
	v_mfma_f32_16x16x32_bf16 v[20:23], v[24:27], v[88:91], 0
	v_mfma_f32_16x16x32_bf16 v[128:131], v[24:27], v[96:99], 0
	v_mfma_f32_16x16x32_bf16 v[20:23], v[28:31], v[92:95], v[20:23]
	v_mfma_f32_16x16x32_bf16 v[176:179], v[28:31], v[108:111], v[128:131]
	v_mfma_f32_16x16x32_bf16 v[24:27], v[0:3], v[120:123], 0
	v_mfma_f32_16x16x32_bf16 v[180:183], v[4:7], v[124:127], v[24:27]
	v_mfma_f32_16x16x32_bf16 v[24:27], v[8:11], v[120:123], 0
	v_mfma_f32_16x16x32_bf16 v[188:191], v[12:15], v[124:127], v[24:27]
	v_mfma_f32_16x16x32_bf16 v[24:27], v[0:3], v[112:115], 0
	v_mfma_f32_16x16x32_bf16 v[192:195], v[4:7], v[116:119], v[24:27]
	v_mfma_f32_16x16x32_bf16 v[24:27], v[8:11], v[112:115], 0
	v_mfma_f32_16x16x32_bf16 v[208:211], v[12:15], v[116:119], v[24:27]
	v_mfma_f32_16x16x32_bf16 v[24:27], v[0:3], v[96:99], 0
	v_mfma_f32_16x16x32_bf16 v[0:3], v[0:3], v[88:91], 0
	v_mfma_f32_16x16x32_bf16 v[212:215], v[4:7], v[108:111], v[24:27]
	v_mfma_f32_16x16x32_bf16 v[24:27], v[8:11], v[96:99], 0
	v_mfma_f32_16x16x32_bf16 v[0:3], v[4:7], v[92:95], v[0:3]
	v_mfma_f32_16x16x32_bf16 v[4:7], v[8:11], v[88:91], 0
	v_mfma_f32_16x16x32_bf16 v[216:219], v[12:15], v[108:111], v[24:27]
	v_mfma_f32_16x16x32_bf16 v[220:223], v[12:15], v[92:95], v[4:7]
	s_barrier
	v_add_u32_e32 v124, s78, v203
	v_add_u32_e32 v125, s83, v203
	s_nop 1
	ds_read_b128 v[4:7], v124
	ds_read_b128 v[8:11], v124 offset:1024
	ds_read_b128 v[224:227], v124 offset:2048
	ds_read_b128 v[228:231], v124 offset:3072
	ds_read_b128 v[232:235], v125
	ds_read_b128 v[236:239], v125 offset:1024
	ds_read_b128 v[240:243], v125 offset:2048
	ds_read_b128 v[244:247], v125 offset:3072
	s_add_u32 s20, s56, 0x70100
	s_addc_u32 s21, s57, 0
	s_mov_b32 m0, s70
	ds_read_b128 v[12:15], v206 offset:32768
	ds_read_b128 v[24:27], v206 offset:33792
	ds_read_b128 v[28:31], v206 offset:34816
	ds_read_b128 v[96:99], v206 offset:35840
	ds_read_b128 v[248:251], v206 offset:36864
	ds_read_b128 v[184:187], v206 offset:37888
	ds_read_b128 v[32:35], v206 offset:38912
	ds_read_b128 v[36:39], v206 offset:39936
	s_nop 0
	global_load_lds_dwordx4 v199, s[20:21]
	s_mov_b32 m0, s71
	s_nop 0
	global_load_lds_dwordx4 v201, s[20:21]
	s_waitcnt vmcnt(8)
	s_waitcnt lgkmcnt(0)
	s_barrier
	s_waitcnt lgkmcnt(0)
	v_mfma_f32_16x16x32_bf16 v[88:91], v[4:7], v[12:15], v[136:139]
	v_mfma_f32_16x16x32_bf16 v[40:43], v[4:7], v[28:31], v[40:43]
	v_mfma_f32_16x16x32_bf16 v[164:167], v[8:11], v[24:27], v[88:91]
	v_mfma_f32_16x16x32_bf16 v[88:91], v[224:227], v[12:15], v[140:143]
	v_mfma_f32_16x16x32_bf16 v[140:143], v[8:11], v[96:99], v[40:43]
	v_mfma_f32_16x16x32_bf16 v[40:43], v[224:227], v[28:31], v[44:47]
	v_mfma_f32_16x16x32_bf16 v[136:139], v[228:231], v[96:99], v[40:43]
	v_mfma_f32_16x16x32_bf16 v[40:43], v[4:7], v[248:251], v[48:51]
	v_mfma_f32_16x16x32_bf16 v[116:119], v[8:11], v[184:187], v[40:43]
	v_mfma_f32_16x16x32_bf16 v[40:43], v[224:227], v[248:251], v[52:55]
	v_mfma_f32_16x16x32_bf16 v[112:115], v[228:231], v[184:187], v[40:43]
	v_mfma_f32_16x16x32_bf16 v[40:43], v[4:7], v[32:35], v[56:59]
	v_mfma_f32_16x16x32_bf16 v[92:95], v[8:11], v[36:39], v[40:43]
	v_mfma_f32_16x16x32_bf16 v[40:43], v[224:227], v[32:35], v[60:63]
	v_mfma_f32_16x16x32_bf16 v[160:163], v[228:231], v[24:27], v[88:91]
	v_mfma_f32_16x16x32_bf16 v[88:91], v[228:231], v[36:39], v[40:43]
	v_mfma_f32_16x16x32_bf16 v[40:43], v[232:235], v[12:15], v[64:67]
	v_mfma_f32_16x16x32_bf16 v[12:15], v[240:243], v[12:15], v[68:71]
	v_mfma_f32_16x16x32_bf16 v[148:151], v[244:247], v[24:27], v[12:15]
	v_mfma_f32_16x16x32_bf16 v[12:15], v[232:235], v[28:31], v[72:75]
	v_mfma_f32_16x16x32_bf16 v[128:131], v[236:239], v[96:99], v[12:15]
	v_mfma_f32_16x16x32_bf16 v[12:15], v[240:243], v[28:31], v[76:79]
	v_mfma_f32_16x16x32_bf16 v[120:123], v[244:247], v[96:99], v[12:15]
	v_mfma_f32_16x16x32_bf16 v[12:15], v[232:235], v[248:251], v[80:83]
	v_mfma_f32_16x16x32_bf16 v[108:111], v[236:239], v[184:187], v[12:15]
	v_mfma_f32_16x16x32_bf16 v[12:15], v[240:243], v[248:251], v[84:87]
	v_mfma_f32_16x16x32_bf16 v[96:99], v[244:247], v[184:187], v[12:15]
	v_mfma_f32_16x16x32_bf16 v[12:15], v[232:235], v[32:35], v[100:103]
	v_mfma_f32_16x16x32_bf16 v[84:87], v[236:239], v[36:39], v[12:15]
	v_mfma_f32_16x16x32_bf16 v[12:15], v[240:243], v[32:35], v[104:107]
	v_mfma_f32_16x16x32_bf16 v[156:159], v[236:239], v[24:27], v[40:43]
	v_mfma_f32_16x16x32_bf16 v[72:75], v[244:247], v[36:39], v[12:15]
	s_barrier
	s_add_i32 s20, s78, s26
	s_mov_b32 m0, s20
	s_add_i32 s21, s20, 0x2000
	ds_read_b128 v[32:35], v206 offset:49152
	ds_read_b128 v[36:39], v206 offset:50176
	ds_read_b128 v[48:51], v206 offset:51200
	ds_read_b128 v[52:55], v206 offset:52224
	ds_read_b128 v[76:79], v206 offset:53248
	ds_read_b128 v[80:83], v206 offset:54272
	ds_read_b128 v[100:103], v206 offset:55296
	ds_read_b128 v[104:107], v206 offset:56320
	s_nop 0
	global_load_lds_dwordx4 v200, s[58:59]
	s_mov_b32 m0, s21
	s_nop 0
	global_load_lds_dwordx4 v202, s[58:59]
	s_add_u32 s58, s54, 0x20180
	s_addc_u32 s59, s55, 0
	s_add_i32 s45, s83, s26
	s_mov_b32 m0, s45
	s_add_i32 s47, s45, 0x2000
	s_nop 0
	global_load_lds_dwordx4 v200, s[58:59]
	s_mov_b32 m0, s47
	s_nop 0
	global_load_lds_dwordx4 v202, s[58:59]
	s_mov_b32 m0, s72
	s_nop 0
	global_load_lds_dwordx4 v199, s[60:61]
	s_mov_b32 m0, s73
	s_nop 0
	global_load_lds_dwordx4 v201, s[60:61]
	s_waitcnt vmcnt(8)
	s_waitcnt lgkmcnt(0)
	s_barrier
	s_waitcnt lgkmcnt(0)
	v_mfma_f32_16x16x32_bf16 v[12:15], v[4:7], v[32:35], v[132:135]
	v_mfma_f32_16x16x32_bf16 v[68:71], v[8:11], v[36:39], v[12:15]
	v_mfma_f32_16x16x32_bf16 v[12:15], v[224:227], v[32:35], v[144:147]
	v_mfma_f32_16x16x32_bf16 v[64:67], v[228:231], v[36:39], v[12:15]
	v_mfma_f32_16x16x32_bf16 v[12:15], v[4:7], v[48:51], v[152:155]
	v_mfma_f32_16x16x32_bf16 v[44:47], v[8:11], v[52:55], v[12:15]
	v_mfma_f32_16x16x32_bf16 v[12:15], v[224:227], v[48:51], v[168:171]
	v_mfma_f32_16x16x32_bf16 v[40:43], v[228:231], v[52:55], v[12:15]
	v_mfma_f32_16x16x32_bf16 v[12:15], v[4:7], v[76:79], v[172:175]
	v_mfma_f32_16x16x32_bf16 v[28:31], v[8:11], v[80:83], v[12:15]
	v_mfma_f32_16x16x32_bf16 v[12:15], v[224:227], v[76:79], v[176:179]
	v_mfma_f32_16x16x32_bf16 v[4:7], v[4:7], v[100:103], v[16:19]
	v_mfma_f32_16x16x32_bf16 v[24:27], v[228:231], v[80:83], v[12:15]
	v_mfma_f32_16x16x32_bf16 v[12:15], v[8:11], v[104:107], v[4:7]
	v_mfma_f32_16x16x32_bf16 v[4:7], v[224:227], v[100:103], v[20:23]
	v_mfma_f32_16x16x32_bf16 v[8:11], v[228:231], v[104:107], v[4:7]
	v_mfma_f32_16x16x32_bf16 v[4:7], v[232:235], v[32:35], v[180:183]
	v_mfma_f32_16x16x32_bf16 v[60:63], v[236:239], v[36:39], v[4:7]
	v_mfma_f32_16x16x32_bf16 v[4:7], v[240:243], v[32:35], v[188:191]
	v_mfma_f32_16x16x32_bf16 v[56:59], v[244:247], v[36:39], v[4:7]
	v_mfma_f32_16x16x32_bf16 v[4:7], v[232:235], v[48:51], v[192:195]
	v_mfma_f32_16x16x32_bf16 v[36:39], v[236:239], v[52:55], v[4:7]
	v_mfma_f32_16x16x32_bf16 v[4:7], v[240:243], v[48:51], v[208:211]
	v_mfma_f32_16x16x32_bf16 v[32:35], v[244:247], v[52:55], v[4:7]
	v_mfma_f32_16x16x32_bf16 v[4:7], v[232:235], v[76:79], v[212:215]
	v_mfma_f32_16x16x32_bf16 v[20:23], v[236:239], v[80:83], v[4:7]
	v_mfma_f32_16x16x32_bf16 v[4:7], v[240:243], v[76:79], v[216:219]
	v_mfma_f32_16x16x32_bf16 v[0:3], v[232:235], v[100:103], v[0:3]
	v_mfma_f32_16x16x32_bf16 v[16:19], v[244:247], v[80:83], v[4:7]
	v_mfma_f32_16x16x32_bf16 v[4:7], v[236:239], v[104:107], v[0:3]
	v_mfma_f32_16x16x32_bf16 v[0:3], v[240:243], v[100:103], v[220:223]
	v_mfma_f32_16x16x32_bf16 v[0:3], v[244:247], v[104:107], v[0:3]
	s_barrier
	s_add_u32 s62, s56, 0x100
	s_addc_u32 s63, s57, 0
	s_add_u32 s53, s54, 0x200
	s_addc_u32 s79, s55, 0
	s_mov_b32 s80, 0
.LBB0_2481:
	s_add_u32 s54, s62, 0x100
	s_addc_u32 s55, s63, 0
	s_cmp_eq_u32 s80, 4
	s_cselect_b32 s60, s48, s54
	s_cselect_b32 s61, s49, s55
	s_cselect_b32 s58, s12, s53
	s_cselect_b32 s59, s5, s79
	s_add_u32 s56, s60, 0x80
	s_addc_u32 s57, s61, 0
	s_add_i32 s90, 0, 0x10000
	s_add_i32 s91, 0, 0x14000
	v_add_u32_e32 v80, s90, v203
	v_add_u32_e32 v126, s91, v203
	ds_read_b128 v[48:51], v80
	ds_read_b128 v[52:55], v80 offset:1024
	ds_read_b128 v[76:79], v80 offset:2048
	ds_read_b128 v[80:83], v80 offset:3072
	ds_read_b128 v[100:103], v126
	ds_read_b128 v[104:107], v126 offset:1024
	ds_read_b128 v[132:135], v126 offset:2048
	ds_read_b128 v[144:147], v126 offset:3072
	s_add_u32 s62, s62, 0x70080
	s_addc_u32 s63, s63, 0
	s_mov_b32 m0, s0
	ds_read_b128 v[152:155], v206
	ds_read_b128 v[168:171], v206 offset:1024
	ds_read_b128 v[172:175], v206 offset:2048
	ds_read_b128 v[176:179], v206 offset:3072
	ds_read_b128 v[180:183], v206 offset:4096
	ds_read_b128 v[184:187], v206 offset:5120
	ds_read_b128 v[188:191], v206 offset:6144
	ds_read_b128 v[192:195], v206 offset:7168
	s_nop 0
	global_load_lds_dwordx4 v199, s[62:63]
	s_mov_b32 m0, s1
	s_nop 0
	global_load_lds_dwordx4 v201, s[62:63]
	s_waitcnt vmcnt(8)
	s_waitcnt lgkmcnt(0)
	s_barrier
	s_waitcnt lgkmcnt(0)
	v_mfma_f32_16x16x32_bf16 v[164:167], v[48:51], v[152:155], v[164:167]
	v_mfma_f32_16x16x32_bf16 v[160:163], v[76:79], v[152:155], v[160:163]
	v_mfma_f32_16x16x32_bf16 v[140:143], v[48:51], v[172:175], v[140:143]
	v_mfma_f32_16x16x32_bf16 v[136:139], v[76:79], v[172:175], v[136:139]
	v_mfma_f32_16x16x32_bf16 v[116:119], v[48:51], v[180:183], v[116:119]
	v_mfma_f32_16x16x32_bf16 v[112:115], v[76:79], v[180:183], v[112:115]
	v_mfma_f32_16x16x32_bf16 v[92:95], v[48:51], v[188:191], v[92:95]
	v_mfma_f32_16x16x32_bf16 v[88:91], v[76:79], v[188:191], v[88:91]
	v_mfma_f32_16x16x32_bf16 v[164:167], v[52:55], v[168:171], v[164:167]
	v_mfma_f32_16x16x32_bf16 v[160:163], v[80:83], v[168:171], v[160:163]
	v_mfma_f32_16x16x32_bf16 v[140:143], v[52:55], v[176:179], v[140:143]
	v_mfma_f32_16x16x32_bf16 v[136:139], v[80:83], v[176:179], v[136:139]
	v_mfma_f32_16x16x32_bf16 v[116:119], v[52:55], v[184:187], v[116:119]
	v_mfma_f32_16x16x32_bf16 v[112:115], v[80:83], v[184:187], v[112:115]
	v_mfma_f32_16x16x32_bf16 v[92:95], v[52:55], v[192:195], v[92:95]
	v_mfma_f32_16x16x32_bf16 v[88:91], v[80:83], v[192:195], v[88:91]
	v_mfma_f32_16x16x32_bf16 v[156:159], v[100:103], v[152:155], v[156:159]
	v_mfma_f32_16x16x32_bf16 v[148:151], v[132:135], v[152:155], v[148:151]
	v_mfma_f32_16x16x32_bf16 v[126:129], v[100:103], v[172:175], v[128:131]
	v_mfma_f32_16x16x32_bf16 v[120:123], v[132:135], v[172:175], v[120:123]
	v_mfma_f32_16x16x32_bf16 v[108:111], v[100:103], v[180:183], v[108:111]
	v_mfma_f32_16x16x32_bf16 v[96:99], v[132:135], v[180:183], v[96:99]
	v_mfma_f32_16x16x32_bf16 v[84:87], v[100:103], v[188:191], v[84:87]
	v_mfma_f32_16x16x32_bf16 v[72:75], v[132:135], v[188:191], v[72:75]
	v_mfma_f32_16x16x32_bf16 v[156:159], v[104:107], v[168:171], v[156:159]
	v_mfma_f32_16x16x32_bf16 v[148:151], v[144:147], v[168:171], v[148:151]
	v_mfma_f32_16x16x32_bf16 v[126:129], v[104:107], v[176:179], v[126:129]
	v_mfma_f32_16x16x32_bf16 v[120:123], v[144:147], v[176:179], v[120:123]
	v_mfma_f32_16x16x32_bf16 v[108:111], v[104:107], v[184:187], v[108:111]
	v_mfma_f32_16x16x32_bf16 v[96:99], v[144:147], v[184:187], v[96:99]
	v_mfma_f32_16x16x32_bf16 v[84:87], v[104:107], v[192:195], v[84:87]
	v_mfma_f32_16x16x32_bf16 v[72:75], v[144:147], v[192:195], v[72:75]
	s_barrier
	s_add_i32 s62, s90, s26
	s_mov_b32 m0, s62
	ds_read_b128 v[152:155], v206 offset:16384
	ds_read_b128 v[168:171], v206 offset:17408
	ds_read_b128 v[172:175], v206 offset:18432
	ds_read_b128 v[176:179], v206 offset:19456
	ds_read_b128 v[180:183], v206 offset:20480
	ds_read_b128 v[184:187], v206 offset:21504
	ds_read_b128 v[188:191], v206 offset:22528
	ds_read_b128 v[192:195], v206 offset:23552
	s_nop 0
	global_load_lds_dwordx4 v200, s[58:59]
	s_add_i32 m0, s62, 0x2000
	s_add_u32 s62, s58, 0x20000
	s_addc_u32 s63, s59, 0
	s_add_i32 s90, s91, s26
	s_nop 0
	global_load_lds_dwordx4 v202, s[58:59]
	s_mov_b32 m0, s90
	s_nop 0
	global_load_lds_dwordx4 v200, s[62:63]
	s_add_i32 m0, s90, 0x2000
	s_nop 0
	global_load_lds_dwordx4 v202, s[62:63]
	s_mov_b32 m0, s27
	s_nop 0
	global_load_lds_dwordx4 v199, s[60:61]
	s_mov_b32 m0, s69
	s_nop 0
	global_load_lds_dwordx4 v201, s[60:61]
	s_waitcnt vmcnt(8)
	s_waitcnt lgkmcnt(0)
	s_barrier
	s_waitcnt lgkmcnt(0)
	v_mfma_f32_16x16x32_bf16 v[68:71], v[48:51], v[152:155], v[68:71]
	v_mfma_f32_16x16x32_bf16 v[64:67], v[76:79], v[152:155], v[64:67]
	v_mfma_f32_16x16x32_bf16 v[44:47], v[48:51], v[172:175], v[44:47]
	v_mfma_f32_16x16x32_bf16 v[40:43], v[76:79], v[172:175], v[40:43]
	v_mfma_f32_16x16x32_bf16 v[28:31], v[48:51], v[180:183], v[28:31]
	v_mfma_f32_16x16x32_bf16 v[24:27], v[76:79], v[180:183], v[24:27]
	v_mfma_f32_16x16x32_bf16 v[12:15], v[48:51], v[188:191], v[12:15]
	v_mfma_f32_16x16x32_bf16 v[8:11], v[76:79], v[188:191], v[8:11]
	v_mfma_f32_16x16x32_bf16 v[68:71], v[52:55], v[168:171], v[68:71]
	v_mfma_f32_16x16x32_bf16 v[64:67], v[80:83], v[168:171], v[64:67]
	v_mfma_f32_16x16x32_bf16 v[44:47], v[52:55], v[176:179], v[44:47]
	v_mfma_f32_16x16x32_bf16 v[40:43], v[80:83], v[176:179], v[40:43]
	v_mfma_f32_16x16x32_bf16 v[28:31], v[52:55], v[184:187], v[28:31]
	v_mfma_f32_16x16x32_bf16 v[24:27], v[80:83], v[184:187], v[24:27]
	v_mfma_f32_16x16x32_bf16 v[12:15], v[52:55], v[192:195], v[12:15]
	v_mfma_f32_16x16x32_bf16 v[8:11], v[80:83], v[192:195], v[8:11]
	v_mfma_f32_16x16x32_bf16 v[36:39], v[100:103], v[172:175], v[36:39]
	v_mfma_f32_16x16x32_bf16 v[32:35], v[132:135], v[172:175], v[32:35]
	v_mfma_f32_16x16x32_bf16 v[20:23], v[100:103], v[180:183], v[20:23]
	v_mfma_f32_16x16x32_bf16 v[16:19], v[132:135], v[180:183], v[16:19]
	v_mfma_f32_16x16x32_bf16 v[4:7], v[100:103], v[188:191], v[4:7]
	v_mfma_f32_16x16x32_bf16 v[0:3], v[132:135], v[188:191], v[0:3]
	v_mfma_f32_16x16x32_bf16 v[48:51], v[100:103], v[152:155], v[60:63]
	v_mfma_f32_16x16x32_bf16 v[52:55], v[132:135], v[152:155], v[56:59]
	v_mfma_f32_16x16x32_bf16 v[36:39], v[104:107], v[176:179], v[36:39]
	v_mfma_f32_16x16x32_bf16 v[32:35], v[144:147], v[176:179], v[32:35]
	v_mfma_f32_16x16x32_bf16 v[20:23], v[104:107], v[184:187], v[20:23]
	v_mfma_f32_16x16x32_bf16 v[16:19], v[144:147], v[184:187], v[16:19]
	v_mfma_f32_16x16x32_bf16 v[4:7], v[104:107], v[192:195], v[4:7]
	v_mfma_f32_16x16x32_bf16 v[0:3], v[144:147], v[192:195], v[0:3]
	v_mfma_f32_16x16x32_bf16 v[48:51], v[104:107], v[168:171], v[48:51]
	v_mfma_f32_16x16x32_bf16 v[52:55], v[144:147], v[168:171], v[52:55]
	s_barrier
	ds_read_b128 v[56:59], v124
	ds_read_b128 v[60:63], v124 offset:1024
	ds_read_b128 v[76:79], v124 offset:2048
	ds_read_b128 v[80:83], v124 offset:3072
	ds_read_b128 v[100:103], v125
	ds_read_b128 v[104:107], v125 offset:1024
	ds_read_b128 v[132:135], v125 offset:2048
	ds_read_b128 v[144:147], v125 offset:3072
	s_add_u32 s60, s60, 0x70000
	s_addc_u32 s61, s61, 0
	s_mov_b32 m0, s70
	ds_read_b128 v[152:155], v206 offset:32768
	ds_read_b128 v[168:171], v206 offset:33792
	ds_read_b128 v[172:175], v206 offset:34816
	ds_read_b128 v[176:179], v206 offset:35840
	ds_read_b128 v[180:183], v206 offset:36864
	ds_read_b128 v[184:187], v206 offset:37888
	ds_read_b128 v[188:191], v206 offset:38912
	ds_read_b128 v[192:195], v206 offset:39936
	s_nop 0
	global_load_lds_dwordx4 v199, s[60:61]
	s_mov_b32 m0, s71
	s_nop 0
	global_load_lds_dwordx4 v201, s[60:61]
	s_waitcnt vmcnt(8)
	s_waitcnt lgkmcnt(0)
	s_barrier
	s_waitcnt lgkmcnt(0)
	v_mfma_f32_16x16x32_bf16 v[164:167], v[56:59], v[152:155], v[164:167]
	v_mfma_f32_16x16x32_bf16 v[160:163], v[76:79], v[152:155], v[160:163]
	v_mfma_f32_16x16x32_bf16 v[140:143], v[56:59], v[172:175], v[140:143]
	v_mfma_f32_16x16x32_bf16 v[136:139], v[76:79], v[172:175], v[136:139]
	v_mfma_f32_16x16x32_bf16 v[116:119], v[56:59], v[180:183], v[116:119]
	v_mfma_f32_16x16x32_bf16 v[112:115], v[76:79], v[180:183], v[112:115]
	v_mfma_f32_16x16x32_bf16 v[92:95], v[56:59], v[188:191], v[92:95]
	v_mfma_f32_16x16x32_bf16 v[88:91], v[76:79], v[188:191], v[88:91]
	v_mfma_f32_16x16x32_bf16 v[164:167], v[60:63], v[168:171], v[164:167]
	v_mfma_f32_16x16x32_bf16 v[160:163], v[80:83], v[168:171], v[160:163]
	v_mfma_f32_16x16x32_bf16 v[140:143], v[60:63], v[176:179], v[140:143]
	v_mfma_f32_16x16x32_bf16 v[136:139], v[80:83], v[176:179], v[136:139]
	v_mfma_f32_16x16x32_bf16 v[116:119], v[60:63], v[184:187], v[116:119]
	v_mfma_f32_16x16x32_bf16 v[112:115], v[80:83], v[184:187], v[112:115]
	v_mfma_f32_16x16x32_bf16 v[92:95], v[60:63], v[192:195], v[92:95]
	v_mfma_f32_16x16x32_bf16 v[88:91], v[80:83], v[192:195], v[88:91]
	v_mfma_f32_16x16x32_bf16 v[156:159], v[100:103], v[152:155], v[156:159]
	v_mfma_f32_16x16x32_bf16 v[148:151], v[132:135], v[152:155], v[148:151]
	v_mfma_f32_16x16x32_bf16 v[126:129], v[100:103], v[172:175], v[126:129]
	v_mfma_f32_16x16x32_bf16 v[120:123], v[132:135], v[172:175], v[120:123]
	v_mfma_f32_16x16x32_bf16 v[108:111], v[100:103], v[180:183], v[108:111]
	v_mfma_f32_16x16x32_bf16 v[96:99], v[132:135], v[180:183], v[96:99]
	v_mfma_f32_16x16x32_bf16 v[84:87], v[100:103], v[188:191], v[84:87]
	v_mfma_f32_16x16x32_bf16 v[72:75], v[132:135], v[188:191], v[72:75]
	v_mfma_f32_16x16x32_bf16 v[156:159], v[104:107], v[168:171], v[156:159]
	v_mfma_f32_16x16x32_bf16 v[148:151], v[144:147], v[168:171], v[148:151]
	v_mfma_f32_16x16x32_bf16 v[128:131], v[104:107], v[176:179], v[126:129]
	v_mfma_f32_16x16x32_bf16 v[120:123], v[144:147], v[176:179], v[120:123]
	v_mfma_f32_16x16x32_bf16 v[108:111], v[104:107], v[184:187], v[108:111]
	v_mfma_f32_16x16x32_bf16 v[96:99], v[144:147], v[184:187], v[96:99]
	v_mfma_f32_16x16x32_bf16 v[84:87], v[104:107], v[192:195], v[84:87]
	v_mfma_f32_16x16x32_bf16 v[72:75], v[144:147], v[192:195], v[72:75]
	s_barrier
	s_add_u32 s60, s58, 0x80
	s_mov_b32 m0, s20
	s_addc_u32 s61, s59, 0
	ds_read_b128 v[152:155], v206 offset:49152
	ds_read_b128 v[168:171], v206 offset:50176
	ds_read_b128 v[172:175], v206 offset:51200
	ds_read_b128 v[176:179], v206 offset:52224
	ds_read_b128 v[180:183], v206 offset:53248
	ds_read_b128 v[184:187], v206 offset:54272
	ds_read_b128 v[188:191], v206 offset:55296
	ds_read_b128 v[192:195], v206 offset:56320
	s_add_u32 s58, s58, 0x20080
	global_load_lds_dwordx4 v200, s[60:61]
	s_mov_b32 m0, s21
	s_addc_u32 s59, s59, 0
	global_load_lds_dwordx4 v202, s[60:61]
	s_mov_b32 m0, s45
	s_nop 0
	global_load_lds_dwordx4 v200, s[58:59]
	s_mov_b32 m0, s47
	s_nop 0
	global_load_lds_dwordx4 v202, s[58:59]
	s_mov_b32 m0, s72
	s_nop 0
	global_load_lds_dwordx4 v199, s[56:57]
	s_mov_b32 m0, s73
	s_nop 0
	global_load_lds_dwordx4 v201, s[56:57]
	s_waitcnt vmcnt(8)
	s_waitcnt lgkmcnt(0)
	s_barrier
	s_waitcnt lgkmcnt(0)
	v_mfma_f32_16x16x32_bf16 v[68:71], v[56:59], v[152:155], v[68:71]
	v_mfma_f32_16x16x32_bf16 v[64:67], v[76:79], v[152:155], v[64:67]
	v_mfma_f32_16x16x32_bf16 v[44:47], v[56:59], v[172:175], v[44:47]
	v_mfma_f32_16x16x32_bf16 v[40:43], v[76:79], v[172:175], v[40:43]
	v_mfma_f32_16x16x32_bf16 v[28:31], v[56:59], v[180:183], v[28:31]
	v_mfma_f32_16x16x32_bf16 v[24:27], v[76:79], v[180:183], v[24:27]
	v_mfma_f32_16x16x32_bf16 v[12:15], v[56:59], v[188:191], v[12:15]
	v_mfma_f32_16x16x32_bf16 v[8:11], v[76:79], v[188:191], v[8:11]
	v_mfma_f32_16x16x32_bf16 v[68:71], v[60:63], v[168:171], v[68:71]
	v_mfma_f32_16x16x32_bf16 v[64:67], v[80:83], v[168:171], v[64:67]
	v_mfma_f32_16x16x32_bf16 v[44:47], v[60:63], v[176:179], v[44:47]
	v_mfma_f32_16x16x32_bf16 v[40:43], v[80:83], v[176:179], v[40:43]
	v_mfma_f32_16x16x32_bf16 v[28:31], v[60:63], v[184:187], v[28:31]
	v_mfma_f32_16x16x32_bf16 v[24:27], v[80:83], v[184:187], v[24:27]
	v_mfma_f32_16x16x32_bf16 v[12:15], v[60:63], v[192:195], v[12:15]
	v_mfma_f32_16x16x32_bf16 v[8:11], v[80:83], v[192:195], v[8:11]
	v_mfma_f32_16x16x32_bf16 v[48:51], v[100:103], v[152:155], v[48:51]
	v_mfma_f32_16x16x32_bf16 v[60:63], v[104:107], v[168:171], v[48:51]
	v_mfma_f32_16x16x32_bf16 v[48:51], v[132:135], v[152:155], v[52:55]
	v_mfma_f32_16x16x32_bf16 v[36:39], v[100:103], v[172:175], v[36:39]
	v_mfma_f32_16x16x32_bf16 v[32:35], v[132:135], v[172:175], v[32:35]
	v_mfma_f32_16x16x32_bf16 v[20:23], v[100:103], v[180:183], v[20:23]
	v_mfma_f32_16x16x32_bf16 v[16:19], v[132:135], v[180:183], v[16:19]
	v_mfma_f32_16x16x32_bf16 v[4:7], v[100:103], v[188:191], v[4:7]
	v_mfma_f32_16x16x32_bf16 v[0:3], v[132:135], v[188:191], v[0:3]
	v_mfma_f32_16x16x32_bf16 v[56:59], v[144:147], v[168:171], v[48:51]
	v_mfma_f32_16x16x32_bf16 v[36:39], v[104:107], v[176:179], v[36:39]
	v_mfma_f32_16x16x32_bf16 v[32:35], v[144:147], v[176:179], v[32:35]
	v_mfma_f32_16x16x32_bf16 v[20:23], v[104:107], v[184:187], v[20:23]
	v_mfma_f32_16x16x32_bf16 v[16:19], v[144:147], v[184:187], v[16:19]
	v_mfma_f32_16x16x32_bf16 v[4:7], v[104:107], v[192:195], v[4:7]
	v_mfma_f32_16x16x32_bf16 v[0:3], v[144:147], v[192:195], v[0:3]
	s_barrier
	s_add_i32 s80, s80, 2
	s_add_u32 s53, s53, 0x100
	s_addc_u32 s79, s79, 0
	s_cmp_gt_u32 s80, 5
	s_mov_b64 s[62:63], s[54:55]
	s_cbranch_scc0 .LBB0_2481
	s_and_b64 vcc, exec, s[42:43]
	s_cbranch_vccz .LBB0_2484
	s_barrier

.LBB0_2774:
	s_add_u32 s20, s54, 0x100
	s_addc_u32 s21, s55, 0
	s_waitcnt lgkmcnt(0)
	s_add_u32 s50, s52, 0x100
	s_addc_u32 s51, s53, 0
	s_barrier
	s_waitcnt lgkmcnt(0)
	v_mfma_f32_16x16x32_bf16 v[32:35], v[16:19], v[68:71], 0
	v_mfma_f32_16x16x32_bf16 v[36:39], v[24:27], v[68:71], 0
	v_mfma_f32_16x16x32_bf16 v[40:43], v[16:19], v[84:87], 0
	v_mfma_f32_16x16x32_bf16 v[44:47], v[24:27], v[84:87], 0
	v_mfma_f32_16x16x32_bf16 v[48:51], v[16:19], v[92:95], 0
	v_mfma_f32_16x16x32_bf16 v[52:55], v[24:27], v[92:95], 0
	v_mfma_f32_16x16x32_bf16 v[56:59], v[16:19], v[76:79], 0
	v_mfma_f32_16x16x32_bf16 v[60:63], v[24:27], v[76:79], 0
	v_mfma_f32_16x16x32_bf16 v[138:141], v[20:23], v[72:75], v[32:35]
	v_mfma_f32_16x16x32_bf16 v[36:39], v[28:31], v[72:75], v[36:39]
	v_mfma_f32_16x16x32_bf16 v[40:43], v[20:23], v[88:91], v[40:43]
	v_mfma_f32_16x16x32_bf16 v[44:47], v[28:31], v[88:91], v[44:47]
	v_mfma_f32_16x16x32_bf16 v[48:51], v[20:23], v[96:99], v[48:51]
	v_mfma_f32_16x16x32_bf16 v[52:55], v[28:31], v[96:99], v[52:55]
	v_mfma_f32_16x16x32_bf16 v[56:59], v[20:23], v[80:83], v[56:59]
	v_mfma_f32_16x16x32_bf16 v[60:63], v[28:31], v[80:83], v[60:63]
	v_mfma_f32_16x16x32_bf16 v[64:67], v[0:3], v[68:71], 0
	v_mfma_f32_16x16x32_bf16 v[68:71], v[8:11], v[68:71], 0
	v_mfma_f32_16x16x32_bf16 v[64:67], v[4:7], v[72:75], v[64:67]
	v_mfma_f32_16x16x32_bf16 v[68:71], v[12:15], v[72:75], v[68:71]
	v_mfma_f32_16x16x32_bf16 v[72:75], v[0:3], v[84:87], 0
	v_mfma_f32_16x16x32_bf16 v[84:87], v[8:11], v[84:87], 0
	v_mfma_f32_16x16x32_bf16 v[72:75], v[4:7], v[88:91], v[72:75]
	v_mfma_f32_16x16x32_bf16 v[84:87], v[12:15], v[88:91], v[84:87]
	v_mfma_f32_16x16x32_bf16 v[88:91], v[0:3], v[92:95], 0
	v_mfma_f32_16x16x32_bf16 v[92:95], v[8:11], v[92:95], 0
	v_mfma_f32_16x16x32_bf16 v[88:91], v[4:7], v[96:99], v[88:91]
	v_mfma_f32_16x16x32_bf16 v[92:95], v[12:15], v[96:99], v[92:95]
	v_mfma_f32_16x16x32_bf16 v[96:99], v[0:3], v[76:79], 0
	v_mfma_f32_16x16x32_bf16 v[76:79], v[8:11], v[76:79], 0
	v_mfma_f32_16x16x32_bf16 v[108:111], v[4:7], v[80:83], v[96:99]
	v_mfma_f32_16x16x32_bf16 v[112:115], v[12:15], v[80:83], v[76:79]
	s_barrier
	s_mov_b32 m0, s60
	ds_read_b128 v[120:123], v209 offset:16384
	ds_read_b128 v[124:127], v209 offset:17408
	ds_read_b128 v[104:107], v209 offset:18432
	ds_read_b128 v[116:119], v209 offset:19456
	ds_read_b128 v[96:99], v209 offset:20480
	ds_read_b128 v[100:103], v209 offset:21504
	ds_read_b128 v[76:79], v209 offset:22528
	ds_read_b128 v[80:83], v209 offset:23552
	s_nop 0
	global_load_lds_dwordx4 v203, s[50:51]
	s_mov_b32 m0, s61
	s_nop 0
	global_load_lds_dwordx4 v205, s[50:51]
	s_add_u32 s50, s52, 0x80100
	s_addc_u32 s51, s53, 0
	s_mov_b32 m0, s62
	s_and_b64 vcc, exec, s[48:49]
	global_load_lds_dwordx4 v203, s[50:51]
	s_mov_b32 m0, s63
	s_nop 0
	global_load_lds_dwordx4 v205, s[50:51]
	s_mov_b32 m0, s27
	s_mov_b64 s[50:51], -1
	global_load_lds_dwordx4 v202, s[20:21]
	s_mov_b32 m0, s64
	s_nop 0
	global_load_lds_dwordx4 v204, s[20:21]
	s_cbranch_vccz .LBB0_2776
	s_waitcnt vmcnt(8)
	s_mov_b64 s[50:51], 0

.LBB0_2778:
	s_ashr_i32 s43, s42, 31
	s_lshl_b64 s[20:21], s[42:43], 20
	s_add_u32 s48, s13, s20
	s_addc_u32 s49, s82, s21
	s_and_b64 s[20:21], s[46:47], exec
	s_cselect_b32 s3, s49, s55
	s_cselect_b32 s5, s48, s54
	s_ashr_i32 s45, s44, 31
	s_lshl_b64 s[20:21], s[44:45], 20
	s_add_u32 s50, s24, s20
	s_addc_u32 s51, s25, s21
	s_and_b64 s[20:21], s[46:47], exec
	s_cselect_b32 s12, s51, s53
	s_cselect_b32 s20, s50, s52
	s_add_u32 s56, s54, 0x180
	s_waitcnt lgkmcnt(0)
	s_addc_u32 s57, s55, 0
	s_add_u32 s58, s52, 0x180
	s_addc_u32 s59, s53, 0
	s_barrier
	s_waitcnt lgkmcnt(0)
	v_mfma_f32_16x16x32_bf16 v[128:131], v[16:19], v[120:123], 0
	v_mfma_f32_16x16x32_bf16 v[134:137], v[20:23], v[124:127], v[128:131]
	v_mfma_f32_16x16x32_bf16 v[128:131], v[24:27], v[120:123], 0
	v_mfma_f32_16x16x32_bf16 v[156:159], v[28:31], v[124:127], v[128:131]
	v_mfma_f32_16x16x32_bf16 v[128:131], v[16:19], v[104:107], 0
	v_mfma_f32_16x16x32_bf16 v[160:163], v[20:23], v[116:119], v[128:131]
	v_mfma_f32_16x16x32_bf16 v[128:131], v[24:27], v[104:107], 0
	v_mfma_f32_16x16x32_bf16 v[164:167], v[28:31], v[116:119], v[128:131]
	v_mfma_f32_16x16x32_bf16 v[128:131], v[16:19], v[96:99], 0
	v_mfma_f32_16x16x32_bf16 v[16:19], v[16:19], v[76:79], 0
	v_mfma_f32_16x16x32_bf16 v[168:171], v[20:23], v[100:103], v[128:131]
	v_mfma_f32_16x16x32_bf16 v[16:19], v[20:23], v[80:83], v[16:19]
	v_mfma_f32_16x16x32_bf16 v[20:23], v[24:27], v[76:79], 0
	v_mfma_f32_16x16x32_bf16 v[128:131], v[24:27], v[96:99], 0
	v_mfma_f32_16x16x32_bf16 v[20:23], v[28:31], v[80:83], v[20:23]
	v_mfma_f32_16x16x32_bf16 v[172:175], v[28:31], v[100:103], v[128:131]
	v_mfma_f32_16x16x32_bf16 v[24:27], v[0:3], v[120:123], 0
	v_mfma_f32_16x16x32_bf16 v[176:179], v[4:7], v[124:127], v[24:27]
	v_mfma_f32_16x16x32_bf16 v[24:27], v[8:11], v[120:123], 0
	v_mfma_f32_16x16x32_bf16 v[180:183], v[12:15], v[124:127], v[24:27]
	v_mfma_f32_16x16x32_bf16 v[24:27], v[0:3], v[104:107], 0
	v_mfma_f32_16x16x32_bf16 v[186:189], v[4:7], v[116:119], v[24:27]
	v_mfma_f32_16x16x32_bf16 v[24:27], v[8:11], v[104:107], 0
	v_mfma_f32_16x16x32_bf16 v[190:193], v[12:15], v[116:119], v[24:27]
	v_mfma_f32_16x16x32_bf16 v[24:27], v[0:3], v[96:99], 0
	v_mfma_f32_16x16x32_bf16 v[0:3], v[0:3], v[76:79], 0
	v_mfma_f32_16x16x32_bf16 v[194:197], v[4:7], v[100:103], v[24:27]
	v_mfma_f32_16x16x32_bf16 v[24:27], v[8:11], v[96:99], 0
	v_mfma_f32_16x16x32_bf16 v[0:3], v[4:7], v[80:83], v[0:3]
	v_mfma_f32_16x16x32_bf16 v[4:7], v[8:11], v[76:79], 0
	v_mfma_f32_16x16x32_bf16 v[198:201], v[12:15], v[100:103], v[24:27]
	v_mfma_f32_16x16x32_bf16 v[212:215], v[12:15], v[80:83], v[4:7]
	s_barrier
	v_add_u32_e32 v132, s74, v206
	v_add_u32_e32 v133, s75, v206
	s_nop 1
	ds_read_b128 v[4:7], v132
	ds_read_b128 v[8:11], v132 offset:1024
	ds_read_b128 v[216:219], v132 offset:2048
	ds_read_b128 v[220:223], v132 offset:3072
	ds_read_b128 v[224:227], v133
	ds_read_b128 v[228:231], v133 offset:1024
	ds_read_b128 v[232:235], v133 offset:2048
	ds_read_b128 v[236:239], v133 offset:3072
	s_add_u32 s78, s54, 0x80100
	s_addc_u32 s79, s55, 0
	s_mov_b32 m0, s65
	ds_read_b128 v[12:15], v209 offset:32768
	ds_read_b128 v[24:27], v209 offset:33792
	ds_read_b128 v[28:31], v209 offset:34816
	ds_read_b128 v[96:99], v209 offset:35840
	ds_read_b128 v[240:243], v209 offset:36864
	ds_read_b128 v[244:247], v209 offset:37888
	ds_read_b128 v[248:251], v209 offset:38912
	ds_read_b128 v[32:35], v209 offset:39936
	s_nop 0
	global_load_lds_dwordx4 v202, s[78:79]
	s_mov_b32 m0, s66
	s_nop 0
	global_load_lds_dwordx4 v204, s[78:79]
	s_waitcnt vmcnt(8)
	s_waitcnt lgkmcnt(0)
	s_barrier
	s_waitcnt lgkmcnt(0)
	v_mfma_f32_16x16x32_bf16 v[36:39], v[216:219], v[12:15], v[36:39]
	v_mfma_f32_16x16x32_bf16 v[148:151], v[220:223], v[24:27], v[36:39]
	v_mfma_f32_16x16x32_bf16 v[36:39], v[4:7], v[28:31], v[40:43]
	v_mfma_f32_16x16x32_bf16 v[128:131], v[8:11], v[96:99], v[36:39]
	v_mfma_f32_16x16x32_bf16 v[36:39], v[216:219], v[28:31], v[44:47]
	v_mfma_f32_16x16x32_bf16 v[124:127], v[220:223], v[96:99], v[36:39]
	v_mfma_f32_16x16x32_bf16 v[36:39], v[4:7], v[240:243], v[48:51]
	v_mfma_f32_16x16x32_bf16 v[104:107], v[8:11], v[244:247], v[36:39]
	v_mfma_f32_16x16x32_bf16 v[36:39], v[216:219], v[240:243], v[52:55]
	v_mfma_f32_16x16x32_bf16 v[100:103], v[220:223], v[244:247], v[36:39]
	v_mfma_f32_16x16x32_bf16 v[36:39], v[4:7], v[248:251], v[56:59]
	v_mfma_f32_16x16x32_bf16 v[76:79], v[4:7], v[12:15], v[138:141]
	v_mfma_f32_16x16x32_bf16 v[80:83], v[8:11], v[32:35], v[36:39]
	v_mfma_f32_16x16x32_bf16 v[36:39], v[216:219], v[248:251], v[60:63]
	v_mfma_f32_16x16x32_bf16 v[152:155], v[8:11], v[24:27], v[76:79]
	v_mfma_f32_16x16x32_bf16 v[76:79], v[220:223], v[32:35], v[36:39]
	v_mfma_f32_16x16x32_bf16 v[36:39], v[224:227], v[12:15], v[64:67]
	v_mfma_f32_16x16x32_bf16 v[12:15], v[232:235], v[12:15], v[68:71]
	v_mfma_f32_16x16x32_bf16 v[140:143], v[236:239], v[24:27], v[12:15]
	v_mfma_f32_16x16x32_bf16 v[12:15], v[224:227], v[28:31], v[72:75]
	v_mfma_f32_16x16x32_bf16 v[120:123], v[228:231], v[96:99], v[12:15]
	v_mfma_f32_16x16x32_bf16 v[12:15], v[232:235], v[28:31], v[84:87]
	v_mfma_f32_16x16x32_bf16 v[116:119], v[236:239], v[96:99], v[12:15]
	v_mfma_f32_16x16x32_bf16 v[12:15], v[224:227], v[240:243], v[88:91]
	v_mfma_f32_16x16x32_bf16 v[96:99], v[228:231], v[244:247], v[12:15]
	v_mfma_f32_16x16x32_bf16 v[12:15], v[232:235], v[240:243], v[92:95]
	v_mfma_f32_16x16x32_bf16 v[92:95], v[236:239], v[244:247], v[12:15]
	v_mfma_f32_16x16x32_bf16 v[12:15], v[224:227], v[248:251], v[108:111]
	v_mfma_f32_16x16x32_bf16 v[72:75], v[228:231], v[32:35], v[12:15]
	v_mfma_f32_16x16x32_bf16 v[12:15], v[232:235], v[248:251], v[112:115]
	v_mfma_f32_16x16x32_bf16 v[144:147], v[228:231], v[24:27], v[36:39]
	v_mfma_f32_16x16x32_bf16 v[68:71], v[236:239], v[32:35], v[12:15]
	s_barrier
	s_add_i32 s21, s74, s26
	s_mov_b32 m0, s21
	s_add_i32 s43, s21, 0x2000
	ds_read_b128 v[32:35], v209 offset:49152
	ds_read_b128 v[36:39], v209 offset:50176
	ds_read_b128 v[60:63], v209 offset:51200
	ds_read_b128 v[84:87], v209 offset:52224
	ds_read_b128 v[88:91], v209 offset:53248
	ds_read_b128 v[108:111], v209 offset:54272
	ds_read_b128 v[112:115], v209 offset:55296
	ds_read_b128 v[240:243], v209 offset:56320
	s_nop 0
	global_load_lds_dwordx4 v203, s[58:59]
	s_mov_b32 m0, s43
	s_nop 0
	global_load_lds_dwordx4 v205, s[58:59]
	s_add_u32 s58, s52, 0x80180
	s_addc_u32 s59, s53, 0
	s_add_i32 s45, s75, s26
	s_mov_b32 m0, s45
	s_add_i32 s78, s45, 0x2000
	s_nop 0
	global_load_lds_dwordx4 v203, s[58:59]
	s_mov_b32 m0, s78
	s_nop 0
	global_load_lds_dwordx4 v205, s[58:59]
	s_mov_b32 m0, s67
	s_nop 0
	global_load_lds_dwordx4 v202, s[56:57]
	s_mov_b32 m0, s68
	s_nop 0
	global_load_lds_dwordx4 v204, s[56:57]
	s_waitcnt vmcnt(8)
	s_waitcnt lgkmcnt(0)
	s_barrier
	s_waitcnt lgkmcnt(0)
	v_mfma_f32_16x16x32_bf16 v[12:15], v[4:7], v[32:35], v[134:137]
	v_mfma_f32_16x16x32_bf16 v[64:67], v[8:11], v[36:39], v[12:15]
	v_mfma_f32_16x16x32_bf16 v[12:15], v[216:219], v[32:35], v[156:159]
	v_mfma_f32_16x16x32_bf16 v[56:59], v[220:223], v[36:39], v[12:15]
	v_mfma_f32_16x16x32_bf16 v[12:15], v[4:7], v[60:63], v[160:163]
	v_mfma_f32_16x16x32_bf16 v[44:47], v[8:11], v[84:87], v[12:15]
	v_mfma_f32_16x16x32_bf16 v[12:15], v[216:219], v[60:63], v[164:167]
	v_mfma_f32_16x16x32_bf16 v[40:43], v[220:223], v[84:87], v[12:15]
	v_mfma_f32_16x16x32_bf16 v[12:15], v[4:7], v[88:91], v[168:171]
	v_mfma_f32_16x16x32_bf16 v[28:31], v[8:11], v[108:111], v[12:15]
	v_mfma_f32_16x16x32_bf16 v[12:15], v[216:219], v[88:91], v[172:175]
	v_mfma_f32_16x16x32_bf16 v[4:7], v[4:7], v[112:115], v[16:19]
	v_mfma_f32_16x16x32_bf16 v[24:27], v[220:223], v[108:111], v[12:15]
	v_mfma_f32_16x16x32_bf16 v[12:15], v[8:11], v[240:243], v[4:7]
	v_mfma_f32_16x16x32_bf16 v[4:7], v[216:219], v[112:115], v[20:23]
	v_mfma_f32_16x16x32_bf16 v[8:11], v[220:223], v[240:243], v[4:7]
	v_mfma_f32_16x16x32_bf16 v[4:7], v[224:227], v[32:35], v[176:179]
	v_mfma_f32_16x16x32_bf16 v[52:55], v[228:231], v[36:39], v[4:7]
	v_mfma_f32_16x16x32_bf16 v[4:7], v[232:235], v[32:35], v[180:183]
	v_mfma_f32_16x16x32_bf16 v[48:51], v[236:239], v[36:39], v[4:7]
	v_mfma_f32_16x16x32_bf16 v[4:7], v[224:227], v[60:63], v[186:189]
	v_mfma_f32_16x16x32_bf16 v[36:39], v[228:231], v[84:87], v[4:7]
	v_mfma_f32_16x16x32_bf16 v[4:7], v[232:235], v[60:63], v[190:193]
	v_mfma_f32_16x16x32_bf16 v[32:35], v[236:239], v[84:87], v[4:7]
	v_mfma_f32_16x16x32_bf16 v[4:7], v[224:227], v[88:91], v[194:197]
	v_mfma_f32_16x16x32_bf16 v[20:23], v[228:231], v[108:111], v[4:7]
	v_mfma_f32_16x16x32_bf16 v[4:7], v[232:235], v[88:91], v[198:201]
	v_mfma_f32_16x16x32_bf16 v[0:3], v[224:227], v[112:115], v[0:3]
	v_mfma_f32_16x16x32_bf16 v[16:19], v[236:239], v[108:111], v[4:7]
	v_mfma_f32_16x16x32_bf16 v[4:7], v[228:231], v[240:243], v[0:3]
	v_mfma_f32_16x16x32_bf16 v[0:3], v[232:235], v[112:115], v[212:215]
	v_mfma_f32_16x16x32_bf16 v[0:3], v[236:239], v[240:243], v[0:3]
	s_barrier
	s_add_u32 s79, s54, 0x200
	s_addc_u32 s80, s55, 0
	s_add_u32 s81, s52, 0x200
	s_addc_u32 s83, s53, 0
	s_add_u32 s52, s54, 0x80180
	s_addc_u32 s53, s55, 0
	s_mov_b32 s84, 0
.LBB0_2779:
	s_cmp_eq_u32 s84, 28
	s_cselect_b32 s58, s5, s79
	s_cselect_b32 s59, s3, s80
	s_cselect_b32 s56, s20, s81
	s_cselect_b32 s57, s12, s83
	s_add_u32 s54, s58, 0x80
	s_addc_u32 s55, s59, 0
	s_add_i32 s85, 0, 0x10000
	s_add_i32 s88, 0, 0x14000
	v_add_u32_e32 v108, s85, v206
	v_add_u32_e32 v138, s88, v206
	ds_read_b128 v[60:63], v108
	ds_read_b128 v[84:87], v108 offset:1024
	ds_read_b128 v[88:91], v108 offset:2048
	ds_read_b128 v[108:111], v108 offset:3072
	ds_read_b128 v[112:115], v138
	ds_read_b128 v[134:137], v138 offset:1024
	ds_read_b128 v[156:159], v138 offset:2048
	ds_read_b128 v[160:163], v138 offset:3072
	s_mov_b32 m0, s0
	ds_read_b128 v[164:167], v209
	ds_read_b128 v[168:171], v209 offset:1024
	ds_read_b128 v[172:175], v209 offset:2048
	ds_read_b128 v[176:179], v209 offset:3072
	ds_read_b128 v[180:183], v209 offset:4096
	ds_read_b128 v[186:189], v209 offset:5120
	ds_read_b128 v[190:193], v209 offset:6144
	ds_read_b128 v[194:197], v209 offset:7168
	s_nop 0
	global_load_lds_dwordx4 v202, s[52:53]
	s_mov_b32 m0, s1
	s_nop 0
	global_load_lds_dwordx4 v204, s[52:53]
	s_waitcnt vmcnt(8)
	s_waitcnt lgkmcnt(0)
	s_barrier
	s_waitcnt lgkmcnt(0)
	v_mfma_f32_16x16x32_bf16 v[152:155], v[60:63], v[164:167], v[152:155]
	v_mfma_f32_16x16x32_bf16 v[148:151], v[88:91], v[164:167], v[148:151]
	v_mfma_f32_16x16x32_bf16 v[128:131], v[60:63], v[172:175], v[128:131]
	v_mfma_f32_16x16x32_bf16 v[124:127], v[88:91], v[172:175], v[124:127]
	v_mfma_f32_16x16x32_bf16 v[104:107], v[60:63], v[180:183], v[104:107]
	v_mfma_f32_16x16x32_bf16 v[100:103], v[88:91], v[180:183], v[100:103]
	v_mfma_f32_16x16x32_bf16 v[80:83], v[60:63], v[190:193], v[80:83]
	v_mfma_f32_16x16x32_bf16 v[76:79], v[88:91], v[190:193], v[76:79]
	v_mfma_f32_16x16x32_bf16 v[152:155], v[84:87], v[168:171], v[152:155]
	v_mfma_f32_16x16x32_bf16 v[148:151], v[108:111], v[168:171], v[148:151]
	v_mfma_f32_16x16x32_bf16 v[128:131], v[84:87], v[176:179], v[128:131]
	v_mfma_f32_16x16x32_bf16 v[124:127], v[108:111], v[176:179], v[124:127]
	v_mfma_f32_16x16x32_bf16 v[104:107], v[84:87], v[186:189], v[104:107]
	v_mfma_f32_16x16x32_bf16 v[100:103], v[108:111], v[186:189], v[100:103]
	v_mfma_f32_16x16x32_bf16 v[80:83], v[84:87], v[194:197], v[80:83]
	v_mfma_f32_16x16x32_bf16 v[76:79], v[108:111], v[194:197], v[76:79]
	v_mfma_f32_16x16x32_bf16 v[144:147], v[112:115], v[164:167], v[144:147]
	v_mfma_f32_16x16x32_bf16 v[138:141], v[156:159], v[164:167], v[140:143]
	v_mfma_f32_16x16x32_bf16 v[120:123], v[112:115], v[172:175], v[120:123]
	v_mfma_f32_16x16x32_bf16 v[116:119], v[156:159], v[172:175], v[116:119]
	v_mfma_f32_16x16x32_bf16 v[96:99], v[112:115], v[180:183], v[96:99]
	v_mfma_f32_16x16x32_bf16 v[92:95], v[156:159], v[180:183], v[92:95]
	v_mfma_f32_16x16x32_bf16 v[72:75], v[112:115], v[190:193], v[72:75]
	v_mfma_f32_16x16x32_bf16 v[68:71], v[156:159], v[190:193], v[68:71]
	v_mfma_f32_16x16x32_bf16 v[144:147], v[134:137], v[168:171], v[144:147]
	v_mfma_f32_16x16x32_bf16 v[138:141], v[160:163], v[168:171], v[138:141]
	v_mfma_f32_16x16x32_bf16 v[120:123], v[134:137], v[176:179], v[120:123]
	v_mfma_f32_16x16x32_bf16 v[116:119], v[160:163], v[176:179], v[116:119]
	v_mfma_f32_16x16x32_bf16 v[96:99], v[134:137], v[186:189], v[96:99]
	v_mfma_f32_16x16x32_bf16 v[92:95], v[160:163], v[186:189], v[92:95]
	v_mfma_f32_16x16x32_bf16 v[72:75], v[134:137], v[194:197], v[72:75]
	v_mfma_f32_16x16x32_bf16 v[68:71], v[160:163], v[194:197], v[68:71]
	s_barrier
	s_add_i32 s85, s85, s26
	s_mov_b32 m0, s85
	ds_read_b128 v[164:167], v209 offset:16384
	ds_read_b128 v[168:171], v209 offset:17408
	ds_read_b128 v[172:175], v209 offset:18432
	ds_read_b128 v[176:179], v209 offset:19456
	ds_read_b128 v[180:183], v209 offset:20480
	ds_read_b128 v[186:189], v209 offset:21504
	ds_read_b128 v[190:193], v209 offset:22528
	ds_read_b128 v[194:197], v209 offset:23552
	s_nop 0
	global_load_lds_dwordx4 v203, s[56:57]
	s_add_i32 m0, s85, 0x2000
	s_add_u32 s86, s56, 0x80000
	s_addc_u32 s87, s57, 0
	s_add_i32 s85, s88, s26
	s_nop 0
	global_load_lds_dwordx4 v205, s[56:57]
	s_mov_b32 m0, s85
	s_nop 0
	global_load_lds_dwordx4 v203, s[86:87]
	s_add_i32 m0, s85, 0x2000
	s_nop 0
	global_load_lds_dwordx4 v205, s[86:87]
	s_mov_b32 m0, s27
	s_nop 0
	global_load_lds_dwordx4 v202, s[58:59]
	s_mov_b32 m0, s64
	s_nop 0
	global_load_lds_dwordx4 v204, s[58:59]
	s_waitcnt vmcnt(8)
	s_waitcnt lgkmcnt(0)
	s_barrier
	s_waitcnt lgkmcnt(0)
	v_mfma_f32_16x16x32_bf16 v[64:67], v[60:63], v[164:167], v[64:67]
	v_mfma_f32_16x16x32_bf16 v[56:59], v[88:91], v[164:167], v[56:59]
	v_mfma_f32_16x16x32_bf16 v[44:47], v[60:63], v[172:175], v[44:47]
	v_mfma_f32_16x16x32_bf16 v[40:43], v[88:91], v[172:175], v[40:43]
	v_mfma_f32_16x16x32_bf16 v[28:31], v[60:63], v[180:183], v[28:31]
	v_mfma_f32_16x16x32_bf16 v[24:27], v[88:91], v[180:183], v[24:27]
	v_mfma_f32_16x16x32_bf16 v[12:15], v[60:63], v[190:193], v[12:15]
	v_mfma_f32_16x16x32_bf16 v[8:11], v[88:91], v[190:193], v[8:11]
	v_mfma_f32_16x16x32_bf16 v[64:67], v[84:87], v[168:171], v[64:67]
	v_mfma_f32_16x16x32_bf16 v[56:59], v[108:111], v[168:171], v[56:59]
	v_mfma_f32_16x16x32_bf16 v[44:47], v[84:87], v[176:179], v[44:47]
	v_mfma_f32_16x16x32_bf16 v[40:43], v[108:111], v[176:179], v[40:43]
	v_mfma_f32_16x16x32_bf16 v[28:31], v[84:87], v[186:189], v[28:31]
	v_mfma_f32_16x16x32_bf16 v[24:27], v[108:111], v[186:189], v[24:27]
	v_mfma_f32_16x16x32_bf16 v[12:15], v[84:87], v[194:197], v[12:15]
	v_mfma_f32_16x16x32_bf16 v[8:11], v[108:111], v[194:197], v[8:11]
	v_mfma_f32_16x16x32_bf16 v[52:55], v[112:115], v[164:167], v[52:55]
	v_mfma_f32_16x16x32_bf16 v[48:51], v[156:159], v[164:167], v[48:51]
	v_mfma_f32_16x16x32_bf16 v[36:39], v[112:115], v[172:175], v[36:39]
	v_mfma_f32_16x16x32_bf16 v[32:35], v[156:159], v[172:175], v[32:35]
	v_mfma_f32_16x16x32_bf16 v[20:23], v[112:115], v[180:183], v[20:23]
	v_mfma_f32_16x16x32_bf16 v[16:19], v[156:159], v[180:183], v[16:19]
	v_mfma_f32_16x16x32_bf16 v[4:7], v[112:115], v[190:193], v[4:7]
	v_mfma_f32_16x16x32_bf16 v[0:3], v[156:159], v[190:193], v[0:3]
	v_mfma_f32_16x16x32_bf16 v[52:55], v[134:137], v[168:171], v[52:55]
	v_mfma_f32_16x16x32_bf16 v[48:51], v[160:163], v[168:171], v[48:51]
	v_mfma_f32_16x16x32_bf16 v[36:39], v[134:137], v[176:179], v[36:39]
	v_mfma_f32_16x16x32_bf16 v[32:35], v[160:163], v[176:179], v[32:35]
	v_mfma_f32_16x16x32_bf16 v[20:23], v[134:137], v[186:189], v[20:23]
	v_mfma_f32_16x16x32_bf16 v[16:19], v[160:163], v[186:189], v[16:19]
	v_mfma_f32_16x16x32_bf16 v[4:7], v[134:137], v[194:197], v[4:7]
	v_mfma_f32_16x16x32_bf16 v[0:3], v[160:163], v[194:197], v[0:3]
	s_barrier
	ds_read_b128 v[60:63], v132
	ds_read_b128 v[84:87], v132 offset:1024
	ds_read_b128 v[88:91], v132 offset:2048
	ds_read_b128 v[108:111], v132 offset:3072
	ds_read_b128 v[112:115], v133
	ds_read_b128 v[134:137], v133 offset:1024
	ds_read_b128 v[156:159], v133 offset:2048
	ds_read_b128 v[160:163], v133 offset:3072
	s_add_u32 s58, s58, 0x80000
	s_addc_u32 s59, s59, 0
	s_mov_b32 m0, s65
	ds_read_b128 v[164:167], v209 offset:32768
	ds_read_b128 v[168:171], v209 offset:33792
	ds_read_b128 v[172:175], v209 offset:34816
	ds_read_b128 v[176:179], v209 offset:35840
	ds_read_b128 v[180:183], v209 offset:36864
	ds_read_b128 v[186:189], v209 offset:37888
	ds_read_b128 v[190:193], v209 offset:38912
	ds_read_b128 v[194:197], v209 offset:39936
	s_nop 0
	global_load_lds_dwordx4 v202, s[58:59]
	s_mov_b32 m0, s66
	s_nop 0
	global_load_lds_dwordx4 v204, s[58:59]
	s_waitcnt vmcnt(8)
	s_waitcnt lgkmcnt(0)
	s_barrier
	s_waitcnt lgkmcnt(0)
	v_mfma_f32_16x16x32_bf16 v[152:155], v[60:63], v[164:167], v[152:155]
	v_mfma_f32_16x16x32_bf16 v[148:151], v[88:91], v[164:167], v[148:151]
	v_mfma_f32_16x16x32_bf16 v[128:131], v[60:63], v[172:175], v[128:131]
	v_mfma_f32_16x16x32_bf16 v[124:127], v[88:91], v[172:175], v[124:127]
	v_mfma_f32_16x16x32_bf16 v[104:107], v[60:63], v[180:183], v[104:107]
	v_mfma_f32_16x16x32_bf16 v[100:103], v[88:91], v[180:183], v[100:103]
	v_mfma_f32_16x16x32_bf16 v[80:83], v[60:63], v[190:193], v[80:83]
	v_mfma_f32_16x16x32_bf16 v[76:79], v[88:91], v[190:193], v[76:79]
	v_mfma_f32_16x16x32_bf16 v[152:155], v[84:87], v[168:171], v[152:155]
	v_mfma_f32_16x16x32_bf16 v[148:151], v[108:111], v[168:171], v[148:151]
	v_mfma_f32_16x16x32_bf16 v[128:131], v[84:87], v[176:179], v[128:131]
	v_mfma_f32_16x16x32_bf16 v[124:127], v[108:111], v[176:179], v[124:127]
	v_mfma_f32_16x16x32_bf16 v[104:107], v[84:87], v[186:189], v[104:107]
	v_mfma_f32_16x16x32_bf16 v[100:103], v[108:111], v[186:189], v[100:103]
	v_mfma_f32_16x16x32_bf16 v[80:83], v[84:87], v[194:197], v[80:83]
	v_mfma_f32_16x16x32_bf16 v[76:79], v[108:111], v[194:197], v[76:79]
	v_mfma_f32_16x16x32_bf16 v[142:145], v[112:115], v[164:167], v[144:147]
	v_mfma_f32_16x16x32_bf16 v[138:141], v[156:159], v[164:167], v[138:141]
	v_mfma_f32_16x16x32_bf16 v[120:123], v[112:115], v[172:175], v[120:123]
	v_mfma_f32_16x16x32_bf16 v[116:119], v[156:159], v[172:175], v[116:119]
	v_mfma_f32_16x16x32_bf16 v[96:99], v[112:115], v[180:183], v[96:99]
	v_mfma_f32_16x16x32_bf16 v[92:95], v[156:159], v[180:183], v[92:95]
	v_mfma_f32_16x16x32_bf16 v[72:75], v[112:115], v[190:193], v[72:75]
	v_mfma_f32_16x16x32_bf16 v[68:71], v[156:159], v[190:193], v[68:71]
	v_mfma_f32_16x16x32_bf16 v[144:147], v[134:137], v[168:171], v[142:145]
	v_mfma_f32_16x16x32_bf16 v[140:143], v[160:163], v[168:171], v[138:141]
	v_mfma_f32_16x16x32_bf16 v[120:123], v[134:137], v[176:179], v[120:123]
	v_mfma_f32_16x16x32_bf16 v[116:119], v[160:163], v[176:179], v[116:119]
	v_mfma_f32_16x16x32_bf16 v[96:99], v[134:137], v[186:189], v[96:99]
	v_mfma_f32_16x16x32_bf16 v[92:95], v[160:163], v[186:189], v[92:95]
	v_mfma_f32_16x16x32_bf16 v[72:75], v[134:137], v[194:197], v[72:75]
	v_mfma_f32_16x16x32_bf16 v[68:71], v[160:163], v[194:197], v[68:71]
	s_barrier
	s_add_u32 s58, s56, 0x80
	s_mov_b32 m0, s21
	s_addc_u32 s59, s57, 0
	ds_read_b128 v[164:167], v209 offset:49152
	ds_read_b128 v[168:171], v209 offset:50176
	ds_read_b128 v[172:175], v209 offset:51200
	ds_read_b128 v[176:179], v209 offset:52224
	ds_read_b128 v[180:183], v209 offset:53248
	ds_read_b128 v[186:189], v209 offset:54272
	ds_read_b128 v[190:193], v209 offset:55296
	ds_read_b128 v[194:197], v209 offset:56320
	s_add_u32 s56, s56, 0x80080
	global_load_lds_dwordx4 v203, s[58:59]
	s_mov_b32 m0, s43
	s_addc_u32 s57, s57, 0
	global_load_lds_dwordx4 v205, s[58:59]
	s_mov_b32 m0, s45
	s_nop 0
	global_load_lds_dwordx4 v203, s[56:57]
	s_mov_b32 m0, s78
	s_nop 0
	global_load_lds_dwordx4 v205, s[56:57]
	s_mov_b32 m0, s67
	s_nop 0
	global_load_lds_dwordx4 v202, s[54:55]
	s_mov_b32 m0, s68
	s_nop 0
	global_load_lds_dwordx4 v204, s[54:55]
	s_waitcnt vmcnt(8)
	s_waitcnt lgkmcnt(0)
	s_barrier
	s_waitcnt lgkmcnt(0)
	v_mfma_f32_16x16x32_bf16 v[64:67], v[60:63], v[164:167], v[64:67]
	v_mfma_f32_16x16x32_bf16 v[56:59], v[88:91], v[164:167], v[56:59]
	v_mfma_f32_16x16x32_bf16 v[44:47], v[60:63], v[172:175], v[44:47]
	v_mfma_f32_16x16x32_bf16 v[40:43], v[88:91], v[172:175], v[40:43]
	v_mfma_f32_16x16x32_bf16 v[28:31], v[60:63], v[180:183], v[28:31]
	v_mfma_f32_16x16x32_bf16 v[24:27], v[88:91], v[180:183], v[24:27]
	v_mfma_f32_16x16x32_bf16 v[12:15], v[60:63], v[190:193], v[12:15]
	v_mfma_f32_16x16x32_bf16 v[8:11], v[88:91], v[190:193], v[8:11]
	v_mfma_f32_16x16x32_bf16 v[64:67], v[84:87], v[168:171], v[64:67]
	v_mfma_f32_16x16x32_bf16 v[56:59], v[108:111], v[168:171], v[56:59]
	v_mfma_f32_16x16x32_bf16 v[44:47], v[84:87], v[176:179], v[44:47]
	v_mfma_f32_16x16x32_bf16 v[40:43], v[108:111], v[176:179], v[40:43]
	v_mfma_f32_16x16x32_bf16 v[28:31], v[84:87], v[186:189], v[28:31]
	v_mfma_f32_16x16x32_bf16 v[24:27], v[108:111], v[186:189], v[24:27]
	v_mfma_f32_16x16x32_bf16 v[12:15], v[84:87], v[194:197], v[12:15]
	v_mfma_f32_16x16x32_bf16 v[8:11], v[108:111], v[194:197], v[8:11]
	v_mfma_f32_16x16x32_bf16 v[52:55], v[112:115], v[164:167], v[52:55]
	v_mfma_f32_16x16x32_bf16 v[48:51], v[156:159], v[164:167], v[48:51]
	v_mfma_f32_16x16x32_bf16 v[36:39], v[112:115], v[172:175], v[36:39]
	v_mfma_f32_16x16x32_bf16 v[32:35], v[156:159], v[172:175], v[32:35]
	v_mfma_f32_16x16x32_bf16 v[20:23], v[112:115], v[180:183], v[20:23]
	v_mfma_f32_16x16x32_bf16 v[16:19], v[156:159], v[180:183], v[16:19]
	v_mfma_f32_16x16x32_bf16 v[4:7], v[112:115], v[190:193], v[4:7]
	v_mfma_f32_16x16x32_bf16 v[0:3], v[156:159], v[190:193], v[0:3]
	v_mfma_f32_16x16x32_bf16 v[52:55], v[134:137], v[168:171], v[52:55]
	v_mfma_f32_16x16x32_bf16 v[48:51], v[160:163], v[168:171], v[48:51]
	v_mfma_f32_16x16x32_bf16 v[36:39], v[134:137], v[176:179], v[36:39]
	v_mfma_f32_16x16x32_bf16 v[32:35], v[160:163], v[176:179], v[32:35]
	v_mfma_f32_16x16x32_bf16 v[20:23], v[134:137], v[186:189], v[20:23]
	v_mfma_f32_16x16x32_bf16 v[16:19], v[160:163], v[186:189], v[16:19]
	v_mfma_f32_16x16x32_bf16 v[4:7], v[134:137], v[194:197], v[4:7]
	v_mfma_f32_16x16x32_bf16 v[0:3], v[160:163], v[194:197], v[0:3]
	s_barrier
	s_add_i32 s84, s84, 2
	s_add_u32 s79, s79, 0x100
	s_addc_u32 s80, s80, 0
	s_add_u32 s81, s81, 0x100
	s_addc_u32 s83, s83, 0
	s_add_u32 s52, s52, 0x100
	s_addc_u32 s53, s53, 0
	s_cmp_gt_u32 s84, 29
	s_cbranch_scc0 .LBB0_2779
	s_and_b64 vcc, exec, s[34:35]
	s_cbranch_vccz .LBB0_2782
	s_barrier

.LBB0_2884:
	s_add_u32 s20, s46, 0x100
	s_addc_u32 s21, s47, 0
	s_waitcnt lgkmcnt(0)
	s_add_u32 s38, s44, 0x100
	s_addc_u32 s39, s45, 0
	s_barrier
	s_waitcnt lgkmcnt(0)
	v_mfma_f32_16x16x32_bf16 v[32:35], v[16:19], v[72:75], 0
	v_mfma_f32_16x16x32_bf16 v[36:39], v[24:27], v[72:75], 0
	v_mfma_f32_16x16x32_bf16 v[40:43], v[16:19], v[84:87], 0
	v_mfma_f32_16x16x32_bf16 v[44:47], v[24:27], v[84:87], 0
	v_mfma_f32_16x16x32_bf16 v[48:51], v[16:19], v[88:91], 0
	v_mfma_f32_16x16x32_bf16 v[52:55], v[24:27], v[88:91], 0
	v_mfma_f32_16x16x32_bf16 v[56:59], v[16:19], v[68:71], 0
	v_mfma_f32_16x16x32_bf16 v[60:63], v[24:27], v[68:71], 0
	v_mfma_f32_16x16x32_bf16 v[32:35], v[20:23], v[76:79], v[32:35]
	v_mfma_f32_16x16x32_bf16 v[36:39], v[28:31], v[76:79], v[36:39]
	v_mfma_f32_16x16x32_bf16 v[40:43], v[20:23], v[92:95], v[40:43]
	v_mfma_f32_16x16x32_bf16 v[44:47], v[28:31], v[92:95], v[44:47]
	v_mfma_f32_16x16x32_bf16 v[48:51], v[20:23], v[96:99], v[48:51]
	v_mfma_f32_16x16x32_bf16 v[52:55], v[28:31], v[96:99], v[52:55]
	v_mfma_f32_16x16x32_bf16 v[56:59], v[20:23], v[80:83], v[56:59]
	v_mfma_f32_16x16x32_bf16 v[60:63], v[28:31], v[80:83], v[60:63]
	v_mfma_f32_16x16x32_bf16 v[64:67], v[0:3], v[72:75], 0
	v_mfma_f32_16x16x32_bf16 v[72:75], v[8:11], v[72:75], 0
	v_mfma_f32_16x16x32_bf16 v[64:67], v[4:7], v[76:79], v[64:67]
	v_mfma_f32_16x16x32_bf16 v[72:75], v[12:15], v[76:79], v[72:75]
	v_mfma_f32_16x16x32_bf16 v[76:79], v[0:3], v[84:87], 0
	v_mfma_f32_16x16x32_bf16 v[84:87], v[8:11], v[84:87], 0
	v_mfma_f32_16x16x32_bf16 v[76:79], v[4:7], v[92:95], v[76:79]
	v_mfma_f32_16x16x32_bf16 v[84:87], v[12:15], v[92:95], v[84:87]
	v_mfma_f32_16x16x32_bf16 v[92:95], v[0:3], v[88:91], 0
	v_mfma_f32_16x16x32_bf16 v[88:91], v[8:11], v[88:91], 0
	v_mfma_f32_16x16x32_bf16 v[128:131], v[12:15], v[96:99], v[88:91]
	v_mfma_f32_16x16x32_bf16 v[88:91], v[0:3], v[68:71], 0
	v_mfma_f32_16x16x32_bf16 v[68:71], v[8:11], v[68:71], 0
	v_mfma_f32_16x16x32_bf16 v[92:95], v[4:7], v[96:99], v[92:95]
	v_mfma_f32_16x16x32_bf16 v[132:135], v[4:7], v[80:83], v[88:91]
	v_mfma_f32_16x16x32_bf16 v[136:139], v[12:15], v[80:83], v[68:71]
	s_barrier
	s_mov_b32 m0, s41
	ds_read_b128 v[108:111], v150 offset:16384
	ds_read_b128 v[112:115], v150 offset:17408
	ds_read_b128 v[100:103], v150 offset:18432
	ds_read_b128 v[104:107], v150 offset:19456
	ds_read_b128 v[88:91], v150 offset:20480
	ds_read_b128 v[96:99], v150 offset:21504
	ds_read_b128 v[68:71], v150 offset:22528
	ds_read_b128 v[80:83], v150 offset:23552
	s_nop 0
	global_load_lds_dwordx4 v144, s[38:39]
	s_mov_b32 m0, s43
	s_nop 0
	global_load_lds_dwordx4 v146, s[38:39]
	s_add_u32 s38, s44, 0x80100
	s_addc_u32 s39, s45, 0
	s_mov_b32 m0, s54
	s_and_b64 vcc, exec, s[36:37]
	global_load_lds_dwordx4 v144, s[38:39]
	s_mov_b32 m0, s55
	s_nop 0
	global_load_lds_dwordx4 v146, s[38:39]
	s_mov_b32 m0, s26
	s_mov_b64 s[38:39], -1
	global_load_lds_dwordx4 v143, s[20:21]
	s_mov_b32 m0, s56
	s_nop 0
	global_load_lds_dwordx4 v145, s[20:21]
	s_cbranch_vccz .LBB0_2886
	s_waitcnt vmcnt(8)
	s_mov_b64 s[38:39], 0

.LBB0_2888:
	s_ashr_i32 s7, s6, 31
	s_lshl_b64 s[20:21], s[6:7], 20
	s_add_u32 s36, s14, s20
	s_addc_u32 s37, s15, s21
	s_ashr_i32 s9, s8, 31
	s_lshl_b64 s[20:21], s[8:9], 20
	s_add_u32 s38, s17, s20
	s_addc_u32 s39, s24, s21
	s_add_u32 s48, s46, 0x180
	s_addc_u32 s49, s47, 0
	s_waitcnt lgkmcnt(0)
	s_and_b64 s[20:21], s[34:35], exec
	s_cselect_b32 s9, s39, s45
	s_cselect_b32 s12, s38, s44
	s_cselect_b32 s20, s37, s47
	s_cselect_b32 s21, s36, s46
	s_add_u32 s50, s44, 0x180
	s_addc_u32 s51, s45, 0
	s_barrier
	s_waitcnt lgkmcnt(0)
	v_mfma_f32_16x16x32_bf16 v[116:119], v[16:19], v[108:111], 0
	v_mfma_f32_16x16x32_bf16 v[154:157], v[20:23], v[112:115], v[116:119]
	v_mfma_f32_16x16x32_bf16 v[116:119], v[24:27], v[108:111], 0
	v_mfma_f32_16x16x32_bf16 v[158:161], v[28:31], v[112:115], v[116:119]
	v_mfma_f32_16x16x32_bf16 v[116:119], v[16:19], v[100:103], 0
	v_mfma_f32_16x16x32_bf16 v[162:165], v[20:23], v[104:107], v[116:119]
	v_mfma_f32_16x16x32_bf16 v[116:119], v[24:27], v[100:103], 0
	v_mfma_f32_16x16x32_bf16 v[166:169], v[28:31], v[104:107], v[116:119]
	v_mfma_f32_16x16x32_bf16 v[116:119], v[16:19], v[88:91], 0
	v_mfma_f32_16x16x32_bf16 v[16:19], v[16:19], v[68:71], 0
	v_mfma_f32_16x16x32_bf16 v[170:173], v[20:23], v[96:99], v[116:119]
	v_mfma_f32_16x16x32_bf16 v[116:119], v[24:27], v[88:91], 0
	v_mfma_f32_16x16x32_bf16 v[20:23], v[20:23], v[80:83], v[16:19]
	v_mfma_f32_16x16x32_bf16 v[16:19], v[24:27], v[68:71], 0
	v_mfma_f32_16x16x32_bf16 v[174:177], v[28:31], v[96:99], v[116:119]
	v_mfma_f32_16x16x32_bf16 v[28:31], v[28:31], v[80:83], v[16:19]
	v_mfma_f32_16x16x32_bf16 v[16:19], v[0:3], v[108:111], 0
	v_mfma_f32_16x16x32_bf16 v[178:181], v[4:7], v[112:115], v[16:19]
	v_mfma_f32_16x16x32_bf16 v[16:19], v[8:11], v[108:111], 0
	v_mfma_f32_16x16x32_bf16 v[182:185], v[12:15], v[112:115], v[16:19]
	v_mfma_f32_16x16x32_bf16 v[16:19], v[0:3], v[100:103], 0
	v_mfma_f32_16x16x32_bf16 v[186:189], v[4:7], v[104:107], v[16:19]
	v_mfma_f32_16x16x32_bf16 v[16:19], v[8:11], v[100:103], 0
	v_mfma_f32_16x16x32_bf16 v[190:193], v[12:15], v[104:107], v[16:19]
	v_mfma_f32_16x16x32_bf16 v[16:19], v[0:3], v[88:91], 0
	v_mfma_f32_16x16x32_bf16 v[0:3], v[0:3], v[68:71], 0
	v_mfma_f32_16x16x32_bf16 v[194:197], v[4:7], v[96:99], v[16:19]
	v_mfma_f32_16x16x32_bf16 v[16:19], v[8:11], v[88:91], 0
	v_mfma_f32_16x16x32_bf16 v[4:7], v[4:7], v[80:83], v[0:3]
	v_mfma_f32_16x16x32_bf16 v[0:3], v[8:11], v[68:71], 0
	v_mfma_f32_16x16x32_bf16 v[198:201], v[12:15], v[96:99], v[16:19]
	v_mfma_f32_16x16x32_bf16 v[202:205], v[12:15], v[80:83], v[0:3]
	s_barrier
	v_add_u32_e32 v152, s66, v147
	v_add_u32_e32 v153, s67, v147
	s_nop 1
	ds_read_b128 v[0:3], v152
	ds_read_b128 v[8:11], v152 offset:1024
	ds_read_b128 v[12:15], v152 offset:2048
	ds_read_b128 v[206:209], v152 offset:3072
	ds_read_b128 v[210:213], v153
	ds_read_b128 v[214:217], v153 offset:1024
	ds_read_b128 v[218:221], v153 offset:2048
	ds_read_b128 v[222:225], v153 offset:3072
	s_add_u32 s52, s46, 0x80100
	s_addc_u32 s53, s47, 0
	s_mov_b32 m0, s57
	ds_read_b128 v[16:19], v150 offset:32768
	ds_read_b128 v[24:27], v150 offset:33792
	ds_read_b128 v[100:103], v150 offset:34816
	ds_read_b128 v[226:229], v150 offset:35840
	ds_read_b128 v[230:233], v150 offset:36864
	ds_read_b128 v[234:237], v150 offset:37888
	ds_read_b128 v[238:241], v150 offset:38912
	ds_read_b128 v[242:245], v150 offset:39936
	s_nop 0
	global_load_lds_dwordx4 v143, s[52:53]
	s_mov_b32 m0, s58
	s_nop 0
	global_load_lds_dwordx4 v145, s[52:53]
	s_waitcnt vmcnt(8)
	s_waitcnt lgkmcnt(0)
	s_barrier
	s_waitcnt lgkmcnt(0)
	v_mfma_f32_16x16x32_bf16 v[32:35], v[0:3], v[16:19], v[32:35]
	v_mfma_f32_16x16x32_bf16 v[120:123], v[8:11], v[24:27], v[32:35]
	v_mfma_f32_16x16x32_bf16 v[32:35], v[12:15], v[16:19], v[36:39]
	v_mfma_f32_16x16x32_bf16 v[112:115], v[206:209], v[24:27], v[32:35]
	v_mfma_f32_16x16x32_bf16 v[32:35], v[0:3], v[100:103], v[40:43]
	v_mfma_f32_16x16x32_bf16 v[104:107], v[8:11], v[226:229], v[32:35]
	v_mfma_f32_16x16x32_bf16 v[32:35], v[12:15], v[100:103], v[44:47]
	v_mfma_f32_16x16x32_bf16 v[96:99], v[206:209], v[226:229], v[32:35]
	v_mfma_f32_16x16x32_bf16 v[32:35], v[0:3], v[230:233], v[48:51]
	v_mfma_f32_16x16x32_bf16 v[88:91], v[8:11], v[234:237], v[32:35]
	v_mfma_f32_16x16x32_bf16 v[32:35], v[12:15], v[230:233], v[52:55]
	v_mfma_f32_16x16x32_bf16 v[80:83], v[206:209], v[234:237], v[32:35]
	v_mfma_f32_16x16x32_bf16 v[32:35], v[0:3], v[238:241], v[56:59]
	v_mfma_f32_16x16x32_bf16 v[68:71], v[8:11], v[242:245], v[32:35]
	v_mfma_f32_16x16x32_bf16 v[32:35], v[12:15], v[238:241], v[60:63]
	v_mfma_f32_16x16x32_bf16 v[52:55], v[206:209], v[242:245], v[32:35]
	v_mfma_f32_16x16x32_bf16 v[32:35], v[210:213], v[16:19], v[64:67]
	v_mfma_f32_16x16x32_bf16 v[16:19], v[218:221], v[16:19], v[72:75]
	v_mfma_f32_16x16x32_bf16 v[116:119], v[222:225], v[24:27], v[16:19]
	v_mfma_f32_16x16x32_bf16 v[16:19], v[210:213], v[100:103], v[76:79]
	v_mfma_f32_16x16x32_bf16 v[108:111], v[214:217], v[226:229], v[16:19]
	v_mfma_f32_16x16x32_bf16 v[16:19], v[218:221], v[100:103], v[84:87]
	v_mfma_f32_16x16x32_bf16 v[100:103], v[222:225], v[226:229], v[16:19]
	v_mfma_f32_16x16x32_bf16 v[16:19], v[210:213], v[230:233], v[92:95]
	v_mfma_f32_16x16x32_bf16 v[92:95], v[214:217], v[234:237], v[16:19]
	v_mfma_f32_16x16x32_bf16 v[16:19], v[218:221], v[230:233], v[128:131]
	v_mfma_f32_16x16x32_bf16 v[84:87], v[222:225], v[234:237], v[16:19]
	v_mfma_f32_16x16x32_bf16 v[16:19], v[210:213], v[238:241], v[132:135]
	v_mfma_f32_16x16x32_bf16 v[76:79], v[214:217], v[242:245], v[16:19]
	v_mfma_f32_16x16x32_bf16 v[16:19], v[218:221], v[238:241], v[136:139]
	v_mfma_f32_16x16x32_bf16 v[124:127], v[214:217], v[24:27], v[32:35]
	v_mfma_f32_16x16x32_bf16 v[60:63], v[222:225], v[242:245], v[16:19]
	s_barrier
	s_add_i32 s71, s66, s25
	s_mov_b32 m0, s71
	s_add_i32 s72, s71, 0x2000
	ds_read_b128 v[36:39], v150 offset:49152
	ds_read_b128 v[44:47], v150 offset:50176
	ds_read_b128 v[128:131], v150 offset:51200
	ds_read_b128 v[132:135], v150 offset:52224
	ds_read_b128 v[136:139], v150 offset:53248
	ds_read_b128 v[226:229], v150 offset:54272
	ds_read_b128 v[230:233], v150 offset:55296
	ds_read_b128 v[234:237], v150 offset:56320
	s_nop 0
	global_load_lds_dwordx4 v144, s[50:51]
	s_mov_b32 m0, s72
	s_nop 0
	global_load_lds_dwordx4 v146, s[50:51]
	s_add_u32 s50, s44, 0x80180
	s_addc_u32 s51, s45, 0
	s_add_i32 s73, s67, s25
	s_mov_b32 m0, s73
	s_add_i32 s74, s73, 0x2000
	s_nop 0
	global_load_lds_dwordx4 v144, s[50:51]
	s_mov_b32 m0, s74
	s_nop 0
	global_load_lds_dwordx4 v146, s[50:51]
	s_mov_b32 m0, s59
	s_nop 0
	global_load_lds_dwordx4 v143, s[48:49]
	s_mov_b32 m0, s60
	s_nop 0
	global_load_lds_dwordx4 v145, s[48:49]
	s_waitcnt vmcnt(8)
	s_waitcnt lgkmcnt(0)
	s_barrier
	s_waitcnt lgkmcnt(0)
	v_mfma_f32_16x16x32_bf16 v[16:19], v[0:3], v[36:39], v[154:157]
	v_mfma_f32_16x16x32_bf16 v[64:67], v[8:11], v[44:47], v[16:19]
	v_mfma_f32_16x16x32_bf16 v[16:19], v[12:15], v[36:39], v[158:161]
	v_mfma_f32_16x16x32_bf16 v[48:51], v[206:209], v[44:47], v[16:19]
	v_mfma_f32_16x16x32_bf16 v[16:19], v[0:3], v[128:131], v[162:165]
	v_mfma_f32_16x16x32_bf16 v[40:43], v[8:11], v[132:135], v[16:19]
	v_mfma_f32_16x16x32_bf16 v[16:19], v[12:15], v[128:131], v[166:169]
	v_mfma_f32_16x16x32_bf16 v[32:35], v[206:209], v[132:135], v[16:19]
	v_mfma_f32_16x16x32_bf16 v[16:19], v[0:3], v[136:139], v[170:173]
	v_mfma_f32_16x16x32_bf16 v[0:3], v[0:3], v[230:233], v[20:23]
	v_mfma_f32_16x16x32_bf16 v[24:27], v[8:11], v[226:229], v[16:19]
	v_mfma_f32_16x16x32_bf16 v[16:19], v[12:15], v[136:139], v[174:177]
	v_mfma_f32_16x16x32_bf16 v[8:11], v[8:11], v[234:237], v[0:3]
	v_mfma_f32_16x16x32_bf16 v[0:3], v[12:15], v[230:233], v[28:31]
	v_mfma_f32_16x16x32_bf16 v[16:19], v[206:209], v[226:229], v[16:19]
	v_mfma_f32_16x16x32_bf16 v[0:3], v[206:209], v[234:237], v[0:3]
	v_mfma_f32_16x16x32_bf16 v[12:15], v[210:213], v[36:39], v[178:181]
	v_mfma_f32_16x16x32_bf16 v[72:75], v[214:217], v[44:47], v[12:15]
	v_mfma_f32_16x16x32_bf16 v[12:15], v[218:221], v[36:39], v[182:185]
	v_mfma_f32_16x16x32_bf16 v[56:59], v[222:225], v[44:47], v[12:15]
	v_mfma_f32_16x16x32_bf16 v[12:15], v[210:213], v[128:131], v[186:189]
	v_mfma_f32_16x16x32_bf16 v[44:47], v[214:217], v[132:135], v[12:15]
	v_mfma_f32_16x16x32_bf16 v[12:15], v[218:221], v[128:131], v[190:193]
	v_mfma_f32_16x16x32_bf16 v[36:39], v[222:225], v[132:135], v[12:15]
	v_mfma_f32_16x16x32_bf16 v[12:15], v[210:213], v[136:139], v[194:197]
	v_mfma_f32_16x16x32_bf16 v[28:31], v[214:217], v[226:229], v[12:15]
	v_mfma_f32_16x16x32_bf16 v[12:15], v[218:221], v[136:139], v[198:201]
	v_mfma_f32_16x16x32_bf16 v[4:7], v[210:213], v[230:233], v[4:7]
	v_mfma_f32_16x16x32_bf16 v[20:23], v[222:225], v[226:229], v[12:15]
	v_mfma_f32_16x16x32_bf16 v[12:15], v[214:217], v[234:237], v[4:7]
	v_mfma_f32_16x16x32_bf16 v[4:7], v[218:221], v[230:233], v[202:205]
	v_mfma_f32_16x16x32_bf16 v[4:7], v[222:225], v[234:237], v[4:7]
	s_barrier
	s_add_u32 s52, s46, 0x100
	s_addc_u32 s53, s47, 0
	s_add_u32 s75, s44, 0x200
	s_addc_u32 s76, s45, 0
	s_mov_b32 s77, 0
.LBB0_2889:
	s_add_u32 s44, s52, 0x100
	s_addc_u32 s45, s53, 0
	s_cmp_eq_u32 s77, 28
	s_cselect_b32 s50, s21, s44
	s_cselect_b32 s51, s20, s45
	s_cselect_b32 s48, s12, s75
	s_cselect_b32 s49, s9, s76
	s_add_u32 s46, s50, 0x80
	s_addc_u32 s47, s51, 0
	s_add_i32 s78, 0, 0x10000
	s_add_i32 s79, 0, 0x14000
	v_add_u32_e32 v154, s78, v147
	v_add_u32_e32 v170, s79, v147
	ds_read_b128 v[128:131], v154
	ds_read_b128 v[132:135], v154 offset:1024
	ds_read_b128 v[136:139], v154 offset:2048
	ds_read_b128 v[154:157], v154 offset:3072
	ds_read_b128 v[158:161], v170
	ds_read_b128 v[162:165], v170 offset:1024
	ds_read_b128 v[166:169], v170 offset:2048
	ds_read_b128 v[170:173], v170 offset:3072
	s_add_u32 s52, s52, 0x80080
	s_addc_u32 s53, s53, 0
	s_mov_b32 m0, s0
	ds_read_b128 v[174:177], v150
	ds_read_b128 v[178:181], v150 offset:1024
	ds_read_b128 v[182:185], v150 offset:2048
	ds_read_b128 v[186:189], v150 offset:3072
	ds_read_b128 v[190:193], v150 offset:4096
	ds_read_b128 v[194:197], v150 offset:5120
	ds_read_b128 v[198:201], v150 offset:6144
	ds_read_b128 v[202:205], v150 offset:7168
	s_nop 0
	global_load_lds_dwordx4 v143, s[52:53]
	s_mov_b32 m0, s1
	s_nop 0
	global_load_lds_dwordx4 v145, s[52:53]
	s_waitcnt vmcnt(8)
	s_waitcnt lgkmcnt(0)
	s_barrier
	s_waitcnt lgkmcnt(0)
	v_mfma_f32_16x16x32_bf16 v[120:123], v[128:131], v[174:177], v[120:123]
	v_mfma_f32_16x16x32_bf16 v[112:115], v[136:139], v[174:177], v[112:115]
	v_mfma_f32_16x16x32_bf16 v[104:107], v[128:131], v[182:185], v[104:107]
	v_mfma_f32_16x16x32_bf16 v[96:99], v[136:139], v[182:185], v[96:99]
	v_mfma_f32_16x16x32_bf16 v[88:91], v[128:131], v[190:193], v[88:91]
	v_mfma_f32_16x16x32_bf16 v[80:83], v[136:139], v[190:193], v[80:83]
	v_mfma_f32_16x16x32_bf16 v[68:71], v[128:131], v[198:201], v[68:71]
	v_mfma_f32_16x16x32_bf16 v[52:55], v[136:139], v[198:201], v[52:55]
	v_mfma_f32_16x16x32_bf16 v[120:123], v[132:135], v[178:181], v[120:123]
	v_mfma_f32_16x16x32_bf16 v[112:115], v[154:157], v[178:181], v[112:115]
	v_mfma_f32_16x16x32_bf16 v[104:107], v[132:135], v[186:189], v[104:107]
	v_mfma_f32_16x16x32_bf16 v[96:99], v[154:157], v[186:189], v[96:99]
	v_mfma_f32_16x16x32_bf16 v[88:91], v[132:135], v[194:197], v[88:91]
	v_mfma_f32_16x16x32_bf16 v[80:83], v[154:157], v[194:197], v[80:83]
	v_mfma_f32_16x16x32_bf16 v[68:71], v[132:135], v[202:205], v[68:71]
	v_mfma_f32_16x16x32_bf16 v[52:55], v[154:157], v[202:205], v[52:55]
	v_mfma_f32_16x16x32_bf16 v[124:127], v[158:161], v[174:177], v[124:127]
	v_mfma_f32_16x16x32_bf16 v[116:119], v[166:169], v[174:177], v[116:119]
	v_mfma_f32_16x16x32_bf16 v[108:111], v[158:161], v[182:185], v[108:111]
	v_mfma_f32_16x16x32_bf16 v[100:103], v[166:169], v[182:185], v[100:103]
	v_mfma_f32_16x16x32_bf16 v[92:95], v[158:161], v[190:193], v[92:95]
	v_mfma_f32_16x16x32_bf16 v[84:87], v[166:169], v[190:193], v[84:87]
	v_mfma_f32_16x16x32_bf16 v[76:79], v[158:161], v[198:201], v[76:79]
	v_mfma_f32_16x16x32_bf16 v[60:63], v[166:169], v[198:201], v[60:63]
	v_mfma_f32_16x16x32_bf16 v[124:127], v[162:165], v[178:181], v[124:127]
	v_mfma_f32_16x16x32_bf16 v[116:119], v[170:173], v[178:181], v[116:119]
	v_mfma_f32_16x16x32_bf16 v[108:111], v[162:165], v[186:189], v[108:111]
	v_mfma_f32_16x16x32_bf16 v[100:103], v[170:173], v[186:189], v[100:103]
	v_mfma_f32_16x16x32_bf16 v[92:95], v[162:165], v[194:197], v[92:95]
	v_mfma_f32_16x16x32_bf16 v[84:87], v[170:173], v[194:197], v[84:87]
	v_mfma_f32_16x16x32_bf16 v[76:79], v[162:165], v[202:205], v[76:79]
	v_mfma_f32_16x16x32_bf16 v[60:63], v[170:173], v[202:205], v[60:63]
	s_barrier
	s_add_i32 s52, s78, s25
	s_mov_b32 m0, s52
	ds_read_b128 v[174:177], v150 offset:16384
	ds_read_b128 v[178:181], v150 offset:17408
	ds_read_b128 v[182:185], v150 offset:18432
	ds_read_b128 v[186:189], v150 offset:19456
	ds_read_b128 v[190:193], v150 offset:20480
	ds_read_b128 v[194:197], v150 offset:21504
	ds_read_b128 v[198:201], v150 offset:22528
	ds_read_b128 v[202:205], v150 offset:23552
	s_nop 0
	global_load_lds_dwordx4 v144, s[48:49]
	s_add_i32 m0, s52, 0x2000
	s_add_u32 s52, s48, 0x80000
	s_addc_u32 s53, s49, 0
	s_add_i32 s78, s79, s25
	s_nop 0
	global_load_lds_dwordx4 v146, s[48:49]
	s_mov_b32 m0, s78
	s_nop 0
	global_load_lds_dwordx4 v144, s[52:53]
	s_add_i32 m0, s78, 0x2000
	s_nop 0
	global_load_lds_dwordx4 v146, s[52:53]
	s_mov_b32 m0, s26
	s_nop 0
	global_load_lds_dwordx4 v143, s[50:51]
	s_mov_b32 m0, s56
	s_nop 0
	global_load_lds_dwordx4 v145, s[50:51]
	s_waitcnt vmcnt(8)
	s_waitcnt lgkmcnt(0)
	s_barrier
	s_waitcnt lgkmcnt(0)
	v_mfma_f32_16x16x32_bf16 v[64:67], v[128:131], v[174:177], v[64:67]
	v_mfma_f32_16x16x32_bf16 v[48:51], v[136:139], v[174:177], v[48:51]
	v_mfma_f32_16x16x32_bf16 v[40:43], v[128:131], v[182:185], v[40:43]
	v_mfma_f32_16x16x32_bf16 v[32:35], v[136:139], v[182:185], v[32:35]
	v_mfma_f32_16x16x32_bf16 v[24:27], v[128:131], v[190:193], v[24:27]
	v_mfma_f32_16x16x32_bf16 v[16:19], v[136:139], v[190:193], v[16:19]
	v_mfma_f32_16x16x32_bf16 v[8:11], v[128:131], v[198:201], v[8:11]
	v_mfma_f32_16x16x32_bf16 v[0:3], v[136:139], v[198:201], v[0:3]
	v_mfma_f32_16x16x32_bf16 v[64:67], v[132:135], v[178:181], v[64:67]
	v_mfma_f32_16x16x32_bf16 v[48:51], v[154:157], v[178:181], v[48:51]
	v_mfma_f32_16x16x32_bf16 v[40:43], v[132:135], v[186:189], v[40:43]
	v_mfma_f32_16x16x32_bf16 v[32:35], v[154:157], v[186:189], v[32:35]
	v_mfma_f32_16x16x32_bf16 v[24:27], v[132:135], v[194:197], v[24:27]
	v_mfma_f32_16x16x32_bf16 v[16:19], v[154:157], v[194:197], v[16:19]
	v_mfma_f32_16x16x32_bf16 v[8:11], v[132:135], v[202:205], v[8:11]
	v_mfma_f32_16x16x32_bf16 v[0:3], v[154:157], v[202:205], v[0:3]
	v_mfma_f32_16x16x32_bf16 v[72:75], v[158:161], v[174:177], v[72:75]
	v_mfma_f32_16x16x32_bf16 v[56:59], v[166:169], v[174:177], v[56:59]
	v_mfma_f32_16x16x32_bf16 v[44:47], v[158:161], v[182:185], v[44:47]
	v_mfma_f32_16x16x32_bf16 v[36:39], v[166:169], v[182:185], v[36:39]
	v_mfma_f32_16x16x32_bf16 v[28:31], v[158:161], v[190:193], v[28:31]
	v_mfma_f32_16x16x32_bf16 v[20:23], v[166:169], v[190:193], v[20:23]
	v_mfma_f32_16x16x32_bf16 v[12:15], v[158:161], v[198:201], v[12:15]
	v_mfma_f32_16x16x32_bf16 v[4:7], v[166:169], v[198:201], v[4:7]
	v_mfma_f32_16x16x32_bf16 v[72:75], v[162:165], v[178:181], v[72:75]
	v_mfma_f32_16x16x32_bf16 v[56:59], v[170:173], v[178:181], v[56:59]
	v_mfma_f32_16x16x32_bf16 v[44:47], v[162:165], v[186:189], v[44:47]
	v_mfma_f32_16x16x32_bf16 v[36:39], v[170:173], v[186:189], v[36:39]
	v_mfma_f32_16x16x32_bf16 v[28:31], v[162:165], v[194:197], v[28:31]
	v_mfma_f32_16x16x32_bf16 v[20:23], v[170:173], v[194:197], v[20:23]
	v_mfma_f32_16x16x32_bf16 v[12:15], v[162:165], v[202:205], v[12:15]
	v_mfma_f32_16x16x32_bf16 v[4:7], v[170:173], v[202:205], v[4:7]
	s_barrier
	ds_read_b128 v[128:131], v152
	ds_read_b128 v[132:135], v152 offset:1024
	ds_read_b128 v[136:139], v152 offset:2048
	ds_read_b128 v[154:157], v152 offset:3072
	ds_read_b128 v[158:161], v153
	ds_read_b128 v[162:165], v153 offset:1024
	ds_read_b128 v[166:169], v153 offset:2048
	ds_read_b128 v[170:173], v153 offset:3072
	s_add_u32 s50, s50, 0x80000
	s_addc_u32 s51, s51, 0
	s_mov_b32 m0, s57
	ds_read_b128 v[174:177], v150 offset:32768
	ds_read_b128 v[178:181], v150 offset:33792
	ds_read_b128 v[182:185], v150 offset:34816
	ds_read_b128 v[186:189], v150 offset:35840
	ds_read_b128 v[190:193], v150 offset:36864
	ds_read_b128 v[194:197], v150 offset:37888
	ds_read_b128 v[198:201], v150 offset:38912
	ds_read_b128 v[202:205], v150 offset:39936
	s_nop 0
	global_load_lds_dwordx4 v143, s[50:51]
	s_mov_b32 m0, s58
	s_nop 0
	global_load_lds_dwordx4 v145, s[50:51]
	s_waitcnt vmcnt(8)
	s_waitcnt lgkmcnt(0)
	s_barrier
	s_waitcnt lgkmcnt(0)
	v_mfma_f32_16x16x32_bf16 v[120:123], v[128:131], v[174:177], v[120:123]
	v_mfma_f32_16x16x32_bf16 v[112:115], v[136:139], v[174:177], v[112:115]
	v_mfma_f32_16x16x32_bf16 v[104:107], v[128:131], v[182:185], v[104:107]
	v_mfma_f32_16x16x32_bf16 v[96:99], v[136:139], v[182:185], v[96:99]
	v_mfma_f32_16x16x32_bf16 v[88:91], v[128:131], v[190:193], v[88:91]
	v_mfma_f32_16x16x32_bf16 v[80:83], v[136:139], v[190:193], v[80:83]
	v_mfma_f32_16x16x32_bf16 v[68:71], v[128:131], v[198:201], v[68:71]
	v_mfma_f32_16x16x32_bf16 v[52:55], v[136:139], v[198:201], v[52:55]
	v_mfma_f32_16x16x32_bf16 v[120:123], v[132:135], v[178:181], v[120:123]
	v_mfma_f32_16x16x32_bf16 v[112:115], v[154:157], v[178:181], v[112:115]
	v_mfma_f32_16x16x32_bf16 v[104:107], v[132:135], v[186:189], v[104:107]
	v_mfma_f32_16x16x32_bf16 v[96:99], v[154:157], v[186:189], v[96:99]
	v_mfma_f32_16x16x32_bf16 v[88:91], v[132:135], v[194:197], v[88:91]
	v_mfma_f32_16x16x32_bf16 v[80:83], v[154:157], v[194:197], v[80:83]
	v_mfma_f32_16x16x32_bf16 v[68:71], v[132:135], v[202:205], v[68:71]
	v_mfma_f32_16x16x32_bf16 v[52:55], v[154:157], v[202:205], v[52:55]
	v_mfma_f32_16x16x32_bf16 v[124:127], v[158:161], v[174:177], v[124:127]
	v_mfma_f32_16x16x32_bf16 v[116:119], v[166:169], v[174:177], v[116:119]
	v_mfma_f32_16x16x32_bf16 v[108:111], v[158:161], v[182:185], v[108:111]
	v_mfma_f32_16x16x32_bf16 v[100:103], v[166:169], v[182:185], v[100:103]
	v_mfma_f32_16x16x32_bf16 v[92:95], v[158:161], v[190:193], v[92:95]
	v_mfma_f32_16x16x32_bf16 v[84:87], v[166:169], v[190:193], v[84:87]
	v_mfma_f32_16x16x32_bf16 v[76:79], v[158:161], v[198:201], v[76:79]
	v_mfma_f32_16x16x32_bf16 v[60:63], v[166:169], v[198:201], v[60:63]
	v_mfma_f32_16x16x32_bf16 v[124:127], v[162:165], v[178:181], v[124:127]
	v_mfma_f32_16x16x32_bf16 v[116:119], v[170:173], v[178:181], v[116:119]
	v_mfma_f32_16x16x32_bf16 v[108:111], v[162:165], v[186:189], v[108:111]
	v_mfma_f32_16x16x32_bf16 v[100:103], v[170:173], v[186:189], v[100:103]
	v_mfma_f32_16x16x32_bf16 v[92:95], v[162:165], v[194:197], v[92:95]
	v_mfma_f32_16x16x32_bf16 v[84:87], v[170:173], v[194:197], v[84:87]
	v_mfma_f32_16x16x32_bf16 v[76:79], v[162:165], v[202:205], v[76:79]
	v_mfma_f32_16x16x32_bf16 v[60:63], v[170:173], v[202:205], v[60:63]
	s_barrier
	s_add_u32 s50, s48, 0x80
	s_mov_b32 m0, s71
	s_addc_u32 s51, s49, 0
	ds_read_b128 v[174:177], v150 offset:49152
	ds_read_b128 v[178:181], v150 offset:50176
	ds_read_b128 v[182:185], v150 offset:51200
	ds_read_b128 v[186:189], v150 offset:52224
	ds_read_b128 v[190:193], v150 offset:53248
	ds_read_b128 v[194:197], v150 offset:54272
	ds_read_b128 v[198:201], v150 offset:55296
	ds_read_b128 v[202:205], v150 offset:56320
	s_add_u32 s48, s48, 0x80080
	global_load_lds_dwordx4 v144, s[50:51]
	s_mov_b32 m0, s72
	s_addc_u32 s49, s49, 0
	global_load_lds_dwordx4 v146, s[50:51]
	s_mov_b32 m0, s73
	s_nop 0
	global_load_lds_dwordx4 v144, s[48:49]
	s_mov_b32 m0, s74
	s_nop 0
	global_load_lds_dwordx4 v146, s[48:49]
	s_mov_b32 m0, s59
	s_nop 0
	global_load_lds_dwordx4 v143, s[46:47]
	s_mov_b32 m0, s60
	s_nop 0
	global_load_lds_dwordx4 v145, s[46:47]
	s_waitcnt vmcnt(8)
	s_waitcnt lgkmcnt(0)
	s_barrier
	s_waitcnt lgkmcnt(0)
	v_mfma_f32_16x16x32_bf16 v[64:67], v[128:131], v[174:177], v[64:67]
	v_mfma_f32_16x16x32_bf16 v[48:51], v[136:139], v[174:177], v[48:51]
	v_mfma_f32_16x16x32_bf16 v[40:43], v[128:131], v[182:185], v[40:43]
	v_mfma_f32_16x16x32_bf16 v[32:35], v[136:139], v[182:185], v[32:35]
	v_mfma_f32_16x16x32_bf16 v[24:27], v[128:131], v[190:193], v[24:27]
	v_mfma_f32_16x16x32_bf16 v[16:19], v[136:139], v[190:193], v[16:19]
	v_mfma_f32_16x16x32_bf16 v[8:11], v[128:131], v[198:201], v[8:11]
	v_mfma_f32_16x16x32_bf16 v[0:3], v[136:139], v[198:201], v[0:3]
	v_mfma_f32_16x16x32_bf16 v[64:67], v[132:135], v[178:181], v[64:67]
	v_mfma_f32_16x16x32_bf16 v[48:51], v[154:157], v[178:181], v[48:51]
	v_mfma_f32_16x16x32_bf16 v[40:43], v[132:135], v[186:189], v[40:43]
	v_mfma_f32_16x16x32_bf16 v[32:35], v[154:157], v[186:189], v[32:35]
	v_mfma_f32_16x16x32_bf16 v[24:27], v[132:135], v[194:197], v[24:27]
	v_mfma_f32_16x16x32_bf16 v[16:19], v[154:157], v[194:197], v[16:19]
	v_mfma_f32_16x16x32_bf16 v[8:11], v[132:135], v[202:205], v[8:11]
	v_mfma_f32_16x16x32_bf16 v[0:3], v[154:157], v[202:205], v[0:3]
	v_mfma_f32_16x16x32_bf16 v[72:75], v[158:161], v[174:177], v[72:75]
	v_mfma_f32_16x16x32_bf16 v[56:59], v[166:169], v[174:177], v[56:59]
	v_mfma_f32_16x16x32_bf16 v[44:47], v[158:161], v[182:185], v[44:47]
	v_mfma_f32_16x16x32_bf16 v[36:39], v[166:169], v[182:185], v[36:39]
	v_mfma_f32_16x16x32_bf16 v[28:31], v[158:161], v[190:193], v[28:31]
	v_mfma_f32_16x16x32_bf16 v[20:23], v[166:169], v[190:193], v[20:23]
	v_mfma_f32_16x16x32_bf16 v[12:15], v[158:161], v[198:201], v[12:15]
	v_mfma_f32_16x16x32_bf16 v[4:7], v[166:169], v[198:201], v[4:7]
	v_mfma_f32_16x16x32_bf16 v[72:75], v[162:165], v[178:181], v[72:75]
	v_mfma_f32_16x16x32_bf16 v[56:59], v[170:173], v[178:181], v[56:59]
	v_mfma_f32_16x16x32_bf16 v[44:47], v[162:165], v[186:189], v[44:47]
	v_mfma_f32_16x16x32_bf16 v[36:39], v[170:173], v[186:189], v[36:39]
	v_mfma_f32_16x16x32_bf16 v[28:31], v[162:165], v[194:197], v[28:31]
	v_mfma_f32_16x16x32_bf16 v[20:23], v[170:173], v[194:197], v[20:23]
	v_mfma_f32_16x16x32_bf16 v[12:15], v[162:165], v[202:205], v[12:15]
	v_mfma_f32_16x16x32_bf16 v[4:7], v[170:173], v[202:205], v[4:7]
	s_barrier
	s_add_i32 s77, s77, 2
	s_add_u32 s75, s75, 0x100
	s_addc_u32 s76, s76, 0
	s_cmp_gt_u32 s77, 29
	s_mov_b64 s[52:53], s[44:45]
	s_cbranch_scc0 .LBB0_2889
	s_and_b64 vcc, exec, s[4:5]
	s_cbranch_vccz .LBB0_2892
	s_barrier

.LBB0_2982:
	s_add_u32 s20, s48, 0x100
	s_addc_u32 s21, s49, 0
	s_waitcnt lgkmcnt(0)
	s_add_u32 s52, s4, 0x100
	s_addc_u32 s53, s5, 0
	s_barrier
	s_waitcnt lgkmcnt(0)
	v_mfma_f32_16x16x32_bf16 v[32:35], v[16:19], v[68:71], 0
	v_mfma_f32_16x16x32_bf16 v[36:39], v[24:27], v[68:71], 0
	v_mfma_f32_16x16x32_bf16 v[40:43], v[16:19], v[84:87], 0
	v_mfma_f32_16x16x32_bf16 v[44:47], v[24:27], v[84:87], 0
	v_mfma_f32_16x16x32_bf16 v[48:51], v[16:19], v[92:95], 0
	v_mfma_f32_16x16x32_bf16 v[52:55], v[24:27], v[92:95], 0
	v_mfma_f32_16x16x32_bf16 v[56:59], v[16:19], v[76:79], 0
	v_mfma_f32_16x16x32_bf16 v[60:63], v[24:27], v[76:79], 0
	v_mfma_f32_16x16x32_bf16 v[138:141], v[20:23], v[72:75], v[32:35]
	v_mfma_f32_16x16x32_bf16 v[36:39], v[28:31], v[72:75], v[36:39]
	v_mfma_f32_16x16x32_bf16 v[40:43], v[20:23], v[88:91], v[40:43]
	v_mfma_f32_16x16x32_bf16 v[44:47], v[28:31], v[88:91], v[44:47]
	v_mfma_f32_16x16x32_bf16 v[48:51], v[20:23], v[96:99], v[48:51]
	v_mfma_f32_16x16x32_bf16 v[52:55], v[28:31], v[96:99], v[52:55]
	v_mfma_f32_16x16x32_bf16 v[56:59], v[20:23], v[80:83], v[56:59]
	v_mfma_f32_16x16x32_bf16 v[60:63], v[28:31], v[80:83], v[60:63]
	v_mfma_f32_16x16x32_bf16 v[64:67], v[0:3], v[68:71], 0
	v_mfma_f32_16x16x32_bf16 v[68:71], v[8:11], v[68:71], 0
	v_mfma_f32_16x16x32_bf16 v[64:67], v[4:7], v[72:75], v[64:67]
	v_mfma_f32_16x16x32_bf16 v[68:71], v[12:15], v[72:75], v[68:71]
	v_mfma_f32_16x16x32_bf16 v[72:75], v[0:3], v[84:87], 0
	v_mfma_f32_16x16x32_bf16 v[84:87], v[8:11], v[84:87], 0
	v_mfma_f32_16x16x32_bf16 v[72:75], v[4:7], v[88:91], v[72:75]
	v_mfma_f32_16x16x32_bf16 v[84:87], v[12:15], v[88:91], v[84:87]
	v_mfma_f32_16x16x32_bf16 v[88:91], v[0:3], v[92:95], 0
	v_mfma_f32_16x16x32_bf16 v[92:95], v[8:11], v[92:95], 0
	v_mfma_f32_16x16x32_bf16 v[88:91], v[4:7], v[96:99], v[88:91]
	v_mfma_f32_16x16x32_bf16 v[92:95], v[12:15], v[96:99], v[92:95]
	v_mfma_f32_16x16x32_bf16 v[96:99], v[0:3], v[76:79], 0
	v_mfma_f32_16x16x32_bf16 v[76:79], v[8:11], v[76:79], 0
	v_mfma_f32_16x16x32_bf16 v[108:111], v[4:7], v[80:83], v[96:99]
	v_mfma_f32_16x16x32_bf16 v[112:115], v[12:15], v[80:83], v[76:79]
	s_barrier
	s_mov_b32 m0, s27
	ds_read_b128 v[120:123], v209 offset:16384
	ds_read_b128 v[124:127], v209 offset:17408
	ds_read_b128 v[104:107], v209 offset:18432
	ds_read_b128 v[116:119], v209 offset:19456
	ds_read_b128 v[96:99], v209 offset:20480
	ds_read_b128 v[100:103], v209 offset:21504
	ds_read_b128 v[76:79], v209 offset:22528
	ds_read_b128 v[80:83], v209 offset:23552
	s_nop 0
	global_load_lds_dwordx4 v203, s[52:53]
	s_mov_b32 m0, s54
	s_nop 0
	global_load_lds_dwordx4 v205, s[52:53]
	s_add_u32 s52, s4, 0x160100
	s_addc_u32 s53, s5, 0
	s_mov_b32 m0, s55
	s_and_b64 vcc, exec, s[50:51]
	global_load_lds_dwordx4 v203, s[52:53]
	s_mov_b32 m0, s56
	s_nop 0
	global_load_lds_dwordx4 v205, s[52:53]
	s_mov_b32 m0, s26
	s_mov_b64 s[52:53], -1
	global_load_lds_dwordx4 v202, s[20:21]
	s_mov_b32 m0, s57
	s_nop 0
	global_load_lds_dwordx4 v204, s[20:21]
	s_cbranch_vccz .LBB0_2984
	s_waitcnt vmcnt(8)
	s_mov_b64 s[52:53], 0

.LBB0_2986:
	s_add_u32 s50, s48, 0x180
	s_waitcnt lgkmcnt(0)
	s_addc_u32 s51, s49, 0
	s_add_u32 s52, s4, 0x180
	s_addc_u32 s53, s5, 0
	s_barrier
	s_waitcnt lgkmcnt(0)
	v_mfma_f32_16x16x32_bf16 v[128:131], v[16:19], v[120:123], 0
	v_mfma_f32_16x16x32_bf16 v[134:137], v[20:23], v[124:127], v[128:131]
	v_mfma_f32_16x16x32_bf16 v[128:131], v[24:27], v[120:123], 0
	v_mfma_f32_16x16x32_bf16 v[156:159], v[28:31], v[124:127], v[128:131]
	v_mfma_f32_16x16x32_bf16 v[128:131], v[16:19], v[104:107], 0
	v_mfma_f32_16x16x32_bf16 v[160:163], v[20:23], v[116:119], v[128:131]
	v_mfma_f32_16x16x32_bf16 v[128:131], v[24:27], v[104:107], 0
	v_mfma_f32_16x16x32_bf16 v[164:167], v[28:31], v[116:119], v[128:131]
	v_mfma_f32_16x16x32_bf16 v[128:131], v[16:19], v[96:99], 0
	v_mfma_f32_16x16x32_bf16 v[16:19], v[16:19], v[76:79], 0
	v_mfma_f32_16x16x32_bf16 v[168:171], v[20:23], v[100:103], v[128:131]
	v_mfma_f32_16x16x32_bf16 v[16:19], v[20:23], v[80:83], v[16:19]
	v_mfma_f32_16x16x32_bf16 v[20:23], v[24:27], v[76:79], 0
	v_mfma_f32_16x16x32_bf16 v[128:131], v[24:27], v[96:99], 0
	v_mfma_f32_16x16x32_bf16 v[20:23], v[28:31], v[80:83], v[20:23]
	v_mfma_f32_16x16x32_bf16 v[172:175], v[28:31], v[100:103], v[128:131]
	v_mfma_f32_16x16x32_bf16 v[24:27], v[0:3], v[120:123], 0
	v_mfma_f32_16x16x32_bf16 v[176:179], v[4:7], v[124:127], v[24:27]
	v_mfma_f32_16x16x32_bf16 v[24:27], v[8:11], v[120:123], 0
	v_mfma_f32_16x16x32_bf16 v[180:183], v[12:15], v[124:127], v[24:27]
	v_mfma_f32_16x16x32_bf16 v[24:27], v[0:3], v[104:107], 0
	v_mfma_f32_16x16x32_bf16 v[186:189], v[4:7], v[116:119], v[24:27]
	v_mfma_f32_16x16x32_bf16 v[24:27], v[8:11], v[104:107], 0
	v_mfma_f32_16x16x32_bf16 v[190:193], v[12:15], v[116:119], v[24:27]
	v_mfma_f32_16x16x32_bf16 v[24:27], v[0:3], v[96:99], 0
	v_mfma_f32_16x16x32_bf16 v[0:3], v[0:3], v[76:79], 0
	v_mfma_f32_16x16x32_bf16 v[194:197], v[4:7], v[100:103], v[24:27]
	v_mfma_f32_16x16x32_bf16 v[24:27], v[8:11], v[96:99], 0
	v_mfma_f32_16x16x32_bf16 v[0:3], v[4:7], v[80:83], v[0:3]
	v_mfma_f32_16x16x32_bf16 v[4:7], v[8:11], v[76:79], 0
	v_mfma_f32_16x16x32_bf16 v[198:201], v[12:15], v[100:103], v[24:27]
	v_mfma_f32_16x16x32_bf16 v[212:215], v[12:15], v[80:83], v[4:7]
	s_barrier
	v_add_u32_e32 v132, s67, v206
	v_add_u32_e32 v133, s68, v206
	s_nop 1
	ds_read_b128 v[4:7], v132
	ds_read_b128 v[8:11], v132 offset:1024
	ds_read_b128 v[216:219], v132 offset:2048
	ds_read_b128 v[220:223], v132 offset:3072
	ds_read_b128 v[224:227], v133
	ds_read_b128 v[228:231], v133 offset:1024
	ds_read_b128 v[232:235], v133 offset:2048
	ds_read_b128 v[236:239], v133 offset:3072
	s_add_u32 s20, s48, 0x160100
	s_addc_u32 s21, s49, 0
	s_mov_b32 m0, s58
	ds_read_b128 v[12:15], v209 offset:32768
	ds_read_b128 v[24:27], v209 offset:33792
	ds_read_b128 v[28:31], v209 offset:34816
	ds_read_b128 v[96:99], v209 offset:35840
	ds_read_b128 v[240:243], v209 offset:36864
	ds_read_b128 v[244:247], v209 offset:37888
	ds_read_b128 v[248:251], v209 offset:38912
	ds_read_b128 v[32:35], v209 offset:39936
	s_nop 0
	global_load_lds_dwordx4 v202, s[20:21]
	s_mov_b32 m0, s59
	s_nop 0
	global_load_lds_dwordx4 v204, s[20:21]
	s_waitcnt vmcnt(8)
	s_waitcnt lgkmcnt(0)
	s_barrier
	s_waitcnt lgkmcnt(0)
	v_mfma_f32_16x16x32_bf16 v[36:39], v[216:219], v[12:15], v[36:39]
	v_mfma_f32_16x16x32_bf16 v[148:151], v[220:223], v[24:27], v[36:39]
	v_mfma_f32_16x16x32_bf16 v[36:39], v[4:7], v[28:31], v[40:43]
	v_mfma_f32_16x16x32_bf16 v[128:131], v[8:11], v[96:99], v[36:39]
	v_mfma_f32_16x16x32_bf16 v[36:39], v[216:219], v[28:31], v[44:47]
	v_mfma_f32_16x16x32_bf16 v[124:127], v[220:223], v[96:99], v[36:39]
	v_mfma_f32_16x16x32_bf16 v[36:39], v[4:7], v[240:243], v[48:51]
	v_mfma_f32_16x16x32_bf16 v[104:107], v[8:11], v[244:247], v[36:39]
	v_mfma_f32_16x16x32_bf16 v[36:39], v[216:219], v[240:243], v[52:55]
	v_mfma_f32_16x16x32_bf16 v[100:103], v[220:223], v[244:247], v[36:39]
	v_mfma_f32_16x16x32_bf16 v[36:39], v[4:7], v[248:251], v[56:59]
	v_mfma_f32_16x16x32_bf16 v[76:79], v[4:7], v[12:15], v[138:141]
	v_mfma_f32_16x16x32_bf16 v[80:83], v[8:11], v[32:35], v[36:39]
	v_mfma_f32_16x16x32_bf16 v[36:39], v[216:219], v[248:251], v[60:63]
	v_mfma_f32_16x16x32_bf16 v[152:155], v[8:11], v[24:27], v[76:79]
	v_mfma_f32_16x16x32_bf16 v[76:79], v[220:223], v[32:35], v[36:39]
	v_mfma_f32_16x16x32_bf16 v[36:39], v[224:227], v[12:15], v[64:67]
	v_mfma_f32_16x16x32_bf16 v[12:15], v[232:235], v[12:15], v[68:71]
	v_mfma_f32_16x16x32_bf16 v[140:143], v[236:239], v[24:27], v[12:15]
	v_mfma_f32_16x16x32_bf16 v[12:15], v[224:227], v[28:31], v[72:75]
	v_mfma_f32_16x16x32_bf16 v[120:123], v[228:231], v[96:99], v[12:15]
	v_mfma_f32_16x16x32_bf16 v[12:15], v[232:235], v[28:31], v[84:87]
	v_mfma_f32_16x16x32_bf16 v[116:119], v[236:239], v[96:99], v[12:15]
	v_mfma_f32_16x16x32_bf16 v[12:15], v[224:227], v[240:243], v[88:91]
	v_mfma_f32_16x16x32_bf16 v[96:99], v[228:231], v[244:247], v[12:15]
	v_mfma_f32_16x16x32_bf16 v[12:15], v[232:235], v[240:243], v[92:95]
	v_mfma_f32_16x16x32_bf16 v[92:95], v[236:239], v[244:247], v[12:15]
	v_mfma_f32_16x16x32_bf16 v[12:15], v[224:227], v[248:251], v[108:111]
	v_mfma_f32_16x16x32_bf16 v[72:75], v[228:231], v[32:35], v[12:15]
	v_mfma_f32_16x16x32_bf16 v[12:15], v[232:235], v[248:251], v[112:115]
	v_mfma_f32_16x16x32_bf16 v[144:147], v[228:231], v[24:27], v[36:39]
	v_mfma_f32_16x16x32_bf16 v[68:71], v[236:239], v[32:35], v[12:15]
	s_barrier
	s_add_i32 s12, s67, s25
	s_mov_b32 m0, s12
	s_add_i32 s20, s12, 0x2000
	ds_read_b128 v[32:35], v209 offset:49152
	ds_read_b128 v[36:39], v209 offset:50176
	ds_read_b128 v[60:63], v209 offset:51200
	ds_read_b128 v[84:87], v209 offset:52224
	ds_read_b128 v[88:91], v209 offset:53248
	ds_read_b128 v[108:111], v209 offset:54272
	ds_read_b128 v[112:115], v209 offset:55296
	ds_read_b128 v[240:243], v209 offset:56320
	s_nop 0
	global_load_lds_dwordx4 v203, s[52:53]
	s_mov_b32 m0, s20
	s_nop 0
	global_load_lds_dwordx4 v205, s[52:53]
	s_add_u32 s52, s4, 0x160180
	s_addc_u32 s53, s5, 0
	s_add_i32 s21, s68, s25
	s_mov_b32 m0, s21
	s_add_i32 s72, s21, 0x2000
	s_nop 0
	global_load_lds_dwordx4 v203, s[52:53]
	s_mov_b32 m0, s72
	s_nop 0
	global_load_lds_dwordx4 v205, s[52:53]
	s_mov_b32 m0, s60
	s_nop 0
	global_load_lds_dwordx4 v202, s[50:51]
	s_mov_b32 m0, s61
	s_nop 0
	global_load_lds_dwordx4 v204, s[50:51]
	s_waitcnt vmcnt(8)
	s_waitcnt lgkmcnt(0)
	s_barrier
	s_waitcnt lgkmcnt(0)
	v_mfma_f32_16x16x32_bf16 v[12:15], v[4:7], v[32:35], v[134:137]
	v_mfma_f32_16x16x32_bf16 v[64:67], v[8:11], v[36:39], v[12:15]
	v_mfma_f32_16x16x32_bf16 v[12:15], v[216:219], v[32:35], v[156:159]
	v_mfma_f32_16x16x32_bf16 v[56:59], v[220:223], v[36:39], v[12:15]
	v_mfma_f32_16x16x32_bf16 v[12:15], v[4:7], v[60:63], v[160:163]
	v_mfma_f32_16x16x32_bf16 v[44:47], v[8:11], v[84:87], v[12:15]
	v_mfma_f32_16x16x32_bf16 v[12:15], v[216:219], v[60:63], v[164:167]
	v_mfma_f32_16x16x32_bf16 v[40:43], v[220:223], v[84:87], v[12:15]
	v_mfma_f32_16x16x32_bf16 v[12:15], v[4:7], v[88:91], v[168:171]
	v_mfma_f32_16x16x32_bf16 v[28:31], v[8:11], v[108:111], v[12:15]
	v_mfma_f32_16x16x32_bf16 v[12:15], v[216:219], v[88:91], v[172:175]
	v_mfma_f32_16x16x32_bf16 v[4:7], v[4:7], v[112:115], v[16:19]
	v_mfma_f32_16x16x32_bf16 v[24:27], v[220:223], v[108:111], v[12:15]
	v_mfma_f32_16x16x32_bf16 v[12:15], v[8:11], v[240:243], v[4:7]
	v_mfma_f32_16x16x32_bf16 v[4:7], v[216:219], v[112:115], v[20:23]
	v_mfma_f32_16x16x32_bf16 v[8:11], v[220:223], v[240:243], v[4:7]
	v_mfma_f32_16x16x32_bf16 v[4:7], v[224:227], v[32:35], v[176:179]
	v_mfma_f32_16x16x32_bf16 v[52:55], v[228:231], v[36:39], v[4:7]
	v_mfma_f32_16x16x32_bf16 v[4:7], v[232:235], v[32:35], v[180:183]
	v_mfma_f32_16x16x32_bf16 v[48:51], v[236:239], v[36:39], v[4:7]
	v_mfma_f32_16x16x32_bf16 v[4:7], v[224:227], v[60:63], v[186:189]
	v_mfma_f32_16x16x32_bf16 v[36:39], v[228:231], v[84:87], v[4:7]
	v_mfma_f32_16x16x32_bf16 v[4:7], v[232:235], v[60:63], v[190:193]
	v_mfma_f32_16x16x32_bf16 v[32:35], v[236:239], v[84:87], v[4:7]
	v_mfma_f32_16x16x32_bf16 v[4:7], v[224:227], v[88:91], v[194:197]
	v_mfma_f32_16x16x32_bf16 v[20:23], v[228:231], v[108:111], v[4:7]
	v_mfma_f32_16x16x32_bf16 v[4:7], v[232:235], v[88:91], v[198:201]
	v_mfma_f32_16x16x32_bf16 v[0:3], v[224:227], v[112:115], v[0:3]
	v_mfma_f32_16x16x32_bf16 v[16:19], v[236:239], v[108:111], v[4:7]
	v_mfma_f32_16x16x32_bf16 v[4:7], v[228:231], v[240:243], v[0:3]
	v_mfma_f32_16x16x32_bf16 v[0:3], v[232:235], v[112:115], v[212:215]
	v_mfma_f32_16x16x32_bf16 v[0:3], v[236:239], v[240:243], v[0:3]
	s_barrier
	s_add_u32 s73, s48, 0x200
	s_addc_u32 s74, s49, 0
	s_add_u32 s75, s4, 0x200
	s_addc_u32 s76, s5, 0
	s_add_u32 s4, s48, 0x160180
	s_addc_u32 s5, s49, 0
	s_mov_b32 s77, 0
.LBB0_2987:
	s_cmpk_eq_i32 s77, 0x54
	s_cselect_b32 s52, s44, s73
	s_cselect_b32 s53, s45, s74
	s_cselect_b32 s50, s46, s75
	s_cselect_b32 s51, s47, s76
	s_add_u32 s48, s52, 0x80
	s_addc_u32 s49, s53, 0
	s_add_i32 s78, 0, 0x10000
	s_add_i32 s80, 0, 0x14000
	v_add_u32_e32 v108, s78, v206
	v_add_u32_e32 v138, s80, v206
	ds_read_b128 v[60:63], v108
	ds_read_b128 v[84:87], v108 offset:1024
	ds_read_b128 v[88:91], v108 offset:2048
	ds_read_b128 v[108:111], v108 offset:3072
	ds_read_b128 v[112:115], v138
	ds_read_b128 v[134:137], v138 offset:1024
	ds_read_b128 v[156:159], v138 offset:2048
	ds_read_b128 v[160:163], v138 offset:3072
	s_mov_b32 m0, s0
	ds_read_b128 v[164:167], v209
	ds_read_b128 v[168:171], v209 offset:1024
	ds_read_b128 v[172:175], v209 offset:2048
	ds_read_b128 v[176:179], v209 offset:3072
	ds_read_b128 v[180:183], v209 offset:4096
	ds_read_b128 v[186:189], v209 offset:5120
	ds_read_b128 v[190:193], v209 offset:6144
	ds_read_b128 v[194:197], v209 offset:7168
	s_nop 0
	global_load_lds_dwordx4 v202, s[4:5]
	s_mov_b32 m0, s1
	s_nop 0
	global_load_lds_dwordx4 v204, s[4:5]
	s_waitcnt vmcnt(8)
	s_waitcnt lgkmcnt(0)
	s_barrier
	s_waitcnt lgkmcnt(0)
	v_mfma_f32_16x16x32_bf16 v[152:155], v[60:63], v[164:167], v[152:155]
	v_mfma_f32_16x16x32_bf16 v[148:151], v[88:91], v[164:167], v[148:151]
	v_mfma_f32_16x16x32_bf16 v[128:131], v[60:63], v[172:175], v[128:131]
	v_mfma_f32_16x16x32_bf16 v[124:127], v[88:91], v[172:175], v[124:127]
	v_mfma_f32_16x16x32_bf16 v[104:107], v[60:63], v[180:183], v[104:107]
	v_mfma_f32_16x16x32_bf16 v[100:103], v[88:91], v[180:183], v[100:103]
	v_mfma_f32_16x16x32_bf16 v[80:83], v[60:63], v[190:193], v[80:83]
	v_mfma_f32_16x16x32_bf16 v[76:79], v[88:91], v[190:193], v[76:79]
	v_mfma_f32_16x16x32_bf16 v[152:155], v[84:87], v[168:171], v[152:155]
	v_mfma_f32_16x16x32_bf16 v[148:151], v[108:111], v[168:171], v[148:151]
	v_mfma_f32_16x16x32_bf16 v[128:131], v[84:87], v[176:179], v[128:131]
	v_mfma_f32_16x16x32_bf16 v[124:127], v[108:111], v[176:179], v[124:127]
	v_mfma_f32_16x16x32_bf16 v[104:107], v[84:87], v[186:189], v[104:107]
	v_mfma_f32_16x16x32_bf16 v[100:103], v[108:111], v[186:189], v[100:103]
	v_mfma_f32_16x16x32_bf16 v[80:83], v[84:87], v[194:197], v[80:83]
	v_mfma_f32_16x16x32_bf16 v[76:79], v[108:111], v[194:197], v[76:79]
	v_mfma_f32_16x16x32_bf16 v[144:147], v[112:115], v[164:167], v[144:147]
	v_mfma_f32_16x16x32_bf16 v[138:141], v[156:159], v[164:167], v[140:143]
	v_mfma_f32_16x16x32_bf16 v[120:123], v[112:115], v[172:175], v[120:123]
	v_mfma_f32_16x16x32_bf16 v[116:119], v[156:159], v[172:175], v[116:119]
	v_mfma_f32_16x16x32_bf16 v[96:99], v[112:115], v[180:183], v[96:99]
	v_mfma_f32_16x16x32_bf16 v[92:95], v[156:159], v[180:183], v[92:95]
	v_mfma_f32_16x16x32_bf16 v[72:75], v[112:115], v[190:193], v[72:75]
	v_mfma_f32_16x16x32_bf16 v[68:71], v[156:159], v[190:193], v[68:71]
	v_mfma_f32_16x16x32_bf16 v[144:147], v[134:137], v[168:171], v[144:147]
	v_mfma_f32_16x16x32_bf16 v[138:141], v[160:163], v[168:171], v[138:141]
	v_mfma_f32_16x16x32_bf16 v[120:123], v[134:137], v[176:179], v[120:123]
	v_mfma_f32_16x16x32_bf16 v[116:119], v[160:163], v[176:179], v[116:119]
	v_mfma_f32_16x16x32_bf16 v[96:99], v[134:137], v[186:189], v[96:99]
	v_mfma_f32_16x16x32_bf16 v[92:95], v[160:163], v[186:189], v[92:95]
	v_mfma_f32_16x16x32_bf16 v[72:75], v[134:137], v[194:197], v[72:75]
	v_mfma_f32_16x16x32_bf16 v[68:71], v[160:163], v[194:197], v[68:71]
	s_barrier
	s_add_i32 s78, s78, s25
	s_mov_b32 m0, s78
	ds_read_b128 v[164:167], v209 offset:16384
	ds_read_b128 v[168:171], v209 offset:17408
	ds_read_b128 v[172:175], v209 offset:18432
	ds_read_b128 v[176:179], v209 offset:19456
	ds_read_b128 v[180:183], v209 offset:20480
	ds_read_b128 v[186:189], v209 offset:21504
	ds_read_b128 v[190:193], v209 offset:22528
	ds_read_b128 v[194:197], v209 offset:23552
	s_nop 0
	global_load_lds_dwordx4 v203, s[50:51]
	s_add_i32 m0, s78, 0x2000
	s_add_u32 s78, s50, 0x160000
	s_addc_u32 s79, s51, 0
	s_add_i32 s80, s80, s25
	s_nop 0
	global_load_lds_dwordx4 v205, s[50:51]
	s_mov_b32 m0, s80
	s_nop 0
	global_load_lds_dwordx4 v203, s[78:79]
	s_add_i32 m0, s80, 0x2000
	s_nop 0
	global_load_lds_dwordx4 v205, s[78:79]
	s_mov_b32 m0, s26
	s_nop 0
	global_load_lds_dwordx4 v202, s[52:53]
	s_mov_b32 m0, s57
	s_nop 0
	global_load_lds_dwordx4 v204, s[52:53]
	s_waitcnt vmcnt(8)
	s_waitcnt lgkmcnt(0)
	s_barrier
	s_waitcnt lgkmcnt(0)
	v_mfma_f32_16x16x32_bf16 v[64:67], v[60:63], v[164:167], v[64:67]
	v_mfma_f32_16x16x32_bf16 v[56:59], v[88:91], v[164:167], v[56:59]
	v_mfma_f32_16x16x32_bf16 v[44:47], v[60:63], v[172:175], v[44:47]
	v_mfma_f32_16x16x32_bf16 v[40:43], v[88:91], v[172:175], v[40:43]
	v_mfma_f32_16x16x32_bf16 v[28:31], v[60:63], v[180:183], v[28:31]
	v_mfma_f32_16x16x32_bf16 v[24:27], v[88:91], v[180:183], v[24:27]
	v_mfma_f32_16x16x32_bf16 v[12:15], v[60:63], v[190:193], v[12:15]
	v_mfma_f32_16x16x32_bf16 v[8:11], v[88:91], v[190:193], v[8:11]
	v_mfma_f32_16x16x32_bf16 v[64:67], v[84:87], v[168:171], v[64:67]
	v_mfma_f32_16x16x32_bf16 v[56:59], v[108:111], v[168:171], v[56:59]
	v_mfma_f32_16x16x32_bf16 v[44:47], v[84:87], v[176:179], v[44:47]
	v_mfma_f32_16x16x32_bf16 v[40:43], v[108:111], v[176:179], v[40:43]
	v_mfma_f32_16x16x32_bf16 v[28:31], v[84:87], v[186:189], v[28:31]
	v_mfma_f32_16x16x32_bf16 v[24:27], v[108:111], v[186:189], v[24:27]
	v_mfma_f32_16x16x32_bf16 v[12:15], v[84:87], v[194:197], v[12:15]
	v_mfma_f32_16x16x32_bf16 v[8:11], v[108:111], v[194:197], v[8:11]
	v_mfma_f32_16x16x32_bf16 v[52:55], v[112:115], v[164:167], v[52:55]
	v_mfma_f32_16x16x32_bf16 v[48:51], v[156:159], v[164:167], v[48:51]
	v_mfma_f32_16x16x32_bf16 v[36:39], v[112:115], v[172:175], v[36:39]
	v_mfma_f32_16x16x32_bf16 v[32:35], v[156:159], v[172:175], v[32:35]
	v_mfma_f32_16x16x32_bf16 v[20:23], v[112:115], v[180:183], v[20:23]
	v_mfma_f32_16x16x32_bf16 v[16:19], v[156:159], v[180:183], v[16:19]
	v_mfma_f32_16x16x32_bf16 v[4:7], v[112:115], v[190:193], v[4:7]
	v_mfma_f32_16x16x32_bf16 v[0:3], v[156:159], v[190:193], v[0:3]
	v_mfma_f32_16x16x32_bf16 v[52:55], v[134:137], v[168:171], v[52:55]
	v_mfma_f32_16x16x32_bf16 v[48:51], v[160:163], v[168:171], v[48:51]
	v_mfma_f32_16x16x32_bf16 v[36:39], v[134:137], v[176:179], v[36:39]
	v_mfma_f32_16x16x32_bf16 v[32:35], v[160:163], v[176:179], v[32:35]
	v_mfma_f32_16x16x32_bf16 v[20:23], v[134:137], v[186:189], v[20:23]
	v_mfma_f32_16x16x32_bf16 v[16:19], v[160:163], v[186:189], v[16:19]
	v_mfma_f32_16x16x32_bf16 v[4:7], v[134:137], v[194:197], v[4:7]
	v_mfma_f32_16x16x32_bf16 v[0:3], v[160:163], v[194:197], v[0:3]
	s_barrier
	ds_read_b128 v[60:63], v132
	ds_read_b128 v[84:87], v132 offset:1024
	ds_read_b128 v[88:91], v132 offset:2048
	ds_read_b128 v[108:111], v132 offset:3072
	ds_read_b128 v[112:115], v133
	ds_read_b128 v[134:137], v133 offset:1024
	ds_read_b128 v[156:159], v133 offset:2048
	ds_read_b128 v[160:163], v133 offset:3072
	s_add_u32 s52, s52, 0x160000
	s_addc_u32 s53, s53, 0
	s_mov_b32 m0, s58
	ds_read_b128 v[164:167], v209 offset:32768
	ds_read_b128 v[168:171], v209 offset:33792
	ds_read_b128 v[172:175], v209 offset:34816
	ds_read_b128 v[176:179], v209 offset:35840
	ds_read_b128 v[180:183], v209 offset:36864
	ds_read_b128 v[186:189], v209 offset:37888
	ds_read_b128 v[190:193], v209 offset:38912
	ds_read_b128 v[194:197], v209 offset:39936
	s_nop 0
	global_load_lds_dwordx4 v202, s[52:53]
	s_mov_b32 m0, s59
	s_nop 0
	global_load_lds_dwordx4 v204, s[52:53]
	s_waitcnt vmcnt(8)
	s_waitcnt lgkmcnt(0)
	s_barrier
	s_waitcnt lgkmcnt(0)
	v_mfma_f32_16x16x32_bf16 v[152:155], v[60:63], v[164:167], v[152:155]
	v_mfma_f32_16x16x32_bf16 v[148:151], v[88:91], v[164:167], v[148:151]
	v_mfma_f32_16x16x32_bf16 v[128:131], v[60:63], v[172:175], v[128:131]
	v_mfma_f32_16x16x32_bf16 v[124:127], v[88:91], v[172:175], v[124:127]
	v_mfma_f32_16x16x32_bf16 v[104:107], v[60:63], v[180:183], v[104:107]
	v_mfma_f32_16x16x32_bf16 v[100:103], v[88:91], v[180:183], v[100:103]
	v_mfma_f32_16x16x32_bf16 v[80:83], v[60:63], v[190:193], v[80:83]
	v_mfma_f32_16x16x32_bf16 v[76:79], v[88:91], v[190:193], v[76:79]
	v_mfma_f32_16x16x32_bf16 v[152:155], v[84:87], v[168:171], v[152:155]
	v_mfma_f32_16x16x32_bf16 v[148:151], v[108:111], v[168:171], v[148:151]
	v_mfma_f32_16x16x32_bf16 v[128:131], v[84:87], v[176:179], v[128:131]
	v_mfma_f32_16x16x32_bf16 v[124:127], v[108:111], v[176:179], v[124:127]
	v_mfma_f32_16x16x32_bf16 v[104:107], v[84:87], v[186:189], v[104:107]
	v_mfma_f32_16x16x32_bf16 v[100:103], v[108:111], v[186:189], v[100:103]
	v_mfma_f32_16x16x32_bf16 v[80:83], v[84:87], v[194:197], v[80:83]
	v_mfma_f32_16x16x32_bf16 v[76:79], v[108:111], v[194:197], v[76:79]
	v_mfma_f32_16x16x32_bf16 v[142:145], v[112:115], v[164:167], v[144:147]
	v_mfma_f32_16x16x32_bf16 v[138:141], v[156:159], v[164:167], v[138:141]
	v_mfma_f32_16x16x32_bf16 v[120:123], v[112:115], v[172:175], v[120:123]
	v_mfma_f32_16x16x32_bf16 v[116:119], v[156:159], v[172:175], v[116:119]
	v_mfma_f32_16x16x32_bf16 v[96:99], v[112:115], v[180:183], v[96:99]
	v_mfma_f32_16x16x32_bf16 v[92:95], v[156:159], v[180:183], v[92:95]
	v_mfma_f32_16x16x32_bf16 v[72:75], v[112:115], v[190:193], v[72:75]
	v_mfma_f32_16x16x32_bf16 v[68:71], v[156:159], v[190:193], v[68:71]
	v_mfma_f32_16x16x32_bf16 v[144:147], v[134:137], v[168:171], v[142:145]
	v_mfma_f32_16x16x32_bf16 v[140:143], v[160:163], v[168:171], v[138:141]
	v_mfma_f32_16x16x32_bf16 v[120:123], v[134:137], v[176:179], v[120:123]
	v_mfma_f32_16x16x32_bf16 v[116:119], v[160:163], v[176:179], v[116:119]
	v_mfma_f32_16x16x32_bf16 v[96:99], v[134:137], v[186:189], v[96:99]
	v_mfma_f32_16x16x32_bf16 v[92:95], v[160:163], v[186:189], v[92:95]
	v_mfma_f32_16x16x32_bf16 v[72:75], v[134:137], v[194:197], v[72:75]
	v_mfma_f32_16x16x32_bf16 v[68:71], v[160:163], v[194:197], v[68:71]
	s_barrier
	s_add_u32 s52, s50, 0x80
	s_mov_b32 m0, s12
	s_addc_u32 s53, s51, 0
	ds_read_b128 v[164:167], v209 offset:49152
	ds_read_b128 v[168:171], v209 offset:50176
	ds_read_b128 v[172:175], v209 offset:51200
	ds_read_b128 v[176:179], v209 offset:52224
	ds_read_b128 v[180:183], v209 offset:53248
	ds_read_b128 v[186:189], v209 offset:54272
	ds_read_b128 v[190:193], v209 offset:55296
	ds_read_b128 v[194:197], v209 offset:56320
	s_add_u32 s50, s50, 0x160080
	global_load_lds_dwordx4 v203, s[52:53]
	s_mov_b32 m0, s20
	s_addc_u32 s51, s51, 0
	global_load_lds_dwordx4 v205, s[52:53]
	s_mov_b32 m0, s21
	s_nop 0
	global_load_lds_dwordx4 v203, s[50:51]
	s_mov_b32 m0, s72
	s_nop 0
	global_load_lds_dwordx4 v205, s[50:51]
	s_mov_b32 m0, s60
	s_nop 0
	global_load_lds_dwordx4 v202, s[48:49]
	s_mov_b32 m0, s61
	s_nop 0
	global_load_lds_dwordx4 v204, s[48:49]
	s_waitcnt vmcnt(8)
	s_waitcnt lgkmcnt(0)
	s_barrier
	s_waitcnt lgkmcnt(0)
	v_mfma_f32_16x16x32_bf16 v[64:67], v[60:63], v[164:167], v[64:67]
	v_mfma_f32_16x16x32_bf16 v[56:59], v[88:91], v[164:167], v[56:59]
	v_mfma_f32_16x16x32_bf16 v[44:47], v[60:63], v[172:175], v[44:47]
	v_mfma_f32_16x16x32_bf16 v[40:43], v[88:91], v[172:175], v[40:43]
	v_mfma_f32_16x16x32_bf16 v[28:31], v[60:63], v[180:183], v[28:31]
	v_mfma_f32_16x16x32_bf16 v[24:27], v[88:91], v[180:183], v[24:27]
	v_mfma_f32_16x16x32_bf16 v[12:15], v[60:63], v[190:193], v[12:15]
	v_mfma_f32_16x16x32_bf16 v[8:11], v[88:91], v[190:193], v[8:11]
	v_mfma_f32_16x16x32_bf16 v[64:67], v[84:87], v[168:171], v[64:67]
	v_mfma_f32_16x16x32_bf16 v[56:59], v[108:111], v[168:171], v[56:59]
	v_mfma_f32_16x16x32_bf16 v[44:47], v[84:87], v[176:179], v[44:47]
	v_mfma_f32_16x16x32_bf16 v[40:43], v[108:111], v[176:179], v[40:43]
	v_mfma_f32_16x16x32_bf16 v[28:31], v[84:87], v[186:189], v[28:31]
	v_mfma_f32_16x16x32_bf16 v[24:27], v[108:111], v[186:189], v[24:27]
	v_mfma_f32_16x16x32_bf16 v[12:15], v[84:87], v[194:197], v[12:15]
	v_mfma_f32_16x16x32_bf16 v[8:11], v[108:111], v[194:197], v[8:11]
	v_mfma_f32_16x16x32_bf16 v[52:55], v[112:115], v[164:167], v[52:55]
	v_mfma_f32_16x16x32_bf16 v[48:51], v[156:159], v[164:167], v[48:51]
	v_mfma_f32_16x16x32_bf16 v[36:39], v[112:115], v[172:175], v[36:39]
	v_mfma_f32_16x16x32_bf16 v[32:35], v[156:159], v[172:175], v[32:35]
	v_mfma_f32_16x16x32_bf16 v[20:23], v[112:115], v[180:183], v[20:23]
	v_mfma_f32_16x16x32_bf16 v[16:19], v[156:159], v[180:183], v[16:19]
	v_mfma_f32_16x16x32_bf16 v[4:7], v[112:115], v[190:193], v[4:7]
	v_mfma_f32_16x16x32_bf16 v[0:3], v[156:159], v[190:193], v[0:3]
	v_mfma_f32_16x16x32_bf16 v[52:55], v[134:137], v[168:171], v[52:55]
	v_mfma_f32_16x16x32_bf16 v[48:51], v[160:163], v[168:171], v[48:51]
	v_mfma_f32_16x16x32_bf16 v[36:39], v[134:137], v[176:179], v[36:39]
	v_mfma_f32_16x16x32_bf16 v[32:35], v[160:163], v[176:179], v[32:35]
	v_mfma_f32_16x16x32_bf16 v[20:23], v[134:137], v[186:189], v[20:23]
	v_mfma_f32_16x16x32_bf16 v[16:19], v[160:163], v[186:189], v[16:19]
	v_mfma_f32_16x16x32_bf16 v[4:7], v[134:137], v[194:197], v[4:7]
	v_mfma_f32_16x16x32_bf16 v[0:3], v[160:163], v[194:197], v[0:3]
	s_barrier
	s_add_i32 s77, s77, 2
	s_add_u32 s73, s73, 0x100
	s_addc_u32 s74, s74, 0
	s_add_u32 s75, s75, 0x100
	s_addc_u32 s76, s76, 0
	s_add_u32 s4, s4, 0x100
	s_addc_u32 s5, s5, 0
	s_cmpk_gt_u32 s77, 0x55
	s_cbranch_scc0 .LBB0_2987
	s_and_b64 vcc, exec, s[34:35]
	s_cbranch_vccz .LBB0_2990
	s_barrier
